# residual-GEMM phases (FFN-down, out-proj, xo-proj) back to the baseline LDS-DMA placement (all 6 pieces in the load segment); other GEMMs keep the 14/30 placement
# speedup vs baseline: 1.0116x; 1.0104x over previous
; #define PG8_STAGE(bufoff, gbase, voff) do { _Pragma("unroll") for (int _i = 0; _i < 2; ++_i) \
;         __builtin_amdgcn_global_load_lds((const unsigned*)((const char*)(gbase) + (voff)[_i]), (PG8_LAS unsigned*)(lds + (bufoff) + ldsw + _i * 8192), 16, 0, 0); } while (0)
; #define PG8_LDA(dst, b, h) do { _Pragma("unroll") for (int m = 0; m < 4; ++m) _Pragma("unroll") for (int k = 0; k < 2; ++k) dst[m][k] = *(const PG8_LAS bf16x8*)(lds + PG8_SA(b, h) + aoff + m * 2048 + k * 1024); } while (0)
; #define PG8_LDB(dst, b, h) do { _Pragma("unroll") for (int n = 0; n < 2; ++n) _Pragma("unroll") for (int k = 0; k < 2; ++k) dst[n][k] = *(const PG8_LAS bf16x8*)(lds + PG8_SB(b, h) + boff + n * 2048 + k * 1024); } while (0)
; #define PG8_MMA(ai, bj, At, Bt) do { __builtin_amdgcn_s_setprio(1); _Pragma("unroll") for (int m = 0; m < 4; ++m) _Pragma("unroll") for (int n = 0; n < 2; ++n) _Pragma("unroll") for (int k = 0; k < 2; ++k) \
;         acc[ai][bj][m][n] = __builtin_amdgcn_mfma_f32_16x16x32_bf16(Bt[n][k], At[m][k], acc[ai][bj][m][n], 0, 0, 0); __builtin_amdgcn_s_setprio(0); } while (0)
; #define PG8_WAIT_V(n) asm volatile("s_waitcnt vmcnt(" #n ")" ::: "memory")
; #define PG8_WAIT_L(n) asm volatile("s_waitcnt lgkmcnt(" #n ")" ::: "memory")
; #define PG8_BAR __builtin_amdgcn_s_barrier()
; #define PG8_SCHED __builtin_amdgcn_sched_barrier(0)
; template <class Epi, class Sched, bool ALIGN_EPI = false, bool SP2 = false>
; __device__ __forceinline__ void gemm_phase(PG8_LAS unsigned char* lds, const Gemm g, const Sched& S, const Epi& E) {
;     ...
;             PG8_LDB(B0, 0, 0); PG8_LDB(B1, 0, 1); PG8_SCHED; PG8_LDA(At, 0, 0); PG8_STAGE(PG8_SA(1, 1), a1 + hstep, voffA);
;             PG8_WAIT_V(8); PG8_WAIT_L(0); PG8_BAR; PG8_MMA(0, 0, At, B0); PG8_MMA(0, 1, At, B1); PG8_BAR; PG8_SCHED;
;             PG8_LDA(At, 0, 1); PG8_STAGE(PG8_SB(0, 0), b2, voffB); PG8_STAGE(PG8_SB(0, 1), b2 + hstep, voffB); PG8_STAGE(PG8_SA(0, 0), a2, voffA);
.LBB0_268:
	s_add_u32 s91, s50, 0x100
	s_addc_u32 s92, s51, 0
	s_mov_b32 s93, -2
	s_waitcnt lgkmcnt(0)
	ds_read_b128 v[128:131], v165
	ds_read_b128 v[132:135], v165 offset:1024
	ds_read_b128 v[152:155], v165 offset:2048
	ds_read_b128 v[156:159], v165 offset:3072
	ds_read_b128 v[172:175], v168
	ds_read_b128 v[176:179], v168 offset:1024
	ds_read_b128 v[182:185], v168 offset:2048
	ds_read_b128 v[186:189], v168 offset:3072
	s_add_u32 s50, s10, 0x100
	s_addc_u32 s51, s11, 0
	s_cmp_eq_u32 s93, 40
	s_cselect_b32 s57, s1, s51
	s_cselect_b32 s56, s0, s50
	s_cselect_b32 s55, s49, s92
	s_cselect_b32 s54, s48, s91
	v_lshl_add_u64 v[160:161], s[10:11], 0, v[144:145]
	s_add_i32 m0, s58, 0xc000
	ds_read_b128 v[190:193], v169
	ds_read_b128 v[194:197], v169 offset:1024
	ds_read_b128 v[198:201], v169 offset:2048
	ds_read_b128 v[208:211], v169 offset:3072
	ds_read_b128 v[212:215], v169 offset:4096
	ds_read_b128 v[216:219], v169 offset:5120
	ds_read_b128 v[220:223], v169 offset:6144
	ds_read_b128 v[224:227], v169 offset:7168
	global_load_lds_dwordx4 v[160:161], off
	v_lshl_add_u64 v[160:161], s[10:11], 0, v[146:147]
	s_add_i32 m0, s58, 0xe000
	s_nop 0
	global_load_lds_dwordx4 v[160:161], off
	s_waitcnt vmcnt(8)
	s_waitcnt lgkmcnt(0)
	s_barrier
	s_setprio 1
	s_waitcnt lgkmcnt(0)
	v_mfma_f32_16x16x32_bf16 v[124:127], v[128:131], v[190:193], 0
	v_mfma_f32_16x16x32_bf16 v[120:123], v[152:155], v[190:193], 0
	v_mfma_f32_16x16x32_bf16 v[108:111], v[128:131], v[198:201], 0
	v_mfma_f32_16x16x32_bf16 v[104:107], v[152:155], v[198:201], 0
	v_mfma_f32_16x16x32_bf16 v[92:95], v[128:131], v[212:215], 0
	v_mfma_f32_16x16x32_bf16 v[88:91], v[152:155], v[212:215], 0
	v_mfma_f32_16x16x32_bf16 v[76:79], v[128:131], v[220:223], 0
	v_mfma_f32_16x16x32_bf16 v[72:75], v[152:155], v[220:223], 0
	v_mfma_f32_16x16x32_bf16 v[124:127], v[132:135], v[194:197], v[124:127]
	v_mfma_f32_16x16x32_bf16 v[120:123], v[156:159], v[194:197], v[120:123]
	v_mfma_f32_16x16x32_bf16 v[108:111], v[132:135], v[208:211], v[108:111]
	v_mfma_f32_16x16x32_bf16 v[104:107], v[156:159], v[208:211], v[104:107]
	v_mfma_f32_16x16x32_bf16 v[92:95], v[132:135], v[216:219], v[92:95]
	v_mfma_f32_16x16x32_bf16 v[88:91], v[156:159], v[216:219], v[88:91]
	v_mfma_f32_16x16x32_bf16 v[76:79], v[132:135], v[224:227], v[76:79]
	v_mfma_f32_16x16x32_bf16 v[72:75], v[156:159], v[224:227], v[72:75]
	s_setprio 0
	s_setprio 1
	v_mfma_f32_16x16x32_bf16 v[116:119], v[172:175], v[190:193], 0
	v_mfma_f32_16x16x32_bf16 v[112:115], v[182:185], v[190:193], 0
	v_mfma_f32_16x16x32_bf16 v[100:103], v[172:175], v[198:201], 0
	v_mfma_f32_16x16x32_bf16 v[96:99], v[182:185], v[198:201], 0
	v_mfma_f32_16x16x32_bf16 v[84:87], v[172:175], v[212:215], 0
	v_mfma_f32_16x16x32_bf16 v[80:83], v[182:185], v[212:215], 0
	v_mfma_f32_16x16x32_bf16 v[68:71], v[172:175], v[220:223], 0
	v_mfma_f32_16x16x32_bf16 v[64:67], v[182:185], v[220:223], 0
	v_mfma_f32_16x16x32_bf16 v[116:119], v[176:179], v[194:197], v[116:119]
	v_mfma_f32_16x16x32_bf16 v[112:115], v[186:189], v[194:197], v[112:115]
	v_mfma_f32_16x16x32_bf16 v[100:103], v[176:179], v[208:211], v[100:103]
	v_mfma_f32_16x16x32_bf16 v[96:99], v[186:189], v[208:211], v[96:99]
	v_mfma_f32_16x16x32_bf16 v[84:87], v[176:179], v[216:219], v[84:87]
	v_mfma_f32_16x16x32_bf16 v[80:83], v[186:189], v[216:219], v[80:83]
	v_mfma_f32_16x16x32_bf16 v[68:71], v[176:179], v[224:227], v[68:71]
	v_mfma_f32_16x16x32_bf16 v[64:67], v[186:189], v[224:227], v[64:67]
	s_setprio 0
	s_barrier
	s_add_i32 s3, s65, s43
	v_lshl_add_u64 v[160:161], s[54:55], 0, v[138:139]
	s_mov_b32 m0, s3
	ds_read_b128 v[190:193], v169 offset:16384
	ds_read_b128 v[194:197], v169 offset:17408
	ds_read_b128 v[198:201], v169 offset:18432
	ds_read_b128 v[208:211], v169 offset:19456
	ds_read_b128 v[212:215], v169 offset:20480
	ds_read_b128 v[216:219], v169 offset:21504
	ds_read_b128 v[220:223], v169 offset:22528
	ds_read_b128 v[224:227], v169 offset:23552
	global_load_lds_dwordx4 v[160:161], off
	s_add_i32 m0, s3, 0x2000
	s_add_u32 s10, s54, 0xb0000
	v_lshl_add_u64 v[202:203], s[54:55], 0, v[142:143]
	s_addc_u32 s11, s55, 0
	s_add_i32 s3, s66, s43
	global_load_lds_dwordx4 v[202:203], off
	v_lshl_add_u64 v[228:229], s[10:11], 0, v[138:139]
	s_mov_b32 m0, s3
	global_load_lds_dwordx4 v[228:229], off
	v_lshl_add_u64 v[228:229], s[10:11], 0, v[142:143]
	s_add_i32 m0, s3, 0x2000
	s_nop 0
	global_load_lds_dwordx4 v[228:229], off
	v_lshl_add_u64 v[228:229], s[56:57], 0, v[136:137]
	s_mov_b32 m0, s58
	s_nop 0
	global_load_lds_dwordx4 v[228:229], off
	v_lshl_add_u64 v[230:231], s[56:57], 0, v[140:141]
	s_mov_b32 m0, s59
	s_nop 0
	global_load_lds_dwordx4 v[230:231], off
	s_waitcnt vmcnt(8)
	s_waitcnt lgkmcnt(0)
	s_barrier
; #define PG8_STAGE(bufoff, gbase, voff) do { _Pragma("unroll") for (int _i = 0; _i < 2; ++_i) \
;         __builtin_amdgcn_global_load_lds((const unsigned*)((const char*)(gbase) + (voff)[_i]), (PG8_LAS unsigned*)(lds + (bufoff) + ldsw + _i * 8192), 16, 0, 0); } while (0)
; #define PG8_LDA(dst, b, h) do { _Pragma("unroll") for (int m = 0; m < 4; ++m) _Pragma("unroll") for (int k = 0; k < 2; ++k) dst[m][k] = *(const PG8_LAS bf16x8*)(lds + PG8_SA(b, h) + aoff + m * 2048 + k * 1024); } while (0)
; #define PG8_LDB(dst, b, h) do { _Pragma("unroll") for (int n = 0; n < 2; ++n) _Pragma("unroll") for (int k = 0; k < 2; ++k) dst[n][k] = *(const PG8_LAS bf16x8*)(lds + PG8_SB(b, h) + boff + n * 2048 + k * 1024); } while (0)
; #define PG8_MMA(ai, bj, At, Bt) do { __builtin_amdgcn_s_setprio(1); _Pragma("unroll") for (int m = 0; m < 4; ++m) _Pragma("unroll") for (int n = 0; n < 2; ++n) _Pragma("unroll") for (int k = 0; k < 2; ++k) \
;         acc[ai][bj][m][n] = __builtin_amdgcn_mfma_f32_16x16x32_bf16(Bt[n][k], At[m][k], acc[ai][bj][m][n], 0, 0, 0); __builtin_amdgcn_s_setprio(0); } while (0)
; #define PG8_WAIT_V(n) asm volatile("s_waitcnt vmcnt(" #n ")" ::: "memory")
; #define PG8_WAIT_L(n) asm volatile("s_waitcnt lgkmcnt(" #n ")" ::: "memory")
; #define PG8_BAR __builtin_amdgcn_s_barrier()
; #define PG8_SCHED __builtin_amdgcn_sched_barrier(0)
; template <class Epi, class Sched, bool ALIGN_EPI = false, bool SP2 = false>
; __device__ __forceinline__ void gemm_phase(PG8_LAS unsigned char* lds, const Gemm g, const Sched& S, const Epi& E) {
;     ...
;             PG8_WAIT_V(8); PG8_WAIT_L(0); PG8_BAR; PG8_MMA(1, 0, At, B0); PG8_MMA(1, 1, At, B1); PG8_BAR; PG8_SCHED;
;             PG8_LDB(B0, 1, 0); PG8_LDB(B1, 1, 1); PG8_SCHED; PG8_LDA(At, 1, 0); PG8_STAGE(PG8_SA(0, 1), a2 + hstep, voffA);
;             PG8_WAIT_V(8); PG8_WAIT_L(0); PG8_BAR; PG8_MMA(0, 0, At, B0); PG8_MMA(0, 1, At, B1); PG8_BAR; PG8_SCHED;
	s_setprio 1
	s_waitcnt lgkmcnt(0)
	v_mfma_f32_16x16x32_bf16 v[60:63], v[128:131], v[190:193], 0
	v_mfma_f32_16x16x32_bf16 v[56:59], v[152:155], v[190:193], 0
	v_mfma_f32_16x16x32_bf16 v[44:47], v[128:131], v[198:201], 0
	v_mfma_f32_16x16x32_bf16 v[40:43], v[152:155], v[198:201], 0
	v_mfma_f32_16x16x32_bf16 v[28:31], v[128:131], v[212:215], 0
	v_mfma_f32_16x16x32_bf16 v[24:27], v[152:155], v[212:215], 0
	v_mfma_f32_16x16x32_bf16 v[12:15], v[128:131], v[220:223], 0
	v_mfma_f32_16x16x32_bf16 v[8:11], v[152:155], v[220:223], 0
	v_mfma_f32_16x16x32_bf16 v[60:63], v[132:135], v[194:197], v[60:63]
	v_mfma_f32_16x16x32_bf16 v[56:59], v[156:159], v[194:197], v[56:59]
	v_mfma_f32_16x16x32_bf16 v[44:47], v[132:135], v[208:211], v[44:47]
	v_mfma_f32_16x16x32_bf16 v[40:43], v[156:159], v[208:211], v[40:43]
	v_mfma_f32_16x16x32_bf16 v[28:31], v[132:135], v[216:219], v[28:31]
	v_mfma_f32_16x16x32_bf16 v[24:27], v[156:159], v[216:219], v[24:27]
	v_mfma_f32_16x16x32_bf16 v[12:15], v[132:135], v[224:227], v[12:15]
	v_mfma_f32_16x16x32_bf16 v[8:11], v[156:159], v[224:227], v[8:11]
	s_setprio 0
	s_setprio 1
	v_mfma_f32_16x16x32_bf16 v[52:55], v[172:175], v[190:193], 0
	v_mfma_f32_16x16x32_bf16 v[48:51], v[182:185], v[190:193], 0
	v_mfma_f32_16x16x32_bf16 v[36:39], v[172:175], v[198:201], 0
	v_mfma_f32_16x16x32_bf16 v[32:35], v[182:185], v[198:201], 0
	v_mfma_f32_16x16x32_bf16 v[20:23], v[172:175], v[212:215], 0
	v_mfma_f32_16x16x32_bf16 v[16:19], v[182:185], v[212:215], 0
	v_mfma_f32_16x16x32_bf16 v[4:7], v[172:175], v[220:223], 0
	v_mfma_f32_16x16x32_bf16 v[0:3], v[182:185], v[220:223], 0
	v_mfma_f32_16x16x32_bf16 v[52:55], v[176:179], v[194:197], v[52:55]
	v_mfma_f32_16x16x32_bf16 v[48:51], v[186:189], v[194:197], v[48:51]
	v_mfma_f32_16x16x32_bf16 v[36:39], v[176:179], v[208:211], v[36:39]
	v_mfma_f32_16x16x32_bf16 v[32:35], v[186:189], v[208:211], v[32:35]
	v_mfma_f32_16x16x32_bf16 v[20:23], v[176:179], v[216:219], v[20:23]
	v_mfma_f32_16x16x32_bf16 v[16:19], v[186:189], v[216:219], v[16:19]
	v_mfma_f32_16x16x32_bf16 v[4:7], v[176:179], v[224:227], v[4:7]
	v_mfma_f32_16x16x32_bf16 v[0:3], v[186:189], v[224:227], v[0:3]
	s_setprio 0
	s_barrier
	s_add_i32 s3, 0, 0x18000
	s_add_i32 s14, 0, 0x1c000
	v_add_u32_e32 v156, s3, v163
	v_add_u32_e32 v171, s14, v163
	ds_read_b128 v[128:131], v156
	ds_read_b128 v[132:135], v156 offset:1024
	ds_read_b128 v[152:155], v156 offset:2048
	ds_read_b128 v[156:159], v156 offset:3072
	ds_read_b128 v[172:175], v171
	ds_read_b128 v[176:179], v171 offset:1024
	ds_read_b128 v[182:185], v171 offset:2048
	ds_read_b128 v[186:189], v171 offset:3072
	s_add_u32 s10, s56, 0xb0000
	s_addc_u32 s11, s57, 0
	s_mov_b32 m0, s60
	v_lshl_add_u64 v[232:233], s[10:11], 0, v[136:137]
	ds_read_b128 v[190:193], v169 offset:32768
	ds_read_b128 v[194:197], v169 offset:33792
	ds_read_b128 v[198:201], v169 offset:34816
	ds_read_b128 v[208:211], v169 offset:35840
	ds_read_b128 v[212:215], v169 offset:36864
	ds_read_b128 v[216:219], v169 offset:37888
	ds_read_b128 v[220:223], v169 offset:38912
	ds_read_b128 v[224:227], v169 offset:39936
	global_load_lds_dwordx4 v[232:233], off
	v_lshl_add_u64 v[232:233], s[10:11], 0, v[140:141]
	s_mov_b32 m0, s61
	s_nop 0
	global_load_lds_dwordx4 v[232:233], off
	s_waitcnt vmcnt(8)
	s_waitcnt lgkmcnt(0)
	s_barrier
	s_setprio 1
	s_waitcnt lgkmcnt(0)
	v_mfma_f32_16x16x32_bf16 v[124:127], v[128:131], v[190:193], v[124:127]
	v_mfma_f32_16x16x32_bf16 v[120:123], v[152:155], v[190:193], v[120:123]
	v_mfma_f32_16x16x32_bf16 v[108:111], v[128:131], v[198:201], v[108:111]
	v_mfma_f32_16x16x32_bf16 v[104:107], v[152:155], v[198:201], v[104:107]
	v_mfma_f32_16x16x32_bf16 v[92:95], v[128:131], v[212:215], v[92:95]
	v_mfma_f32_16x16x32_bf16 v[88:91], v[152:155], v[212:215], v[88:91]
	v_mfma_f32_16x16x32_bf16 v[76:79], v[128:131], v[220:223], v[76:79]
	v_mfma_f32_16x16x32_bf16 v[72:75], v[152:155], v[220:223], v[72:75]
	v_mfma_f32_16x16x32_bf16 v[124:127], v[132:135], v[194:197], v[124:127]
	v_mfma_f32_16x16x32_bf16 v[120:123], v[156:159], v[194:197], v[120:123]
	v_mfma_f32_16x16x32_bf16 v[108:111], v[132:135], v[208:211], v[108:111]
	v_mfma_f32_16x16x32_bf16 v[104:107], v[156:159], v[208:211], v[104:107]
	v_mfma_f32_16x16x32_bf16 v[92:95], v[132:135], v[216:219], v[92:95]
	v_mfma_f32_16x16x32_bf16 v[88:91], v[156:159], v[216:219], v[88:91]
	v_mfma_f32_16x16x32_bf16 v[76:79], v[132:135], v[224:227], v[76:79]
	v_mfma_f32_16x16x32_bf16 v[72:75], v[156:159], v[224:227], v[72:75]
	s_setprio 0
	s_setprio 1
	v_mfma_f32_16x16x32_bf16 v[116:119], v[172:175], v[190:193], v[116:119]
	v_mfma_f32_16x16x32_bf16 v[112:115], v[182:185], v[190:193], v[112:115]
	v_mfma_f32_16x16x32_bf16 v[100:103], v[172:175], v[198:201], v[100:103]
	v_mfma_f32_16x16x32_bf16 v[96:99], v[182:185], v[198:201], v[96:99]
	v_mfma_f32_16x16x32_bf16 v[84:87], v[172:175], v[212:215], v[84:87]
	v_mfma_f32_16x16x32_bf16 v[80:83], v[182:185], v[212:215], v[80:83]
	v_mfma_f32_16x16x32_bf16 v[68:71], v[172:175], v[220:223], v[68:71]
	v_mfma_f32_16x16x32_bf16 v[64:67], v[182:185], v[220:223], v[64:67]
	v_mfma_f32_16x16x32_bf16 v[116:119], v[176:179], v[194:197], v[116:119]
	v_mfma_f32_16x16x32_bf16 v[112:115], v[186:189], v[194:197], v[112:115]
	v_mfma_f32_16x16x32_bf16 v[100:103], v[176:179], v[208:211], v[100:103]
	v_mfma_f32_16x16x32_bf16 v[96:99], v[186:189], v[208:211], v[96:99]
	v_mfma_f32_16x16x32_bf16 v[84:87], v[176:179], v[216:219], v[84:87]
	v_mfma_f32_16x16x32_bf16 v[80:83], v[186:189], v[216:219], v[80:83]
	v_mfma_f32_16x16x32_bf16 v[68:71], v[176:179], v[224:227], v[68:71]
	v_mfma_f32_16x16x32_bf16 v[64:67], v[186:189], v[224:227], v[64:67]
	s_setprio 0
	s_barrier
; #define PG8_STAGE(bufoff, gbase, voff) do { _Pragma("unroll") for (int _i = 0; _i < 2; ++_i) \
;         __builtin_amdgcn_global_load_lds((const unsigned*)((const char*)(gbase) + (voff)[_i]), (PG8_LAS unsigned*)(lds + (bufoff) + ldsw + _i * 8192), 16, 0, 0); } while (0)
; #define PG8_LDA(dst, b, h) do { _Pragma("unroll") for (int m = 0; m < 4; ++m) _Pragma("unroll") for (int k = 0; k < 2; ++k) dst[m][k] = *(const PG8_LAS bf16x8*)(lds + PG8_SA(b, h) + aoff + m * 2048 + k * 1024); } while (0)
; #define PG8_LDB(dst, b, h) do { _Pragma("unroll") for (int n = 0; n < 2; ++n) _Pragma("unroll") for (int k = 0; k < 2; ++k) dst[n][k] = *(const PG8_LAS bf16x8*)(lds + PG8_SB(b, h) + boff + n * 2048 + k * 1024); } while (0)
; #define PG8_MMA(ai, bj, At, Bt) do { __builtin_amdgcn_s_setprio(1); _Pragma("unroll") for (int m = 0; m < 4; ++m) _Pragma("unroll") for (int n = 0; n < 2; ++n) _Pragma("unroll") for (int k = 0; k < 2; ++k) \
;         acc[ai][bj][m][n] = __builtin_amdgcn_mfma_f32_16x16x32_bf16(Bt[n][k], At[m][k], acc[ai][bj][m][n], 0, 0, 0); __builtin_amdgcn_s_setprio(0); } while (0)
; #define PG8_WAIT_V(n) asm volatile("s_waitcnt vmcnt(" #n ")" ::: "memory")
; #define PG8_WAIT_L(n) asm volatile("s_waitcnt lgkmcnt(" #n ")" ::: "memory")
; #define PG8_BAR __builtin_amdgcn_s_barrier()
; #define PG8_SCHED __builtin_amdgcn_sched_barrier(0)
; template <class Epi, class Sched, bool ALIGN_EPI = false, bool SP2 = false>
; __device__ __forceinline__ void gemm_phase(PG8_LAS unsigned char* lds, const Gemm g, const Sched& S, const Epi& E) {
;     ...
;             PG8_LDB(B0, 0, 0); PG8_LDB(B1, 0, 1); PG8_SCHED; PG8_LDA(At, 0, 0); PG8_STAGE(PG8_SA(1, 1), a1 + hstep, voffA);
;     ...
;             PG8_LDA(At, 1, 1); PG8_STAGE(PG8_SB(1, 0), b3, voffB); PG8_STAGE(PG8_SB(1, 1), b3 + hstep, voffB); PG8_STAGE(PG8_SA(1, 0), a3, voffA);
;             PG8_WAIT_V(8); PG8_WAIT_L(0); PG8_BAR; PG8_MMA(1, 0, At, B0); PG8_MMA(1, 1, At, B1); PG8_BAR; PG8_SCHED;
	s_add_i32 s3, s3, s43
	v_lshl_add_u64 v[160:161], v[160:161], 0, s[40:41]
	s_mov_b32 m0, s3
	ds_read_b128 v[190:193], v169 offset:49152
	ds_read_b128 v[194:197], v169 offset:50176
	ds_read_b128 v[198:201], v169 offset:51200
	ds_read_b128 v[208:211], v169 offset:52224
	ds_read_b128 v[212:215], v169 offset:53248
	ds_read_b128 v[216:219], v169 offset:54272
	ds_read_b128 v[220:223], v169 offset:55296
	ds_read_b128 v[224:227], v169 offset:56320
	global_load_lds_dwordx4 v[160:161], off
	s_add_i32 m0, s3, 0x2000
	s_add_u32 s10, s54, 0xb0080
	v_lshl_add_u64 v[160:161], v[202:203], 0, s[40:41]
	s_addc_u32 s11, s55, 0
	s_add_i32 s3, s14, s43
	global_load_lds_dwordx4 v[160:161], off
	v_lshl_add_u64 v[160:161], s[10:11], 0, v[138:139]
	s_mov_b32 m0, s3
	s_nop 0
	global_load_lds_dwordx4 v[160:161], off
	v_lshl_add_u64 v[160:161], s[10:11], 0, v[142:143]
	s_add_i32 m0, s3, 0x2000
	s_nop 0
	global_load_lds_dwordx4 v[160:161], off
	v_lshl_add_u64 v[160:161], v[228:229], 0, s[40:41]
	s_mov_b32 m0, s63
	s_nop 0
	global_load_lds_dwordx4 v[160:161], off
	v_lshl_add_u64 v[160:161], v[230:231], 0, s[40:41]
	s_mov_b32 m0, s64
	s_nop 0
	global_load_lds_dwordx4 v[160:161], off
	s_waitcnt vmcnt(8)
	s_waitcnt lgkmcnt(0)
	s_barrier
	s_setprio 1
	s_waitcnt lgkmcnt(0)
	v_mfma_f32_16x16x32_bf16 v[60:63], v[128:131], v[190:193], v[60:63]
	v_mfma_f32_16x16x32_bf16 v[56:59], v[152:155], v[190:193], v[56:59]
	v_mfma_f32_16x16x32_bf16 v[44:47], v[128:131], v[198:201], v[44:47]
	v_mfma_f32_16x16x32_bf16 v[40:43], v[152:155], v[198:201], v[40:43]
	v_mfma_f32_16x16x32_bf16 v[28:31], v[128:131], v[212:215], v[28:31]
	v_mfma_f32_16x16x32_bf16 v[24:27], v[152:155], v[212:215], v[24:27]
	v_mfma_f32_16x16x32_bf16 v[12:15], v[128:131], v[220:223], v[12:15]
	v_mfma_f32_16x16x32_bf16 v[8:11], v[152:155], v[220:223], v[8:11]
	v_mfma_f32_16x16x32_bf16 v[60:63], v[132:135], v[194:197], v[60:63]
	v_mfma_f32_16x16x32_bf16 v[56:59], v[156:159], v[194:197], v[56:59]
	v_mfma_f32_16x16x32_bf16 v[44:47], v[132:135], v[208:211], v[44:47]
	v_mfma_f32_16x16x32_bf16 v[40:43], v[156:159], v[208:211], v[40:43]
	v_mfma_f32_16x16x32_bf16 v[28:31], v[132:135], v[216:219], v[28:31]
	v_mfma_f32_16x16x32_bf16 v[24:27], v[156:159], v[216:219], v[24:27]
	v_mfma_f32_16x16x32_bf16 v[12:15], v[132:135], v[224:227], v[12:15]
	v_mfma_f32_16x16x32_bf16 v[8:11], v[156:159], v[224:227], v[8:11]
	s_setprio 0
	s_setprio 1
	v_mfma_f32_16x16x32_bf16 v[52:55], v[172:175], v[190:193], v[52:55]
	v_mfma_f32_16x16x32_bf16 v[48:51], v[182:185], v[190:193], v[48:51]
	v_mfma_f32_16x16x32_bf16 v[36:39], v[172:175], v[198:201], v[36:39]
	v_mfma_f32_16x16x32_bf16 v[32:35], v[182:185], v[198:201], v[32:35]
	v_mfma_f32_16x16x32_bf16 v[20:23], v[172:175], v[212:215], v[20:23]
	v_mfma_f32_16x16x32_bf16 v[16:19], v[182:185], v[212:215], v[16:19]
	v_mfma_f32_16x16x32_bf16 v[4:7], v[172:175], v[220:223], v[4:7]
	v_mfma_f32_16x16x32_bf16 v[0:3], v[182:185], v[220:223], v[0:3]
	v_mfma_f32_16x16x32_bf16 v[52:55], v[176:179], v[194:197], v[52:55]
	v_mfma_f32_16x16x32_bf16 v[48:51], v[186:189], v[194:197], v[48:51]
	v_mfma_f32_16x16x32_bf16 v[36:39], v[176:179], v[208:211], v[36:39]
	v_mfma_f32_16x16x32_bf16 v[32:35], v[186:189], v[208:211], v[32:35]
	v_mfma_f32_16x16x32_bf16 v[20:23], v[176:179], v[216:219], v[20:23]
	v_mfma_f32_16x16x32_bf16 v[16:19], v[186:189], v[216:219], v[16:19]
	v_mfma_f32_16x16x32_bf16 v[4:7], v[176:179], v[224:227], v[4:7]
	v_mfma_f32_16x16x32_bf16 v[0:3], v[186:189], v[224:227], v[0:3]
	s_setprio 0
	s_barrier
	s_add_i32 s93, s93, 2
	s_add_u32 s91, s91, 0x100
	s_addc_u32 s92, s92, 0
	s_mov_b64 s[10:11], s[50:51]
.LBB0_269:
	ds_read_b128 v[128:131], v165
	ds_read_b128 v[132:135], v165 offset:1024
	ds_read_b128 v[152:155], v165 offset:2048
	ds_read_b128 v[156:159], v165 offset:3072
	ds_read_b128 v[172:175], v168
	ds_read_b128 v[176:179], v168 offset:1024
	ds_read_b128 v[182:185], v168 offset:2048
	ds_read_b128 v[186:189], v168 offset:3072
	s_add_u32 s50, s10, 0x100
	s_addc_u32 s51, s11, 0
	s_cmp_eq_u32 s93, 40
	s_cselect_b32 s57, s1, s51
	s_cselect_b32 s56, s0, s50
	s_cselect_b32 s55, s49, s92
	s_cselect_b32 s54, s48, s91
	v_lshl_add_u64 v[160:161], s[10:11], 0, v[144:145]
	s_add_i32 m0, s58, 0xc000
	ds_read_b128 v[190:193], v169
	ds_read_b128 v[194:197], v169 offset:1024
	ds_read_b128 v[198:201], v169 offset:2048
	ds_read_b128 v[208:211], v169 offset:3072
	ds_read_b128 v[212:215], v169 offset:4096
	ds_read_b128 v[216:219], v169 offset:5120
	ds_read_b128 v[220:223], v169 offset:6144
	ds_read_b128 v[224:227], v169 offset:7168
	global_load_lds_dwordx4 v[160:161], off
	v_lshl_add_u64 v[160:161], s[10:11], 0, v[146:147]
	s_add_i32 m0, s58, 0xe000
	s_nop 0
	global_load_lds_dwordx4 v[160:161], off
	s_waitcnt vmcnt(8)
	s_waitcnt lgkmcnt(0)
	s_barrier
; #define PG8_STAGE(bufoff, gbase, voff) do { _Pragma("unroll") for (int _i = 0; _i < 2; ++_i) \
;         __builtin_amdgcn_global_load_lds((const unsigned*)((const char*)(gbase) + (voff)[_i]), (PG8_LAS unsigned*)(lds + (bufoff) + ldsw + _i * 8192), 16, 0, 0); } while (0)
; #define PG8_LDA(dst, b, h) do { _Pragma("unroll") for (int m = 0; m < 4; ++m) _Pragma("unroll") for (int k = 0; k < 2; ++k) dst[m][k] = *(const PG8_LAS bf16x8*)(lds + PG8_SA(b, h) + aoff + m * 2048 + k * 1024); } while (0)
; #define PG8_MMA(ai, bj, At, Bt) do { __builtin_amdgcn_s_setprio(1); _Pragma("unroll") for (int m = 0; m < 4; ++m) _Pragma("unroll") for (int n = 0; n < 2; ++n) _Pragma("unroll") for (int k = 0; k < 2; ++k) \
;         acc[ai][bj][m][n] = __builtin_amdgcn_mfma_f32_16x16x32_bf16(Bt[n][k], At[m][k], acc[ai][bj][m][n], 0, 0, 0); __builtin_amdgcn_s_setprio(0); } while (0)
; #define PG8_WAIT_V(n) asm volatile("s_waitcnt vmcnt(" #n ")" ::: "memory")
; #define PG8_WAIT_L(n) asm volatile("s_waitcnt lgkmcnt(" #n ")" ::: "memory")
; #define PG8_BAR __builtin_amdgcn_s_barrier()
; #define PG8_SCHED __builtin_amdgcn_sched_barrier(0)
; template <class Epi, class Sched, bool ALIGN_EPI = false, bool SP2 = false>
; __device__ __forceinline__ void gemm_phase(PG8_LAS unsigned char* lds, const Gemm g, const Sched& S, const Epi& E) {
;     ...
;             PG8_WAIT_V(8); PG8_WAIT_L(0); PG8_BAR; PG8_MMA(0, 0, At, B0); PG8_MMA(0, 1, At, B1); PG8_BAR; PG8_SCHED;
;             PG8_LDA(At, 0, 1); PG8_STAGE(PG8_SB(0, 0), b2, voffB); PG8_STAGE(PG8_SB(0, 1), b2 + hstep, voffB); PG8_STAGE(PG8_SA(0, 0), a2, voffA);
;             PG8_WAIT_V(8); PG8_WAIT_L(0); PG8_BAR; PG8_MMA(1, 0, At, B0); PG8_MMA(1, 1, At, B1); PG8_BAR; PG8_SCHED;
	s_setprio 1
	s_waitcnt lgkmcnt(0)
	v_mfma_f32_16x16x32_bf16 v[124:127], v[128:131], v[190:193], v[124:127]
	v_mfma_f32_16x16x32_bf16 v[120:123], v[152:155], v[190:193], v[120:123]
	v_mfma_f32_16x16x32_bf16 v[108:111], v[128:131], v[198:201], v[108:111]
	v_mfma_f32_16x16x32_bf16 v[104:107], v[152:155], v[198:201], v[104:107]
	v_mfma_f32_16x16x32_bf16 v[92:95], v[128:131], v[212:215], v[92:95]
	v_mfma_f32_16x16x32_bf16 v[88:91], v[152:155], v[212:215], v[88:91]
	v_mfma_f32_16x16x32_bf16 v[76:79], v[128:131], v[220:223], v[76:79]
	v_mfma_f32_16x16x32_bf16 v[72:75], v[152:155], v[220:223], v[72:75]
	v_mfma_f32_16x16x32_bf16 v[124:127], v[132:135], v[194:197], v[124:127]
	v_mfma_f32_16x16x32_bf16 v[120:123], v[156:159], v[194:197], v[120:123]
	v_mfma_f32_16x16x32_bf16 v[108:111], v[132:135], v[208:211], v[108:111]
	v_mfma_f32_16x16x32_bf16 v[104:107], v[156:159], v[208:211], v[104:107]
	v_mfma_f32_16x16x32_bf16 v[92:95], v[132:135], v[216:219], v[92:95]
	v_mfma_f32_16x16x32_bf16 v[88:91], v[156:159], v[216:219], v[88:91]
	v_mfma_f32_16x16x32_bf16 v[76:79], v[132:135], v[224:227], v[76:79]
	v_mfma_f32_16x16x32_bf16 v[72:75], v[156:159], v[224:227], v[72:75]
	s_setprio 0
	s_setprio 1
	v_mfma_f32_16x16x32_bf16 v[116:119], v[172:175], v[190:193], v[116:119]
	v_mfma_f32_16x16x32_bf16 v[112:115], v[182:185], v[190:193], v[112:115]
	v_mfma_f32_16x16x32_bf16 v[100:103], v[172:175], v[198:201], v[100:103]
	v_mfma_f32_16x16x32_bf16 v[96:99], v[182:185], v[198:201], v[96:99]
	v_mfma_f32_16x16x32_bf16 v[84:87], v[172:175], v[212:215], v[84:87]
	v_mfma_f32_16x16x32_bf16 v[80:83], v[182:185], v[212:215], v[80:83]
	v_mfma_f32_16x16x32_bf16 v[68:71], v[172:175], v[220:223], v[68:71]
	v_mfma_f32_16x16x32_bf16 v[64:67], v[182:185], v[220:223], v[64:67]
	v_mfma_f32_16x16x32_bf16 v[116:119], v[176:179], v[194:197], v[116:119]
	v_mfma_f32_16x16x32_bf16 v[112:115], v[186:189], v[194:197], v[112:115]
	v_mfma_f32_16x16x32_bf16 v[100:103], v[176:179], v[208:211], v[100:103]
	v_mfma_f32_16x16x32_bf16 v[96:99], v[186:189], v[208:211], v[96:99]
	v_mfma_f32_16x16x32_bf16 v[84:87], v[176:179], v[216:219], v[84:87]
	v_mfma_f32_16x16x32_bf16 v[80:83], v[186:189], v[216:219], v[80:83]
	v_mfma_f32_16x16x32_bf16 v[68:71], v[176:179], v[224:227], v[68:71]
	v_mfma_f32_16x16x32_bf16 v[64:67], v[186:189], v[224:227], v[64:67]
	s_setprio 0
	s_barrier
	s_add_i32 s3, s65, s43
	v_lshl_add_u64 v[160:161], s[54:55], 0, v[138:139]
	s_mov_b32 m0, s3
	ds_read_b128 v[190:193], v169 offset:16384
	ds_read_b128 v[194:197], v169 offset:17408
	ds_read_b128 v[198:201], v169 offset:18432
	ds_read_b128 v[208:211], v169 offset:19456
	ds_read_b128 v[212:215], v169 offset:20480
	ds_read_b128 v[216:219], v169 offset:21504
	ds_read_b128 v[220:223], v169 offset:22528
	ds_read_b128 v[224:227], v169 offset:23552
	global_load_lds_dwordx4 v[160:161], off
	s_add_i32 m0, s3, 0x2000
	s_add_u32 s10, s54, 0xb0000
	v_lshl_add_u64 v[202:203], s[54:55], 0, v[142:143]
	s_addc_u32 s11, s55, 0
	s_add_i32 s3, s66, s43
	global_load_lds_dwordx4 v[202:203], off
	v_lshl_add_u64 v[228:229], s[10:11], 0, v[138:139]
	s_mov_b32 m0, s3
	global_load_lds_dwordx4 v[228:229], off
	v_lshl_add_u64 v[228:229], s[10:11], 0, v[142:143]
	s_add_i32 m0, s3, 0x2000
	s_nop 0
	global_load_lds_dwordx4 v[228:229], off
	v_lshl_add_u64 v[228:229], s[56:57], 0, v[136:137]
	s_mov_b32 m0, s58
	s_nop 0
	global_load_lds_dwordx4 v[228:229], off
	v_lshl_add_u64 v[230:231], s[56:57], 0, v[140:141]
	s_mov_b32 m0, s59
	s_nop 0
	global_load_lds_dwordx4 v[230:231], off
	s_waitcnt vmcnt(8)
	s_waitcnt lgkmcnt(0)
	s_barrier
	s_setprio 1
	s_waitcnt lgkmcnt(0)
	v_mfma_f32_16x16x32_bf16 v[60:63], v[128:131], v[190:193], v[60:63]
	v_mfma_f32_16x16x32_bf16 v[56:59], v[152:155], v[190:193], v[56:59]
	v_mfma_f32_16x16x32_bf16 v[44:47], v[128:131], v[198:201], v[44:47]
	v_mfma_f32_16x16x32_bf16 v[40:43], v[152:155], v[198:201], v[40:43]
	v_mfma_f32_16x16x32_bf16 v[28:31], v[128:131], v[212:215], v[28:31]
	v_mfma_f32_16x16x32_bf16 v[24:27], v[152:155], v[212:215], v[24:27]
	v_mfma_f32_16x16x32_bf16 v[12:15], v[128:131], v[220:223], v[12:15]
	v_mfma_f32_16x16x32_bf16 v[8:11], v[152:155], v[220:223], v[8:11]
	v_mfma_f32_16x16x32_bf16 v[60:63], v[132:135], v[194:197], v[60:63]
	v_mfma_f32_16x16x32_bf16 v[56:59], v[156:159], v[194:197], v[56:59]
	v_mfma_f32_16x16x32_bf16 v[44:47], v[132:135], v[208:211], v[44:47]
	v_mfma_f32_16x16x32_bf16 v[40:43], v[156:159], v[208:211], v[40:43]
	v_mfma_f32_16x16x32_bf16 v[28:31], v[132:135], v[216:219], v[28:31]
	v_mfma_f32_16x16x32_bf16 v[24:27], v[156:159], v[216:219], v[24:27]
	v_mfma_f32_16x16x32_bf16 v[12:15], v[132:135], v[224:227], v[12:15]
	v_mfma_f32_16x16x32_bf16 v[8:11], v[156:159], v[224:227], v[8:11]
	s_setprio 0
	s_setprio 1
	v_mfma_f32_16x16x32_bf16 v[52:55], v[172:175], v[190:193], v[52:55]
	v_mfma_f32_16x16x32_bf16 v[48:51], v[182:185], v[190:193], v[48:51]
	v_mfma_f32_16x16x32_bf16 v[36:39], v[172:175], v[198:201], v[36:39]
	v_mfma_f32_16x16x32_bf16 v[32:35], v[182:185], v[198:201], v[32:35]
	v_mfma_f32_16x16x32_bf16 v[20:23], v[172:175], v[212:215], v[20:23]
	v_mfma_f32_16x16x32_bf16 v[16:19], v[182:185], v[212:215], v[16:19]
	v_mfma_f32_16x16x32_bf16 v[4:7], v[172:175], v[220:223], v[4:7]
	v_mfma_f32_16x16x32_bf16 v[0:3], v[182:185], v[220:223], v[0:3]
	v_mfma_f32_16x16x32_bf16 v[52:55], v[176:179], v[194:197], v[52:55]
	v_mfma_f32_16x16x32_bf16 v[48:51], v[186:189], v[194:197], v[48:51]
	v_mfma_f32_16x16x32_bf16 v[36:39], v[176:179], v[208:211], v[36:39]
	v_mfma_f32_16x16x32_bf16 v[32:35], v[186:189], v[208:211], v[32:35]
	v_mfma_f32_16x16x32_bf16 v[20:23], v[176:179], v[216:219], v[20:23]
	v_mfma_f32_16x16x32_bf16 v[16:19], v[186:189], v[216:219], v[16:19]
	v_mfma_f32_16x16x32_bf16 v[4:7], v[176:179], v[224:227], v[4:7]
	v_mfma_f32_16x16x32_bf16 v[0:3], v[186:189], v[224:227], v[0:3]
	s_setprio 0
	s_barrier
; #define PG8_STAGE(bufoff, gbase, voff) do { _Pragma("unroll") for (int _i = 0; _i < 2; ++_i) \
;         __builtin_amdgcn_global_load_lds((const unsigned*)((const char*)(gbase) + (voff)[_i]), (PG8_LAS unsigned*)(lds + (bufoff) + ldsw + _i * 8192), 16, 0, 0); } while (0)
; #define PG8_LDA(dst, b, h) do { _Pragma("unroll") for (int m = 0; m < 4; ++m) _Pragma("unroll") for (int k = 0; k < 2; ++k) dst[m][k] = *(const PG8_LAS bf16x8*)(lds + PG8_SA(b, h) + aoff + m * 2048 + k * 1024); } while (0)
; #define PG8_LDB(dst, b, h) do { _Pragma("unroll") for (int n = 0; n < 2; ++n) _Pragma("unroll") for (int k = 0; k < 2; ++k) dst[n][k] = *(const PG8_LAS bf16x8*)(lds + PG8_SB(b, h) + boff + n * 2048 + k * 1024); } while (0)
; #define PG8_MMA(ai, bj, At, Bt) do { __builtin_amdgcn_s_setprio(1); _Pragma("unroll") for (int m = 0; m < 4; ++m) _Pragma("unroll") for (int n = 0; n < 2; ++n) _Pragma("unroll") for (int k = 0; k < 2; ++k) \
;         acc[ai][bj][m][n] = __builtin_amdgcn_mfma_f32_16x16x32_bf16(Bt[n][k], At[m][k], acc[ai][bj][m][n], 0, 0, 0); __builtin_amdgcn_s_setprio(0); } while (0)
; #define PG8_WAIT_V(n) asm volatile("s_waitcnt vmcnt(" #n ")" ::: "memory")
; #define PG8_WAIT_L(n) asm volatile("s_waitcnt lgkmcnt(" #n ")" ::: "memory")
; #define PG8_BAR __builtin_amdgcn_s_barrier()
; #define PG8_SCHED __builtin_amdgcn_sched_barrier(0)
; template <class Epi, class Sched, bool ALIGN_EPI = false, bool SP2 = false>
; __device__ __forceinline__ void gemm_phase(PG8_LAS unsigned char* lds, const Gemm g, const Sched& S, const Epi& E) {
;     ...
;             PG8_LDB(B0, 1, 0); PG8_LDB(B1, 1, 1); PG8_SCHED; PG8_LDA(At, 1, 0); PG8_STAGE(PG8_SA(0, 1), a2 + hstep, voffA);
;             PG8_WAIT_V(8); PG8_WAIT_L(0); PG8_BAR; PG8_MMA(0, 0, At, B0); PG8_MMA(0, 1, At, B1); PG8_BAR; PG8_SCHED;
	s_add_i32 s3, 0, 0x18000
	s_add_i32 s14, 0, 0x1c000
	v_add_u32_e32 v156, s3, v163
	v_add_u32_e32 v171, s14, v163
	ds_read_b128 v[128:131], v156
	ds_read_b128 v[132:135], v156 offset:1024
	ds_read_b128 v[152:155], v156 offset:2048
	ds_read_b128 v[156:159], v156 offset:3072
	ds_read_b128 v[172:175], v171
	ds_read_b128 v[176:179], v171 offset:1024
	ds_read_b128 v[182:185], v171 offset:2048
	ds_read_b128 v[186:189], v171 offset:3072
	s_add_u32 s10, s56, 0xb0000
	s_addc_u32 s11, s57, 0
	s_mov_b32 m0, s60
	v_lshl_add_u64 v[232:233], s[10:11], 0, v[136:137]
	ds_read_b128 v[190:193], v169 offset:32768
	ds_read_b128 v[194:197], v169 offset:33792
	ds_read_b128 v[198:201], v169 offset:34816
	ds_read_b128 v[208:211], v169 offset:35840
	ds_read_b128 v[212:215], v169 offset:36864
	ds_read_b128 v[216:219], v169 offset:37888
	ds_read_b128 v[220:223], v169 offset:38912
	ds_read_b128 v[224:227], v169 offset:39936
	global_load_lds_dwordx4 v[232:233], off
	v_lshl_add_u64 v[232:233], s[10:11], 0, v[140:141]
	s_mov_b32 m0, s61
	s_nop 0
	global_load_lds_dwordx4 v[232:233], off
	s_waitcnt vmcnt(8)
	s_waitcnt lgkmcnt(0)
	s_barrier
	s_setprio 1
	s_waitcnt lgkmcnt(0)
	v_mfma_f32_16x16x32_bf16 v[124:127], v[128:131], v[190:193], v[124:127]
	v_mfma_f32_16x16x32_bf16 v[120:123], v[152:155], v[190:193], v[120:123]
	v_mfma_f32_16x16x32_bf16 v[108:111], v[128:131], v[198:201], v[108:111]
	v_mfma_f32_16x16x32_bf16 v[104:107], v[152:155], v[198:201], v[104:107]
	v_mfma_f32_16x16x32_bf16 v[92:95], v[128:131], v[212:215], v[92:95]
	v_mfma_f32_16x16x32_bf16 v[88:91], v[152:155], v[212:215], v[88:91]
	v_mfma_f32_16x16x32_bf16 v[76:79], v[128:131], v[220:223], v[76:79]
	v_mfma_f32_16x16x32_bf16 v[72:75], v[152:155], v[220:223], v[72:75]
	v_mfma_f32_16x16x32_bf16 v[124:127], v[132:135], v[194:197], v[124:127]
	v_mfma_f32_16x16x32_bf16 v[120:123], v[156:159], v[194:197], v[120:123]
	v_mfma_f32_16x16x32_bf16 v[108:111], v[132:135], v[208:211], v[108:111]
	v_mfma_f32_16x16x32_bf16 v[104:107], v[156:159], v[208:211], v[104:107]
	v_mfma_f32_16x16x32_bf16 v[92:95], v[132:135], v[216:219], v[92:95]
	v_mfma_f32_16x16x32_bf16 v[88:91], v[156:159], v[216:219], v[88:91]
	v_mfma_f32_16x16x32_bf16 v[76:79], v[132:135], v[224:227], v[76:79]
	v_mfma_f32_16x16x32_bf16 v[72:75], v[156:159], v[224:227], v[72:75]
	s_setprio 0
	s_setprio 1
	v_mfma_f32_16x16x32_bf16 v[116:119], v[172:175], v[190:193], v[116:119]
	v_mfma_f32_16x16x32_bf16 v[112:115], v[182:185], v[190:193], v[112:115]
	v_mfma_f32_16x16x32_bf16 v[100:103], v[172:175], v[198:201], v[100:103]
	v_mfma_f32_16x16x32_bf16 v[96:99], v[182:185], v[198:201], v[96:99]
	v_mfma_f32_16x16x32_bf16 v[84:87], v[172:175], v[212:215], v[84:87]
	v_mfma_f32_16x16x32_bf16 v[80:83], v[182:185], v[212:215], v[80:83]
	v_mfma_f32_16x16x32_bf16 v[68:71], v[172:175], v[220:223], v[68:71]
	v_mfma_f32_16x16x32_bf16 v[64:67], v[182:185], v[220:223], v[64:67]
	v_mfma_f32_16x16x32_bf16 v[116:119], v[176:179], v[194:197], v[116:119]
	v_mfma_f32_16x16x32_bf16 v[112:115], v[186:189], v[194:197], v[112:115]
	v_mfma_f32_16x16x32_bf16 v[100:103], v[176:179], v[208:211], v[100:103]
	v_mfma_f32_16x16x32_bf16 v[96:99], v[186:189], v[208:211], v[96:99]
	v_mfma_f32_16x16x32_bf16 v[84:87], v[176:179], v[216:219], v[84:87]
	v_mfma_f32_16x16x32_bf16 v[80:83], v[186:189], v[216:219], v[80:83]
	v_mfma_f32_16x16x32_bf16 v[68:71], v[176:179], v[224:227], v[68:71]
	v_mfma_f32_16x16x32_bf16 v[64:67], v[186:189], v[224:227], v[64:67]
	s_setprio 0
	s_barrier
; #define PG8_STAGE(bufoff, gbase, voff) do { _Pragma("unroll") for (int _i = 0; _i < 2; ++_i) \
;         __builtin_amdgcn_global_load_lds((const unsigned*)((const char*)(gbase) + (voff)[_i]), (PG8_LAS unsigned*)(lds + (bufoff) + ldsw + _i * 8192), 16, 0, 0); } while (0)
; #define PG8_LDA(dst, b, h) do { _Pragma("unroll") for (int m = 0; m < 4; ++m) _Pragma("unroll") for (int k = 0; k < 2; ++k) dst[m][k] = *(const PG8_LAS bf16x8*)(lds + PG8_SA(b, h) + aoff + m * 2048 + k * 1024); } while (0)
; #define PG8_MMA(ai, bj, At, Bt) do { __builtin_amdgcn_s_setprio(1); _Pragma("unroll") for (int m = 0; m < 4; ++m) _Pragma("unroll") for (int n = 0; n < 2; ++n) _Pragma("unroll") for (int k = 0; k < 2; ++k) \
;         acc[ai][bj][m][n] = __builtin_amdgcn_mfma_f32_16x16x32_bf16(Bt[n][k], At[m][k], acc[ai][bj][m][n], 0, 0, 0); __builtin_amdgcn_s_setprio(0); } while (0)
; #define PG8_WAIT_V(n) asm volatile("s_waitcnt vmcnt(" #n ")" ::: "memory")
; #define PG8_WAIT_L(n) asm volatile("s_waitcnt lgkmcnt(" #n ")" ::: "memory")
; #define PG8_BAR __builtin_amdgcn_s_barrier()
; #define PG8_SCHED __builtin_amdgcn_sched_barrier(0)
; template <class Epi, class Sched, bool ALIGN_EPI = false, bool SP2 = false>
; __device__ __forceinline__ void gemm_phase(PG8_LAS unsigned char* lds, const Gemm g, const Sched& S, const Epi& E) {
;     ...
;             PG8_LDA(At, 1, 1); PG8_STAGE(PG8_SB(1, 0), b3, voffB); PG8_STAGE(PG8_SB(1, 1), b3 + hstep, voffB); PG8_STAGE(PG8_SA(1, 0), a3, voffA);
;             PG8_WAIT_V(8); PG8_WAIT_L(0); PG8_BAR; PG8_MMA(1, 0, At, B0); PG8_MMA(1, 1, At, B1); PG8_BAR; PG8_SCHED;
;     ...
;         if constexpr (ALIGN_EPI) { if (wr == 0) PG8_BAR; }
	s_add_i32 s3, s3, s43
	v_lshl_add_u64 v[160:161], v[160:161], 0, s[40:41]
	s_mov_b32 m0, s3
	ds_read_b128 v[190:193], v169 offset:49152
	ds_read_b128 v[194:197], v169 offset:50176
	ds_read_b128 v[198:201], v169 offset:51200
	ds_read_b128 v[208:211], v169 offset:52224
	ds_read_b128 v[212:215], v169 offset:53248
	ds_read_b128 v[216:219], v169 offset:54272
	ds_read_b128 v[220:223], v169 offset:55296
	ds_read_b128 v[224:227], v169 offset:56320
	global_load_lds_dwordx4 v[160:161], off
	s_add_i32 m0, s3, 0x2000
	s_add_u32 s10, s54, 0xb0080
	v_lshl_add_u64 v[160:161], v[202:203], 0, s[40:41]
	s_addc_u32 s11, s55, 0
	s_add_i32 s3, s14, s43
	global_load_lds_dwordx4 v[160:161], off
	v_lshl_add_u64 v[160:161], s[10:11], 0, v[138:139]
	s_mov_b32 m0, s3
	s_nop 0
	global_load_lds_dwordx4 v[160:161], off
	v_lshl_add_u64 v[160:161], s[10:11], 0, v[142:143]
	s_add_i32 m0, s3, 0x2000
	s_nop 0
	global_load_lds_dwordx4 v[160:161], off
	v_lshl_add_u64 v[160:161], v[228:229], 0, s[40:41]
	s_mov_b32 m0, s63
	s_nop 0
	global_load_lds_dwordx4 v[160:161], off
	v_lshl_add_u64 v[160:161], v[230:231], 0, s[40:41]
	s_mov_b32 m0, s64
	s_nop 0
	global_load_lds_dwordx4 v[160:161], off
	s_waitcnt vmcnt(8)
	s_waitcnt lgkmcnt(0)
	s_barrier
	s_setprio 1
	s_waitcnt lgkmcnt(0)
	v_mfma_f32_16x16x32_bf16 v[60:63], v[128:131], v[190:193], v[60:63]
	v_mfma_f32_16x16x32_bf16 v[56:59], v[152:155], v[190:193], v[56:59]
	v_mfma_f32_16x16x32_bf16 v[44:47], v[128:131], v[198:201], v[44:47]
	v_mfma_f32_16x16x32_bf16 v[40:43], v[152:155], v[198:201], v[40:43]
	v_mfma_f32_16x16x32_bf16 v[28:31], v[128:131], v[212:215], v[28:31]
	v_mfma_f32_16x16x32_bf16 v[24:27], v[152:155], v[212:215], v[24:27]
	v_mfma_f32_16x16x32_bf16 v[12:15], v[128:131], v[220:223], v[12:15]
	v_mfma_f32_16x16x32_bf16 v[8:11], v[152:155], v[220:223], v[8:11]
	v_mfma_f32_16x16x32_bf16 v[60:63], v[132:135], v[194:197], v[60:63]
	v_mfma_f32_16x16x32_bf16 v[56:59], v[156:159], v[194:197], v[56:59]
	v_mfma_f32_16x16x32_bf16 v[44:47], v[132:135], v[208:211], v[44:47]
	v_mfma_f32_16x16x32_bf16 v[40:43], v[156:159], v[208:211], v[40:43]
	v_mfma_f32_16x16x32_bf16 v[28:31], v[132:135], v[216:219], v[28:31]
	v_mfma_f32_16x16x32_bf16 v[24:27], v[156:159], v[216:219], v[24:27]
	v_mfma_f32_16x16x32_bf16 v[12:15], v[132:135], v[224:227], v[12:15]
	v_mfma_f32_16x16x32_bf16 v[8:11], v[156:159], v[224:227], v[8:11]
	s_setprio 0
	s_setprio 1
	v_mfma_f32_16x16x32_bf16 v[52:55], v[172:175], v[190:193], v[52:55]
	v_mfma_f32_16x16x32_bf16 v[48:51], v[182:185], v[190:193], v[48:51]
	v_mfma_f32_16x16x32_bf16 v[36:39], v[172:175], v[198:201], v[36:39]
	v_mfma_f32_16x16x32_bf16 v[32:35], v[182:185], v[198:201], v[32:35]
	v_mfma_f32_16x16x32_bf16 v[20:23], v[172:175], v[212:215], v[20:23]
	v_mfma_f32_16x16x32_bf16 v[16:19], v[182:185], v[212:215], v[16:19]
	v_mfma_f32_16x16x32_bf16 v[4:7], v[172:175], v[220:223], v[4:7]
	v_mfma_f32_16x16x32_bf16 v[0:3], v[182:185], v[220:223], v[0:3]
	v_mfma_f32_16x16x32_bf16 v[52:55], v[176:179], v[194:197], v[52:55]
	v_mfma_f32_16x16x32_bf16 v[48:51], v[186:189], v[194:197], v[48:51]
	v_mfma_f32_16x16x32_bf16 v[36:39], v[176:179], v[208:211], v[36:39]
	v_mfma_f32_16x16x32_bf16 v[32:35], v[186:189], v[208:211], v[32:35]
	v_mfma_f32_16x16x32_bf16 v[20:23], v[176:179], v[216:219], v[20:23]
	v_mfma_f32_16x16x32_bf16 v[16:19], v[186:189], v[216:219], v[16:19]
	v_mfma_f32_16x16x32_bf16 v[4:7], v[176:179], v[224:227], v[4:7]
	v_mfma_f32_16x16x32_bf16 v[0:3], v[186:189], v[224:227], v[0:3]
	s_setprio 0
	s_barrier
	s_add_i32 s93, s93, 2
	s_add_u32 s91, s91, 0x100
	s_addc_u32 s92, s92, 0
	s_cmp_gt_u32 s93, 41
	s_mov_b64 s[10:11], s[50:51]
	s_cbranch_scc0 .LBB0_269
	s_and_b64 vcc, exec, s[44:45]
	s_cbranch_vccz .LBB0_272
	s_barrier

; #define PG8_STAGE(bufoff, gbase, voff) do { _Pragma("unroll") for (int _i = 0; _i < 2; ++_i) \
;         __builtin_amdgcn_global_load_lds((const unsigned*)((const char*)(gbase) + (voff)[_i]), (PG8_LAS unsigned*)(lds + (bufoff) + ldsw + _i * 8192), 16, 0, 0); } while (0)
; #define PG8_LDA(dst, b, h) do { _Pragma("unroll") for (int m = 0; m < 4; ++m) _Pragma("unroll") for (int k = 0; k < 2; ++k) dst[m][k] = *(const PG8_LAS bf16x8*)(lds + PG8_SA(b, h) + aoff + m * 2048 + k * 1024); } while (0)
; #define PG8_LDB(dst, b, h) do { _Pragma("unroll") for (int n = 0; n < 2; ++n) _Pragma("unroll") for (int k = 0; k < 2; ++k) dst[n][k] = *(const PG8_LAS bf16x8*)(lds + PG8_SB(b, h) + boff + n * 2048 + k * 1024); } while (0)
; #define PG8_WAIT_V(n) asm volatile("s_waitcnt vmcnt(" #n ")" ::: "memory")
; #define PG8_BAR __builtin_amdgcn_s_barrier()
; template <class Epi, class Sched, bool ALIGN_EPI = false, bool SP2 = false>
; __device__ __forceinline__ void gemm_phase(PG8_LAS unsigned char* lds, const Gemm g, const Sched& S, const Epi& E) {
;     ...
;         const bool has_next = S.next(ui + 1, nxt);
;         const char* nA = has_next ? (const char*)g.A + (size_t)nxt.pm * tstep : cA; const char* nB = has_next ? (const char*)g.Bt + (size_t)nxt.pn * tstep : cB;
;         for (int t = 0; t < nt; t += 2) {
;             const bool last = (t == nt - 2);
;             const char* a1 = cA + (size_t)(t + 1) * kstep;
;             const char* a2 = last ? nA : cA + (size_t)(t + 2) * kstep; const char* b2 = last ? nB : cB + (size_t)(t + 2) * kstep;
;             const char* a3 = a2 + kstep; const char* b3 = b2 + kstep;
;             if (last && has_next) S.a_ready(nxt);
;             if constexpr (SP2) {
;             PG8_LDB(B0, 0, 0); PG8_LDB(B1, 0, 1); PG8_SCHED; PG8_LDA(At, 0, 0); PG8_STAGE(PG8_SA(1, 1), a1 + hstep, voffA);
;             PG8_WAIT_V(8); PG8_WAIT_L(0); PG8_BAR; PG8_MMA(0, 0, At, B0); PG8_MMA(0, 1, At, B1); PG8_BAR; PG8_SCHED;
;             PG8_LDA(At, 0, 1); PG8_STAGE(PG8_SB(0, 0), b2, voffB); PG8_STAGE(PG8_SB(0, 1), b2 + hstep, voffB); PG8_STAGE(PG8_SA(0, 0), a2, voffA);
;     ...
;         for (int a = 0; a < 2; ++a)
; #pragma unroll
;             for (int b = 0; b < 2; ++b)
; #pragma unroll
;                 for (int m = 0; m < 4; ++m)
; #pragma unroll
;                     for (int n = 0; n < 2; ++n) acc[a][b][m][n] = (f32x4){0.f, 0.f, 0.f, 0.f};
.LBB0_649:
	s_ashr_i32 s51, s50, 31
	s_lshl_b64 s[14:15], s[50:51], 19
	s_add_u32 s52, s40, s14
	s_addc_u32 s53, s41, s15
	s_and_b64 s[14:15], s[8:9], exec
	s_cselect_b32 s51, s53, s61
	s_cselect_b32 s57, s52, s60
	s_ashr_i32 s49, s48, 31
	s_lshl_b64 s[14:15], s[48:49], 19
	s_add_u32 s54, s82, s14
	s_addc_u32 s55, s83, s15
	s_and_b64 s[14:15], s[8:9], exec
	s_cselect_b32 s49, s55, s63
	s_cselect_b32 s89, s54, s62
	s_add_u32 s60, s60, 0x40080
	s_addc_u32 s61, s61, 0
	s_add_u32 s90, s62, 0x100
	s_addc_u32 s91, s63, 0
	s_mov_b32 s92, -2
	s_waitcnt lgkmcnt(0)
	s_waitcnt vmcnt(0)
	ds_read_b128 v[148:151], v155
	ds_read_b128 v[160:163], v155 offset:1024
	ds_read_b128 v[164:167], v155 offset:2048
	ds_read_b128 v[168:171], v155 offset:3072
	ds_read_b128 v[172:175], v156
	ds_read_b128 v[176:179], v156 offset:1024
	ds_read_b128 v[182:185], v156 offset:2048
	ds_read_b128 v[186:189], v156 offset:3072
	s_add_u32 s3, s60, 0xfffc0080
	s_addc_u32 s14, s61, -1
	s_cmp_eq_u32 s92, 12
	s_cselect_b32 s65, s51, s14
	s_cselect_b32 s64, s57, s3
	s_cselect_b32 s63, s49, s91
	s_cselect_b32 s62, s89, s90
	v_lshl_add_u64 v[202:203], s[60:61], 0, v[140:141]
	s_add_i32 m0, s43, 0xc000
	ds_read_b128 v[190:193], v157
	ds_read_b128 v[194:197], v157 offset:1024
	ds_read_b128 v[198:201], v157 offset:2048
	ds_read_b128 v[208:211], v157 offset:3072
	ds_read_b128 v[212:215], v157 offset:4096
	ds_read_b128 v[216:219], v157 offset:5120
	ds_read_b128 v[220:223], v157 offset:6144
	ds_read_b128 v[224:227], v157 offset:7168
	global_load_lds_dwordx4 v[202:203], off
	v_lshl_add_u64 v[202:203], s[60:61], 0, v[142:143]
	s_add_i32 m0, s43, 0xe000
	s_nop 0
	global_load_lds_dwordx4 v[202:203], off
	s_waitcnt vmcnt(8)
	s_waitcnt lgkmcnt(0)
	s_barrier
	s_setprio 1
	s_waitcnt lgkmcnt(0)
	v_mfma_f32_16x16x32_bf16 v[124:127], v[148:151], v[190:193], 0
	v_mfma_f32_16x16x32_bf16 v[120:123], v[164:167], v[190:193], 0
	v_mfma_f32_16x16x32_bf16 v[108:111], v[148:151], v[198:201], 0
	v_mfma_f32_16x16x32_bf16 v[104:107], v[164:167], v[198:201], 0
	v_mfma_f32_16x16x32_bf16 v[92:95], v[148:151], v[212:215], 0
	v_mfma_f32_16x16x32_bf16 v[88:91], v[164:167], v[212:215], 0
	v_mfma_f32_16x16x32_bf16 v[76:79], v[148:151], v[220:223], 0
	v_mfma_f32_16x16x32_bf16 v[72:75], v[164:167], v[220:223], 0
	v_mfma_f32_16x16x32_bf16 v[124:127], v[160:163], v[194:197], v[124:127]
	v_mfma_f32_16x16x32_bf16 v[120:123], v[168:171], v[194:197], v[120:123]
	v_mfma_f32_16x16x32_bf16 v[108:111], v[160:163], v[208:211], v[108:111]
	v_mfma_f32_16x16x32_bf16 v[104:107], v[168:171], v[208:211], v[104:107]
	v_mfma_f32_16x16x32_bf16 v[92:95], v[160:163], v[216:219], v[92:95]
	v_mfma_f32_16x16x32_bf16 v[88:91], v[168:171], v[216:219], v[88:91]
	v_mfma_f32_16x16x32_bf16 v[76:79], v[160:163], v[224:227], v[76:79]
	v_mfma_f32_16x16x32_bf16 v[72:75], v[168:171], v[224:227], v[72:75]
	s_setprio 0
	s_setprio 1
	v_mfma_f32_16x16x32_bf16 v[116:119], v[172:175], v[190:193], 0
	v_mfma_f32_16x16x32_bf16 v[112:115], v[182:185], v[190:193], 0
	v_mfma_f32_16x16x32_bf16 v[100:103], v[172:175], v[198:201], 0
	v_mfma_f32_16x16x32_bf16 v[96:99], v[182:185], v[198:201], 0
	v_mfma_f32_16x16x32_bf16 v[84:87], v[172:175], v[212:215], 0
	v_mfma_f32_16x16x32_bf16 v[80:83], v[182:185], v[212:215], 0
	v_mfma_f32_16x16x32_bf16 v[68:71], v[172:175], v[220:223], 0
	v_mfma_f32_16x16x32_bf16 v[64:67], v[182:185], v[220:223], 0
	v_mfma_f32_16x16x32_bf16 v[116:119], v[176:179], v[194:197], v[116:119]
	v_mfma_f32_16x16x32_bf16 v[112:115], v[186:189], v[194:197], v[112:115]
	v_mfma_f32_16x16x32_bf16 v[100:103], v[176:179], v[208:211], v[100:103]
	v_mfma_f32_16x16x32_bf16 v[96:99], v[186:189], v[208:211], v[96:99]
	v_mfma_f32_16x16x32_bf16 v[84:87], v[176:179], v[216:219], v[84:87]
	v_mfma_f32_16x16x32_bf16 v[80:83], v[186:189], v[216:219], v[80:83]
	v_mfma_f32_16x16x32_bf16 v[68:71], v[176:179], v[224:227], v[68:71]
	v_mfma_f32_16x16x32_bf16 v[64:67], v[186:189], v[224:227], v[64:67]
	s_setprio 0
	s_barrier
	s_add_i32 s3, s85, s34
	v_lshl_add_u64 v[202:203], s[62:63], 0, v[134:135]
	s_mov_b32 m0, s3
	ds_read_b128 v[190:193], v157 offset:16384
	ds_read_b128 v[194:197], v157 offset:17408
	ds_read_b128 v[198:201], v157 offset:18432
	ds_read_b128 v[208:211], v157 offset:19456
	ds_read_b128 v[212:215], v157 offset:20480
	ds_read_b128 v[216:219], v157 offset:21504
	ds_read_b128 v[220:223], v157 offset:22528
	ds_read_b128 v[224:227], v157 offset:23552
	global_load_lds_dwordx4 v[202:203], off
	s_add_i32 m0, s3, 0x2000
	s_add_u32 s14, s62, 0x40000
	v_lshl_add_u64 v[228:229], s[62:63], 0, v[138:139]
	s_addc_u32 s15, s63, 0
	s_add_i32 s3, s86, s34
	global_load_lds_dwordx4 v[228:229], off
	v_lshl_add_u64 v[230:231], s[14:15], 0, v[134:135]
	s_mov_b32 m0, s3
	global_load_lds_dwordx4 v[230:231], off
	v_lshl_add_u64 v[230:231], s[14:15], 0, v[138:139]
	s_add_i32 m0, s3, 0x2000
	s_nop 0
	global_load_lds_dwordx4 v[230:231], off
	v_lshl_add_u64 v[230:231], s[64:65], 0, v[132:133]
	s_mov_b32 m0, s43
	s_nop 0
	global_load_lds_dwordx4 v[230:231], off
	v_lshl_add_u64 v[232:233], s[64:65], 0, v[136:137]
	s_mov_b32 m0, s59
	s_nop 0
	global_load_lds_dwordx4 v[232:233], off
	s_waitcnt vmcnt(8)
	s_waitcnt lgkmcnt(0)
	s_barrier
; #define PG8_STAGE(bufoff, gbase, voff) do { _Pragma("unroll") for (int _i = 0; _i < 2; ++_i) \
;         __builtin_amdgcn_global_load_lds((const unsigned*)((const char*)(gbase) + (voff)[_i]), (PG8_LAS unsigned*)(lds + (bufoff) + ldsw + _i * 8192), 16, 0, 0); } while (0)
; #define PG8_LDA(dst, b, h) do { _Pragma("unroll") for (int m = 0; m < 4; ++m) _Pragma("unroll") for (int k = 0; k < 2; ++k) dst[m][k] = *(const PG8_LAS bf16x8*)(lds + PG8_SA(b, h) + aoff + m * 2048 + k * 1024); } while (0)
; #define PG8_LDB(dst, b, h) do { _Pragma("unroll") for (int n = 0; n < 2; ++n) _Pragma("unroll") for (int k = 0; k < 2; ++k) dst[n][k] = *(const PG8_LAS bf16x8*)(lds + PG8_SB(b, h) + boff + n * 2048 + k * 1024); } while (0)
; #define PG8_MMA(ai, bj, At, Bt) do { __builtin_amdgcn_s_setprio(1); _Pragma("unroll") for (int m = 0; m < 4; ++m) _Pragma("unroll") for (int n = 0; n < 2; ++n) _Pragma("unroll") for (int k = 0; k < 2; ++k) \
;         acc[ai][bj][m][n] = __builtin_amdgcn_mfma_f32_16x16x32_bf16(Bt[n][k], At[m][k], acc[ai][bj][m][n], 0, 0, 0); __builtin_amdgcn_s_setprio(0); } while (0)
; #define PG8_WAIT_V(n) asm volatile("s_waitcnt vmcnt(" #n ")" ::: "memory")
; #define PG8_WAIT_L(n) asm volatile("s_waitcnt lgkmcnt(" #n ")" ::: "memory")
; #define PG8_BAR __builtin_amdgcn_s_barrier()
; #define PG8_SCHED __builtin_amdgcn_sched_barrier(0)
; template <class Epi, class Sched, bool ALIGN_EPI = false, bool SP2 = false>
; __device__ __forceinline__ void gemm_phase(PG8_LAS unsigned char* lds, const Gemm g, const Sched& S, const Epi& E) {
;     ...
;             PG8_WAIT_V(8); PG8_WAIT_L(0); PG8_BAR; PG8_MMA(1, 0, At, B0); PG8_MMA(1, 1, At, B1); PG8_BAR; PG8_SCHED;
;             PG8_LDB(B0, 1, 0); PG8_LDB(B1, 1, 1); PG8_SCHED; PG8_LDA(At, 1, 0); PG8_STAGE(PG8_SA(0, 1), a2 + hstep, voffA);
;             PG8_WAIT_V(8); PG8_WAIT_L(0); PG8_BAR; PG8_MMA(0, 0, At, B0); PG8_MMA(0, 1, At, B1); PG8_BAR; PG8_SCHED;
	s_setprio 1
	s_waitcnt lgkmcnt(0)
	v_mfma_f32_16x16x32_bf16 v[60:63], v[148:151], v[190:193], 0
	v_mfma_f32_16x16x32_bf16 v[56:59], v[164:167], v[190:193], 0
	v_mfma_f32_16x16x32_bf16 v[44:47], v[148:151], v[198:201], 0
	v_mfma_f32_16x16x32_bf16 v[40:43], v[164:167], v[198:201], 0
	v_mfma_f32_16x16x32_bf16 v[28:31], v[148:151], v[212:215], 0
	v_mfma_f32_16x16x32_bf16 v[24:27], v[164:167], v[212:215], 0
	v_mfma_f32_16x16x32_bf16 v[12:15], v[148:151], v[220:223], 0
	v_mfma_f32_16x16x32_bf16 v[8:11], v[164:167], v[220:223], 0
	v_mfma_f32_16x16x32_bf16 v[60:63], v[160:163], v[194:197], v[60:63]
	v_mfma_f32_16x16x32_bf16 v[56:59], v[168:171], v[194:197], v[56:59]
	v_mfma_f32_16x16x32_bf16 v[44:47], v[160:163], v[208:211], v[44:47]
	v_mfma_f32_16x16x32_bf16 v[40:43], v[168:171], v[208:211], v[40:43]
	v_mfma_f32_16x16x32_bf16 v[28:31], v[160:163], v[216:219], v[28:31]
	v_mfma_f32_16x16x32_bf16 v[24:27], v[168:171], v[216:219], v[24:27]
	v_mfma_f32_16x16x32_bf16 v[12:15], v[160:163], v[224:227], v[12:15]
	v_mfma_f32_16x16x32_bf16 v[8:11], v[168:171], v[224:227], v[8:11]
	s_setprio 0
	s_setprio 1
	v_mfma_f32_16x16x32_bf16 v[52:55], v[172:175], v[190:193], 0
	v_mfma_f32_16x16x32_bf16 v[48:51], v[182:185], v[190:193], 0
	v_mfma_f32_16x16x32_bf16 v[36:39], v[172:175], v[198:201], 0
	v_mfma_f32_16x16x32_bf16 v[32:35], v[182:185], v[198:201], 0
	v_mfma_f32_16x16x32_bf16 v[20:23], v[172:175], v[212:215], 0
	v_mfma_f32_16x16x32_bf16 v[16:19], v[182:185], v[212:215], 0
	v_mfma_f32_16x16x32_bf16 v[4:7], v[172:175], v[220:223], 0
	v_mfma_f32_16x16x32_bf16 v[0:3], v[182:185], v[220:223], 0
	v_mfma_f32_16x16x32_bf16 v[52:55], v[176:179], v[194:197], v[52:55]
	v_mfma_f32_16x16x32_bf16 v[48:51], v[186:189], v[194:197], v[48:51]
	v_mfma_f32_16x16x32_bf16 v[36:39], v[176:179], v[208:211], v[36:39]
	v_mfma_f32_16x16x32_bf16 v[32:35], v[186:189], v[208:211], v[32:35]
	v_mfma_f32_16x16x32_bf16 v[20:23], v[176:179], v[216:219], v[20:23]
	v_mfma_f32_16x16x32_bf16 v[16:19], v[186:189], v[216:219], v[16:19]
	v_mfma_f32_16x16x32_bf16 v[4:7], v[176:179], v[224:227], v[4:7]
	v_mfma_f32_16x16x32_bf16 v[0:3], v[186:189], v[224:227], v[0:3]
	s_setprio 0
	s_barrier
	s_add_i32 s3, 0, 0x18000
	v_add_u32_e32 v159, s3, v131
	s_add_i32 s33, 0, 0x1c000
	ds_read_b128 v[148:151], v159
	ds_read_b128 v[160:163], v159 offset:1024
	ds_read_b128 v[164:167], v159 offset:2048
	ds_read_b128 v[168:171], v159 offset:3072
	v_add_u32_e32 v159, s33, v131
	ds_read_b128 v[172:175], v159
	ds_read_b128 v[176:179], v159 offset:1024
	ds_read_b128 v[182:185], v159 offset:2048
	ds_read_b128 v[186:189], v159 offset:3072
	s_add_u32 s14, s64, 0x40000
	s_addc_u32 s15, s65, 0
	s_mov_b32 m0, s66
	v_lshl_add_u64 v[234:235], s[14:15], 0, v[132:133]
	ds_read_b128 v[190:193], v157 offset:32768
	ds_read_b128 v[194:197], v157 offset:33792
	ds_read_b128 v[198:201], v157 offset:34816
	ds_read_b128 v[208:211], v157 offset:35840
	ds_read_b128 v[212:215], v157 offset:36864
	ds_read_b128 v[216:219], v157 offset:37888
	ds_read_b128 v[220:223], v157 offset:38912
	ds_read_b128 v[224:227], v157 offset:39936
	global_load_lds_dwordx4 v[234:235], off
	v_lshl_add_u64 v[234:235], s[14:15], 0, v[136:137]
	s_mov_b32 m0, s67
	s_nop 0
	global_load_lds_dwordx4 v[234:235], off
	s_waitcnt vmcnt(8)
	s_waitcnt lgkmcnt(0)
	s_barrier
	s_setprio 1
	s_waitcnt lgkmcnt(0)
	v_mfma_f32_16x16x32_bf16 v[124:127], v[148:151], v[190:193], v[124:127]
	v_mfma_f32_16x16x32_bf16 v[120:123], v[164:167], v[190:193], v[120:123]
	v_mfma_f32_16x16x32_bf16 v[108:111], v[148:151], v[198:201], v[108:111]
	v_mfma_f32_16x16x32_bf16 v[104:107], v[164:167], v[198:201], v[104:107]
	v_mfma_f32_16x16x32_bf16 v[92:95], v[148:151], v[212:215], v[92:95]
	v_mfma_f32_16x16x32_bf16 v[88:91], v[164:167], v[212:215], v[88:91]
	v_mfma_f32_16x16x32_bf16 v[76:79], v[148:151], v[220:223], v[76:79]
	v_mfma_f32_16x16x32_bf16 v[72:75], v[164:167], v[220:223], v[72:75]
	v_mfma_f32_16x16x32_bf16 v[124:127], v[160:163], v[194:197], v[124:127]
	v_mfma_f32_16x16x32_bf16 v[120:123], v[168:171], v[194:197], v[120:123]
	v_mfma_f32_16x16x32_bf16 v[108:111], v[160:163], v[208:211], v[108:111]
	v_mfma_f32_16x16x32_bf16 v[104:107], v[168:171], v[208:211], v[104:107]
	v_mfma_f32_16x16x32_bf16 v[92:95], v[160:163], v[216:219], v[92:95]
	v_mfma_f32_16x16x32_bf16 v[88:91], v[168:171], v[216:219], v[88:91]
	v_mfma_f32_16x16x32_bf16 v[76:79], v[160:163], v[224:227], v[76:79]
	v_mfma_f32_16x16x32_bf16 v[72:75], v[168:171], v[224:227], v[72:75]
	s_setprio 0
	s_setprio 1
	v_mfma_f32_16x16x32_bf16 v[116:119], v[172:175], v[190:193], v[116:119]
	v_mfma_f32_16x16x32_bf16 v[112:115], v[182:185], v[190:193], v[112:115]
	v_mfma_f32_16x16x32_bf16 v[100:103], v[172:175], v[198:201], v[100:103]
	v_mfma_f32_16x16x32_bf16 v[96:99], v[182:185], v[198:201], v[96:99]
	v_mfma_f32_16x16x32_bf16 v[84:87], v[172:175], v[212:215], v[84:87]
	v_mfma_f32_16x16x32_bf16 v[80:83], v[182:185], v[212:215], v[80:83]
	v_mfma_f32_16x16x32_bf16 v[68:71], v[172:175], v[220:223], v[68:71]
	v_mfma_f32_16x16x32_bf16 v[64:67], v[182:185], v[220:223], v[64:67]
	v_mfma_f32_16x16x32_bf16 v[116:119], v[176:179], v[194:197], v[116:119]
	v_mfma_f32_16x16x32_bf16 v[112:115], v[186:189], v[194:197], v[112:115]
	v_mfma_f32_16x16x32_bf16 v[100:103], v[176:179], v[208:211], v[100:103]
	v_mfma_f32_16x16x32_bf16 v[96:99], v[186:189], v[208:211], v[96:99]
	v_mfma_f32_16x16x32_bf16 v[84:87], v[176:179], v[216:219], v[84:87]
	v_mfma_f32_16x16x32_bf16 v[80:83], v[186:189], v[216:219], v[80:83]
	v_mfma_f32_16x16x32_bf16 v[68:71], v[176:179], v[224:227], v[68:71]
	v_mfma_f32_16x16x32_bf16 v[64:67], v[186:189], v[224:227], v[64:67]
	s_setprio 0
	s_barrier
; #define PG8_STAGE(bufoff, gbase, voff) do { _Pragma("unroll") for (int _i = 0; _i < 2; ++_i) \
;         __builtin_amdgcn_global_load_lds((const unsigned*)((const char*)(gbase) + (voff)[_i]), (PG8_LAS unsigned*)(lds + (bufoff) + ldsw + _i * 8192), 16, 0, 0); } while (0)
; #define PG8_LDA(dst, b, h) do { _Pragma("unroll") for (int m = 0; m < 4; ++m) _Pragma("unroll") for (int k = 0; k < 2; ++k) dst[m][k] = *(const PG8_LAS bf16x8*)(lds + PG8_SA(b, h) + aoff + m * 2048 + k * 1024); } while (0)
; #define PG8_LDB(dst, b, h) do { _Pragma("unroll") for (int n = 0; n < 2; ++n) _Pragma("unroll") for (int k = 0; k < 2; ++k) dst[n][k] = *(const PG8_LAS bf16x8*)(lds + PG8_SB(b, h) + boff + n * 2048 + k * 1024); } while (0)
; #define PG8_MMA(ai, bj, At, Bt) do { __builtin_amdgcn_s_setprio(1); _Pragma("unroll") for (int m = 0; m < 4; ++m) _Pragma("unroll") for (int n = 0; n < 2; ++n) _Pragma("unroll") for (int k = 0; k < 2; ++k) \
;         acc[ai][bj][m][n] = __builtin_amdgcn_mfma_f32_16x16x32_bf16(Bt[n][k], At[m][k], acc[ai][bj][m][n], 0, 0, 0); __builtin_amdgcn_s_setprio(0); } while (0)
; #define PG8_WAIT_V(n) asm volatile("s_waitcnt vmcnt(" #n ")" ::: "memory")
; #define PG8_WAIT_L(n) asm volatile("s_waitcnt lgkmcnt(" #n ")" ::: "memory")
; #define PG8_BAR __builtin_amdgcn_s_barrier()
; #define PG8_SCHED __builtin_amdgcn_sched_barrier(0)
; template <class Epi, class Sched, bool ALIGN_EPI = false, bool SP2 = false>
; __device__ __forceinline__ void gemm_phase(PG8_LAS unsigned char* lds, const Gemm g, const Sched& S, const Epi& E) {
;     ...
;             PG8_LDB(B0, 0, 0); PG8_LDB(B1, 0, 1); PG8_SCHED; PG8_LDA(At, 0, 0); PG8_STAGE(PG8_SA(1, 1), a1 + hstep, voffA);
;             PG8_WAIT_V(8); PG8_WAIT_L(0); PG8_BAR; PG8_MMA(0, 0, At, B0); PG8_MMA(0, 1, At, B1); PG8_BAR; PG8_SCHED;
;     ...
;             PG8_LDA(At, 1, 1); PG8_STAGE(PG8_SB(1, 0), b3, voffB); PG8_STAGE(PG8_SB(1, 1), b3 + hstep, voffB); PG8_STAGE(PG8_SA(1, 0), a3, voffA);
;             PG8_WAIT_V(8); PG8_WAIT_L(0); PG8_BAR; PG8_MMA(1, 0, At, B0); PG8_MMA(1, 1, At, B1); PG8_BAR; PG8_SCHED;
	s_add_i32 s3, s3, s34
	v_lshl_add_u64 v[202:203], v[202:203], 0, s[38:39]
	s_mov_b32 m0, s3
	ds_read_b128 v[190:193], v157 offset:49152
	ds_read_b128 v[194:197], v157 offset:50176
	ds_read_b128 v[198:201], v157 offset:51200
	ds_read_b128 v[208:211], v157 offset:52224
	ds_read_b128 v[212:215], v157 offset:53248
	ds_read_b128 v[216:219], v157 offset:54272
	ds_read_b128 v[220:223], v157 offset:55296
	ds_read_b128 v[224:227], v157 offset:56320
	global_load_lds_dwordx4 v[202:203], off
	s_add_i32 m0, s3, 0x2000
	s_add_u32 s14, s62, 0x40080
	v_lshl_add_u64 v[202:203], v[228:229], 0, s[38:39]
	s_addc_u32 s15, s63, 0
	s_add_i32 s3, s33, s34
	global_load_lds_dwordx4 v[202:203], off
	v_lshl_add_u64 v[202:203], s[14:15], 0, v[134:135]
	s_mov_b32 m0, s3
	s_nop 0
	global_load_lds_dwordx4 v[202:203], off
	v_lshl_add_u64 v[202:203], s[14:15], 0, v[138:139]
	s_add_i32 m0, s3, 0x2000
	s_nop 0
	global_load_lds_dwordx4 v[202:203], off
	v_lshl_add_u64 v[202:203], v[230:231], 0, s[38:39]
	s_mov_b32 m0, s75
	s_nop 0
	global_load_lds_dwordx4 v[202:203], off
	v_lshl_add_u64 v[202:203], v[232:233], 0, s[38:39]
	s_mov_b32 m0, s84
	s_nop 0
	global_load_lds_dwordx4 v[202:203], off
	s_waitcnt vmcnt(8)
	s_waitcnt lgkmcnt(0)
	s_barrier
	s_setprio 1
	s_waitcnt lgkmcnt(0)
	v_mfma_f32_16x16x32_bf16 v[60:63], v[148:151], v[190:193], v[60:63]
	v_mfma_f32_16x16x32_bf16 v[56:59], v[164:167], v[190:193], v[56:59]
	v_mfma_f32_16x16x32_bf16 v[44:47], v[148:151], v[198:201], v[44:47]
	v_mfma_f32_16x16x32_bf16 v[40:43], v[164:167], v[198:201], v[40:43]
	v_mfma_f32_16x16x32_bf16 v[28:31], v[148:151], v[212:215], v[28:31]
	v_mfma_f32_16x16x32_bf16 v[24:27], v[164:167], v[212:215], v[24:27]
	v_mfma_f32_16x16x32_bf16 v[12:15], v[148:151], v[220:223], v[12:15]
	v_mfma_f32_16x16x32_bf16 v[8:11], v[164:167], v[220:223], v[8:11]
	v_mfma_f32_16x16x32_bf16 v[60:63], v[160:163], v[194:197], v[60:63]
	v_mfma_f32_16x16x32_bf16 v[56:59], v[168:171], v[194:197], v[56:59]
	v_mfma_f32_16x16x32_bf16 v[44:47], v[160:163], v[208:211], v[44:47]
	v_mfma_f32_16x16x32_bf16 v[40:43], v[168:171], v[208:211], v[40:43]
	v_mfma_f32_16x16x32_bf16 v[28:31], v[160:163], v[216:219], v[28:31]
	v_mfma_f32_16x16x32_bf16 v[24:27], v[168:171], v[216:219], v[24:27]
	v_mfma_f32_16x16x32_bf16 v[12:15], v[160:163], v[224:227], v[12:15]
	v_mfma_f32_16x16x32_bf16 v[8:11], v[168:171], v[224:227], v[8:11]
	s_setprio 0
	s_setprio 1
	v_mfma_f32_16x16x32_bf16 v[52:55], v[172:175], v[190:193], v[52:55]
	v_mfma_f32_16x16x32_bf16 v[48:51], v[182:185], v[190:193], v[48:51]
	v_mfma_f32_16x16x32_bf16 v[36:39], v[172:175], v[198:201], v[36:39]
	v_mfma_f32_16x16x32_bf16 v[32:35], v[182:185], v[198:201], v[32:35]
	v_mfma_f32_16x16x32_bf16 v[20:23], v[172:175], v[212:215], v[20:23]
	v_mfma_f32_16x16x32_bf16 v[16:19], v[182:185], v[212:215], v[16:19]
	v_mfma_f32_16x16x32_bf16 v[4:7], v[172:175], v[220:223], v[4:7]
	v_mfma_f32_16x16x32_bf16 v[0:3], v[182:185], v[220:223], v[0:3]
	v_mfma_f32_16x16x32_bf16 v[52:55], v[176:179], v[194:197], v[52:55]
	v_mfma_f32_16x16x32_bf16 v[48:51], v[186:189], v[194:197], v[48:51]
	v_mfma_f32_16x16x32_bf16 v[36:39], v[176:179], v[208:211], v[36:39]
	v_mfma_f32_16x16x32_bf16 v[32:35], v[186:189], v[208:211], v[32:35]
	v_mfma_f32_16x16x32_bf16 v[20:23], v[176:179], v[216:219], v[20:23]
	v_mfma_f32_16x16x32_bf16 v[16:19], v[186:189], v[216:219], v[16:19]
	v_mfma_f32_16x16x32_bf16 v[4:7], v[176:179], v[224:227], v[4:7]
	v_mfma_f32_16x16x32_bf16 v[0:3], v[186:189], v[224:227], v[0:3]
	s_setprio 0
	s_barrier
	s_add_i32 s92, s92, 2
	s_add_u32 s60, s60, 0x100
	s_addc_u32 s61, s61, 0
	s_add_u32 s90, s90, 0x100
	s_addc_u32 s91, s91, 0
.LBB0_650:
	ds_read_b128 v[148:151], v155
	ds_read_b128 v[160:163], v155 offset:1024
	ds_read_b128 v[164:167], v155 offset:2048
	ds_read_b128 v[168:171], v155 offset:3072
	ds_read_b128 v[172:175], v156
	ds_read_b128 v[176:179], v156 offset:1024
	ds_read_b128 v[182:185], v156 offset:2048
	ds_read_b128 v[186:189], v156 offset:3072
	s_add_u32 s3, s60, 0xfffc0080
	s_addc_u32 s14, s61, -1
	s_cmp_eq_u32 s92, 12
	s_cselect_b32 s65, s51, s14
	s_cselect_b32 s64, s57, s3
	s_cselect_b32 s63, s49, s91
	s_cselect_b32 s62, s89, s90
	v_lshl_add_u64 v[202:203], s[60:61], 0, v[140:141]
	s_add_i32 m0, s43, 0xc000
	ds_read_b128 v[190:193], v157
	ds_read_b128 v[194:197], v157 offset:1024
	ds_read_b128 v[198:201], v157 offset:2048
	ds_read_b128 v[208:211], v157 offset:3072
	ds_read_b128 v[212:215], v157 offset:4096
	ds_read_b128 v[216:219], v157 offset:5120
	ds_read_b128 v[220:223], v157 offset:6144
	ds_read_b128 v[224:227], v157 offset:7168
	global_load_lds_dwordx4 v[202:203], off
	v_lshl_add_u64 v[202:203], s[60:61], 0, v[142:143]
	s_add_i32 m0, s43, 0xe000
	s_nop 0
	global_load_lds_dwordx4 v[202:203], off
	s_waitcnt vmcnt(8)
	s_waitcnt lgkmcnt(0)
	s_barrier
; #define PG8_STAGE(bufoff, gbase, voff) do { _Pragma("unroll") for (int _i = 0; _i < 2; ++_i) \
;         __builtin_amdgcn_global_load_lds((const unsigned*)((const char*)(gbase) + (voff)[_i]), (PG8_LAS unsigned*)(lds + (bufoff) + ldsw + _i * 8192), 16, 0, 0); } while (0)
; #define PG8_LDA(dst, b, h) do { _Pragma("unroll") for (int m = 0; m < 4; ++m) _Pragma("unroll") for (int k = 0; k < 2; ++k) dst[m][k] = *(const PG8_LAS bf16x8*)(lds + PG8_SA(b, h) + aoff + m * 2048 + k * 1024); } while (0)
; #define PG8_MMA(ai, bj, At, Bt) do { __builtin_amdgcn_s_setprio(1); _Pragma("unroll") for (int m = 0; m < 4; ++m) _Pragma("unroll") for (int n = 0; n < 2; ++n) _Pragma("unroll") for (int k = 0; k < 2; ++k) \
;         acc[ai][bj][m][n] = __builtin_amdgcn_mfma_f32_16x16x32_bf16(Bt[n][k], At[m][k], acc[ai][bj][m][n], 0, 0, 0); __builtin_amdgcn_s_setprio(0); } while (0)
; #define PG8_WAIT_V(n) asm volatile("s_waitcnt vmcnt(" #n ")" ::: "memory")
; #define PG8_WAIT_L(n) asm volatile("s_waitcnt lgkmcnt(" #n ")" ::: "memory")
; #define PG8_BAR __builtin_amdgcn_s_barrier()
; #define PG8_SCHED __builtin_amdgcn_sched_barrier(0)
; template <class Epi, class Sched, bool ALIGN_EPI = false, bool SP2 = false>
; __device__ __forceinline__ void gemm_phase(PG8_LAS unsigned char* lds, const Gemm g, const Sched& S, const Epi& E) {
;     ...
;             PG8_WAIT_V(8); PG8_WAIT_L(0); PG8_BAR; PG8_MMA(0, 0, At, B0); PG8_MMA(0, 1, At, B1); PG8_BAR; PG8_SCHED;
;             PG8_LDA(At, 0, 1); PG8_STAGE(PG8_SB(0, 0), b2, voffB); PG8_STAGE(PG8_SB(0, 1), b2 + hstep, voffB); PG8_STAGE(PG8_SA(0, 0), a2, voffA);
;             PG8_WAIT_V(8); PG8_WAIT_L(0); PG8_BAR; PG8_MMA(1, 0, At, B0); PG8_MMA(1, 1, At, B1); PG8_BAR; PG8_SCHED;
	s_setprio 1
	s_waitcnt lgkmcnt(0)
	v_mfma_f32_16x16x32_bf16 v[124:127], v[148:151], v[190:193], v[124:127]
	v_mfma_f32_16x16x32_bf16 v[120:123], v[164:167], v[190:193], v[120:123]
	v_mfma_f32_16x16x32_bf16 v[108:111], v[148:151], v[198:201], v[108:111]
	v_mfma_f32_16x16x32_bf16 v[104:107], v[164:167], v[198:201], v[104:107]
	v_mfma_f32_16x16x32_bf16 v[92:95], v[148:151], v[212:215], v[92:95]
	v_mfma_f32_16x16x32_bf16 v[88:91], v[164:167], v[212:215], v[88:91]
	v_mfma_f32_16x16x32_bf16 v[76:79], v[148:151], v[220:223], v[76:79]
	v_mfma_f32_16x16x32_bf16 v[72:75], v[164:167], v[220:223], v[72:75]
	v_mfma_f32_16x16x32_bf16 v[124:127], v[160:163], v[194:197], v[124:127]
	v_mfma_f32_16x16x32_bf16 v[120:123], v[168:171], v[194:197], v[120:123]
	v_mfma_f32_16x16x32_bf16 v[108:111], v[160:163], v[208:211], v[108:111]
	v_mfma_f32_16x16x32_bf16 v[104:107], v[168:171], v[208:211], v[104:107]
	v_mfma_f32_16x16x32_bf16 v[92:95], v[160:163], v[216:219], v[92:95]
	v_mfma_f32_16x16x32_bf16 v[88:91], v[168:171], v[216:219], v[88:91]
	v_mfma_f32_16x16x32_bf16 v[76:79], v[160:163], v[224:227], v[76:79]
	v_mfma_f32_16x16x32_bf16 v[72:75], v[168:171], v[224:227], v[72:75]
	s_setprio 0
	s_setprio 1
	v_mfma_f32_16x16x32_bf16 v[116:119], v[172:175], v[190:193], v[116:119]
	v_mfma_f32_16x16x32_bf16 v[112:115], v[182:185], v[190:193], v[112:115]
	v_mfma_f32_16x16x32_bf16 v[100:103], v[172:175], v[198:201], v[100:103]
	v_mfma_f32_16x16x32_bf16 v[96:99], v[182:185], v[198:201], v[96:99]
	v_mfma_f32_16x16x32_bf16 v[84:87], v[172:175], v[212:215], v[84:87]
	v_mfma_f32_16x16x32_bf16 v[80:83], v[182:185], v[212:215], v[80:83]
	v_mfma_f32_16x16x32_bf16 v[68:71], v[172:175], v[220:223], v[68:71]
	v_mfma_f32_16x16x32_bf16 v[64:67], v[182:185], v[220:223], v[64:67]
	v_mfma_f32_16x16x32_bf16 v[116:119], v[176:179], v[194:197], v[116:119]
	v_mfma_f32_16x16x32_bf16 v[112:115], v[186:189], v[194:197], v[112:115]
	v_mfma_f32_16x16x32_bf16 v[100:103], v[176:179], v[208:211], v[100:103]
	v_mfma_f32_16x16x32_bf16 v[96:99], v[186:189], v[208:211], v[96:99]
	v_mfma_f32_16x16x32_bf16 v[84:87], v[176:179], v[216:219], v[84:87]
	v_mfma_f32_16x16x32_bf16 v[80:83], v[186:189], v[216:219], v[80:83]
	v_mfma_f32_16x16x32_bf16 v[68:71], v[176:179], v[224:227], v[68:71]
	v_mfma_f32_16x16x32_bf16 v[64:67], v[186:189], v[224:227], v[64:67]
	s_setprio 0
	s_barrier
	s_add_i32 s3, s85, s34
	v_lshl_add_u64 v[202:203], s[62:63], 0, v[134:135]
	s_mov_b32 m0, s3
	ds_read_b128 v[190:193], v157 offset:16384
	ds_read_b128 v[194:197], v157 offset:17408
	ds_read_b128 v[198:201], v157 offset:18432
	ds_read_b128 v[208:211], v157 offset:19456
	ds_read_b128 v[212:215], v157 offset:20480
	ds_read_b128 v[216:219], v157 offset:21504
	ds_read_b128 v[220:223], v157 offset:22528
	ds_read_b128 v[224:227], v157 offset:23552
	global_load_lds_dwordx4 v[202:203], off
	s_add_i32 m0, s3, 0x2000
	s_add_u32 s14, s62, 0x40000
	v_lshl_add_u64 v[228:229], s[62:63], 0, v[138:139]
	s_addc_u32 s15, s63, 0
	s_add_i32 s3, s86, s34
	global_load_lds_dwordx4 v[228:229], off
	v_lshl_add_u64 v[230:231], s[14:15], 0, v[134:135]
	s_mov_b32 m0, s3
	global_load_lds_dwordx4 v[230:231], off
	v_lshl_add_u64 v[230:231], s[14:15], 0, v[138:139]
	s_add_i32 m0, s3, 0x2000
	s_nop 0
	global_load_lds_dwordx4 v[230:231], off
	v_lshl_add_u64 v[230:231], s[64:65], 0, v[132:133]
	s_mov_b32 m0, s43
	s_nop 0
	global_load_lds_dwordx4 v[230:231], off
	v_lshl_add_u64 v[232:233], s[64:65], 0, v[136:137]
	s_mov_b32 m0, s59
	s_nop 0
	global_load_lds_dwordx4 v[232:233], off
	s_waitcnt vmcnt(8)
	s_waitcnt lgkmcnt(0)
	s_barrier
	s_setprio 1
	s_waitcnt lgkmcnt(0)
	v_mfma_f32_16x16x32_bf16 v[60:63], v[148:151], v[190:193], v[60:63]
	v_mfma_f32_16x16x32_bf16 v[56:59], v[164:167], v[190:193], v[56:59]
	v_mfma_f32_16x16x32_bf16 v[44:47], v[148:151], v[198:201], v[44:47]
	v_mfma_f32_16x16x32_bf16 v[40:43], v[164:167], v[198:201], v[40:43]
	v_mfma_f32_16x16x32_bf16 v[28:31], v[148:151], v[212:215], v[28:31]
	v_mfma_f32_16x16x32_bf16 v[24:27], v[164:167], v[212:215], v[24:27]
	v_mfma_f32_16x16x32_bf16 v[12:15], v[148:151], v[220:223], v[12:15]
	v_mfma_f32_16x16x32_bf16 v[8:11], v[164:167], v[220:223], v[8:11]
	v_mfma_f32_16x16x32_bf16 v[60:63], v[160:163], v[194:197], v[60:63]
	v_mfma_f32_16x16x32_bf16 v[56:59], v[168:171], v[194:197], v[56:59]
	v_mfma_f32_16x16x32_bf16 v[44:47], v[160:163], v[208:211], v[44:47]
	v_mfma_f32_16x16x32_bf16 v[40:43], v[168:171], v[208:211], v[40:43]
	v_mfma_f32_16x16x32_bf16 v[28:31], v[160:163], v[216:219], v[28:31]
	v_mfma_f32_16x16x32_bf16 v[24:27], v[168:171], v[216:219], v[24:27]
	v_mfma_f32_16x16x32_bf16 v[12:15], v[160:163], v[224:227], v[12:15]
	v_mfma_f32_16x16x32_bf16 v[8:11], v[168:171], v[224:227], v[8:11]
	s_setprio 0
	s_setprio 1
	v_mfma_f32_16x16x32_bf16 v[52:55], v[172:175], v[190:193], v[52:55]
	v_mfma_f32_16x16x32_bf16 v[48:51], v[182:185], v[190:193], v[48:51]
	v_mfma_f32_16x16x32_bf16 v[36:39], v[172:175], v[198:201], v[36:39]
	v_mfma_f32_16x16x32_bf16 v[32:35], v[182:185], v[198:201], v[32:35]
	v_mfma_f32_16x16x32_bf16 v[20:23], v[172:175], v[212:215], v[20:23]
	v_mfma_f32_16x16x32_bf16 v[16:19], v[182:185], v[212:215], v[16:19]
	v_mfma_f32_16x16x32_bf16 v[4:7], v[172:175], v[220:223], v[4:7]
	v_mfma_f32_16x16x32_bf16 v[0:3], v[182:185], v[220:223], v[0:3]
	v_mfma_f32_16x16x32_bf16 v[52:55], v[176:179], v[194:197], v[52:55]
	v_mfma_f32_16x16x32_bf16 v[48:51], v[186:189], v[194:197], v[48:51]
	v_mfma_f32_16x16x32_bf16 v[36:39], v[176:179], v[208:211], v[36:39]
	v_mfma_f32_16x16x32_bf16 v[32:35], v[186:189], v[208:211], v[32:35]
	v_mfma_f32_16x16x32_bf16 v[20:23], v[176:179], v[216:219], v[20:23]
	v_mfma_f32_16x16x32_bf16 v[16:19], v[186:189], v[216:219], v[16:19]
	v_mfma_f32_16x16x32_bf16 v[4:7], v[176:179], v[224:227], v[4:7]
	v_mfma_f32_16x16x32_bf16 v[0:3], v[186:189], v[224:227], v[0:3]
	s_setprio 0
	s_barrier
; #define PG8_STAGE(bufoff, gbase, voff) do { _Pragma("unroll") for (int _i = 0; _i < 2; ++_i) \
;         __builtin_amdgcn_global_load_lds((const unsigned*)((const char*)(gbase) + (voff)[_i]), (PG8_LAS unsigned*)(lds + (bufoff) + ldsw + _i * 8192), 16, 0, 0); } while (0)
; #define PG8_LDA(dst, b, h) do { _Pragma("unroll") for (int m = 0; m < 4; ++m) _Pragma("unroll") for (int k = 0; k < 2; ++k) dst[m][k] = *(const PG8_LAS bf16x8*)(lds + PG8_SA(b, h) + aoff + m * 2048 + k * 1024); } while (0)
; #define PG8_LDB(dst, b, h) do { _Pragma("unroll") for (int n = 0; n < 2; ++n) _Pragma("unroll") for (int k = 0; k < 2; ++k) dst[n][k] = *(const PG8_LAS bf16x8*)(lds + PG8_SB(b, h) + boff + n * 2048 + k * 1024); } while (0)
; #define PG8_MMA(ai, bj, At, Bt) do { __builtin_amdgcn_s_setprio(1); _Pragma("unroll") for (int m = 0; m < 4; ++m) _Pragma("unroll") for (int n = 0; n < 2; ++n) _Pragma("unroll") for (int k = 0; k < 2; ++k) \
;         acc[ai][bj][m][n] = __builtin_amdgcn_mfma_f32_16x16x32_bf16(Bt[n][k], At[m][k], acc[ai][bj][m][n], 0, 0, 0); __builtin_amdgcn_s_setprio(0); } while (0)
; #define PG8_WAIT_V(n) asm volatile("s_waitcnt vmcnt(" #n ")" ::: "memory")
; #define PG8_WAIT_L(n) asm volatile("s_waitcnt lgkmcnt(" #n ")" ::: "memory")
; #define PG8_BAR __builtin_amdgcn_s_barrier()
; #define PG8_SCHED __builtin_amdgcn_sched_barrier(0)
; template <class Epi, class Sched, bool ALIGN_EPI = false, bool SP2 = false>
; __device__ __forceinline__ void gemm_phase(PG8_LAS unsigned char* lds, const Gemm g, const Sched& S, const Epi& E) {
;     ...
;             PG8_LDB(B0, 1, 0); PG8_LDB(B1, 1, 1); PG8_SCHED; PG8_LDA(At, 1, 0); PG8_STAGE(PG8_SA(0, 1), a2 + hstep, voffA);
;             PG8_WAIT_V(8); PG8_WAIT_L(0); PG8_BAR; PG8_MMA(0, 0, At, B0); PG8_MMA(0, 1, At, B1); PG8_BAR; PG8_SCHED;
	s_add_i32 s3, 0, 0x18000
	v_add_u32_e32 v159, s3, v131
	s_add_i32 s33, 0, 0x1c000
	ds_read_b128 v[148:151], v159
	ds_read_b128 v[160:163], v159 offset:1024
	ds_read_b128 v[164:167], v159 offset:2048
	ds_read_b128 v[168:171], v159 offset:3072
	v_add_u32_e32 v159, s33, v131
	ds_read_b128 v[172:175], v159
	ds_read_b128 v[176:179], v159 offset:1024
	ds_read_b128 v[182:185], v159 offset:2048
	ds_read_b128 v[186:189], v159 offset:3072
	s_add_u32 s14, s64, 0x40000
	s_addc_u32 s15, s65, 0
	s_mov_b32 m0, s66
	v_lshl_add_u64 v[234:235], s[14:15], 0, v[132:133]
	ds_read_b128 v[190:193], v157 offset:32768
	ds_read_b128 v[194:197], v157 offset:33792
	ds_read_b128 v[198:201], v157 offset:34816
	ds_read_b128 v[208:211], v157 offset:35840
	ds_read_b128 v[212:215], v157 offset:36864
	ds_read_b128 v[216:219], v157 offset:37888
	ds_read_b128 v[220:223], v157 offset:38912
	ds_read_b128 v[224:227], v157 offset:39936
	global_load_lds_dwordx4 v[234:235], off
	v_lshl_add_u64 v[234:235], s[14:15], 0, v[136:137]
	s_mov_b32 m0, s67
	s_nop 0
	global_load_lds_dwordx4 v[234:235], off
	s_waitcnt vmcnt(8)
	s_waitcnt lgkmcnt(0)
	s_barrier
	s_setprio 1
	s_waitcnt lgkmcnt(0)
	v_mfma_f32_16x16x32_bf16 v[124:127], v[148:151], v[190:193], v[124:127]
	v_mfma_f32_16x16x32_bf16 v[120:123], v[164:167], v[190:193], v[120:123]
	v_mfma_f32_16x16x32_bf16 v[108:111], v[148:151], v[198:201], v[108:111]
	v_mfma_f32_16x16x32_bf16 v[104:107], v[164:167], v[198:201], v[104:107]
	v_mfma_f32_16x16x32_bf16 v[92:95], v[148:151], v[212:215], v[92:95]
	v_mfma_f32_16x16x32_bf16 v[88:91], v[164:167], v[212:215], v[88:91]
	v_mfma_f32_16x16x32_bf16 v[76:79], v[148:151], v[220:223], v[76:79]
	v_mfma_f32_16x16x32_bf16 v[72:75], v[164:167], v[220:223], v[72:75]
	v_mfma_f32_16x16x32_bf16 v[124:127], v[160:163], v[194:197], v[124:127]
	v_mfma_f32_16x16x32_bf16 v[120:123], v[168:171], v[194:197], v[120:123]
	v_mfma_f32_16x16x32_bf16 v[108:111], v[160:163], v[208:211], v[108:111]
	v_mfma_f32_16x16x32_bf16 v[104:107], v[168:171], v[208:211], v[104:107]
	v_mfma_f32_16x16x32_bf16 v[92:95], v[160:163], v[216:219], v[92:95]
	v_mfma_f32_16x16x32_bf16 v[88:91], v[168:171], v[216:219], v[88:91]
	v_mfma_f32_16x16x32_bf16 v[76:79], v[160:163], v[224:227], v[76:79]
	v_mfma_f32_16x16x32_bf16 v[72:75], v[168:171], v[224:227], v[72:75]
	s_setprio 0
	s_setprio 1
	v_mfma_f32_16x16x32_bf16 v[116:119], v[172:175], v[190:193], v[116:119]
	v_mfma_f32_16x16x32_bf16 v[112:115], v[182:185], v[190:193], v[112:115]
	v_mfma_f32_16x16x32_bf16 v[100:103], v[172:175], v[198:201], v[100:103]
	v_mfma_f32_16x16x32_bf16 v[96:99], v[182:185], v[198:201], v[96:99]
	v_mfma_f32_16x16x32_bf16 v[84:87], v[172:175], v[212:215], v[84:87]
	v_mfma_f32_16x16x32_bf16 v[80:83], v[182:185], v[212:215], v[80:83]
	v_mfma_f32_16x16x32_bf16 v[68:71], v[172:175], v[220:223], v[68:71]
	v_mfma_f32_16x16x32_bf16 v[64:67], v[182:185], v[220:223], v[64:67]
	v_mfma_f32_16x16x32_bf16 v[116:119], v[176:179], v[194:197], v[116:119]
	v_mfma_f32_16x16x32_bf16 v[112:115], v[186:189], v[194:197], v[112:115]
	v_mfma_f32_16x16x32_bf16 v[100:103], v[176:179], v[208:211], v[100:103]
	v_mfma_f32_16x16x32_bf16 v[96:99], v[186:189], v[208:211], v[96:99]
	v_mfma_f32_16x16x32_bf16 v[84:87], v[176:179], v[216:219], v[84:87]
	v_mfma_f32_16x16x32_bf16 v[80:83], v[186:189], v[216:219], v[80:83]
	v_mfma_f32_16x16x32_bf16 v[68:71], v[176:179], v[224:227], v[68:71]
	v_mfma_f32_16x16x32_bf16 v[64:67], v[186:189], v[224:227], v[64:67]
	s_setprio 0
	s_barrier
; #define PG8_STAGE(bufoff, gbase, voff) do { _Pragma("unroll") for (int _i = 0; _i < 2; ++_i) \
;         __builtin_amdgcn_global_load_lds((const unsigned*)((const char*)(gbase) + (voff)[_i]), (PG8_LAS unsigned*)(lds + (bufoff) + ldsw + _i * 8192), 16, 0, 0); } while (0)
; #define PG8_LDA(dst, b, h) do { _Pragma("unroll") for (int m = 0; m < 4; ++m) _Pragma("unroll") for (int k = 0; k < 2; ++k) dst[m][k] = *(const PG8_LAS bf16x8*)(lds + PG8_SA(b, h) + aoff + m * 2048 + k * 1024); } while (0)
; #define PG8_MMA(ai, bj, At, Bt) do { __builtin_amdgcn_s_setprio(1); _Pragma("unroll") for (int m = 0; m < 4; ++m) _Pragma("unroll") for (int n = 0; n < 2; ++n) _Pragma("unroll") for (int k = 0; k < 2; ++k) \
;         acc[ai][bj][m][n] = __builtin_amdgcn_mfma_f32_16x16x32_bf16(Bt[n][k], At[m][k], acc[ai][bj][m][n], 0, 0, 0); __builtin_amdgcn_s_setprio(0); } while (0)
; #define PG8_WAIT_V(n) asm volatile("s_waitcnt vmcnt(" #n ")" ::: "memory")
; #define PG8_WAIT_L(n) asm volatile("s_waitcnt lgkmcnt(" #n ")" ::: "memory")
; #define PG8_BAR __builtin_amdgcn_s_barrier()
; #define PG8_SCHED __builtin_amdgcn_sched_barrier(0)
; template <class Epi, class Sched, bool ALIGN_EPI = false, bool SP2 = false>
; __device__ __forceinline__ void gemm_phase(PG8_LAS unsigned char* lds, const Gemm g, const Sched& S, const Epi& E) {
;     ...
;             PG8_LDA(At, 1, 1); PG8_STAGE(PG8_SB(1, 0), b3, voffB); PG8_STAGE(PG8_SB(1, 1), b3 + hstep, voffB); PG8_STAGE(PG8_SA(1, 0), a3, voffA);
;             PG8_WAIT_V(8); PG8_WAIT_L(0); PG8_BAR; PG8_MMA(1, 0, At, B0); PG8_MMA(1, 1, At, B1); PG8_BAR; PG8_SCHED;
;     ...
;         if constexpr (ALIGN_EPI) { if (wr == 0) PG8_BAR; }
	s_add_i32 s3, s3, s34
	v_lshl_add_u64 v[202:203], v[202:203], 0, s[38:39]
	s_mov_b32 m0, s3
	ds_read_b128 v[190:193], v157 offset:49152
	ds_read_b128 v[194:197], v157 offset:50176
	ds_read_b128 v[198:201], v157 offset:51200
	ds_read_b128 v[208:211], v157 offset:52224
	ds_read_b128 v[212:215], v157 offset:53248
	ds_read_b128 v[216:219], v157 offset:54272
	ds_read_b128 v[220:223], v157 offset:55296
	ds_read_b128 v[224:227], v157 offset:56320
	global_load_lds_dwordx4 v[202:203], off
	s_add_i32 m0, s3, 0x2000
	s_add_u32 s14, s62, 0x40080
	v_lshl_add_u64 v[202:203], v[228:229], 0, s[38:39]
	s_addc_u32 s15, s63, 0
	s_add_i32 s3, s33, s34
	global_load_lds_dwordx4 v[202:203], off
	v_lshl_add_u64 v[202:203], s[14:15], 0, v[134:135]
	s_mov_b32 m0, s3
	s_nop 0
	global_load_lds_dwordx4 v[202:203], off
	v_lshl_add_u64 v[202:203], s[14:15], 0, v[138:139]
	s_add_i32 m0, s3, 0x2000
	s_nop 0
	global_load_lds_dwordx4 v[202:203], off
	v_lshl_add_u64 v[202:203], v[230:231], 0, s[38:39]
	s_mov_b32 m0, s75
	s_nop 0
	global_load_lds_dwordx4 v[202:203], off
	v_lshl_add_u64 v[202:203], v[232:233], 0, s[38:39]
	s_mov_b32 m0, s84
	s_nop 0
	global_load_lds_dwordx4 v[202:203], off
	s_waitcnt vmcnt(8)
	s_waitcnt lgkmcnt(0)
	s_barrier
	s_setprio 1
	s_waitcnt lgkmcnt(0)
	v_mfma_f32_16x16x32_bf16 v[60:63], v[148:151], v[190:193], v[60:63]
	v_mfma_f32_16x16x32_bf16 v[56:59], v[164:167], v[190:193], v[56:59]
	v_mfma_f32_16x16x32_bf16 v[44:47], v[148:151], v[198:201], v[44:47]
	v_mfma_f32_16x16x32_bf16 v[40:43], v[164:167], v[198:201], v[40:43]
	v_mfma_f32_16x16x32_bf16 v[28:31], v[148:151], v[212:215], v[28:31]
	v_mfma_f32_16x16x32_bf16 v[24:27], v[164:167], v[212:215], v[24:27]
	v_mfma_f32_16x16x32_bf16 v[12:15], v[148:151], v[220:223], v[12:15]
	v_mfma_f32_16x16x32_bf16 v[8:11], v[164:167], v[220:223], v[8:11]
	v_mfma_f32_16x16x32_bf16 v[60:63], v[160:163], v[194:197], v[60:63]
	v_mfma_f32_16x16x32_bf16 v[56:59], v[168:171], v[194:197], v[56:59]
	v_mfma_f32_16x16x32_bf16 v[44:47], v[160:163], v[208:211], v[44:47]
	v_mfma_f32_16x16x32_bf16 v[40:43], v[168:171], v[208:211], v[40:43]
	v_mfma_f32_16x16x32_bf16 v[28:31], v[160:163], v[216:219], v[28:31]
	v_mfma_f32_16x16x32_bf16 v[24:27], v[168:171], v[216:219], v[24:27]
	v_mfma_f32_16x16x32_bf16 v[12:15], v[160:163], v[224:227], v[12:15]
	v_mfma_f32_16x16x32_bf16 v[8:11], v[168:171], v[224:227], v[8:11]
	s_setprio 0
	s_setprio 1
	v_mfma_f32_16x16x32_bf16 v[52:55], v[172:175], v[190:193], v[52:55]
	v_mfma_f32_16x16x32_bf16 v[48:51], v[182:185], v[190:193], v[48:51]
	v_mfma_f32_16x16x32_bf16 v[36:39], v[172:175], v[198:201], v[36:39]
	v_mfma_f32_16x16x32_bf16 v[32:35], v[182:185], v[198:201], v[32:35]
	v_mfma_f32_16x16x32_bf16 v[20:23], v[172:175], v[212:215], v[20:23]
	v_mfma_f32_16x16x32_bf16 v[16:19], v[182:185], v[212:215], v[16:19]
	v_mfma_f32_16x16x32_bf16 v[4:7], v[172:175], v[220:223], v[4:7]
	v_mfma_f32_16x16x32_bf16 v[0:3], v[182:185], v[220:223], v[0:3]
	v_mfma_f32_16x16x32_bf16 v[52:55], v[176:179], v[194:197], v[52:55]
	v_mfma_f32_16x16x32_bf16 v[48:51], v[186:189], v[194:197], v[48:51]
	v_mfma_f32_16x16x32_bf16 v[36:39], v[176:179], v[208:211], v[36:39]
	v_mfma_f32_16x16x32_bf16 v[32:35], v[186:189], v[208:211], v[32:35]
	v_mfma_f32_16x16x32_bf16 v[20:23], v[176:179], v[216:219], v[20:23]
	v_mfma_f32_16x16x32_bf16 v[16:19], v[186:189], v[216:219], v[16:19]
	v_mfma_f32_16x16x32_bf16 v[4:7], v[176:179], v[224:227], v[4:7]
	v_mfma_f32_16x16x32_bf16 v[0:3], v[186:189], v[224:227], v[0:3]
	s_setprio 0
	s_barrier
	s_add_i32 s92, s92, 2
	s_add_u32 s60, s60, 0x100
	s_addc_u32 s61, s61, 0
	s_add_u32 s90, s90, 0x100
	s_addc_u32 s91, s91, 0
	s_cmp_gt_u32 s92, 13
	s_cbranch_scc0 .LBB0_650
	s_and_b64 vcc, exec, s[44:45]
	s_cbranch_vccz .LBB0_653
	s_barrier

; #define PG8_STAGE(bufoff, gbase, voff) do { _Pragma("unroll") for (int _i = 0; _i < 2; ++_i) \
;         __builtin_amdgcn_global_load_lds((const unsigned*)((const char*)(gbase) + (voff)[_i]), (PG8_LAS unsigned*)(lds + (bufoff) + ldsw + _i * 8192), 16, 0, 0); } while (0)
; #define PG8_LDA(dst, b, h) do { _Pragma("unroll") for (int m = 0; m < 4; ++m) _Pragma("unroll") for (int k = 0; k < 2; ++k) dst[m][k] = *(const PG8_LAS bf16x8*)(lds + PG8_SA(b, h) + aoff + m * 2048 + k * 1024); } while (0)
; #define PG8_LDB(dst, b, h) do { _Pragma("unroll") for (int n = 0; n < 2; ++n) _Pragma("unroll") for (int k = 0; k < 2; ++k) dst[n][k] = *(const PG8_LAS bf16x8*)(lds + PG8_SB(b, h) + boff + n * 2048 + k * 1024); } while (0)
; #define PG8_MMA(ai, bj, At, Bt) do { __builtin_amdgcn_s_setprio(1); _Pragma("unroll") for (int m = 0; m < 4; ++m) _Pragma("unroll") for (int n = 0; n < 2; ++n) _Pragma("unroll") for (int k = 0; k < 2; ++k) \
;         acc[ai][bj][m][n] = __builtin_amdgcn_mfma_f32_16x16x32_bf16(Bt[n][k], At[m][k], acc[ai][bj][m][n], 0, 0, 0); __builtin_amdgcn_s_setprio(0); } while (0)
; #define PG8_BAR __builtin_amdgcn_s_barrier()
; template <class Epi, class Sched, bool ALIGN_EPI = false, bool SP2 = false>
; __device__ __forceinline__ void gemm_phase(PG8_LAS unsigned char* lds, const Gemm g, const Sched& S, const Epi& E) {
;     ...
;         const bool has_next = S.next(ui + 1, nxt);
;         const char* nA = has_next ? (const char*)g.A + (size_t)nxt.pm * tstep : cA; const char* nB = has_next ? (const char*)g.Bt + (size_t)nxt.pn * tstep : cB;
;         for (int t = 0; t < nt; t += 2) {
;             const bool last = (t == nt - 2);
;             const char* a1 = cA + (size_t)(t + 1) * kstep;
;             const char* a2 = last ? nA : cA + (size_t)(t + 2) * kstep; const char* b2 = last ? nB : cB + (size_t)(t + 2) * kstep;
;             const char* a3 = a2 + kstep; const char* b3 = b2 + kstep;
;             if (last && has_next) S.a_ready(nxt);
;             if constexpr (SP2) {
;             PG8_LDB(B0, 0, 0); PG8_LDB(B1, 0, 1); PG8_SCHED; PG8_LDA(At, 0, 0); PG8_STAGE(PG8_SA(1, 1), a1 + hstep, voffA);
;             PG8_WAIT_V(8); PG8_WAIT_L(0); PG8_BAR; PG8_MMA(0, 0, At, B0); PG8_MMA(0, 1, At, B1); PG8_BAR; PG8_SCHED;
;             PG8_LDA(At, 0, 1); PG8_STAGE(PG8_SB(0, 0), b2, voffB); PG8_STAGE(PG8_SB(0, 1), b2 + hstep, voffB); PG8_STAGE(PG8_SA(0, 0), a2, voffA);
.LBB0_872:
	s_ashr_i32 s49, s48, 31
	s_lshl_b64 s[50:51], s[48:49], 18
	s_add_u32 s50, s92, s50
	s_addc_u32 s51, s93, s51
	s_and_b64 s[52:53], s[10:11], exec
	s_cselect_b32 s49, s51, s59
	s_cselect_b32 s55, s50, s58
	s_ashr_i32 s45, s44, 31
	s_lshl_b64 s[52:53], s[44:45], 18
	s_add_u32 s52, s76, s52
	s_addc_u32 s53, s77, s53
	s_and_b64 s[62:63], s[10:11], exec
	s_cselect_b32 s45, s53, s61
	s_cselect_b32 s84, s52, s60
	s_add_u32 s58, s58, 0x20080
	s_addc_u32 s59, s59, 0
	s_add_u32 s85, s60, 0x100
	s_addc_u32 s86, s61, 0
	s_mov_b32 s87, -2
	s_waitcnt lgkmcnt(0)
	ds_read_b128 v[144:147], v151
	ds_read_b128 v[156:159], v151 offset:1024
	ds_read_b128 v[160:163], v151 offset:2048
	ds_read_b128 v[164:167], v151 offset:3072
	ds_read_b128 v[168:171], v152
	ds_read_b128 v[172:175], v152 offset:1024
	ds_read_b128 v[176:179], v152 offset:2048
	ds_read_b128 v[182:185], v152 offset:3072
	s_add_u32 s3, s58, 0xfffe0080
	s_addc_u32 s33, s59, -1
	s_cmp_eq_u32 s87, 4
	s_cselect_b32 s63, s49, s33
	s_cselect_b32 s62, s55, s3
	s_cselect_b32 s61, s45, s86
	s_cselect_b32 s60, s84, s85
	v_lshl_add_u64 v[202:203], s[58:59], 0, v[136:137]
	s_add_i32 m0, s15, 0xc000
	ds_read_b128 v[186:189], v153
	ds_read_b128 v[190:193], v153 offset:1024
	ds_read_b128 v[194:197], v153 offset:2048
	ds_read_b128 v[198:201], v153 offset:3072
	ds_read_b128 v[208:211], v153 offset:4096
	ds_read_b128 v[212:215], v153 offset:5120
	ds_read_b128 v[216:219], v153 offset:6144
	ds_read_b128 v[220:223], v153 offset:7168
	global_load_lds_dwordx4 v[202:203], off
	v_lshl_add_u64 v[202:203], s[58:59], 0, v[138:139]
	s_add_i32 m0, s15, 0xe000
	s_nop 0
	global_load_lds_dwordx4 v[202:203], off
	s_waitcnt vmcnt(8)
	s_waitcnt lgkmcnt(0)
	s_barrier
	s_setprio 1
	s_waitcnt lgkmcnt(0)
	v_mfma_f32_16x16x32_bf16 v[124:127], v[144:147], v[186:189], 0
	v_mfma_f32_16x16x32_bf16 v[120:123], v[160:163], v[186:189], 0
	v_mfma_f32_16x16x32_bf16 v[108:111], v[144:147], v[194:197], 0
	v_mfma_f32_16x16x32_bf16 v[104:107], v[160:163], v[194:197], 0
	v_mfma_f32_16x16x32_bf16 v[92:95], v[144:147], v[208:211], 0
	v_mfma_f32_16x16x32_bf16 v[88:91], v[160:163], v[208:211], 0
	v_mfma_f32_16x16x32_bf16 v[76:79], v[144:147], v[216:219], 0
	v_mfma_f32_16x16x32_bf16 v[72:75], v[160:163], v[216:219], 0
	v_mfma_f32_16x16x32_bf16 v[124:127], v[156:159], v[190:193], v[124:127]
	v_mfma_f32_16x16x32_bf16 v[120:123], v[164:167], v[190:193], v[120:123]
	v_mfma_f32_16x16x32_bf16 v[108:111], v[156:159], v[198:201], v[108:111]
	v_mfma_f32_16x16x32_bf16 v[104:107], v[164:167], v[198:201], v[104:107]
	v_mfma_f32_16x16x32_bf16 v[92:95], v[156:159], v[212:215], v[92:95]
	v_mfma_f32_16x16x32_bf16 v[88:91], v[164:167], v[212:215], v[88:91]
	v_mfma_f32_16x16x32_bf16 v[76:79], v[156:159], v[220:223], v[76:79]
	v_mfma_f32_16x16x32_bf16 v[72:75], v[164:167], v[220:223], v[72:75]
	s_setprio 0
	s_setprio 1
	v_mfma_f32_16x16x32_bf16 v[116:119], v[168:171], v[186:189], 0
	v_mfma_f32_16x16x32_bf16 v[112:115], v[176:179], v[186:189], 0
	v_mfma_f32_16x16x32_bf16 v[100:103], v[168:171], v[194:197], 0
	v_mfma_f32_16x16x32_bf16 v[96:99], v[176:179], v[194:197], 0
	v_mfma_f32_16x16x32_bf16 v[84:87], v[168:171], v[208:211], 0
	v_mfma_f32_16x16x32_bf16 v[80:83], v[176:179], v[208:211], 0
	v_mfma_f32_16x16x32_bf16 v[68:71], v[168:171], v[216:219], 0
	v_mfma_f32_16x16x32_bf16 v[64:67], v[176:179], v[216:219], 0
	v_mfma_f32_16x16x32_bf16 v[116:119], v[172:175], v[190:193], v[116:119]
	v_mfma_f32_16x16x32_bf16 v[112:115], v[182:185], v[190:193], v[112:115]
	v_mfma_f32_16x16x32_bf16 v[100:103], v[172:175], v[198:201], v[100:103]
	v_mfma_f32_16x16x32_bf16 v[96:99], v[182:185], v[198:201], v[96:99]
	v_mfma_f32_16x16x32_bf16 v[84:87], v[172:175], v[212:215], v[84:87]
	v_mfma_f32_16x16x32_bf16 v[80:83], v[182:185], v[212:215], v[80:83]
	v_mfma_f32_16x16x32_bf16 v[68:71], v[172:175], v[220:223], v[68:71]
	v_mfma_f32_16x16x32_bf16 v[64:67], v[182:185], v[220:223], v[64:67]
	s_setprio 0
	s_barrier
	s_add_i32 s3, s74, s14
	v_lshl_add_u64 v[202:203], s[60:61], 0, v[130:131]
	s_mov_b32 m0, s3
	ds_read_b128 v[186:189], v153 offset:16384
	ds_read_b128 v[190:193], v153 offset:17408
	ds_read_b128 v[194:197], v153 offset:18432
	ds_read_b128 v[198:201], v153 offset:19456
	ds_read_b128 v[208:211], v153 offset:20480
	ds_read_b128 v[212:215], v153 offset:21504
	ds_read_b128 v[216:219], v153 offset:22528
	ds_read_b128 v[220:223], v153 offset:23552
	global_load_lds_dwordx4 v[202:203], off
	s_add_i32 m0, s3, 0x2000
	s_add_u32 s78, s60, 0x20000
	v_lshl_add_u64 v[224:225], s[60:61], 0, v[134:135]
	s_addc_u32 s79, s61, 0
	s_add_i32 s3, s75, s14
	global_load_lds_dwordx4 v[224:225], off
	v_lshl_add_u64 v[226:227], s[78:79], 0, v[130:131]
	s_mov_b32 m0, s3
	global_load_lds_dwordx4 v[226:227], off
	v_lshl_add_u64 v[226:227], s[78:79], 0, v[134:135]
	s_add_i32 m0, s3, 0x2000
	s_nop 0
	global_load_lds_dwordx4 v[226:227], off
	v_lshl_add_u64 v[226:227], s[62:63], 0, v[128:129]
	s_mov_b32 m0, s15
	s_nop 0
	global_load_lds_dwordx4 v[226:227], off
	v_lshl_add_u64 v[228:229], s[62:63], 0, v[132:133]
	s_mov_b32 m0, s34
	s_nop 0
	global_load_lds_dwordx4 v[228:229], off
	s_waitcnt vmcnt(8)
	s_waitcnt lgkmcnt(0)
	s_barrier
; #define PG8_STAGE(bufoff, gbase, voff) do { _Pragma("unroll") for (int _i = 0; _i < 2; ++_i) \
;         __builtin_amdgcn_global_load_lds((const unsigned*)((const char*)(gbase) + (voff)[_i]), (PG8_LAS unsigned*)(lds + (bufoff) + ldsw + _i * 8192), 16, 0, 0); } while (0)
; #define PG8_LDA(dst, b, h) do { _Pragma("unroll") for (int m = 0; m < 4; ++m) _Pragma("unroll") for (int k = 0; k < 2; ++k) dst[m][k] = *(const PG8_LAS bf16x8*)(lds + PG8_SA(b, h) + aoff + m * 2048 + k * 1024); } while (0)
; #define PG8_LDB(dst, b, h) do { _Pragma("unroll") for (int n = 0; n < 2; ++n) _Pragma("unroll") for (int k = 0; k < 2; ++k) dst[n][k] = *(const PG8_LAS bf16x8*)(lds + PG8_SB(b, h) + boff + n * 2048 + k * 1024); } while (0)
; #define PG8_MMA(ai, bj, At, Bt) do { __builtin_amdgcn_s_setprio(1); _Pragma("unroll") for (int m = 0; m < 4; ++m) _Pragma("unroll") for (int n = 0; n < 2; ++n) _Pragma("unroll") for (int k = 0; k < 2; ++k) \
;         acc[ai][bj][m][n] = __builtin_amdgcn_mfma_f32_16x16x32_bf16(Bt[n][k], At[m][k], acc[ai][bj][m][n], 0, 0, 0); __builtin_amdgcn_s_setprio(0); } while (0)
; #define PG8_WAIT_V(n) asm volatile("s_waitcnt vmcnt(" #n ")" ::: "memory")
; #define PG8_WAIT_L(n) asm volatile("s_waitcnt lgkmcnt(" #n ")" ::: "memory")
; #define PG8_BAR __builtin_amdgcn_s_barrier()
; #define PG8_SCHED __builtin_amdgcn_sched_barrier(0)
; template <class Epi, class Sched, bool ALIGN_EPI = false, bool SP2 = false>
; __device__ __forceinline__ void gemm_phase(PG8_LAS unsigned char* lds, const Gemm g, const Sched& S, const Epi& E) {
;     ...
;             PG8_WAIT_V(8); PG8_WAIT_L(0); PG8_BAR; PG8_MMA(1, 0, At, B0); PG8_MMA(1, 1, At, B1); PG8_BAR; PG8_SCHED;
;             PG8_LDB(B0, 1, 0); PG8_LDB(B1, 1, 1); PG8_SCHED; PG8_LDA(At, 1, 0); PG8_STAGE(PG8_SA(0, 1), a2 + hstep, voffA);
;             PG8_WAIT_V(8); PG8_WAIT_L(0); PG8_BAR; PG8_MMA(0, 0, At, B0); PG8_MMA(0, 1, At, B1); PG8_BAR; PG8_SCHED;
	s_setprio 1
	s_waitcnt lgkmcnt(0)
	v_mfma_f32_16x16x32_bf16 v[60:63], v[144:147], v[186:189], 0
	v_mfma_f32_16x16x32_bf16 v[56:59], v[160:163], v[186:189], 0
	v_mfma_f32_16x16x32_bf16 v[44:47], v[144:147], v[194:197], 0
	v_mfma_f32_16x16x32_bf16 v[40:43], v[160:163], v[194:197], 0
	v_mfma_f32_16x16x32_bf16 v[28:31], v[144:147], v[208:211], 0
	v_mfma_f32_16x16x32_bf16 v[24:27], v[160:163], v[208:211], 0
	v_mfma_f32_16x16x32_bf16 v[12:15], v[144:147], v[216:219], 0
	v_mfma_f32_16x16x32_bf16 v[8:11], v[160:163], v[216:219], 0
	v_mfma_f32_16x16x32_bf16 v[60:63], v[156:159], v[190:193], v[60:63]
	v_mfma_f32_16x16x32_bf16 v[56:59], v[164:167], v[190:193], v[56:59]
	v_mfma_f32_16x16x32_bf16 v[44:47], v[156:159], v[198:201], v[44:47]
	v_mfma_f32_16x16x32_bf16 v[40:43], v[164:167], v[198:201], v[40:43]
	v_mfma_f32_16x16x32_bf16 v[28:31], v[156:159], v[212:215], v[28:31]
	v_mfma_f32_16x16x32_bf16 v[24:27], v[164:167], v[212:215], v[24:27]
	v_mfma_f32_16x16x32_bf16 v[12:15], v[156:159], v[220:223], v[12:15]
	v_mfma_f32_16x16x32_bf16 v[8:11], v[164:167], v[220:223], v[8:11]
	s_setprio 0
	s_setprio 1
	v_mfma_f32_16x16x32_bf16 v[52:55], v[168:171], v[186:189], 0
	v_mfma_f32_16x16x32_bf16 v[48:51], v[176:179], v[186:189], 0
	v_mfma_f32_16x16x32_bf16 v[36:39], v[168:171], v[194:197], 0
	v_mfma_f32_16x16x32_bf16 v[32:35], v[176:179], v[194:197], 0
	v_mfma_f32_16x16x32_bf16 v[20:23], v[168:171], v[208:211], 0
	v_mfma_f32_16x16x32_bf16 v[16:19], v[176:179], v[208:211], 0
	v_mfma_f32_16x16x32_bf16 v[4:7], v[168:171], v[216:219], 0
	v_mfma_f32_16x16x32_bf16 v[0:3], v[176:179], v[216:219], 0
	v_mfma_f32_16x16x32_bf16 v[52:55], v[172:175], v[190:193], v[52:55]
	v_mfma_f32_16x16x32_bf16 v[48:51], v[182:185], v[190:193], v[48:51]
	v_mfma_f32_16x16x32_bf16 v[36:39], v[172:175], v[198:201], v[36:39]
	v_mfma_f32_16x16x32_bf16 v[32:35], v[182:185], v[198:201], v[32:35]
	v_mfma_f32_16x16x32_bf16 v[20:23], v[172:175], v[212:215], v[20:23]
	v_mfma_f32_16x16x32_bf16 v[16:19], v[182:185], v[212:215], v[16:19]
	v_mfma_f32_16x16x32_bf16 v[4:7], v[172:175], v[220:223], v[4:7]
	v_mfma_f32_16x16x32_bf16 v[0:3], v[182:185], v[220:223], v[0:3]
	s_setprio 0
	s_barrier
	s_add_i32 s3, 0, 0x18000
	v_add_u32_e32 v155, s3, v149
	s_add_i32 s33, 0, 0x1c000
	ds_read_b128 v[144:147], v155
	ds_read_b128 v[156:159], v155 offset:1024
	ds_read_b128 v[160:163], v155 offset:2048
	ds_read_b128 v[164:167], v155 offset:3072
	v_add_u32_e32 v155, s33, v149
	ds_read_b128 v[168:171], v155
	ds_read_b128 v[172:175], v155 offset:1024
	ds_read_b128 v[176:179], v155 offset:2048
	ds_read_b128 v[182:185], v155 offset:3072
	s_add_u32 s62, s62, 0x20000
	s_addc_u32 s63, s63, 0
	s_mov_b32 m0, s57
	v_lshl_add_u64 v[230:231], s[62:63], 0, v[128:129]
	ds_read_b128 v[186:189], v153 offset:32768
	ds_read_b128 v[190:193], v153 offset:33792
	ds_read_b128 v[194:197], v153 offset:34816
	ds_read_b128 v[198:201], v153 offset:35840
	ds_read_b128 v[208:211], v153 offset:36864
	ds_read_b128 v[212:215], v153 offset:37888
	ds_read_b128 v[216:219], v153 offset:38912
	ds_read_b128 v[220:223], v153 offset:39936
	global_load_lds_dwordx4 v[230:231], off
	v_lshl_add_u64 v[230:231], s[62:63], 0, v[132:133]
	s_mov_b32 m0, s64
	s_nop 0
	global_load_lds_dwordx4 v[230:231], off
	s_waitcnt vmcnt(8)
	s_waitcnt lgkmcnt(0)
	s_barrier
	s_setprio 1
	s_waitcnt lgkmcnt(0)
	v_mfma_f32_16x16x32_bf16 v[124:127], v[144:147], v[186:189], v[124:127]
	v_mfma_f32_16x16x32_bf16 v[120:123], v[160:163], v[186:189], v[120:123]
	v_mfma_f32_16x16x32_bf16 v[108:111], v[144:147], v[194:197], v[108:111]
	v_mfma_f32_16x16x32_bf16 v[104:107], v[160:163], v[194:197], v[104:107]
	v_mfma_f32_16x16x32_bf16 v[92:95], v[144:147], v[208:211], v[92:95]
	v_mfma_f32_16x16x32_bf16 v[88:91], v[160:163], v[208:211], v[88:91]
	v_mfma_f32_16x16x32_bf16 v[76:79], v[144:147], v[216:219], v[76:79]
	v_mfma_f32_16x16x32_bf16 v[72:75], v[160:163], v[216:219], v[72:75]
	v_mfma_f32_16x16x32_bf16 v[124:127], v[156:159], v[190:193], v[124:127]
	v_mfma_f32_16x16x32_bf16 v[120:123], v[164:167], v[190:193], v[120:123]
	v_mfma_f32_16x16x32_bf16 v[108:111], v[156:159], v[198:201], v[108:111]
	v_mfma_f32_16x16x32_bf16 v[104:107], v[164:167], v[198:201], v[104:107]
	v_mfma_f32_16x16x32_bf16 v[92:95], v[156:159], v[212:215], v[92:95]
	v_mfma_f32_16x16x32_bf16 v[88:91], v[164:167], v[212:215], v[88:91]
	v_mfma_f32_16x16x32_bf16 v[76:79], v[156:159], v[220:223], v[76:79]
	v_mfma_f32_16x16x32_bf16 v[72:75], v[164:167], v[220:223], v[72:75]
	s_setprio 0
	s_setprio 1
	v_mfma_f32_16x16x32_bf16 v[116:119], v[168:171], v[186:189], v[116:119]
	v_mfma_f32_16x16x32_bf16 v[112:115], v[176:179], v[186:189], v[112:115]
	v_mfma_f32_16x16x32_bf16 v[100:103], v[168:171], v[194:197], v[100:103]
	v_mfma_f32_16x16x32_bf16 v[96:99], v[176:179], v[194:197], v[96:99]
	v_mfma_f32_16x16x32_bf16 v[84:87], v[168:171], v[208:211], v[84:87]
	v_mfma_f32_16x16x32_bf16 v[80:83], v[176:179], v[208:211], v[80:83]
	v_mfma_f32_16x16x32_bf16 v[68:71], v[168:171], v[216:219], v[68:71]
	v_mfma_f32_16x16x32_bf16 v[64:67], v[176:179], v[216:219], v[64:67]
	v_mfma_f32_16x16x32_bf16 v[116:119], v[172:175], v[190:193], v[116:119]
	v_mfma_f32_16x16x32_bf16 v[112:115], v[182:185], v[190:193], v[112:115]
	v_mfma_f32_16x16x32_bf16 v[100:103], v[172:175], v[198:201], v[100:103]
	v_mfma_f32_16x16x32_bf16 v[96:99], v[182:185], v[198:201], v[96:99]
	v_mfma_f32_16x16x32_bf16 v[84:87], v[172:175], v[212:215], v[84:87]
	v_mfma_f32_16x16x32_bf16 v[80:83], v[182:185], v[212:215], v[80:83]
	v_mfma_f32_16x16x32_bf16 v[68:71], v[172:175], v[220:223], v[68:71]
	v_mfma_f32_16x16x32_bf16 v[64:67], v[182:185], v[220:223], v[64:67]
	s_setprio 0
	s_barrier
; #define PG8_STAGE(bufoff, gbase, voff) do { _Pragma("unroll") for (int _i = 0; _i < 2; ++_i) \
;         __builtin_amdgcn_global_load_lds((const unsigned*)((const char*)(gbase) + (voff)[_i]), (PG8_LAS unsigned*)(lds + (bufoff) + ldsw + _i * 8192), 16, 0, 0); } while (0)
; #define PG8_LDA(dst, b, h) do { _Pragma("unroll") for (int m = 0; m < 4; ++m) _Pragma("unroll") for (int k = 0; k < 2; ++k) dst[m][k] = *(const PG8_LAS bf16x8*)(lds + PG8_SA(b, h) + aoff + m * 2048 + k * 1024); } while (0)
; #define PG8_LDB(dst, b, h) do { _Pragma("unroll") for (int n = 0; n < 2; ++n) _Pragma("unroll") for (int k = 0; k < 2; ++k) dst[n][k] = *(const PG8_LAS bf16x8*)(lds + PG8_SB(b, h) + boff + n * 2048 + k * 1024); } while (0)
; #define PG8_MMA(ai, bj, At, Bt) do { __builtin_amdgcn_s_setprio(1); _Pragma("unroll") for (int m = 0; m < 4; ++m) _Pragma("unroll") for (int n = 0; n < 2; ++n) _Pragma("unroll") for (int k = 0; k < 2; ++k) \
;         acc[ai][bj][m][n] = __builtin_amdgcn_mfma_f32_16x16x32_bf16(Bt[n][k], At[m][k], acc[ai][bj][m][n], 0, 0, 0); __builtin_amdgcn_s_setprio(0); } while (0)
; #define PG8_WAIT_V(n) asm volatile("s_waitcnt vmcnt(" #n ")" ::: "memory")
; #define PG8_WAIT_L(n) asm volatile("s_waitcnt lgkmcnt(" #n ")" ::: "memory")
; #define PG8_BAR __builtin_amdgcn_s_barrier()
; #define PG8_SCHED __builtin_amdgcn_sched_barrier(0)
; template <class Epi, class Sched, bool ALIGN_EPI = false, bool SP2 = false>
; __device__ __forceinline__ void gemm_phase(PG8_LAS unsigned char* lds, const Gemm g, const Sched& S, const Epi& E) {
;     ...
;             PG8_LDB(B0, 0, 0); PG8_LDB(B1, 0, 1); PG8_SCHED; PG8_LDA(At, 0, 0); PG8_STAGE(PG8_SA(1, 1), a1 + hstep, voffA);
;             PG8_WAIT_V(8); PG8_WAIT_L(0); PG8_BAR; PG8_MMA(0, 0, At, B0); PG8_MMA(0, 1, At, B1); PG8_BAR; PG8_SCHED;
;     ...
;             PG8_LDA(At, 1, 1); PG8_STAGE(PG8_SB(1, 0), b3, voffB); PG8_STAGE(PG8_SB(1, 1), b3 + hstep, voffB); PG8_STAGE(PG8_SA(1, 0), a3, voffA);
;             PG8_WAIT_V(8); PG8_WAIT_L(0); PG8_BAR; PG8_MMA(1, 0, At, B0); PG8_MMA(1, 1, At, B1); PG8_BAR; PG8_SCHED;
	s_add_i32 s3, s3, s14
	v_lshl_add_u64 v[202:203], v[202:203], 0, s[38:39]
	s_mov_b32 m0, s3
	ds_read_b128 v[186:189], v153 offset:49152
	ds_read_b128 v[190:193], v153 offset:50176
	ds_read_b128 v[194:197], v153 offset:51200
	ds_read_b128 v[198:201], v153 offset:52224
	ds_read_b128 v[208:211], v153 offset:53248
	ds_read_b128 v[212:215], v153 offset:54272
	ds_read_b128 v[216:219], v153 offset:55296
	ds_read_b128 v[220:223], v153 offset:56320
	global_load_lds_dwordx4 v[202:203], off
	s_add_i32 m0, s3, 0x2000
	s_add_u32 s60, s60, 0x20080
	v_lshl_add_u64 v[202:203], v[224:225], 0, s[38:39]
	s_addc_u32 s61, s61, 0
	s_add_i32 s3, s33, s14
	global_load_lds_dwordx4 v[202:203], off
	v_lshl_add_u64 v[202:203], s[60:61], 0, v[130:131]
	s_mov_b32 m0, s3
	s_nop 0
	global_load_lds_dwordx4 v[202:203], off
	v_lshl_add_u64 v[202:203], s[60:61], 0, v[134:135]
	s_add_i32 m0, s3, 0x2000
	s_nop 0
	global_load_lds_dwordx4 v[202:203], off
	v_lshl_add_u64 v[202:203], v[226:227], 0, s[38:39]
	s_mov_b32 m0, s66
	s_nop 0
	global_load_lds_dwordx4 v[202:203], off
	v_lshl_add_u64 v[202:203], v[228:229], 0, s[38:39]
	s_mov_b32 m0, s67
	s_nop 0
	global_load_lds_dwordx4 v[202:203], off
	s_waitcnt vmcnt(8)
	s_waitcnt lgkmcnt(0)
	s_barrier
	s_setprio 1
	s_waitcnt lgkmcnt(0)
	v_mfma_f32_16x16x32_bf16 v[60:63], v[144:147], v[186:189], v[60:63]
	v_mfma_f32_16x16x32_bf16 v[56:59], v[160:163], v[186:189], v[56:59]
	v_mfma_f32_16x16x32_bf16 v[44:47], v[144:147], v[194:197], v[44:47]
	v_mfma_f32_16x16x32_bf16 v[40:43], v[160:163], v[194:197], v[40:43]
	v_mfma_f32_16x16x32_bf16 v[28:31], v[144:147], v[208:211], v[28:31]
	v_mfma_f32_16x16x32_bf16 v[24:27], v[160:163], v[208:211], v[24:27]
	v_mfma_f32_16x16x32_bf16 v[12:15], v[144:147], v[216:219], v[12:15]
	v_mfma_f32_16x16x32_bf16 v[8:11], v[160:163], v[216:219], v[8:11]
	v_mfma_f32_16x16x32_bf16 v[60:63], v[156:159], v[190:193], v[60:63]
	v_mfma_f32_16x16x32_bf16 v[56:59], v[164:167], v[190:193], v[56:59]
	v_mfma_f32_16x16x32_bf16 v[44:47], v[156:159], v[198:201], v[44:47]
	v_mfma_f32_16x16x32_bf16 v[40:43], v[164:167], v[198:201], v[40:43]
	v_mfma_f32_16x16x32_bf16 v[28:31], v[156:159], v[212:215], v[28:31]
	v_mfma_f32_16x16x32_bf16 v[24:27], v[164:167], v[212:215], v[24:27]
	v_mfma_f32_16x16x32_bf16 v[12:15], v[156:159], v[220:223], v[12:15]
	v_mfma_f32_16x16x32_bf16 v[8:11], v[164:167], v[220:223], v[8:11]
	s_setprio 0
	s_setprio 1
	v_mfma_f32_16x16x32_bf16 v[52:55], v[168:171], v[186:189], v[52:55]
	v_mfma_f32_16x16x32_bf16 v[48:51], v[176:179], v[186:189], v[48:51]
	v_mfma_f32_16x16x32_bf16 v[36:39], v[168:171], v[194:197], v[36:39]
	v_mfma_f32_16x16x32_bf16 v[32:35], v[176:179], v[194:197], v[32:35]
	v_mfma_f32_16x16x32_bf16 v[20:23], v[168:171], v[208:211], v[20:23]
	v_mfma_f32_16x16x32_bf16 v[16:19], v[176:179], v[208:211], v[16:19]
	v_mfma_f32_16x16x32_bf16 v[4:7], v[168:171], v[216:219], v[4:7]
	v_mfma_f32_16x16x32_bf16 v[0:3], v[176:179], v[216:219], v[0:3]
	v_mfma_f32_16x16x32_bf16 v[52:55], v[172:175], v[190:193], v[52:55]
	v_mfma_f32_16x16x32_bf16 v[48:51], v[182:185], v[190:193], v[48:51]
	v_mfma_f32_16x16x32_bf16 v[36:39], v[172:175], v[198:201], v[36:39]
	v_mfma_f32_16x16x32_bf16 v[32:35], v[182:185], v[198:201], v[32:35]
	v_mfma_f32_16x16x32_bf16 v[20:23], v[172:175], v[212:215], v[20:23]
	v_mfma_f32_16x16x32_bf16 v[16:19], v[182:185], v[212:215], v[16:19]
	v_mfma_f32_16x16x32_bf16 v[4:7], v[172:175], v[220:223], v[4:7]
	v_mfma_f32_16x16x32_bf16 v[0:3], v[182:185], v[220:223], v[0:3]
	s_setprio 0
	s_barrier
	s_add_i32 s87, s87, 2
	s_add_u32 s58, s58, 0x100
	s_addc_u32 s59, s59, 0
	s_add_u32 s85, s85, 0x100
	s_addc_u32 s86, s86, 0
.LBB0_873:
	ds_read_b128 v[144:147], v151
	ds_read_b128 v[156:159], v151 offset:1024
	ds_read_b128 v[160:163], v151 offset:2048
	ds_read_b128 v[164:167], v151 offset:3072
	ds_read_b128 v[168:171], v152
	ds_read_b128 v[172:175], v152 offset:1024
	ds_read_b128 v[176:179], v152 offset:2048
	ds_read_b128 v[182:185], v152 offset:3072
	s_add_u32 s3, s58, 0xfffe0080
	s_addc_u32 s33, s59, -1
	s_cmp_eq_u32 s87, 4
	s_cselect_b32 s63, s49, s33
	s_cselect_b32 s62, s55, s3
	s_cselect_b32 s61, s45, s86
	s_cselect_b32 s60, s84, s85
	v_lshl_add_u64 v[202:203], s[58:59], 0, v[136:137]
	s_add_i32 m0, s15, 0xc000
	ds_read_b128 v[186:189], v153
	ds_read_b128 v[190:193], v153 offset:1024
	ds_read_b128 v[194:197], v153 offset:2048
	ds_read_b128 v[198:201], v153 offset:3072
	ds_read_b128 v[208:211], v153 offset:4096
	ds_read_b128 v[212:215], v153 offset:5120
	ds_read_b128 v[216:219], v153 offset:6144
	ds_read_b128 v[220:223], v153 offset:7168
	global_load_lds_dwordx4 v[202:203], off
	v_lshl_add_u64 v[202:203], s[58:59], 0, v[138:139]
	s_add_i32 m0, s15, 0xe000
	s_nop 0
	global_load_lds_dwordx4 v[202:203], off
	s_waitcnt vmcnt(8)
	s_waitcnt lgkmcnt(0)
	s_barrier
; #define PG8_STAGE(bufoff, gbase, voff) do { _Pragma("unroll") for (int _i = 0; _i < 2; ++_i) \
;         __builtin_amdgcn_global_load_lds((const unsigned*)((const char*)(gbase) + (voff)[_i]), (PG8_LAS unsigned*)(lds + (bufoff) + ldsw + _i * 8192), 16, 0, 0); } while (0)
; #define PG8_LDA(dst, b, h) do { _Pragma("unroll") for (int m = 0; m < 4; ++m) _Pragma("unroll") for (int k = 0; k < 2; ++k) dst[m][k] = *(const PG8_LAS bf16x8*)(lds + PG8_SA(b, h) + aoff + m * 2048 + k * 1024); } while (0)
; #define PG8_MMA(ai, bj, At, Bt) do { __builtin_amdgcn_s_setprio(1); _Pragma("unroll") for (int m = 0; m < 4; ++m) _Pragma("unroll") for (int n = 0; n < 2; ++n) _Pragma("unroll") for (int k = 0; k < 2; ++k) \
;         acc[ai][bj][m][n] = __builtin_amdgcn_mfma_f32_16x16x32_bf16(Bt[n][k], At[m][k], acc[ai][bj][m][n], 0, 0, 0); __builtin_amdgcn_s_setprio(0); } while (0)
; #define PG8_WAIT_V(n) asm volatile("s_waitcnt vmcnt(" #n ")" ::: "memory")
; #define PG8_WAIT_L(n) asm volatile("s_waitcnt lgkmcnt(" #n ")" ::: "memory")
; #define PG8_BAR __builtin_amdgcn_s_barrier()
; #define PG8_SCHED __builtin_amdgcn_sched_barrier(0)
; template <class Epi, class Sched, bool ALIGN_EPI = false, bool SP2 = false>
; __device__ __forceinline__ void gemm_phase(PG8_LAS unsigned char* lds, const Gemm g, const Sched& S, const Epi& E) {
;     ...
;             PG8_WAIT_V(8); PG8_WAIT_L(0); PG8_BAR; PG8_MMA(0, 0, At, B0); PG8_MMA(0, 1, At, B1); PG8_BAR; PG8_SCHED;
;             PG8_LDA(At, 0, 1); PG8_STAGE(PG8_SB(0, 0), b2, voffB); PG8_STAGE(PG8_SB(0, 1), b2 + hstep, voffB); PG8_STAGE(PG8_SA(0, 0), a2, voffA);
;             PG8_WAIT_V(8); PG8_WAIT_L(0); PG8_BAR; PG8_MMA(1, 0, At, B0); PG8_MMA(1, 1, At, B1); PG8_BAR; PG8_SCHED;
	s_setprio 1
	s_waitcnt lgkmcnt(0)
	v_mfma_f32_16x16x32_bf16 v[124:127], v[144:147], v[186:189], v[124:127]
	v_mfma_f32_16x16x32_bf16 v[120:123], v[160:163], v[186:189], v[120:123]
	v_mfma_f32_16x16x32_bf16 v[108:111], v[144:147], v[194:197], v[108:111]
	v_mfma_f32_16x16x32_bf16 v[104:107], v[160:163], v[194:197], v[104:107]
	v_mfma_f32_16x16x32_bf16 v[92:95], v[144:147], v[208:211], v[92:95]
	v_mfma_f32_16x16x32_bf16 v[88:91], v[160:163], v[208:211], v[88:91]
	v_mfma_f32_16x16x32_bf16 v[76:79], v[144:147], v[216:219], v[76:79]
	v_mfma_f32_16x16x32_bf16 v[72:75], v[160:163], v[216:219], v[72:75]
	v_mfma_f32_16x16x32_bf16 v[124:127], v[156:159], v[190:193], v[124:127]
	v_mfma_f32_16x16x32_bf16 v[120:123], v[164:167], v[190:193], v[120:123]
	v_mfma_f32_16x16x32_bf16 v[108:111], v[156:159], v[198:201], v[108:111]
	v_mfma_f32_16x16x32_bf16 v[104:107], v[164:167], v[198:201], v[104:107]
	v_mfma_f32_16x16x32_bf16 v[92:95], v[156:159], v[212:215], v[92:95]
	v_mfma_f32_16x16x32_bf16 v[88:91], v[164:167], v[212:215], v[88:91]
	v_mfma_f32_16x16x32_bf16 v[76:79], v[156:159], v[220:223], v[76:79]
	v_mfma_f32_16x16x32_bf16 v[72:75], v[164:167], v[220:223], v[72:75]
	s_setprio 0
	s_setprio 1
	v_mfma_f32_16x16x32_bf16 v[116:119], v[168:171], v[186:189], v[116:119]
	v_mfma_f32_16x16x32_bf16 v[112:115], v[176:179], v[186:189], v[112:115]
	v_mfma_f32_16x16x32_bf16 v[100:103], v[168:171], v[194:197], v[100:103]
	v_mfma_f32_16x16x32_bf16 v[96:99], v[176:179], v[194:197], v[96:99]
	v_mfma_f32_16x16x32_bf16 v[84:87], v[168:171], v[208:211], v[84:87]
	v_mfma_f32_16x16x32_bf16 v[80:83], v[176:179], v[208:211], v[80:83]
	v_mfma_f32_16x16x32_bf16 v[68:71], v[168:171], v[216:219], v[68:71]
	v_mfma_f32_16x16x32_bf16 v[64:67], v[176:179], v[216:219], v[64:67]
	v_mfma_f32_16x16x32_bf16 v[116:119], v[172:175], v[190:193], v[116:119]
	v_mfma_f32_16x16x32_bf16 v[112:115], v[182:185], v[190:193], v[112:115]
	v_mfma_f32_16x16x32_bf16 v[100:103], v[172:175], v[198:201], v[100:103]
	v_mfma_f32_16x16x32_bf16 v[96:99], v[182:185], v[198:201], v[96:99]
	v_mfma_f32_16x16x32_bf16 v[84:87], v[172:175], v[212:215], v[84:87]
	v_mfma_f32_16x16x32_bf16 v[80:83], v[182:185], v[212:215], v[80:83]
	v_mfma_f32_16x16x32_bf16 v[68:71], v[172:175], v[220:223], v[68:71]
	v_mfma_f32_16x16x32_bf16 v[64:67], v[182:185], v[220:223], v[64:67]
	s_setprio 0
	s_barrier
	s_add_i32 s3, s74, s14
	v_lshl_add_u64 v[202:203], s[60:61], 0, v[130:131]
	s_mov_b32 m0, s3
	ds_read_b128 v[186:189], v153 offset:16384
	ds_read_b128 v[190:193], v153 offset:17408
	ds_read_b128 v[194:197], v153 offset:18432
	ds_read_b128 v[198:201], v153 offset:19456
	ds_read_b128 v[208:211], v153 offset:20480
	ds_read_b128 v[212:215], v153 offset:21504
	ds_read_b128 v[216:219], v153 offset:22528
	ds_read_b128 v[220:223], v153 offset:23552
	global_load_lds_dwordx4 v[202:203], off
	s_add_i32 m0, s3, 0x2000
	s_add_u32 s78, s60, 0x20000
	v_lshl_add_u64 v[224:225], s[60:61], 0, v[134:135]
	s_addc_u32 s79, s61, 0
	s_add_i32 s3, s75, s14
	global_load_lds_dwordx4 v[224:225], off
	v_lshl_add_u64 v[226:227], s[78:79], 0, v[130:131]
	s_mov_b32 m0, s3
	global_load_lds_dwordx4 v[226:227], off
	v_lshl_add_u64 v[226:227], s[78:79], 0, v[134:135]
	s_add_i32 m0, s3, 0x2000
	s_nop 0
	global_load_lds_dwordx4 v[226:227], off
	v_lshl_add_u64 v[226:227], s[62:63], 0, v[128:129]
	s_mov_b32 m0, s15
	s_nop 0
	global_load_lds_dwordx4 v[226:227], off
	v_lshl_add_u64 v[228:229], s[62:63], 0, v[132:133]
	s_mov_b32 m0, s34
	s_nop 0
	global_load_lds_dwordx4 v[228:229], off
	s_waitcnt vmcnt(8)
	s_waitcnt lgkmcnt(0)
	s_barrier
	s_setprio 1
	s_waitcnt lgkmcnt(0)
	v_mfma_f32_16x16x32_bf16 v[60:63], v[144:147], v[186:189], v[60:63]
	v_mfma_f32_16x16x32_bf16 v[56:59], v[160:163], v[186:189], v[56:59]
	v_mfma_f32_16x16x32_bf16 v[44:47], v[144:147], v[194:197], v[44:47]
	v_mfma_f32_16x16x32_bf16 v[40:43], v[160:163], v[194:197], v[40:43]
	v_mfma_f32_16x16x32_bf16 v[28:31], v[144:147], v[208:211], v[28:31]
	v_mfma_f32_16x16x32_bf16 v[24:27], v[160:163], v[208:211], v[24:27]
	v_mfma_f32_16x16x32_bf16 v[12:15], v[144:147], v[216:219], v[12:15]
	v_mfma_f32_16x16x32_bf16 v[8:11], v[160:163], v[216:219], v[8:11]
	v_mfma_f32_16x16x32_bf16 v[60:63], v[156:159], v[190:193], v[60:63]
	v_mfma_f32_16x16x32_bf16 v[56:59], v[164:167], v[190:193], v[56:59]
	v_mfma_f32_16x16x32_bf16 v[44:47], v[156:159], v[198:201], v[44:47]
	v_mfma_f32_16x16x32_bf16 v[40:43], v[164:167], v[198:201], v[40:43]
	v_mfma_f32_16x16x32_bf16 v[28:31], v[156:159], v[212:215], v[28:31]
	v_mfma_f32_16x16x32_bf16 v[24:27], v[164:167], v[212:215], v[24:27]
	v_mfma_f32_16x16x32_bf16 v[12:15], v[156:159], v[220:223], v[12:15]
	v_mfma_f32_16x16x32_bf16 v[8:11], v[164:167], v[220:223], v[8:11]
	s_setprio 0
	s_setprio 1
	v_mfma_f32_16x16x32_bf16 v[52:55], v[168:171], v[186:189], v[52:55]
	v_mfma_f32_16x16x32_bf16 v[48:51], v[176:179], v[186:189], v[48:51]
	v_mfma_f32_16x16x32_bf16 v[36:39], v[168:171], v[194:197], v[36:39]
	v_mfma_f32_16x16x32_bf16 v[32:35], v[176:179], v[194:197], v[32:35]
	v_mfma_f32_16x16x32_bf16 v[20:23], v[168:171], v[208:211], v[20:23]
	v_mfma_f32_16x16x32_bf16 v[16:19], v[176:179], v[208:211], v[16:19]
	v_mfma_f32_16x16x32_bf16 v[4:7], v[168:171], v[216:219], v[4:7]
	v_mfma_f32_16x16x32_bf16 v[0:3], v[176:179], v[216:219], v[0:3]
	v_mfma_f32_16x16x32_bf16 v[52:55], v[172:175], v[190:193], v[52:55]
	v_mfma_f32_16x16x32_bf16 v[48:51], v[182:185], v[190:193], v[48:51]
	v_mfma_f32_16x16x32_bf16 v[36:39], v[172:175], v[198:201], v[36:39]
	v_mfma_f32_16x16x32_bf16 v[32:35], v[182:185], v[198:201], v[32:35]
	v_mfma_f32_16x16x32_bf16 v[20:23], v[172:175], v[212:215], v[20:23]
	v_mfma_f32_16x16x32_bf16 v[16:19], v[182:185], v[212:215], v[16:19]
	v_mfma_f32_16x16x32_bf16 v[4:7], v[172:175], v[220:223], v[4:7]
	v_mfma_f32_16x16x32_bf16 v[0:3], v[182:185], v[220:223], v[0:3]
	s_setprio 0
	s_barrier
; #define PG8_STAGE(bufoff, gbase, voff) do { _Pragma("unroll") for (int _i = 0; _i < 2; ++_i) \
;         __builtin_amdgcn_global_load_lds((const unsigned*)((const char*)(gbase) + (voff)[_i]), (PG8_LAS unsigned*)(lds + (bufoff) + ldsw + _i * 8192), 16, 0, 0); } while (0)
; #define PG8_LDA(dst, b, h) do { _Pragma("unroll") for (int m = 0; m < 4; ++m) _Pragma("unroll") for (int k = 0; k < 2; ++k) dst[m][k] = *(const PG8_LAS bf16x8*)(lds + PG8_SA(b, h) + aoff + m * 2048 + k * 1024); } while (0)
; #define PG8_LDB(dst, b, h) do { _Pragma("unroll") for (int n = 0; n < 2; ++n) _Pragma("unroll") for (int k = 0; k < 2; ++k) dst[n][k] = *(const PG8_LAS bf16x8*)(lds + PG8_SB(b, h) + boff + n * 2048 + k * 1024); } while (0)
; #define PG8_MMA(ai, bj, At, Bt) do { __builtin_amdgcn_s_setprio(1); _Pragma("unroll") for (int m = 0; m < 4; ++m) _Pragma("unroll") for (int n = 0; n < 2; ++n) _Pragma("unroll") for (int k = 0; k < 2; ++k) \
;         acc[ai][bj][m][n] = __builtin_amdgcn_mfma_f32_16x16x32_bf16(Bt[n][k], At[m][k], acc[ai][bj][m][n], 0, 0, 0); __builtin_amdgcn_s_setprio(0); } while (0)
; #define PG8_WAIT_V(n) asm volatile("s_waitcnt vmcnt(" #n ")" ::: "memory")
; #define PG8_WAIT_L(n) asm volatile("s_waitcnt lgkmcnt(" #n ")" ::: "memory")
; #define PG8_BAR __builtin_amdgcn_s_barrier()
; #define PG8_SCHED __builtin_amdgcn_sched_barrier(0)
; template <class Epi, class Sched, bool ALIGN_EPI = false, bool SP2 = false>
; __device__ __forceinline__ void gemm_phase(PG8_LAS unsigned char* lds, const Gemm g, const Sched& S, const Epi& E) {
;     ...
;             PG8_LDB(B0, 1, 0); PG8_LDB(B1, 1, 1); PG8_SCHED; PG8_LDA(At, 1, 0); PG8_STAGE(PG8_SA(0, 1), a2 + hstep, voffA);
;             PG8_WAIT_V(8); PG8_WAIT_L(0); PG8_BAR; PG8_MMA(0, 0, At, B0); PG8_MMA(0, 1, At, B1); PG8_BAR; PG8_SCHED;
	s_add_i32 s3, 0, 0x18000
	v_add_u32_e32 v155, s3, v149
	s_add_i32 s33, 0, 0x1c000
	ds_read_b128 v[144:147], v155
	ds_read_b128 v[156:159], v155 offset:1024
	ds_read_b128 v[160:163], v155 offset:2048
	ds_read_b128 v[164:167], v155 offset:3072
	v_add_u32_e32 v155, s33, v149
	ds_read_b128 v[168:171], v155
	ds_read_b128 v[172:175], v155 offset:1024
	ds_read_b128 v[176:179], v155 offset:2048
	ds_read_b128 v[182:185], v155 offset:3072
	s_add_u32 s62, s62, 0x20000
	s_addc_u32 s63, s63, 0
	s_mov_b32 m0, s57
	v_lshl_add_u64 v[230:231], s[62:63], 0, v[128:129]
	ds_read_b128 v[186:189], v153 offset:32768
	ds_read_b128 v[190:193], v153 offset:33792
	ds_read_b128 v[194:197], v153 offset:34816
	ds_read_b128 v[198:201], v153 offset:35840
	ds_read_b128 v[208:211], v153 offset:36864
	ds_read_b128 v[212:215], v153 offset:37888
	ds_read_b128 v[216:219], v153 offset:38912
	ds_read_b128 v[220:223], v153 offset:39936
	global_load_lds_dwordx4 v[230:231], off
	v_lshl_add_u64 v[230:231], s[62:63], 0, v[132:133]
	s_mov_b32 m0, s64
	s_nop 0
	global_load_lds_dwordx4 v[230:231], off
	s_waitcnt vmcnt(8)
	s_waitcnt lgkmcnt(0)
	s_barrier
	s_setprio 1
	s_waitcnt lgkmcnt(0)
	v_mfma_f32_16x16x32_bf16 v[124:127], v[144:147], v[186:189], v[124:127]
	v_mfma_f32_16x16x32_bf16 v[120:123], v[160:163], v[186:189], v[120:123]
	v_mfma_f32_16x16x32_bf16 v[108:111], v[144:147], v[194:197], v[108:111]
	v_mfma_f32_16x16x32_bf16 v[104:107], v[160:163], v[194:197], v[104:107]
	v_mfma_f32_16x16x32_bf16 v[92:95], v[144:147], v[208:211], v[92:95]
	v_mfma_f32_16x16x32_bf16 v[88:91], v[160:163], v[208:211], v[88:91]
	v_mfma_f32_16x16x32_bf16 v[76:79], v[144:147], v[216:219], v[76:79]
	v_mfma_f32_16x16x32_bf16 v[72:75], v[160:163], v[216:219], v[72:75]
	v_mfma_f32_16x16x32_bf16 v[124:127], v[156:159], v[190:193], v[124:127]
	v_mfma_f32_16x16x32_bf16 v[120:123], v[164:167], v[190:193], v[120:123]
	v_mfma_f32_16x16x32_bf16 v[108:111], v[156:159], v[198:201], v[108:111]
	v_mfma_f32_16x16x32_bf16 v[104:107], v[164:167], v[198:201], v[104:107]
	v_mfma_f32_16x16x32_bf16 v[92:95], v[156:159], v[212:215], v[92:95]
	v_mfma_f32_16x16x32_bf16 v[88:91], v[164:167], v[212:215], v[88:91]
	v_mfma_f32_16x16x32_bf16 v[76:79], v[156:159], v[220:223], v[76:79]
	v_mfma_f32_16x16x32_bf16 v[72:75], v[164:167], v[220:223], v[72:75]
	s_setprio 0
	s_setprio 1
	v_mfma_f32_16x16x32_bf16 v[116:119], v[168:171], v[186:189], v[116:119]
	v_mfma_f32_16x16x32_bf16 v[112:115], v[176:179], v[186:189], v[112:115]
	v_mfma_f32_16x16x32_bf16 v[100:103], v[168:171], v[194:197], v[100:103]
	v_mfma_f32_16x16x32_bf16 v[96:99], v[176:179], v[194:197], v[96:99]
	v_mfma_f32_16x16x32_bf16 v[84:87], v[168:171], v[208:211], v[84:87]
	v_mfma_f32_16x16x32_bf16 v[80:83], v[176:179], v[208:211], v[80:83]
	v_mfma_f32_16x16x32_bf16 v[68:71], v[168:171], v[216:219], v[68:71]
	v_mfma_f32_16x16x32_bf16 v[64:67], v[176:179], v[216:219], v[64:67]
	v_mfma_f32_16x16x32_bf16 v[116:119], v[172:175], v[190:193], v[116:119]
	v_mfma_f32_16x16x32_bf16 v[112:115], v[182:185], v[190:193], v[112:115]
	v_mfma_f32_16x16x32_bf16 v[100:103], v[172:175], v[198:201], v[100:103]
	v_mfma_f32_16x16x32_bf16 v[96:99], v[182:185], v[198:201], v[96:99]
	v_mfma_f32_16x16x32_bf16 v[84:87], v[172:175], v[212:215], v[84:87]
	v_mfma_f32_16x16x32_bf16 v[80:83], v[182:185], v[212:215], v[80:83]
	v_mfma_f32_16x16x32_bf16 v[68:71], v[172:175], v[220:223], v[68:71]
	v_mfma_f32_16x16x32_bf16 v[64:67], v[182:185], v[220:223], v[64:67]
	s_setprio 0
	s_barrier
; #define PG8_STAGE(bufoff, gbase, voff) do { _Pragma("unroll") for (int _i = 0; _i < 2; ++_i) \
;         __builtin_amdgcn_global_load_lds((const unsigned*)((const char*)(gbase) + (voff)[_i]), (PG8_LAS unsigned*)(lds + (bufoff) + ldsw + _i * 8192), 16, 0, 0); } while (0)
; #define PG8_LDA(dst, b, h) do { _Pragma("unroll") for (int m = 0; m < 4; ++m) _Pragma("unroll") for (int k = 0; k < 2; ++k) dst[m][k] = *(const PG8_LAS bf16x8*)(lds + PG8_SA(b, h) + aoff + m * 2048 + k * 1024); } while (0)
; #define PG8_MMA(ai, bj, At, Bt) do { __builtin_amdgcn_s_setprio(1); _Pragma("unroll") for (int m = 0; m < 4; ++m) _Pragma("unroll") for (int n = 0; n < 2; ++n) _Pragma("unroll") for (int k = 0; k < 2; ++k) \
;         acc[ai][bj][m][n] = __builtin_amdgcn_mfma_f32_16x16x32_bf16(Bt[n][k], At[m][k], acc[ai][bj][m][n], 0, 0, 0); __builtin_amdgcn_s_setprio(0); } while (0)
; #define PG8_WAIT_V(n) asm volatile("s_waitcnt vmcnt(" #n ")" ::: "memory")
; #define PG8_WAIT_L(n) asm volatile("s_waitcnt lgkmcnt(" #n ")" ::: "memory")
; #define PG8_BAR __builtin_amdgcn_s_barrier()
; #define PG8_SCHED __builtin_amdgcn_sched_barrier(0)
; template <class Epi, class Sched, bool ALIGN_EPI = false, bool SP2 = false>
; __device__ __forceinline__ void gemm_phase(PG8_LAS unsigned char* lds, const Gemm g, const Sched& S, const Epi& E) {
;     ...
;             PG8_LDA(At, 1, 1); PG8_STAGE(PG8_SB(1, 0), b3, voffB); PG8_STAGE(PG8_SB(1, 1), b3 + hstep, voffB); PG8_STAGE(PG8_SA(1, 0), a3, voffA);
;             PG8_WAIT_V(8); PG8_WAIT_L(0); PG8_BAR; PG8_MMA(1, 0, At, B0); PG8_MMA(1, 1, At, B1); PG8_BAR; PG8_SCHED;
;     ...
;         if constexpr (ALIGN_EPI) { if (wr == 0) PG8_BAR; }
	s_add_i32 s3, s3, s14
	v_lshl_add_u64 v[202:203], v[202:203], 0, s[38:39]
	s_mov_b32 m0, s3
	ds_read_b128 v[186:189], v153 offset:49152
	ds_read_b128 v[190:193], v153 offset:50176
	ds_read_b128 v[194:197], v153 offset:51200
	ds_read_b128 v[198:201], v153 offset:52224
	ds_read_b128 v[208:211], v153 offset:53248
	ds_read_b128 v[212:215], v153 offset:54272
	ds_read_b128 v[216:219], v153 offset:55296
	ds_read_b128 v[220:223], v153 offset:56320
	global_load_lds_dwordx4 v[202:203], off
	s_add_i32 m0, s3, 0x2000
	s_add_u32 s60, s60, 0x20080
	v_lshl_add_u64 v[202:203], v[224:225], 0, s[38:39]
	s_addc_u32 s61, s61, 0
	s_add_i32 s3, s33, s14
	global_load_lds_dwordx4 v[202:203], off
	v_lshl_add_u64 v[202:203], s[60:61], 0, v[130:131]
	s_mov_b32 m0, s3
	s_nop 0
	global_load_lds_dwordx4 v[202:203], off
	v_lshl_add_u64 v[202:203], s[60:61], 0, v[134:135]
	s_add_i32 m0, s3, 0x2000
	s_nop 0
	global_load_lds_dwordx4 v[202:203], off
	v_lshl_add_u64 v[202:203], v[226:227], 0, s[38:39]
	s_mov_b32 m0, s66
	s_nop 0
	global_load_lds_dwordx4 v[202:203], off
	v_lshl_add_u64 v[202:203], v[228:229], 0, s[38:39]
	s_mov_b32 m0, s67
	s_nop 0
	global_load_lds_dwordx4 v[202:203], off
	s_waitcnt vmcnt(8)
	s_waitcnt lgkmcnt(0)
	s_barrier
	s_setprio 1
	s_waitcnt lgkmcnt(0)
	v_mfma_f32_16x16x32_bf16 v[60:63], v[144:147], v[186:189], v[60:63]
	v_mfma_f32_16x16x32_bf16 v[56:59], v[160:163], v[186:189], v[56:59]
	v_mfma_f32_16x16x32_bf16 v[44:47], v[144:147], v[194:197], v[44:47]
	v_mfma_f32_16x16x32_bf16 v[40:43], v[160:163], v[194:197], v[40:43]
	v_mfma_f32_16x16x32_bf16 v[28:31], v[144:147], v[208:211], v[28:31]
	v_mfma_f32_16x16x32_bf16 v[24:27], v[160:163], v[208:211], v[24:27]
	v_mfma_f32_16x16x32_bf16 v[12:15], v[144:147], v[216:219], v[12:15]
	v_mfma_f32_16x16x32_bf16 v[8:11], v[160:163], v[216:219], v[8:11]
	v_mfma_f32_16x16x32_bf16 v[60:63], v[156:159], v[190:193], v[60:63]
	v_mfma_f32_16x16x32_bf16 v[56:59], v[164:167], v[190:193], v[56:59]
	v_mfma_f32_16x16x32_bf16 v[44:47], v[156:159], v[198:201], v[44:47]
	v_mfma_f32_16x16x32_bf16 v[40:43], v[164:167], v[198:201], v[40:43]
	v_mfma_f32_16x16x32_bf16 v[28:31], v[156:159], v[212:215], v[28:31]
	v_mfma_f32_16x16x32_bf16 v[24:27], v[164:167], v[212:215], v[24:27]
	v_mfma_f32_16x16x32_bf16 v[12:15], v[156:159], v[220:223], v[12:15]
	v_mfma_f32_16x16x32_bf16 v[8:11], v[164:167], v[220:223], v[8:11]
	s_setprio 0
	s_setprio 1
	v_mfma_f32_16x16x32_bf16 v[52:55], v[168:171], v[186:189], v[52:55]
	v_mfma_f32_16x16x32_bf16 v[48:51], v[176:179], v[186:189], v[48:51]
	v_mfma_f32_16x16x32_bf16 v[36:39], v[168:171], v[194:197], v[36:39]
	v_mfma_f32_16x16x32_bf16 v[32:35], v[176:179], v[194:197], v[32:35]
	v_mfma_f32_16x16x32_bf16 v[20:23], v[168:171], v[208:211], v[20:23]
	v_mfma_f32_16x16x32_bf16 v[16:19], v[176:179], v[208:211], v[16:19]
	v_mfma_f32_16x16x32_bf16 v[4:7], v[168:171], v[216:219], v[4:7]
	v_mfma_f32_16x16x32_bf16 v[0:3], v[176:179], v[216:219], v[0:3]
	v_mfma_f32_16x16x32_bf16 v[52:55], v[172:175], v[190:193], v[52:55]
	v_mfma_f32_16x16x32_bf16 v[48:51], v[182:185], v[190:193], v[48:51]
	v_mfma_f32_16x16x32_bf16 v[36:39], v[172:175], v[198:201], v[36:39]
	v_mfma_f32_16x16x32_bf16 v[32:35], v[182:185], v[198:201], v[32:35]
	v_mfma_f32_16x16x32_bf16 v[20:23], v[172:175], v[212:215], v[20:23]
	v_mfma_f32_16x16x32_bf16 v[16:19], v[182:185], v[212:215], v[16:19]
	v_mfma_f32_16x16x32_bf16 v[4:7], v[172:175], v[220:223], v[4:7]
	v_mfma_f32_16x16x32_bf16 v[0:3], v[182:185], v[220:223], v[0:3]
	s_setprio 0
	s_barrier
	s_add_i32 s87, s87, 2
	s_add_u32 s58, s58, 0x100
	s_addc_u32 s59, s59, 0
	s_add_u32 s85, s85, 0x100
	s_addc_u32 s86, s86, 0
	s_cmp_gt_u32 s87, 5
	s_cbranch_scc0 .LBB0_873
	s_and_b64 vcc, exec, s[42:43]
	s_cbranch_vccz .LBB0_876
	s_barrier

; #define PG8_STAGE(bufoff, gbase, voff) do { _Pragma("unroll") for (int _i = 0; _i < 2; ++_i) \
;         __builtin_amdgcn_global_load_lds((const unsigned*)((const char*)(gbase) + (voff)[_i]), (PG8_LAS unsigned*)(lds + (bufoff) + ldsw + _i * 8192), 16, 0, 0); } while (0)
; #define PG8_LDA(dst, b, h) do { _Pragma("unroll") for (int m = 0; m < 4; ++m) _Pragma("unroll") for (int k = 0; k < 2; ++k) dst[m][k] = *(const PG8_LAS bf16x8*)(lds + PG8_SA(b, h) + aoff + m * 2048 + k * 1024); } while (0)
; #define PG8_LDB(dst, b, h) do { _Pragma("unroll") for (int n = 0; n < 2; ++n) _Pragma("unroll") for (int k = 0; k < 2; ++k) dst[n][k] = *(const PG8_LAS bf16x8*)(lds + PG8_SB(b, h) + boff + n * 2048 + k * 1024); } while (0)
; #define PG8_MMA(ai, bj, At, Bt) do { __builtin_amdgcn_s_setprio(1); _Pragma("unroll") for (int m = 0; m < 4; ++m) _Pragma("unroll") for (int n = 0; n < 2; ++n) _Pragma("unroll") for (int k = 0; k < 2; ++k) \
;         acc[ai][bj][m][n] = __builtin_amdgcn_mfma_f32_16x16x32_bf16(Bt[n][k], At[m][k], acc[ai][bj][m][n], 0, 0, 0); __builtin_amdgcn_s_setprio(0); } while (0)
; #define PG8_BAR __builtin_amdgcn_s_barrier()
; template <class Epi, class Sched, bool ALIGN_EPI = false, bool SP2 = false>
; __device__ __forceinline__ void gemm_phase(PG8_LAS unsigned char* lds, const Gemm g, const Sched& S, const Epi& E) {
;     ...
;         const bool has_next = S.next(ui + 1, nxt);
;         const char* nA = has_next ? (const char*)g.A + (size_t)nxt.pm * tstep : cA; const char* nB = has_next ? (const char*)g.Bt + (size_t)nxt.pn * tstep : cB;
;         for (int t = 0; t < nt; t += 2) {
;             const bool last = (t == nt - 2);
;             const char* a1 = cA + (size_t)(t + 1) * kstep;
;             const char* a2 = last ? nA : cA + (size_t)(t + 2) * kstep; const char* b2 = last ? nB : cB + (size_t)(t + 2) * kstep;
;             const char* a3 = a2 + kstep; const char* b3 = b2 + kstep;
;             if (last && has_next) S.a_ready(nxt);
;             if constexpr (SP2) {
;             PG8_LDB(B0, 0, 0); PG8_LDB(B1, 0, 1); PG8_SCHED; PG8_LDA(At, 0, 0); PG8_STAGE(PG8_SA(1, 1), a1 + hstep, voffA);
;             PG8_WAIT_V(8); PG8_WAIT_L(0); PG8_BAR; PG8_MMA(0, 0, At, B0); PG8_MMA(0, 1, At, B1); PG8_BAR; PG8_SCHED;
;             PG8_LDA(At, 0, 1); PG8_STAGE(PG8_SB(0, 0), b2, voffB); PG8_STAGE(PG8_SB(0, 1), b2 + hstep, voffB); PG8_STAGE(PG8_SA(0, 0), a2, voffA);
.LBB0_1034:
	s_add_u32 s75, s52, 0x100
	s_addc_u32 s76, s53, 0
	s_mov_b32 s77, -2
	s_waitcnt lgkmcnt(0)
	ds_read_b128 v[144:147], v151
	ds_read_b128 v[156:159], v151 offset:1024
	ds_read_b128 v[160:163], v151 offset:2048
	ds_read_b128 v[164:167], v151 offset:3072
	ds_read_b128 v[168:171], v152
	ds_read_b128 v[172:175], v152 offset:1024
	ds_read_b128 v[176:179], v152 offset:2048
	ds_read_b128 v[182:185], v152 offset:3072
	s_add_u32 s52, s50, 0x100
	s_addc_u32 s53, s51, 0
	s_cmp_eq_u32 s77, 40
	s_cselect_b32 s57, s1, s53
	s_cselect_b32 s56, s0, s52
	s_cselect_b32 s55, s49, s76
	s_cselect_b32 s54, s48, s75
	v_lshl_add_u64 v[202:203], s[50:51], 0, v[136:137]
	s_add_i32 m0, s14, 0xc000
	ds_read_b128 v[186:189], v153
	ds_read_b128 v[190:193], v153 offset:1024
	ds_read_b128 v[194:197], v153 offset:2048
	ds_read_b128 v[198:201], v153 offset:3072
	ds_read_b128 v[208:211], v153 offset:4096
	ds_read_b128 v[212:215], v153 offset:5120
	ds_read_b128 v[216:219], v153 offset:6144
	ds_read_b128 v[220:223], v153 offset:7168
	global_load_lds_dwordx4 v[202:203], off
	v_lshl_add_u64 v[202:203], s[50:51], 0, v[138:139]
	s_add_i32 m0, s14, 0xe000
	s_nop 0
	global_load_lds_dwordx4 v[202:203], off
	s_waitcnt vmcnt(8)
	s_waitcnt lgkmcnt(0)
	s_barrier
	s_setprio 1
	s_waitcnt lgkmcnt(0)
	v_mfma_f32_16x16x32_bf16 v[124:127], v[144:147], v[186:189], 0
	v_mfma_f32_16x16x32_bf16 v[120:123], v[160:163], v[186:189], 0
	v_mfma_f32_16x16x32_bf16 v[108:111], v[144:147], v[194:197], 0
	v_mfma_f32_16x16x32_bf16 v[104:107], v[160:163], v[194:197], 0
	v_mfma_f32_16x16x32_bf16 v[92:95], v[144:147], v[208:211], 0
	v_mfma_f32_16x16x32_bf16 v[88:91], v[160:163], v[208:211], 0
	v_mfma_f32_16x16x32_bf16 v[76:79], v[144:147], v[216:219], 0
	v_mfma_f32_16x16x32_bf16 v[72:75], v[160:163], v[216:219], 0
	v_mfma_f32_16x16x32_bf16 v[124:127], v[156:159], v[190:193], v[124:127]
	v_mfma_f32_16x16x32_bf16 v[120:123], v[164:167], v[190:193], v[120:123]
	v_mfma_f32_16x16x32_bf16 v[108:111], v[156:159], v[198:201], v[108:111]
	v_mfma_f32_16x16x32_bf16 v[104:107], v[164:167], v[198:201], v[104:107]
	v_mfma_f32_16x16x32_bf16 v[92:95], v[156:159], v[212:215], v[92:95]
	v_mfma_f32_16x16x32_bf16 v[88:91], v[164:167], v[212:215], v[88:91]
	v_mfma_f32_16x16x32_bf16 v[76:79], v[156:159], v[220:223], v[76:79]
	v_mfma_f32_16x16x32_bf16 v[72:75], v[164:167], v[220:223], v[72:75]
	s_setprio 0
	s_setprio 1
	v_mfma_f32_16x16x32_bf16 v[116:119], v[168:171], v[186:189], 0
	v_mfma_f32_16x16x32_bf16 v[112:115], v[176:179], v[186:189], 0
	v_mfma_f32_16x16x32_bf16 v[100:103], v[168:171], v[194:197], 0
	v_mfma_f32_16x16x32_bf16 v[96:99], v[176:179], v[194:197], 0
	v_mfma_f32_16x16x32_bf16 v[84:87], v[168:171], v[208:211], 0
	v_mfma_f32_16x16x32_bf16 v[80:83], v[176:179], v[208:211], 0
	v_mfma_f32_16x16x32_bf16 v[68:71], v[168:171], v[216:219], 0
	v_mfma_f32_16x16x32_bf16 v[64:67], v[176:179], v[216:219], 0
	v_mfma_f32_16x16x32_bf16 v[116:119], v[172:175], v[190:193], v[116:119]
	v_mfma_f32_16x16x32_bf16 v[112:115], v[182:185], v[190:193], v[112:115]
	v_mfma_f32_16x16x32_bf16 v[100:103], v[172:175], v[198:201], v[100:103]
	v_mfma_f32_16x16x32_bf16 v[96:99], v[182:185], v[198:201], v[96:99]
	v_mfma_f32_16x16x32_bf16 v[84:87], v[172:175], v[212:215], v[84:87]
	v_mfma_f32_16x16x32_bf16 v[80:83], v[182:185], v[212:215], v[80:83]
	v_mfma_f32_16x16x32_bf16 v[68:71], v[172:175], v[220:223], v[68:71]
	v_mfma_f32_16x16x32_bf16 v[64:67], v[182:185], v[220:223], v[64:67]
	s_setprio 0
	s_barrier
	s_add_i32 s50, s61, s3
	v_lshl_add_u64 v[202:203], s[54:55], 0, v[130:131]
	s_mov_b32 m0, s50
	ds_read_b128 v[186:189], v153 offset:16384
	ds_read_b128 v[190:193], v153 offset:17408
	ds_read_b128 v[194:197], v153 offset:18432
	ds_read_b128 v[198:201], v153 offset:19456
	ds_read_b128 v[208:211], v153 offset:20480
	ds_read_b128 v[212:215], v153 offset:21504
	ds_read_b128 v[216:219], v153 offset:22528
	ds_read_b128 v[220:223], v153 offset:23552
	global_load_lds_dwordx4 v[202:203], off
	s_add_i32 m0, s50, 0x2000
	s_add_u32 s50, s54, 0xb0000
	v_lshl_add_u64 v[224:225], s[54:55], 0, v[134:135]
	s_addc_u32 s51, s55, 0
	s_add_i32 s78, s62, s3
	global_load_lds_dwordx4 v[224:225], off
	v_lshl_add_u64 v[226:227], s[50:51], 0, v[130:131]
	s_mov_b32 m0, s78
	global_load_lds_dwordx4 v[226:227], off
	v_lshl_add_u64 v[226:227], s[50:51], 0, v[134:135]
	s_add_i32 m0, s78, 0x2000
	s_nop 0
	global_load_lds_dwordx4 v[226:227], off
	v_lshl_add_u64 v[226:227], s[56:57], 0, v[128:129]
	s_mov_b32 m0, s14
	s_nop 0
	global_load_lds_dwordx4 v[226:227], off
	v_lshl_add_u64 v[228:229], s[56:57], 0, v[132:133]
	s_mov_b32 m0, s15
	s_nop 0
	global_load_lds_dwordx4 v[228:229], off
	s_waitcnt vmcnt(8)
	s_waitcnt lgkmcnt(0)
	s_barrier
; #define PG8_STAGE(bufoff, gbase, voff) do { _Pragma("unroll") for (int _i = 0; _i < 2; ++_i) \
;         __builtin_amdgcn_global_load_lds((const unsigned*)((const char*)(gbase) + (voff)[_i]), (PG8_LAS unsigned*)(lds + (bufoff) + ldsw + _i * 8192), 16, 0, 0); } while (0)
; #define PG8_LDA(dst, b, h) do { _Pragma("unroll") for (int m = 0; m < 4; ++m) _Pragma("unroll") for (int k = 0; k < 2; ++k) dst[m][k] = *(const PG8_LAS bf16x8*)(lds + PG8_SA(b, h) + aoff + m * 2048 + k * 1024); } while (0)
; #define PG8_LDB(dst, b, h) do { _Pragma("unroll") for (int n = 0; n < 2; ++n) _Pragma("unroll") for (int k = 0; k < 2; ++k) dst[n][k] = *(const PG8_LAS bf16x8*)(lds + PG8_SB(b, h) + boff + n * 2048 + k * 1024); } while (0)
; #define PG8_MMA(ai, bj, At, Bt) do { __builtin_amdgcn_s_setprio(1); _Pragma("unroll") for (int m = 0; m < 4; ++m) _Pragma("unroll") for (int n = 0; n < 2; ++n) _Pragma("unroll") for (int k = 0; k < 2; ++k) \
;         acc[ai][bj][m][n] = __builtin_amdgcn_mfma_f32_16x16x32_bf16(Bt[n][k], At[m][k], acc[ai][bj][m][n], 0, 0, 0); __builtin_amdgcn_s_setprio(0); } while (0)
; #define PG8_WAIT_V(n) asm volatile("s_waitcnt vmcnt(" #n ")" ::: "memory")
; #define PG8_WAIT_L(n) asm volatile("s_waitcnt lgkmcnt(" #n ")" ::: "memory")
; #define PG8_BAR __builtin_amdgcn_s_barrier()
; #define PG8_SCHED __builtin_amdgcn_sched_barrier(0)
; template <class Epi, class Sched, bool ALIGN_EPI = false, bool SP2 = false>
; __device__ __forceinline__ void gemm_phase(PG8_LAS unsigned char* lds, const Gemm g, const Sched& S, const Epi& E) {
;     ...
;             PG8_WAIT_V(8); PG8_WAIT_L(0); PG8_BAR; PG8_MMA(1, 0, At, B0); PG8_MMA(1, 1, At, B1); PG8_BAR; PG8_SCHED;
;             PG8_LDB(B0, 1, 0); PG8_LDB(B1, 1, 1); PG8_SCHED; PG8_LDA(At, 1, 0); PG8_STAGE(PG8_SA(0, 1), a2 + hstep, voffA);
;             PG8_WAIT_V(8); PG8_WAIT_L(0); PG8_BAR; PG8_MMA(0, 0, At, B0); PG8_MMA(0, 1, At, B1); PG8_BAR; PG8_SCHED;
	s_setprio 1
	s_waitcnt lgkmcnt(0)
	v_mfma_f32_16x16x32_bf16 v[60:63], v[144:147], v[186:189], 0
	v_mfma_f32_16x16x32_bf16 v[56:59], v[160:163], v[186:189], 0
	v_mfma_f32_16x16x32_bf16 v[44:47], v[144:147], v[194:197], 0
	v_mfma_f32_16x16x32_bf16 v[40:43], v[160:163], v[194:197], 0
	v_mfma_f32_16x16x32_bf16 v[28:31], v[144:147], v[208:211], 0
	v_mfma_f32_16x16x32_bf16 v[24:27], v[160:163], v[208:211], 0
	v_mfma_f32_16x16x32_bf16 v[12:15], v[144:147], v[216:219], 0
	v_mfma_f32_16x16x32_bf16 v[8:11], v[160:163], v[216:219], 0
	v_mfma_f32_16x16x32_bf16 v[60:63], v[156:159], v[190:193], v[60:63]
	v_mfma_f32_16x16x32_bf16 v[56:59], v[164:167], v[190:193], v[56:59]
	v_mfma_f32_16x16x32_bf16 v[44:47], v[156:159], v[198:201], v[44:47]
	v_mfma_f32_16x16x32_bf16 v[40:43], v[164:167], v[198:201], v[40:43]
	v_mfma_f32_16x16x32_bf16 v[28:31], v[156:159], v[212:215], v[28:31]
	v_mfma_f32_16x16x32_bf16 v[24:27], v[164:167], v[212:215], v[24:27]
	v_mfma_f32_16x16x32_bf16 v[12:15], v[156:159], v[220:223], v[12:15]
	v_mfma_f32_16x16x32_bf16 v[8:11], v[164:167], v[220:223], v[8:11]
	s_setprio 0
	s_setprio 1
	v_mfma_f32_16x16x32_bf16 v[52:55], v[168:171], v[186:189], 0
	v_mfma_f32_16x16x32_bf16 v[48:51], v[176:179], v[186:189], 0
	v_mfma_f32_16x16x32_bf16 v[36:39], v[168:171], v[194:197], 0
	v_mfma_f32_16x16x32_bf16 v[32:35], v[176:179], v[194:197], 0
	v_mfma_f32_16x16x32_bf16 v[20:23], v[168:171], v[208:211], 0
	v_mfma_f32_16x16x32_bf16 v[16:19], v[176:179], v[208:211], 0
	v_mfma_f32_16x16x32_bf16 v[4:7], v[168:171], v[216:219], 0
	v_mfma_f32_16x16x32_bf16 v[0:3], v[176:179], v[216:219], 0
	v_mfma_f32_16x16x32_bf16 v[52:55], v[172:175], v[190:193], v[52:55]
	v_mfma_f32_16x16x32_bf16 v[48:51], v[182:185], v[190:193], v[48:51]
	v_mfma_f32_16x16x32_bf16 v[36:39], v[172:175], v[198:201], v[36:39]
	v_mfma_f32_16x16x32_bf16 v[32:35], v[182:185], v[198:201], v[32:35]
	v_mfma_f32_16x16x32_bf16 v[20:23], v[172:175], v[212:215], v[20:23]
	v_mfma_f32_16x16x32_bf16 v[16:19], v[182:185], v[212:215], v[16:19]
	v_mfma_f32_16x16x32_bf16 v[4:7], v[172:175], v[220:223], v[4:7]
	v_mfma_f32_16x16x32_bf16 v[0:3], v[182:185], v[220:223], v[0:3]
	s_setprio 0
	s_barrier
	s_add_i32 s78, 0, 0x18000
	v_add_u32_e32 v155, s78, v149
	s_add_i32 s79, 0, 0x1c000
	ds_read_b128 v[144:147], v155
	ds_read_b128 v[156:159], v155 offset:1024
	ds_read_b128 v[160:163], v155 offset:2048
	ds_read_b128 v[164:167], v155 offset:3072
	v_add_u32_e32 v155, s79, v149
	ds_read_b128 v[168:171], v155
	ds_read_b128 v[172:175], v155 offset:1024
	ds_read_b128 v[176:179], v155 offset:2048
	ds_read_b128 v[182:185], v155 offset:3072
	s_add_u32 s50, s56, 0xb0000
	s_addc_u32 s51, s57, 0
	s_mov_b32 m0, s33
	v_lshl_add_u64 v[230:231], s[50:51], 0, v[128:129]
	ds_read_b128 v[186:189], v153 offset:32768
	ds_read_b128 v[190:193], v153 offset:33792
	ds_read_b128 v[194:197], v153 offset:34816
	ds_read_b128 v[198:201], v153 offset:35840
	ds_read_b128 v[208:211], v153 offset:36864
	ds_read_b128 v[212:215], v153 offset:37888
	ds_read_b128 v[216:219], v153 offset:38912
	ds_read_b128 v[220:223], v153 offset:39936
	global_load_lds_dwordx4 v[230:231], off
	v_lshl_add_u64 v[230:231], s[50:51], 0, v[132:133]
	s_mov_b32 m0, s34
	s_nop 0
	global_load_lds_dwordx4 v[230:231], off
	s_waitcnt vmcnt(8)
	s_waitcnt lgkmcnt(0)
	s_barrier
	s_setprio 1
	s_waitcnt lgkmcnt(0)
	v_mfma_f32_16x16x32_bf16 v[124:127], v[144:147], v[186:189], v[124:127]
	v_mfma_f32_16x16x32_bf16 v[120:123], v[160:163], v[186:189], v[120:123]
	v_mfma_f32_16x16x32_bf16 v[108:111], v[144:147], v[194:197], v[108:111]
	v_mfma_f32_16x16x32_bf16 v[104:107], v[160:163], v[194:197], v[104:107]
	v_mfma_f32_16x16x32_bf16 v[92:95], v[144:147], v[208:211], v[92:95]
	v_mfma_f32_16x16x32_bf16 v[88:91], v[160:163], v[208:211], v[88:91]
	v_mfma_f32_16x16x32_bf16 v[76:79], v[144:147], v[216:219], v[76:79]
	v_mfma_f32_16x16x32_bf16 v[72:75], v[160:163], v[216:219], v[72:75]
	v_mfma_f32_16x16x32_bf16 v[124:127], v[156:159], v[190:193], v[124:127]
	v_mfma_f32_16x16x32_bf16 v[120:123], v[164:167], v[190:193], v[120:123]
	v_mfma_f32_16x16x32_bf16 v[108:111], v[156:159], v[198:201], v[108:111]
	v_mfma_f32_16x16x32_bf16 v[104:107], v[164:167], v[198:201], v[104:107]
	v_mfma_f32_16x16x32_bf16 v[92:95], v[156:159], v[212:215], v[92:95]
	v_mfma_f32_16x16x32_bf16 v[88:91], v[164:167], v[212:215], v[88:91]
	v_mfma_f32_16x16x32_bf16 v[76:79], v[156:159], v[220:223], v[76:79]
	v_mfma_f32_16x16x32_bf16 v[72:75], v[164:167], v[220:223], v[72:75]
	s_setprio 0
	s_setprio 1
	v_mfma_f32_16x16x32_bf16 v[116:119], v[168:171], v[186:189], v[116:119]
	v_mfma_f32_16x16x32_bf16 v[112:115], v[176:179], v[186:189], v[112:115]
	v_mfma_f32_16x16x32_bf16 v[100:103], v[168:171], v[194:197], v[100:103]
	v_mfma_f32_16x16x32_bf16 v[96:99], v[176:179], v[194:197], v[96:99]
	v_mfma_f32_16x16x32_bf16 v[84:87], v[168:171], v[208:211], v[84:87]
	v_mfma_f32_16x16x32_bf16 v[80:83], v[176:179], v[208:211], v[80:83]
	v_mfma_f32_16x16x32_bf16 v[68:71], v[168:171], v[216:219], v[68:71]
	v_mfma_f32_16x16x32_bf16 v[64:67], v[176:179], v[216:219], v[64:67]
	v_mfma_f32_16x16x32_bf16 v[116:119], v[172:175], v[190:193], v[116:119]
	v_mfma_f32_16x16x32_bf16 v[112:115], v[182:185], v[190:193], v[112:115]
	v_mfma_f32_16x16x32_bf16 v[100:103], v[172:175], v[198:201], v[100:103]
	v_mfma_f32_16x16x32_bf16 v[96:99], v[182:185], v[198:201], v[96:99]
	v_mfma_f32_16x16x32_bf16 v[84:87], v[172:175], v[212:215], v[84:87]
	v_mfma_f32_16x16x32_bf16 v[80:83], v[182:185], v[212:215], v[80:83]
	v_mfma_f32_16x16x32_bf16 v[68:71], v[172:175], v[220:223], v[68:71]
	v_mfma_f32_16x16x32_bf16 v[64:67], v[182:185], v[220:223], v[64:67]
	s_setprio 0
	s_barrier
; #define PG8_STAGE(bufoff, gbase, voff) do { _Pragma("unroll") for (int _i = 0; _i < 2; ++_i) \
;         __builtin_amdgcn_global_load_lds((const unsigned*)((const char*)(gbase) + (voff)[_i]), (PG8_LAS unsigned*)(lds + (bufoff) + ldsw + _i * 8192), 16, 0, 0); } while (0)
; #define PG8_LDA(dst, b, h) do { _Pragma("unroll") for (int m = 0; m < 4; ++m) _Pragma("unroll") for (int k = 0; k < 2; ++k) dst[m][k] = *(const PG8_LAS bf16x8*)(lds + PG8_SA(b, h) + aoff + m * 2048 + k * 1024); } while (0)
; #define PG8_LDB(dst, b, h) do { _Pragma("unroll") for (int n = 0; n < 2; ++n) _Pragma("unroll") for (int k = 0; k < 2; ++k) dst[n][k] = *(const PG8_LAS bf16x8*)(lds + PG8_SB(b, h) + boff + n * 2048 + k * 1024); } while (0)
; #define PG8_MMA(ai, bj, At, Bt) do { __builtin_amdgcn_s_setprio(1); _Pragma("unroll") for (int m = 0; m < 4; ++m) _Pragma("unroll") for (int n = 0; n < 2; ++n) _Pragma("unroll") for (int k = 0; k < 2; ++k) \
;         acc[ai][bj][m][n] = __builtin_amdgcn_mfma_f32_16x16x32_bf16(Bt[n][k], At[m][k], acc[ai][bj][m][n], 0, 0, 0); __builtin_amdgcn_s_setprio(0); } while (0)
; #define PG8_WAIT_V(n) asm volatile("s_waitcnt vmcnt(" #n ")" ::: "memory")
; #define PG8_WAIT_L(n) asm volatile("s_waitcnt lgkmcnt(" #n ")" ::: "memory")
; #define PG8_BAR __builtin_amdgcn_s_barrier()
; #define PG8_SCHED __builtin_amdgcn_sched_barrier(0)
; template <class Epi, class Sched, bool ALIGN_EPI = false, bool SP2 = false>
; __device__ __forceinline__ void gemm_phase(PG8_LAS unsigned char* lds, const Gemm g, const Sched& S, const Epi& E) {
;     ...
;             PG8_LDB(B0, 0, 0); PG8_LDB(B1, 0, 1); PG8_SCHED; PG8_LDA(At, 0, 0); PG8_STAGE(PG8_SA(1, 1), a1 + hstep, voffA);
;             PG8_WAIT_V(8); PG8_WAIT_L(0); PG8_BAR; PG8_MMA(0, 0, At, B0); PG8_MMA(0, 1, At, B1); PG8_BAR; PG8_SCHED;
;     ...
;             PG8_LDA(At, 1, 1); PG8_STAGE(PG8_SB(1, 0), b3, voffB); PG8_STAGE(PG8_SB(1, 1), b3 + hstep, voffB); PG8_STAGE(PG8_SA(1, 0), a3, voffA);
;             PG8_WAIT_V(8); PG8_WAIT_L(0); PG8_BAR; PG8_MMA(1, 0, At, B0); PG8_MMA(1, 1, At, B1); PG8_BAR; PG8_SCHED;
	s_add_i32 s50, s78, s3
	v_lshl_add_u64 v[202:203], v[202:203], 0, s[42:43]
	s_mov_b32 m0, s50
	ds_read_b128 v[186:189], v153 offset:49152
	ds_read_b128 v[190:193], v153 offset:50176
	ds_read_b128 v[194:197], v153 offset:51200
	ds_read_b128 v[198:201], v153 offset:52224
	ds_read_b128 v[208:211], v153 offset:53248
	ds_read_b128 v[212:215], v153 offset:54272
	ds_read_b128 v[216:219], v153 offset:55296
	ds_read_b128 v[220:223], v153 offset:56320
	global_load_lds_dwordx4 v[202:203], off
	s_add_i32 m0, s50, 0x2000
	s_add_u32 s50, s54, 0xb0080
	v_lshl_add_u64 v[202:203], v[224:225], 0, s[42:43]
	s_addc_u32 s51, s55, 0
	s_add_i32 s54, s79, s3
	global_load_lds_dwordx4 v[202:203], off
	v_lshl_add_u64 v[202:203], s[50:51], 0, v[130:131]
	s_mov_b32 m0, s54
	s_nop 0
	global_load_lds_dwordx4 v[202:203], off
	v_lshl_add_u64 v[202:203], s[50:51], 0, v[134:135]
	s_add_i32 m0, s54, 0x2000
	s_nop 0
	global_load_lds_dwordx4 v[202:203], off
	v_lshl_add_u64 v[202:203], v[226:227], 0, s[42:43]
	s_mov_b32 m0, s59
	s_nop 0
	global_load_lds_dwordx4 v[202:203], off
	v_lshl_add_u64 v[202:203], v[228:229], 0, s[42:43]
	s_mov_b32 m0, s60
	s_nop 0
	global_load_lds_dwordx4 v[202:203], off
	s_waitcnt vmcnt(8)
	s_waitcnt lgkmcnt(0)
	s_barrier
	s_setprio 1
	s_waitcnt lgkmcnt(0)
	v_mfma_f32_16x16x32_bf16 v[60:63], v[144:147], v[186:189], v[60:63]
	v_mfma_f32_16x16x32_bf16 v[56:59], v[160:163], v[186:189], v[56:59]
	v_mfma_f32_16x16x32_bf16 v[44:47], v[144:147], v[194:197], v[44:47]
	v_mfma_f32_16x16x32_bf16 v[40:43], v[160:163], v[194:197], v[40:43]
	v_mfma_f32_16x16x32_bf16 v[28:31], v[144:147], v[208:211], v[28:31]
	v_mfma_f32_16x16x32_bf16 v[24:27], v[160:163], v[208:211], v[24:27]
	v_mfma_f32_16x16x32_bf16 v[12:15], v[144:147], v[216:219], v[12:15]
	v_mfma_f32_16x16x32_bf16 v[8:11], v[160:163], v[216:219], v[8:11]
	v_mfma_f32_16x16x32_bf16 v[60:63], v[156:159], v[190:193], v[60:63]
	v_mfma_f32_16x16x32_bf16 v[56:59], v[164:167], v[190:193], v[56:59]
	v_mfma_f32_16x16x32_bf16 v[44:47], v[156:159], v[198:201], v[44:47]
	v_mfma_f32_16x16x32_bf16 v[40:43], v[164:167], v[198:201], v[40:43]
	v_mfma_f32_16x16x32_bf16 v[28:31], v[156:159], v[212:215], v[28:31]
	v_mfma_f32_16x16x32_bf16 v[24:27], v[164:167], v[212:215], v[24:27]
	v_mfma_f32_16x16x32_bf16 v[12:15], v[156:159], v[220:223], v[12:15]
	v_mfma_f32_16x16x32_bf16 v[8:11], v[164:167], v[220:223], v[8:11]
	s_setprio 0
	s_setprio 1
	v_mfma_f32_16x16x32_bf16 v[52:55], v[168:171], v[186:189], v[52:55]
	v_mfma_f32_16x16x32_bf16 v[48:51], v[176:179], v[186:189], v[48:51]
	v_mfma_f32_16x16x32_bf16 v[36:39], v[168:171], v[194:197], v[36:39]
	v_mfma_f32_16x16x32_bf16 v[32:35], v[176:179], v[194:197], v[32:35]
	v_mfma_f32_16x16x32_bf16 v[20:23], v[168:171], v[208:211], v[20:23]
	v_mfma_f32_16x16x32_bf16 v[16:19], v[176:179], v[208:211], v[16:19]
	v_mfma_f32_16x16x32_bf16 v[4:7], v[168:171], v[216:219], v[4:7]
	v_mfma_f32_16x16x32_bf16 v[0:3], v[176:179], v[216:219], v[0:3]
	v_mfma_f32_16x16x32_bf16 v[52:55], v[172:175], v[190:193], v[52:55]
	v_mfma_f32_16x16x32_bf16 v[48:51], v[182:185], v[190:193], v[48:51]
	v_mfma_f32_16x16x32_bf16 v[36:39], v[172:175], v[198:201], v[36:39]
	v_mfma_f32_16x16x32_bf16 v[32:35], v[182:185], v[198:201], v[32:35]
	v_mfma_f32_16x16x32_bf16 v[20:23], v[172:175], v[212:215], v[20:23]
	v_mfma_f32_16x16x32_bf16 v[16:19], v[182:185], v[212:215], v[16:19]
	v_mfma_f32_16x16x32_bf16 v[4:7], v[172:175], v[220:223], v[4:7]
	v_mfma_f32_16x16x32_bf16 v[0:3], v[182:185], v[220:223], v[0:3]
	s_setprio 0
	s_barrier
	s_add_i32 s77, s77, 2
	s_add_u32 s75, s75, 0x100
	s_addc_u32 s76, s76, 0
	s_mov_b64 s[50:51], s[52:53]
.LBB0_1035:
	ds_read_b128 v[144:147], v151
	ds_read_b128 v[156:159], v151 offset:1024
	ds_read_b128 v[160:163], v151 offset:2048
	ds_read_b128 v[164:167], v151 offset:3072
	ds_read_b128 v[168:171], v152
	ds_read_b128 v[172:175], v152 offset:1024
	ds_read_b128 v[176:179], v152 offset:2048
	ds_read_b128 v[182:185], v152 offset:3072
	s_add_u32 s52, s50, 0x100
	s_addc_u32 s53, s51, 0
	s_cmp_eq_u32 s77, 40
	s_cselect_b32 s57, s1, s53
	s_cselect_b32 s56, s0, s52
	s_cselect_b32 s55, s49, s76
	s_cselect_b32 s54, s48, s75
	v_lshl_add_u64 v[202:203], s[50:51], 0, v[136:137]
	s_add_i32 m0, s14, 0xc000
	ds_read_b128 v[186:189], v153
	ds_read_b128 v[190:193], v153 offset:1024
	ds_read_b128 v[194:197], v153 offset:2048
	ds_read_b128 v[198:201], v153 offset:3072
	ds_read_b128 v[208:211], v153 offset:4096
	ds_read_b128 v[212:215], v153 offset:5120
	ds_read_b128 v[216:219], v153 offset:6144
	ds_read_b128 v[220:223], v153 offset:7168
	global_load_lds_dwordx4 v[202:203], off
	v_lshl_add_u64 v[202:203], s[50:51], 0, v[138:139]
	s_add_i32 m0, s14, 0xe000
	s_nop 0
	global_load_lds_dwordx4 v[202:203], off
	s_waitcnt vmcnt(8)
	s_waitcnt lgkmcnt(0)
	s_barrier
; #define PG8_STAGE(bufoff, gbase, voff) do { _Pragma("unroll") for (int _i = 0; _i < 2; ++_i) \
;         __builtin_amdgcn_global_load_lds((const unsigned*)((const char*)(gbase) + (voff)[_i]), (PG8_LAS unsigned*)(lds + (bufoff) + ldsw + _i * 8192), 16, 0, 0); } while (0)
; #define PG8_LDA(dst, b, h) do { _Pragma("unroll") for (int m = 0; m < 4; ++m) _Pragma("unroll") for (int k = 0; k < 2; ++k) dst[m][k] = *(const PG8_LAS bf16x8*)(lds + PG8_SA(b, h) + aoff + m * 2048 + k * 1024); } while (0)
; #define PG8_MMA(ai, bj, At, Bt) do { __builtin_amdgcn_s_setprio(1); _Pragma("unroll") for (int m = 0; m < 4; ++m) _Pragma("unroll") for (int n = 0; n < 2; ++n) _Pragma("unroll") for (int k = 0; k < 2; ++k) \
;         acc[ai][bj][m][n] = __builtin_amdgcn_mfma_f32_16x16x32_bf16(Bt[n][k], At[m][k], acc[ai][bj][m][n], 0, 0, 0); __builtin_amdgcn_s_setprio(0); } while (0)
; #define PG8_WAIT_V(n) asm volatile("s_waitcnt vmcnt(" #n ")" ::: "memory")
; #define PG8_WAIT_L(n) asm volatile("s_waitcnt lgkmcnt(" #n ")" ::: "memory")
; #define PG8_BAR __builtin_amdgcn_s_barrier()
; #define PG8_SCHED __builtin_amdgcn_sched_barrier(0)
; template <class Epi, class Sched, bool ALIGN_EPI = false, bool SP2 = false>
; __device__ __forceinline__ void gemm_phase(PG8_LAS unsigned char* lds, const Gemm g, const Sched& S, const Epi& E) {
;     ...
;             PG8_WAIT_V(8); PG8_WAIT_L(0); PG8_BAR; PG8_MMA(0, 0, At, B0); PG8_MMA(0, 1, At, B1); PG8_BAR; PG8_SCHED;
;             PG8_LDA(At, 0, 1); PG8_STAGE(PG8_SB(0, 0), b2, voffB); PG8_STAGE(PG8_SB(0, 1), b2 + hstep, voffB); PG8_STAGE(PG8_SA(0, 0), a2, voffA);
;             PG8_WAIT_V(8); PG8_WAIT_L(0); PG8_BAR; PG8_MMA(1, 0, At, B0); PG8_MMA(1, 1, At, B1); PG8_BAR; PG8_SCHED;
	s_setprio 1
	s_waitcnt lgkmcnt(0)
	v_mfma_f32_16x16x32_bf16 v[124:127], v[144:147], v[186:189], v[124:127]
	v_mfma_f32_16x16x32_bf16 v[120:123], v[160:163], v[186:189], v[120:123]
	v_mfma_f32_16x16x32_bf16 v[108:111], v[144:147], v[194:197], v[108:111]
	v_mfma_f32_16x16x32_bf16 v[104:107], v[160:163], v[194:197], v[104:107]
	v_mfma_f32_16x16x32_bf16 v[92:95], v[144:147], v[208:211], v[92:95]
	v_mfma_f32_16x16x32_bf16 v[88:91], v[160:163], v[208:211], v[88:91]
	v_mfma_f32_16x16x32_bf16 v[76:79], v[144:147], v[216:219], v[76:79]
	v_mfma_f32_16x16x32_bf16 v[72:75], v[160:163], v[216:219], v[72:75]
	v_mfma_f32_16x16x32_bf16 v[124:127], v[156:159], v[190:193], v[124:127]
	v_mfma_f32_16x16x32_bf16 v[120:123], v[164:167], v[190:193], v[120:123]
	v_mfma_f32_16x16x32_bf16 v[108:111], v[156:159], v[198:201], v[108:111]
	v_mfma_f32_16x16x32_bf16 v[104:107], v[164:167], v[198:201], v[104:107]
	v_mfma_f32_16x16x32_bf16 v[92:95], v[156:159], v[212:215], v[92:95]
	v_mfma_f32_16x16x32_bf16 v[88:91], v[164:167], v[212:215], v[88:91]
	v_mfma_f32_16x16x32_bf16 v[76:79], v[156:159], v[220:223], v[76:79]
	v_mfma_f32_16x16x32_bf16 v[72:75], v[164:167], v[220:223], v[72:75]
	s_setprio 0
	s_setprio 1
	v_mfma_f32_16x16x32_bf16 v[116:119], v[168:171], v[186:189], v[116:119]
	v_mfma_f32_16x16x32_bf16 v[112:115], v[176:179], v[186:189], v[112:115]
	v_mfma_f32_16x16x32_bf16 v[100:103], v[168:171], v[194:197], v[100:103]
	v_mfma_f32_16x16x32_bf16 v[96:99], v[176:179], v[194:197], v[96:99]
	v_mfma_f32_16x16x32_bf16 v[84:87], v[168:171], v[208:211], v[84:87]
	v_mfma_f32_16x16x32_bf16 v[80:83], v[176:179], v[208:211], v[80:83]
	v_mfma_f32_16x16x32_bf16 v[68:71], v[168:171], v[216:219], v[68:71]
	v_mfma_f32_16x16x32_bf16 v[64:67], v[176:179], v[216:219], v[64:67]
	v_mfma_f32_16x16x32_bf16 v[116:119], v[172:175], v[190:193], v[116:119]
	v_mfma_f32_16x16x32_bf16 v[112:115], v[182:185], v[190:193], v[112:115]
	v_mfma_f32_16x16x32_bf16 v[100:103], v[172:175], v[198:201], v[100:103]
	v_mfma_f32_16x16x32_bf16 v[96:99], v[182:185], v[198:201], v[96:99]
	v_mfma_f32_16x16x32_bf16 v[84:87], v[172:175], v[212:215], v[84:87]
	v_mfma_f32_16x16x32_bf16 v[80:83], v[182:185], v[212:215], v[80:83]
	v_mfma_f32_16x16x32_bf16 v[68:71], v[172:175], v[220:223], v[68:71]
	v_mfma_f32_16x16x32_bf16 v[64:67], v[182:185], v[220:223], v[64:67]
	s_setprio 0
	s_barrier
	s_add_i32 s50, s61, s3
	v_lshl_add_u64 v[202:203], s[54:55], 0, v[130:131]
	s_mov_b32 m0, s50
	ds_read_b128 v[186:189], v153 offset:16384
	ds_read_b128 v[190:193], v153 offset:17408
	ds_read_b128 v[194:197], v153 offset:18432
	ds_read_b128 v[198:201], v153 offset:19456
	ds_read_b128 v[208:211], v153 offset:20480
	ds_read_b128 v[212:215], v153 offset:21504
	ds_read_b128 v[216:219], v153 offset:22528
	ds_read_b128 v[220:223], v153 offset:23552
	global_load_lds_dwordx4 v[202:203], off
	s_add_i32 m0, s50, 0x2000
	s_add_u32 s50, s54, 0xb0000
	v_lshl_add_u64 v[224:225], s[54:55], 0, v[134:135]
	s_addc_u32 s51, s55, 0
	s_add_i32 s78, s62, s3
	global_load_lds_dwordx4 v[224:225], off
	v_lshl_add_u64 v[226:227], s[50:51], 0, v[130:131]
	s_mov_b32 m0, s78
	global_load_lds_dwordx4 v[226:227], off
	v_lshl_add_u64 v[226:227], s[50:51], 0, v[134:135]
	s_add_i32 m0, s78, 0x2000
	s_nop 0
	global_load_lds_dwordx4 v[226:227], off
	v_lshl_add_u64 v[226:227], s[56:57], 0, v[128:129]
	s_mov_b32 m0, s14
	s_nop 0
	global_load_lds_dwordx4 v[226:227], off
	v_lshl_add_u64 v[228:229], s[56:57], 0, v[132:133]
	s_mov_b32 m0, s15
	s_nop 0
	global_load_lds_dwordx4 v[228:229], off
	s_waitcnt vmcnt(8)
	s_waitcnt lgkmcnt(0)
	s_barrier
	s_setprio 1
	s_waitcnt lgkmcnt(0)
	v_mfma_f32_16x16x32_bf16 v[60:63], v[144:147], v[186:189], v[60:63]
	v_mfma_f32_16x16x32_bf16 v[56:59], v[160:163], v[186:189], v[56:59]
	v_mfma_f32_16x16x32_bf16 v[44:47], v[144:147], v[194:197], v[44:47]
	v_mfma_f32_16x16x32_bf16 v[40:43], v[160:163], v[194:197], v[40:43]
	v_mfma_f32_16x16x32_bf16 v[28:31], v[144:147], v[208:211], v[28:31]
	v_mfma_f32_16x16x32_bf16 v[24:27], v[160:163], v[208:211], v[24:27]
	v_mfma_f32_16x16x32_bf16 v[12:15], v[144:147], v[216:219], v[12:15]
	v_mfma_f32_16x16x32_bf16 v[8:11], v[160:163], v[216:219], v[8:11]
	v_mfma_f32_16x16x32_bf16 v[60:63], v[156:159], v[190:193], v[60:63]
	v_mfma_f32_16x16x32_bf16 v[56:59], v[164:167], v[190:193], v[56:59]
	v_mfma_f32_16x16x32_bf16 v[44:47], v[156:159], v[198:201], v[44:47]
	v_mfma_f32_16x16x32_bf16 v[40:43], v[164:167], v[198:201], v[40:43]
	v_mfma_f32_16x16x32_bf16 v[28:31], v[156:159], v[212:215], v[28:31]
	v_mfma_f32_16x16x32_bf16 v[24:27], v[164:167], v[212:215], v[24:27]
	v_mfma_f32_16x16x32_bf16 v[12:15], v[156:159], v[220:223], v[12:15]
	v_mfma_f32_16x16x32_bf16 v[8:11], v[164:167], v[220:223], v[8:11]
	s_setprio 0
	s_setprio 1
	v_mfma_f32_16x16x32_bf16 v[52:55], v[168:171], v[186:189], v[52:55]
	v_mfma_f32_16x16x32_bf16 v[48:51], v[176:179], v[186:189], v[48:51]
	v_mfma_f32_16x16x32_bf16 v[36:39], v[168:171], v[194:197], v[36:39]
	v_mfma_f32_16x16x32_bf16 v[32:35], v[176:179], v[194:197], v[32:35]
	v_mfma_f32_16x16x32_bf16 v[20:23], v[168:171], v[208:211], v[20:23]
	v_mfma_f32_16x16x32_bf16 v[16:19], v[176:179], v[208:211], v[16:19]
	v_mfma_f32_16x16x32_bf16 v[4:7], v[168:171], v[216:219], v[4:7]
	v_mfma_f32_16x16x32_bf16 v[0:3], v[176:179], v[216:219], v[0:3]
	v_mfma_f32_16x16x32_bf16 v[52:55], v[172:175], v[190:193], v[52:55]
	v_mfma_f32_16x16x32_bf16 v[48:51], v[182:185], v[190:193], v[48:51]
	v_mfma_f32_16x16x32_bf16 v[36:39], v[172:175], v[198:201], v[36:39]
	v_mfma_f32_16x16x32_bf16 v[32:35], v[182:185], v[198:201], v[32:35]
	v_mfma_f32_16x16x32_bf16 v[20:23], v[172:175], v[212:215], v[20:23]
	v_mfma_f32_16x16x32_bf16 v[16:19], v[182:185], v[212:215], v[16:19]
	v_mfma_f32_16x16x32_bf16 v[4:7], v[172:175], v[220:223], v[4:7]
	v_mfma_f32_16x16x32_bf16 v[0:3], v[182:185], v[220:223], v[0:3]
	s_setprio 0
	s_barrier
; #define PG8_STAGE(bufoff, gbase, voff) do { _Pragma("unroll") for (int _i = 0; _i < 2; ++_i) \
;         __builtin_amdgcn_global_load_lds((const unsigned*)((const char*)(gbase) + (voff)[_i]), (PG8_LAS unsigned*)(lds + (bufoff) + ldsw + _i * 8192), 16, 0, 0); } while (0)
; #define PG8_LDA(dst, b, h) do { _Pragma("unroll") for (int m = 0; m < 4; ++m) _Pragma("unroll") for (int k = 0; k < 2; ++k) dst[m][k] = *(const PG8_LAS bf16x8*)(lds + PG8_SA(b, h) + aoff + m * 2048 + k * 1024); } while (0)
; #define PG8_LDB(dst, b, h) do { _Pragma("unroll") for (int n = 0; n < 2; ++n) _Pragma("unroll") for (int k = 0; k < 2; ++k) dst[n][k] = *(const PG8_LAS bf16x8*)(lds + PG8_SB(b, h) + boff + n * 2048 + k * 1024); } while (0)
; #define PG8_MMA(ai, bj, At, Bt) do { __builtin_amdgcn_s_setprio(1); _Pragma("unroll") for (int m = 0; m < 4; ++m) _Pragma("unroll") for (int n = 0; n < 2; ++n) _Pragma("unroll") for (int k = 0; k < 2; ++k) \
;         acc[ai][bj][m][n] = __builtin_amdgcn_mfma_f32_16x16x32_bf16(Bt[n][k], At[m][k], acc[ai][bj][m][n], 0, 0, 0); __builtin_amdgcn_s_setprio(0); } while (0)
; #define PG8_WAIT_V(n) asm volatile("s_waitcnt vmcnt(" #n ")" ::: "memory")
; #define PG8_WAIT_L(n) asm volatile("s_waitcnt lgkmcnt(" #n ")" ::: "memory")
; #define PG8_BAR __builtin_amdgcn_s_barrier()
; #define PG8_SCHED __builtin_amdgcn_sched_barrier(0)
; template <class Epi, class Sched, bool ALIGN_EPI = false, bool SP2 = false>
; __device__ __forceinline__ void gemm_phase(PG8_LAS unsigned char* lds, const Gemm g, const Sched& S, const Epi& E) {
;     ...
;             PG8_LDB(B0, 1, 0); PG8_LDB(B1, 1, 1); PG8_SCHED; PG8_LDA(At, 1, 0); PG8_STAGE(PG8_SA(0, 1), a2 + hstep, voffA);
;             PG8_WAIT_V(8); PG8_WAIT_L(0); PG8_BAR; PG8_MMA(0, 0, At, B0); PG8_MMA(0, 1, At, B1); PG8_BAR; PG8_SCHED;
	s_add_i32 s78, 0, 0x18000
	v_add_u32_e32 v155, s78, v149
	s_add_i32 s79, 0, 0x1c000
	ds_read_b128 v[144:147], v155
	ds_read_b128 v[156:159], v155 offset:1024
	ds_read_b128 v[160:163], v155 offset:2048
	ds_read_b128 v[164:167], v155 offset:3072
	v_add_u32_e32 v155, s79, v149
	ds_read_b128 v[168:171], v155
	ds_read_b128 v[172:175], v155 offset:1024
	ds_read_b128 v[176:179], v155 offset:2048
	ds_read_b128 v[182:185], v155 offset:3072
	s_add_u32 s50, s56, 0xb0000
	s_addc_u32 s51, s57, 0
	s_mov_b32 m0, s33
	v_lshl_add_u64 v[230:231], s[50:51], 0, v[128:129]
	ds_read_b128 v[186:189], v153 offset:32768
	ds_read_b128 v[190:193], v153 offset:33792
	ds_read_b128 v[194:197], v153 offset:34816
	ds_read_b128 v[198:201], v153 offset:35840
	ds_read_b128 v[208:211], v153 offset:36864
	ds_read_b128 v[212:215], v153 offset:37888
	ds_read_b128 v[216:219], v153 offset:38912
	ds_read_b128 v[220:223], v153 offset:39936
	global_load_lds_dwordx4 v[230:231], off
	v_lshl_add_u64 v[230:231], s[50:51], 0, v[132:133]
	s_mov_b32 m0, s34
	s_nop 0
	global_load_lds_dwordx4 v[230:231], off
	s_waitcnt vmcnt(8)
	s_waitcnt lgkmcnt(0)
	s_barrier
	s_setprio 1
	s_waitcnt lgkmcnt(0)
	v_mfma_f32_16x16x32_bf16 v[124:127], v[144:147], v[186:189], v[124:127]
	v_mfma_f32_16x16x32_bf16 v[120:123], v[160:163], v[186:189], v[120:123]
	v_mfma_f32_16x16x32_bf16 v[108:111], v[144:147], v[194:197], v[108:111]
	v_mfma_f32_16x16x32_bf16 v[104:107], v[160:163], v[194:197], v[104:107]
	v_mfma_f32_16x16x32_bf16 v[92:95], v[144:147], v[208:211], v[92:95]
	v_mfma_f32_16x16x32_bf16 v[88:91], v[160:163], v[208:211], v[88:91]
	v_mfma_f32_16x16x32_bf16 v[76:79], v[144:147], v[216:219], v[76:79]
	v_mfma_f32_16x16x32_bf16 v[72:75], v[160:163], v[216:219], v[72:75]
	v_mfma_f32_16x16x32_bf16 v[124:127], v[156:159], v[190:193], v[124:127]
	v_mfma_f32_16x16x32_bf16 v[120:123], v[164:167], v[190:193], v[120:123]
	v_mfma_f32_16x16x32_bf16 v[108:111], v[156:159], v[198:201], v[108:111]
	v_mfma_f32_16x16x32_bf16 v[104:107], v[164:167], v[198:201], v[104:107]
	v_mfma_f32_16x16x32_bf16 v[92:95], v[156:159], v[212:215], v[92:95]
	v_mfma_f32_16x16x32_bf16 v[88:91], v[164:167], v[212:215], v[88:91]
	v_mfma_f32_16x16x32_bf16 v[76:79], v[156:159], v[220:223], v[76:79]
	v_mfma_f32_16x16x32_bf16 v[72:75], v[164:167], v[220:223], v[72:75]
	s_setprio 0
	s_setprio 1
	v_mfma_f32_16x16x32_bf16 v[116:119], v[168:171], v[186:189], v[116:119]
	v_mfma_f32_16x16x32_bf16 v[112:115], v[176:179], v[186:189], v[112:115]
	v_mfma_f32_16x16x32_bf16 v[100:103], v[168:171], v[194:197], v[100:103]
	v_mfma_f32_16x16x32_bf16 v[96:99], v[176:179], v[194:197], v[96:99]
	v_mfma_f32_16x16x32_bf16 v[84:87], v[168:171], v[208:211], v[84:87]
	v_mfma_f32_16x16x32_bf16 v[80:83], v[176:179], v[208:211], v[80:83]
	v_mfma_f32_16x16x32_bf16 v[68:71], v[168:171], v[216:219], v[68:71]
	v_mfma_f32_16x16x32_bf16 v[64:67], v[176:179], v[216:219], v[64:67]
	v_mfma_f32_16x16x32_bf16 v[116:119], v[172:175], v[190:193], v[116:119]
	v_mfma_f32_16x16x32_bf16 v[112:115], v[182:185], v[190:193], v[112:115]
	v_mfma_f32_16x16x32_bf16 v[100:103], v[172:175], v[198:201], v[100:103]
	v_mfma_f32_16x16x32_bf16 v[96:99], v[182:185], v[198:201], v[96:99]
	v_mfma_f32_16x16x32_bf16 v[84:87], v[172:175], v[212:215], v[84:87]
	v_mfma_f32_16x16x32_bf16 v[80:83], v[182:185], v[212:215], v[80:83]
	v_mfma_f32_16x16x32_bf16 v[68:71], v[172:175], v[220:223], v[68:71]
	v_mfma_f32_16x16x32_bf16 v[64:67], v[182:185], v[220:223], v[64:67]
	s_setprio 0
	s_barrier
; #define PG8_STAGE(bufoff, gbase, voff) do { _Pragma("unroll") for (int _i = 0; _i < 2; ++_i) \
;         __builtin_amdgcn_global_load_lds((const unsigned*)((const char*)(gbase) + (voff)[_i]), (PG8_LAS unsigned*)(lds + (bufoff) + ldsw + _i * 8192), 16, 0, 0); } while (0)
; #define PG8_LDA(dst, b, h) do { _Pragma("unroll") for (int m = 0; m < 4; ++m) _Pragma("unroll") for (int k = 0; k < 2; ++k) dst[m][k] = *(const PG8_LAS bf16x8*)(lds + PG8_SA(b, h) + aoff + m * 2048 + k * 1024); } while (0)
; #define PG8_MMA(ai, bj, At, Bt) do { __builtin_amdgcn_s_setprio(1); _Pragma("unroll") for (int m = 0; m < 4; ++m) _Pragma("unroll") for (int n = 0; n < 2; ++n) _Pragma("unroll") for (int k = 0; k < 2; ++k) \
;         acc[ai][bj][m][n] = __builtin_amdgcn_mfma_f32_16x16x32_bf16(Bt[n][k], At[m][k], acc[ai][bj][m][n], 0, 0, 0); __builtin_amdgcn_s_setprio(0); } while (0)
; #define PG8_WAIT_V(n) asm volatile("s_waitcnt vmcnt(" #n ")" ::: "memory")
; #define PG8_WAIT_L(n) asm volatile("s_waitcnt lgkmcnt(" #n ")" ::: "memory")
; #define PG8_BAR __builtin_amdgcn_s_barrier()
; #define PG8_SCHED __builtin_amdgcn_sched_barrier(0)
; template <class Epi, class Sched, bool ALIGN_EPI = false, bool SP2 = false>
; __device__ __forceinline__ void gemm_phase(PG8_LAS unsigned char* lds, const Gemm g, const Sched& S, const Epi& E) {
;     ...
;             PG8_LDA(At, 1, 1); PG8_STAGE(PG8_SB(1, 0), b3, voffB); PG8_STAGE(PG8_SB(1, 1), b3 + hstep, voffB); PG8_STAGE(PG8_SA(1, 0), a3, voffA);
;             PG8_WAIT_V(8); PG8_WAIT_L(0); PG8_BAR; PG8_MMA(1, 0, At, B0); PG8_MMA(1, 1, At, B1); PG8_BAR; PG8_SCHED;
;     ...
;         if constexpr (ALIGN_EPI) { if (wr == 0) PG8_BAR; }
	s_add_i32 s50, s78, s3
	v_lshl_add_u64 v[202:203], v[202:203], 0, s[42:43]
	s_mov_b32 m0, s50
	ds_read_b128 v[186:189], v153 offset:49152
	ds_read_b128 v[190:193], v153 offset:50176
	ds_read_b128 v[194:197], v153 offset:51200
	ds_read_b128 v[198:201], v153 offset:52224
	ds_read_b128 v[208:211], v153 offset:53248
	ds_read_b128 v[212:215], v153 offset:54272
	ds_read_b128 v[216:219], v153 offset:55296
	ds_read_b128 v[220:223], v153 offset:56320
	global_load_lds_dwordx4 v[202:203], off
	s_add_i32 m0, s50, 0x2000
	s_add_u32 s50, s54, 0xb0080
	v_lshl_add_u64 v[202:203], v[224:225], 0, s[42:43]
	s_addc_u32 s51, s55, 0
	s_add_i32 s54, s79, s3
	global_load_lds_dwordx4 v[202:203], off
	v_lshl_add_u64 v[202:203], s[50:51], 0, v[130:131]
	s_mov_b32 m0, s54
	s_nop 0
	global_load_lds_dwordx4 v[202:203], off
	v_lshl_add_u64 v[202:203], s[50:51], 0, v[134:135]
	s_add_i32 m0, s54, 0x2000
	s_nop 0
	global_load_lds_dwordx4 v[202:203], off
	v_lshl_add_u64 v[202:203], v[226:227], 0, s[42:43]
	s_mov_b32 m0, s59
	s_nop 0
	global_load_lds_dwordx4 v[202:203], off
	v_lshl_add_u64 v[202:203], v[228:229], 0, s[42:43]
	s_mov_b32 m0, s60
	s_nop 0
	global_load_lds_dwordx4 v[202:203], off
	s_waitcnt vmcnt(8)
	s_waitcnt lgkmcnt(0)
	s_barrier
	s_setprio 1
	s_waitcnt lgkmcnt(0)
	v_mfma_f32_16x16x32_bf16 v[60:63], v[144:147], v[186:189], v[60:63]
	v_mfma_f32_16x16x32_bf16 v[56:59], v[160:163], v[186:189], v[56:59]
	v_mfma_f32_16x16x32_bf16 v[44:47], v[144:147], v[194:197], v[44:47]
	v_mfma_f32_16x16x32_bf16 v[40:43], v[160:163], v[194:197], v[40:43]
	v_mfma_f32_16x16x32_bf16 v[28:31], v[144:147], v[208:211], v[28:31]
	v_mfma_f32_16x16x32_bf16 v[24:27], v[160:163], v[208:211], v[24:27]
	v_mfma_f32_16x16x32_bf16 v[12:15], v[144:147], v[216:219], v[12:15]
	v_mfma_f32_16x16x32_bf16 v[8:11], v[160:163], v[216:219], v[8:11]
	v_mfma_f32_16x16x32_bf16 v[60:63], v[156:159], v[190:193], v[60:63]
	v_mfma_f32_16x16x32_bf16 v[56:59], v[164:167], v[190:193], v[56:59]
	v_mfma_f32_16x16x32_bf16 v[44:47], v[156:159], v[198:201], v[44:47]
	v_mfma_f32_16x16x32_bf16 v[40:43], v[164:167], v[198:201], v[40:43]
	v_mfma_f32_16x16x32_bf16 v[28:31], v[156:159], v[212:215], v[28:31]
	v_mfma_f32_16x16x32_bf16 v[24:27], v[164:167], v[212:215], v[24:27]
	v_mfma_f32_16x16x32_bf16 v[12:15], v[156:159], v[220:223], v[12:15]
	v_mfma_f32_16x16x32_bf16 v[8:11], v[164:167], v[220:223], v[8:11]
	s_setprio 0
	s_setprio 1
	v_mfma_f32_16x16x32_bf16 v[52:55], v[168:171], v[186:189], v[52:55]
	v_mfma_f32_16x16x32_bf16 v[48:51], v[176:179], v[186:189], v[48:51]
	v_mfma_f32_16x16x32_bf16 v[36:39], v[168:171], v[194:197], v[36:39]
	v_mfma_f32_16x16x32_bf16 v[32:35], v[176:179], v[194:197], v[32:35]
	v_mfma_f32_16x16x32_bf16 v[20:23], v[168:171], v[208:211], v[20:23]
	v_mfma_f32_16x16x32_bf16 v[16:19], v[176:179], v[208:211], v[16:19]
	v_mfma_f32_16x16x32_bf16 v[4:7], v[168:171], v[216:219], v[4:7]
	v_mfma_f32_16x16x32_bf16 v[0:3], v[176:179], v[216:219], v[0:3]
	v_mfma_f32_16x16x32_bf16 v[52:55], v[172:175], v[190:193], v[52:55]
	v_mfma_f32_16x16x32_bf16 v[48:51], v[182:185], v[190:193], v[48:51]
	v_mfma_f32_16x16x32_bf16 v[36:39], v[172:175], v[198:201], v[36:39]
	v_mfma_f32_16x16x32_bf16 v[32:35], v[182:185], v[198:201], v[32:35]
	v_mfma_f32_16x16x32_bf16 v[20:23], v[172:175], v[212:215], v[20:23]
	v_mfma_f32_16x16x32_bf16 v[16:19], v[182:185], v[212:215], v[16:19]
	v_mfma_f32_16x16x32_bf16 v[4:7], v[172:175], v[220:223], v[4:7]
	v_mfma_f32_16x16x32_bf16 v[0:3], v[182:185], v[220:223], v[0:3]
	s_setprio 0
	s_barrier
	s_add_i32 s77, s77, 2
	s_add_u32 s75, s75, 0x100
	s_addc_u32 s76, s76, 0
	s_cmp_gt_u32 s77, 41
	s_mov_b64 s[50:51], s[52:53]
	s_cbranch_scc0 .LBB0_1035
	s_and_b64 vcc, exec, s[44:45]
	s_cbranch_vccz .LBB0_1038
	s_barrier

; #define PG8_STAGE(bufoff, gbase, voff) do { _Pragma("unroll") for (int _i = 0; _i < 2; ++_i) \
;         __builtin_amdgcn_global_load_lds((const unsigned*)((const char*)(gbase) + (voff)[_i]), (PG8_LAS unsigned*)(lds + (bufoff) + ldsw + _i * 8192), 16, 0, 0); } while (0)
; #define PG8_LDA(dst, b, h) do { _Pragma("unroll") for (int m = 0; m < 4; ++m) _Pragma("unroll") for (int k = 0; k < 2; ++k) dst[m][k] = *(const PG8_LAS bf16x8*)(lds + PG8_SA(b, h) + aoff + m * 2048 + k * 1024); } while (0)
; #define PG8_LDB(dst, b, h) do { _Pragma("unroll") for (int n = 0; n < 2; ++n) _Pragma("unroll") for (int k = 0; k < 2; ++k) dst[n][k] = *(const PG8_LAS bf16x8*)(lds + PG8_SB(b, h) + boff + n * 2048 + k * 1024); } while (0)
; #define PG8_MMA(ai, bj, At, Bt) do { __builtin_amdgcn_s_setprio(1); _Pragma("unroll") for (int m = 0; m < 4; ++m) _Pragma("unroll") for (int n = 0; n < 2; ++n) _Pragma("unroll") for (int k = 0; k < 2; ++k) \
;         acc[ai][bj][m][n] = __builtin_amdgcn_mfma_f32_16x16x32_bf16(Bt[n][k], At[m][k], acc[ai][bj][m][n], 0, 0, 0); __builtin_amdgcn_s_setprio(0); } while (0)
; #define PG8_BAR __builtin_amdgcn_s_barrier()
; template <class Epi, class Sched, bool ALIGN_EPI = false, bool SP2 = false>
; __device__ __forceinline__ void gemm_phase(PG8_LAS unsigned char* lds, const Gemm g, const Sched& S, const Epi& E) {
;     ...
;         const bool has_next = S.next(ui + 1, nxt);
;         const char* nA = has_next ? (const char*)g.A + (size_t)nxt.pm * tstep : cA; const char* nB = has_next ? (const char*)g.Bt + (size_t)nxt.pn * tstep : cB;
;         for (int t = 0; t < nt; t += 2) {
;             const bool last = (t == nt - 2);
;             const char* a1 = cA + (size_t)(t + 1) * kstep;
;             const char* a2 = last ? nA : cA + (size_t)(t + 2) * kstep; const char* b2 = last ? nB : cB + (size_t)(t + 2) * kstep;
;             const char* a3 = a2 + kstep; const char* b3 = b2 + kstep;
;             if (last && has_next) S.a_ready(nxt);
;             if constexpr (SP2) {
;             PG8_LDB(B0, 0, 0); PG8_LDB(B1, 0, 1); PG8_SCHED; PG8_LDA(At, 0, 0); PG8_STAGE(PG8_SA(1, 1), a1 + hstep, voffA);
;             PG8_WAIT_V(8); PG8_WAIT_L(0); PG8_BAR; PG8_MMA(0, 0, At, B0); PG8_MMA(0, 1, At, B1); PG8_BAR; PG8_SCHED;
;             PG8_LDA(At, 0, 1); PG8_STAGE(PG8_SB(0, 0), b2, voffB); PG8_STAGE(PG8_SB(0, 1), b2 + hstep, voffB); PG8_STAGE(PG8_SA(0, 0), a2, voffA);
.LBB0_1196:
	s_add_u32 s82, s52, 0x100
	s_addc_u32 s83, s53, 0
	s_mov_b32 s84, -2
	s_waitcnt lgkmcnt(0)
	ds_read_b128 v[144:147], v151
	ds_read_b128 v[156:159], v151 offset:1024
	ds_read_b128 v[160:163], v151 offset:2048
	ds_read_b128 v[164:167], v151 offset:3072
	ds_read_b128 v[168:171], v152
	ds_read_b128 v[172:175], v152 offset:1024
	ds_read_b128 v[176:179], v152 offset:2048
	ds_read_b128 v[182:185], v152 offset:3072
	s_add_u32 s52, s50, 0x100
	s_addc_u32 s53, s51, 0
	s_cmp_eq_u32 s84, 40
	s_cselect_b32 s57, s1, s53
	s_cselect_b32 s56, s0, s52
	s_cselect_b32 s55, s49, s83
	s_cselect_b32 s54, s48, s82
	v_lshl_add_u64 v[224:225], s[50:51], 0, v[136:137]
	s_add_i32 m0, s34, 0xc000
	ds_read_b128 v[186:189], v153
	ds_read_b128 v[190:193], v153 offset:1024
	ds_read_b128 v[194:197], v153 offset:2048
	ds_read_b128 v[198:201], v153 offset:3072
	ds_read_b128 v[208:211], v153 offset:4096
	ds_read_b128 v[212:215], v153 offset:5120
	ds_read_b128 v[216:219], v153 offset:6144
	ds_read_b128 v[220:223], v153 offset:7168
	global_load_lds_dwordx4 v[224:225], off
	v_lshl_add_u64 v[224:225], s[50:51], 0, v[138:139]
	s_add_i32 m0, s34, 0xe000
	s_nop 0
	global_load_lds_dwordx4 v[224:225], off
	s_waitcnt vmcnt(8)
	s_waitcnt lgkmcnt(0)
	s_barrier
	s_setprio 1
	s_waitcnt lgkmcnt(0)
	v_mfma_f32_16x16x32_bf16 v[124:127], v[144:147], v[186:189], 0
	v_mfma_f32_16x16x32_bf16 v[120:123], v[160:163], v[186:189], 0
	v_mfma_f32_16x16x32_bf16 v[108:111], v[144:147], v[194:197], 0
	v_mfma_f32_16x16x32_bf16 v[104:107], v[160:163], v[194:197], 0
	v_mfma_f32_16x16x32_bf16 v[92:95], v[144:147], v[208:211], 0
	v_mfma_f32_16x16x32_bf16 v[88:91], v[160:163], v[208:211], 0
	v_mfma_f32_16x16x32_bf16 v[76:79], v[144:147], v[216:219], 0
	v_mfma_f32_16x16x32_bf16 v[72:75], v[160:163], v[216:219], 0
	v_mfma_f32_16x16x32_bf16 v[124:127], v[156:159], v[190:193], v[124:127]
	v_mfma_f32_16x16x32_bf16 v[120:123], v[164:167], v[190:193], v[120:123]
	v_mfma_f32_16x16x32_bf16 v[108:111], v[156:159], v[198:201], v[108:111]
	v_mfma_f32_16x16x32_bf16 v[104:107], v[164:167], v[198:201], v[104:107]
	v_mfma_f32_16x16x32_bf16 v[92:95], v[156:159], v[212:215], v[92:95]
	v_mfma_f32_16x16x32_bf16 v[88:91], v[164:167], v[212:215], v[88:91]
	v_mfma_f32_16x16x32_bf16 v[76:79], v[156:159], v[220:223], v[76:79]
	v_mfma_f32_16x16x32_bf16 v[72:75], v[164:167], v[220:223], v[72:75]
	s_setprio 0
	s_setprio 1
	v_mfma_f32_16x16x32_bf16 v[116:119], v[168:171], v[186:189], 0
	v_mfma_f32_16x16x32_bf16 v[112:115], v[176:179], v[186:189], 0
	v_mfma_f32_16x16x32_bf16 v[100:103], v[168:171], v[194:197], 0
	v_mfma_f32_16x16x32_bf16 v[96:99], v[176:179], v[194:197], 0
	v_mfma_f32_16x16x32_bf16 v[84:87], v[168:171], v[208:211], 0
	v_mfma_f32_16x16x32_bf16 v[80:83], v[176:179], v[208:211], 0
	v_mfma_f32_16x16x32_bf16 v[68:71], v[168:171], v[216:219], 0
	v_mfma_f32_16x16x32_bf16 v[64:67], v[176:179], v[216:219], 0
	v_mfma_f32_16x16x32_bf16 v[116:119], v[172:175], v[190:193], v[116:119]
	v_mfma_f32_16x16x32_bf16 v[112:115], v[182:185], v[190:193], v[112:115]
	v_mfma_f32_16x16x32_bf16 v[100:103], v[172:175], v[198:201], v[100:103]
	v_mfma_f32_16x16x32_bf16 v[96:99], v[182:185], v[198:201], v[96:99]
	v_mfma_f32_16x16x32_bf16 v[84:87], v[172:175], v[212:215], v[84:87]
	v_mfma_f32_16x16x32_bf16 v[80:83], v[182:185], v[212:215], v[80:83]
	v_mfma_f32_16x16x32_bf16 v[68:71], v[172:175], v[220:223], v[68:71]
	v_mfma_f32_16x16x32_bf16 v[64:67], v[182:185], v[220:223], v[64:67]
	s_setprio 0
	s_barrier
	s_add_i32 s50, s64, s33
	v_lshl_add_u64 v[224:225], s[54:55], 0, v[130:131]
	s_mov_b32 m0, s50
	ds_read_b128 v[186:189], v153 offset:16384
	ds_read_b128 v[190:193], v153 offset:17408
	ds_read_b128 v[194:197], v153 offset:18432
	ds_read_b128 v[198:201], v153 offset:19456
	ds_read_b128 v[208:211], v153 offset:20480
	ds_read_b128 v[212:215], v153 offset:21504
	ds_read_b128 v[216:219], v153 offset:22528
	ds_read_b128 v[220:223], v153 offset:23552
	global_load_lds_dwordx4 v[224:225], off
	s_add_i32 m0, s50, 0x2000
	s_add_u32 s50, s54, 0xb0000
	v_lshl_add_u64 v[226:227], s[54:55], 0, v[134:135]
	s_addc_u32 s51, s55, 0
	s_add_i32 s78, s65, s33
	global_load_lds_dwordx4 v[226:227], off
	v_lshl_add_u64 v[228:229], s[50:51], 0, v[130:131]
	s_mov_b32 m0, s78
	global_load_lds_dwordx4 v[228:229], off
	v_lshl_add_u64 v[228:229], s[50:51], 0, v[134:135]
	s_add_i32 m0, s78, 0x2000
	s_nop 0
	global_load_lds_dwordx4 v[228:229], off
	v_lshl_add_u64 v[228:229], s[56:57], 0, v[128:129]
	s_mov_b32 m0, s34
	s_nop 0
	global_load_lds_dwordx4 v[228:229], off
	v_lshl_add_u64 v[230:231], s[56:57], 0, v[132:133]
	s_mov_b32 m0, s58
	s_nop 0
	global_load_lds_dwordx4 v[230:231], off
	s_waitcnt vmcnt(8)
	s_waitcnt lgkmcnt(0)
	s_barrier
; #define PG8_STAGE(bufoff, gbase, voff) do { _Pragma("unroll") for (int _i = 0; _i < 2; ++_i) \
;         __builtin_amdgcn_global_load_lds((const unsigned*)((const char*)(gbase) + (voff)[_i]), (PG8_LAS unsigned*)(lds + (bufoff) + ldsw + _i * 8192), 16, 0, 0); } while (0)
; #define PG8_LDA(dst, b, h) do { _Pragma("unroll") for (int m = 0; m < 4; ++m) _Pragma("unroll") for (int k = 0; k < 2; ++k) dst[m][k] = *(const PG8_LAS bf16x8*)(lds + PG8_SA(b, h) + aoff + m * 2048 + k * 1024); } while (0)
; #define PG8_LDB(dst, b, h) do { _Pragma("unroll") for (int n = 0; n < 2; ++n) _Pragma("unroll") for (int k = 0; k < 2; ++k) dst[n][k] = *(const PG8_LAS bf16x8*)(lds + PG8_SB(b, h) + boff + n * 2048 + k * 1024); } while (0)
; #define PG8_MMA(ai, bj, At, Bt) do { __builtin_amdgcn_s_setprio(1); _Pragma("unroll") for (int m = 0; m < 4; ++m) _Pragma("unroll") for (int n = 0; n < 2; ++n) _Pragma("unroll") for (int k = 0; k < 2; ++k) \
;         acc[ai][bj][m][n] = __builtin_amdgcn_mfma_f32_16x16x32_bf16(Bt[n][k], At[m][k], acc[ai][bj][m][n], 0, 0, 0); __builtin_amdgcn_s_setprio(0); } while (0)
; #define PG8_WAIT_V(n) asm volatile("s_waitcnt vmcnt(" #n ")" ::: "memory")
; #define PG8_WAIT_L(n) asm volatile("s_waitcnt lgkmcnt(" #n ")" ::: "memory")
; #define PG8_BAR __builtin_amdgcn_s_barrier()
; #define PG8_SCHED __builtin_amdgcn_sched_barrier(0)
; template <class Epi, class Sched, bool ALIGN_EPI = false, bool SP2 = false>
; __device__ __forceinline__ void gemm_phase(PG8_LAS unsigned char* lds, const Gemm g, const Sched& S, const Epi& E) {
;     ...
;             PG8_WAIT_V(8); PG8_WAIT_L(0); PG8_BAR; PG8_MMA(1, 0, At, B0); PG8_MMA(1, 1, At, B1); PG8_BAR; PG8_SCHED;
;             PG8_LDB(B0, 1, 0); PG8_LDB(B1, 1, 1); PG8_SCHED; PG8_LDA(At, 1, 0); PG8_STAGE(PG8_SA(0, 1), a2 + hstep, voffA);
;             PG8_WAIT_V(8); PG8_WAIT_L(0); PG8_BAR; PG8_MMA(0, 0, At, B0); PG8_MMA(0, 1, At, B1); PG8_BAR; PG8_SCHED;
	s_setprio 1
	s_waitcnt lgkmcnt(0)
	v_mfma_f32_16x16x32_bf16 v[60:63], v[144:147], v[186:189], 0
	v_mfma_f32_16x16x32_bf16 v[56:59], v[160:163], v[186:189], 0
	v_mfma_f32_16x16x32_bf16 v[44:47], v[144:147], v[194:197], 0
	v_mfma_f32_16x16x32_bf16 v[40:43], v[160:163], v[194:197], 0
	v_mfma_f32_16x16x32_bf16 v[28:31], v[144:147], v[208:211], 0
	v_mfma_f32_16x16x32_bf16 v[24:27], v[160:163], v[208:211], 0
	v_mfma_f32_16x16x32_bf16 v[12:15], v[144:147], v[216:219], 0
	v_mfma_f32_16x16x32_bf16 v[8:11], v[160:163], v[216:219], 0
	v_mfma_f32_16x16x32_bf16 v[60:63], v[156:159], v[190:193], v[60:63]
	v_mfma_f32_16x16x32_bf16 v[56:59], v[164:167], v[190:193], v[56:59]
	v_mfma_f32_16x16x32_bf16 v[44:47], v[156:159], v[198:201], v[44:47]
	v_mfma_f32_16x16x32_bf16 v[40:43], v[164:167], v[198:201], v[40:43]
	v_mfma_f32_16x16x32_bf16 v[28:31], v[156:159], v[212:215], v[28:31]
	v_mfma_f32_16x16x32_bf16 v[24:27], v[164:167], v[212:215], v[24:27]
	v_mfma_f32_16x16x32_bf16 v[12:15], v[156:159], v[220:223], v[12:15]
	v_mfma_f32_16x16x32_bf16 v[8:11], v[164:167], v[220:223], v[8:11]
	s_setprio 0
	s_setprio 1
	v_mfma_f32_16x16x32_bf16 v[52:55], v[168:171], v[186:189], 0
	v_mfma_f32_16x16x32_bf16 v[48:51], v[176:179], v[186:189], 0
	v_mfma_f32_16x16x32_bf16 v[36:39], v[168:171], v[194:197], 0
	v_mfma_f32_16x16x32_bf16 v[32:35], v[176:179], v[194:197], 0
	v_mfma_f32_16x16x32_bf16 v[20:23], v[168:171], v[208:211], 0
	v_mfma_f32_16x16x32_bf16 v[16:19], v[176:179], v[208:211], 0
	v_mfma_f32_16x16x32_bf16 v[4:7], v[168:171], v[216:219], 0
	v_mfma_f32_16x16x32_bf16 v[0:3], v[176:179], v[216:219], 0
	v_mfma_f32_16x16x32_bf16 v[52:55], v[172:175], v[190:193], v[52:55]
	v_mfma_f32_16x16x32_bf16 v[48:51], v[182:185], v[190:193], v[48:51]
	v_mfma_f32_16x16x32_bf16 v[36:39], v[172:175], v[198:201], v[36:39]
	v_mfma_f32_16x16x32_bf16 v[32:35], v[182:185], v[198:201], v[32:35]
	v_mfma_f32_16x16x32_bf16 v[20:23], v[172:175], v[212:215], v[20:23]
	v_mfma_f32_16x16x32_bf16 v[16:19], v[182:185], v[212:215], v[16:19]
	v_mfma_f32_16x16x32_bf16 v[4:7], v[172:175], v[220:223], v[4:7]
	v_mfma_f32_16x16x32_bf16 v[0:3], v[182:185], v[220:223], v[0:3]
	s_setprio 0
	s_barrier
	s_add_i32 s78, 0, 0x18000
	v_add_u32_e32 v155, s78, v149
	s_add_i32 s79, 0, 0x1c000
	ds_read_b128 v[144:147], v155
	ds_read_b128 v[156:159], v155 offset:1024
	ds_read_b128 v[160:163], v155 offset:2048
	ds_read_b128 v[164:167], v155 offset:3072
	v_add_u32_e32 v155, s79, v149
	ds_read_b128 v[168:171], v155
	ds_read_b128 v[172:175], v155 offset:1024
	ds_read_b128 v[176:179], v155 offset:2048
	ds_read_b128 v[182:185], v155 offset:3072
	s_add_u32 s50, s56, 0xb0000
	s_addc_u32 s51, s57, 0
	s_mov_b32 m0, s59
	v_lshl_add_u64 v[232:233], s[50:51], 0, v[128:129]
	ds_read_b128 v[186:189], v153 offset:32768
	ds_read_b128 v[190:193], v153 offset:33792
	ds_read_b128 v[194:197], v153 offset:34816
	ds_read_b128 v[198:201], v153 offset:35840
	ds_read_b128 v[208:211], v153 offset:36864
	ds_read_b128 v[212:215], v153 offset:37888
	ds_read_b128 v[216:219], v153 offset:38912
	ds_read_b128 v[220:223], v153 offset:39936
	global_load_lds_dwordx4 v[232:233], off
	v_lshl_add_u64 v[232:233], s[50:51], 0, v[132:133]
	s_mov_b32 m0, s60
	s_nop 0
	global_load_lds_dwordx4 v[232:233], off
	s_waitcnt vmcnt(8)
	s_waitcnt lgkmcnt(0)
	s_barrier
	s_setprio 1
	s_waitcnt lgkmcnt(0)
	v_mfma_f32_16x16x32_bf16 v[124:127], v[144:147], v[186:189], v[124:127]
	v_mfma_f32_16x16x32_bf16 v[120:123], v[160:163], v[186:189], v[120:123]
	v_mfma_f32_16x16x32_bf16 v[108:111], v[144:147], v[194:197], v[108:111]
	v_mfma_f32_16x16x32_bf16 v[104:107], v[160:163], v[194:197], v[104:107]
	v_mfma_f32_16x16x32_bf16 v[92:95], v[144:147], v[208:211], v[92:95]
	v_mfma_f32_16x16x32_bf16 v[88:91], v[160:163], v[208:211], v[88:91]
	v_mfma_f32_16x16x32_bf16 v[76:79], v[144:147], v[216:219], v[76:79]
	v_mfma_f32_16x16x32_bf16 v[72:75], v[160:163], v[216:219], v[72:75]
	v_mfma_f32_16x16x32_bf16 v[124:127], v[156:159], v[190:193], v[124:127]
	v_mfma_f32_16x16x32_bf16 v[120:123], v[164:167], v[190:193], v[120:123]
	v_mfma_f32_16x16x32_bf16 v[108:111], v[156:159], v[198:201], v[108:111]
	v_mfma_f32_16x16x32_bf16 v[104:107], v[164:167], v[198:201], v[104:107]
	v_mfma_f32_16x16x32_bf16 v[92:95], v[156:159], v[212:215], v[92:95]
	v_mfma_f32_16x16x32_bf16 v[88:91], v[164:167], v[212:215], v[88:91]
	v_mfma_f32_16x16x32_bf16 v[76:79], v[156:159], v[220:223], v[76:79]
	v_mfma_f32_16x16x32_bf16 v[72:75], v[164:167], v[220:223], v[72:75]
	s_setprio 0
	s_setprio 1
	v_mfma_f32_16x16x32_bf16 v[116:119], v[168:171], v[186:189], v[116:119]
	v_mfma_f32_16x16x32_bf16 v[112:115], v[176:179], v[186:189], v[112:115]
	v_mfma_f32_16x16x32_bf16 v[100:103], v[168:171], v[194:197], v[100:103]
	v_mfma_f32_16x16x32_bf16 v[96:99], v[176:179], v[194:197], v[96:99]
	v_mfma_f32_16x16x32_bf16 v[84:87], v[168:171], v[208:211], v[84:87]
	v_mfma_f32_16x16x32_bf16 v[80:83], v[176:179], v[208:211], v[80:83]
	v_mfma_f32_16x16x32_bf16 v[68:71], v[168:171], v[216:219], v[68:71]
	v_mfma_f32_16x16x32_bf16 v[64:67], v[176:179], v[216:219], v[64:67]
	v_mfma_f32_16x16x32_bf16 v[116:119], v[172:175], v[190:193], v[116:119]
	v_mfma_f32_16x16x32_bf16 v[112:115], v[182:185], v[190:193], v[112:115]
	v_mfma_f32_16x16x32_bf16 v[100:103], v[172:175], v[198:201], v[100:103]
	v_mfma_f32_16x16x32_bf16 v[96:99], v[182:185], v[198:201], v[96:99]
	v_mfma_f32_16x16x32_bf16 v[84:87], v[172:175], v[212:215], v[84:87]
	v_mfma_f32_16x16x32_bf16 v[80:83], v[182:185], v[212:215], v[80:83]
	v_mfma_f32_16x16x32_bf16 v[68:71], v[172:175], v[220:223], v[68:71]
	v_mfma_f32_16x16x32_bf16 v[64:67], v[182:185], v[220:223], v[64:67]
	s_setprio 0
	s_barrier
; #define PG8_STAGE(bufoff, gbase, voff) do { _Pragma("unroll") for (int _i = 0; _i < 2; ++_i) \
;         __builtin_amdgcn_global_load_lds((const unsigned*)((const char*)(gbase) + (voff)[_i]), (PG8_LAS unsigned*)(lds + (bufoff) + ldsw + _i * 8192), 16, 0, 0); } while (0)
; #define PG8_LDA(dst, b, h) do { _Pragma("unroll") for (int m = 0; m < 4; ++m) _Pragma("unroll") for (int k = 0; k < 2; ++k) dst[m][k] = *(const PG8_LAS bf16x8*)(lds + PG8_SA(b, h) + aoff + m * 2048 + k * 1024); } while (0)
; #define PG8_LDB(dst, b, h) do { _Pragma("unroll") for (int n = 0; n < 2; ++n) _Pragma("unroll") for (int k = 0; k < 2; ++k) dst[n][k] = *(const PG8_LAS bf16x8*)(lds + PG8_SB(b, h) + boff + n * 2048 + k * 1024); } while (0)
; #define PG8_MMA(ai, bj, At, Bt) do { __builtin_amdgcn_s_setprio(1); _Pragma("unroll") for (int m = 0; m < 4; ++m) _Pragma("unroll") for (int n = 0; n < 2; ++n) _Pragma("unroll") for (int k = 0; k < 2; ++k) \
;         acc[ai][bj][m][n] = __builtin_amdgcn_mfma_f32_16x16x32_bf16(Bt[n][k], At[m][k], acc[ai][bj][m][n], 0, 0, 0); __builtin_amdgcn_s_setprio(0); } while (0)
; #define PG8_WAIT_V(n) asm volatile("s_waitcnt vmcnt(" #n ")" ::: "memory")
; #define PG8_WAIT_L(n) asm volatile("s_waitcnt lgkmcnt(" #n ")" ::: "memory")
; #define PG8_BAR __builtin_amdgcn_s_barrier()
; #define PG8_SCHED __builtin_amdgcn_sched_barrier(0)
; template <class Epi, class Sched, bool ALIGN_EPI = false, bool SP2 = false>
; __device__ __forceinline__ void gemm_phase(PG8_LAS unsigned char* lds, const Gemm g, const Sched& S, const Epi& E) {
;     ...
;             PG8_LDB(B0, 0, 0); PG8_LDB(B1, 0, 1); PG8_SCHED; PG8_LDA(At, 0, 0); PG8_STAGE(PG8_SA(1, 1), a1 + hstep, voffA);
;             PG8_WAIT_V(8); PG8_WAIT_L(0); PG8_BAR; PG8_MMA(0, 0, At, B0); PG8_MMA(0, 1, At, B1); PG8_BAR; PG8_SCHED;
;     ...
;             PG8_LDA(At, 1, 1); PG8_STAGE(PG8_SB(1, 0), b3, voffB); PG8_STAGE(PG8_SB(1, 1), b3 + hstep, voffB); PG8_STAGE(PG8_SA(1, 0), a3, voffA);
;             PG8_WAIT_V(8); PG8_WAIT_L(0); PG8_BAR; PG8_MMA(1, 0, At, B0); PG8_MMA(1, 1, At, B1); PG8_BAR; PG8_SCHED;
	s_add_i32 s50, s78, s33
	v_lshl_add_u64 v[224:225], v[224:225], 0, s[42:43]
	s_mov_b32 m0, s50
	ds_read_b128 v[186:189], v153 offset:49152
	ds_read_b128 v[190:193], v153 offset:50176
	ds_read_b128 v[194:197], v153 offset:51200
	ds_read_b128 v[198:201], v153 offset:52224
	ds_read_b128 v[208:211], v153 offset:53248
	ds_read_b128 v[212:215], v153 offset:54272
	ds_read_b128 v[216:219], v153 offset:55296
	ds_read_b128 v[220:223], v153 offset:56320
	global_load_lds_dwordx4 v[224:225], off
	s_add_i32 m0, s50, 0x2000
	s_add_u32 s50, s54, 0xb0080
	v_lshl_add_u64 v[224:225], v[226:227], 0, s[42:43]
	s_addc_u32 s51, s55, 0
	s_add_i32 s54, s79, s33
	global_load_lds_dwordx4 v[224:225], off
	v_lshl_add_u64 v[224:225], s[50:51], 0, v[130:131]
	s_mov_b32 m0, s54
	s_nop 0
	global_load_lds_dwordx4 v[224:225], off
	v_lshl_add_u64 v[224:225], s[50:51], 0, v[134:135]
	s_add_i32 m0, s54, 0x2000
	s_nop 0
	global_load_lds_dwordx4 v[224:225], off
	v_lshl_add_u64 v[224:225], v[228:229], 0, s[42:43]
	s_mov_b32 m0, s62
	s_nop 0
	global_load_lds_dwordx4 v[224:225], off
	v_lshl_add_u64 v[224:225], v[230:231], 0, s[42:43]
	s_mov_b32 m0, s63
	s_nop 0
	global_load_lds_dwordx4 v[224:225], off
	s_waitcnt vmcnt(8)
	s_waitcnt lgkmcnt(0)
	s_barrier
	s_setprio 1
	s_waitcnt lgkmcnt(0)
	v_mfma_f32_16x16x32_bf16 v[60:63], v[144:147], v[186:189], v[60:63]
	v_mfma_f32_16x16x32_bf16 v[56:59], v[160:163], v[186:189], v[56:59]
	v_mfma_f32_16x16x32_bf16 v[44:47], v[144:147], v[194:197], v[44:47]
	v_mfma_f32_16x16x32_bf16 v[40:43], v[160:163], v[194:197], v[40:43]
	v_mfma_f32_16x16x32_bf16 v[28:31], v[144:147], v[208:211], v[28:31]
	v_mfma_f32_16x16x32_bf16 v[24:27], v[160:163], v[208:211], v[24:27]
	v_mfma_f32_16x16x32_bf16 v[12:15], v[144:147], v[216:219], v[12:15]
	v_mfma_f32_16x16x32_bf16 v[8:11], v[160:163], v[216:219], v[8:11]
	v_mfma_f32_16x16x32_bf16 v[60:63], v[156:159], v[190:193], v[60:63]
	v_mfma_f32_16x16x32_bf16 v[56:59], v[164:167], v[190:193], v[56:59]
	v_mfma_f32_16x16x32_bf16 v[44:47], v[156:159], v[198:201], v[44:47]
	v_mfma_f32_16x16x32_bf16 v[40:43], v[164:167], v[198:201], v[40:43]
	v_mfma_f32_16x16x32_bf16 v[28:31], v[156:159], v[212:215], v[28:31]
	v_mfma_f32_16x16x32_bf16 v[24:27], v[164:167], v[212:215], v[24:27]
	v_mfma_f32_16x16x32_bf16 v[12:15], v[156:159], v[220:223], v[12:15]
	v_mfma_f32_16x16x32_bf16 v[8:11], v[164:167], v[220:223], v[8:11]
	s_setprio 0
	s_setprio 1
	v_mfma_f32_16x16x32_bf16 v[52:55], v[168:171], v[186:189], v[52:55]
	v_mfma_f32_16x16x32_bf16 v[48:51], v[176:179], v[186:189], v[48:51]
	v_mfma_f32_16x16x32_bf16 v[36:39], v[168:171], v[194:197], v[36:39]
	v_mfma_f32_16x16x32_bf16 v[32:35], v[176:179], v[194:197], v[32:35]
	v_mfma_f32_16x16x32_bf16 v[20:23], v[168:171], v[208:211], v[20:23]
	v_mfma_f32_16x16x32_bf16 v[16:19], v[176:179], v[208:211], v[16:19]
	v_mfma_f32_16x16x32_bf16 v[4:7], v[168:171], v[216:219], v[4:7]
	v_mfma_f32_16x16x32_bf16 v[0:3], v[176:179], v[216:219], v[0:3]
	v_mfma_f32_16x16x32_bf16 v[52:55], v[172:175], v[190:193], v[52:55]
	v_mfma_f32_16x16x32_bf16 v[48:51], v[182:185], v[190:193], v[48:51]
	v_mfma_f32_16x16x32_bf16 v[36:39], v[172:175], v[198:201], v[36:39]
	v_mfma_f32_16x16x32_bf16 v[32:35], v[182:185], v[198:201], v[32:35]
	v_mfma_f32_16x16x32_bf16 v[20:23], v[172:175], v[212:215], v[20:23]
	v_mfma_f32_16x16x32_bf16 v[16:19], v[182:185], v[212:215], v[16:19]
	v_mfma_f32_16x16x32_bf16 v[4:7], v[172:175], v[220:223], v[4:7]
	v_mfma_f32_16x16x32_bf16 v[0:3], v[182:185], v[220:223], v[0:3]
	s_setprio 0
	s_barrier
	s_add_i32 s84, s84, 2
	s_add_u32 s82, s82, 0x100
	s_addc_u32 s83, s83, 0
	s_mov_b64 s[50:51], s[52:53]
.LBB0_1197:
	ds_read_b128 v[144:147], v151
	ds_read_b128 v[156:159], v151 offset:1024
	ds_read_b128 v[160:163], v151 offset:2048
	ds_read_b128 v[164:167], v151 offset:3072
	ds_read_b128 v[168:171], v152
	ds_read_b128 v[172:175], v152 offset:1024
	ds_read_b128 v[176:179], v152 offset:2048
	ds_read_b128 v[182:185], v152 offset:3072
	s_add_u32 s52, s50, 0x100
	s_addc_u32 s53, s51, 0
	s_cmp_eq_u32 s84, 40
	s_cselect_b32 s57, s1, s53
	s_cselect_b32 s56, s0, s52
	s_cselect_b32 s55, s49, s83
	s_cselect_b32 s54, s48, s82
	v_lshl_add_u64 v[224:225], s[50:51], 0, v[136:137]
	s_add_i32 m0, s34, 0xc000
	ds_read_b128 v[186:189], v153
	ds_read_b128 v[190:193], v153 offset:1024
	ds_read_b128 v[194:197], v153 offset:2048
	ds_read_b128 v[198:201], v153 offset:3072
	ds_read_b128 v[208:211], v153 offset:4096
	ds_read_b128 v[212:215], v153 offset:5120
	ds_read_b128 v[216:219], v153 offset:6144
	ds_read_b128 v[220:223], v153 offset:7168
	global_load_lds_dwordx4 v[224:225], off
	v_lshl_add_u64 v[224:225], s[50:51], 0, v[138:139]
	s_add_i32 m0, s34, 0xe000
	s_nop 0
	global_load_lds_dwordx4 v[224:225], off
	s_waitcnt vmcnt(8)
	s_waitcnt lgkmcnt(0)
	s_barrier
; #define PG8_STAGE(bufoff, gbase, voff) do { _Pragma("unroll") for (int _i = 0; _i < 2; ++_i) \
;         __builtin_amdgcn_global_load_lds((const unsigned*)((const char*)(gbase) + (voff)[_i]), (PG8_LAS unsigned*)(lds + (bufoff) + ldsw + _i * 8192), 16, 0, 0); } while (0)
; #define PG8_LDA(dst, b, h) do { _Pragma("unroll") for (int m = 0; m < 4; ++m) _Pragma("unroll") for (int k = 0; k < 2; ++k) dst[m][k] = *(const PG8_LAS bf16x8*)(lds + PG8_SA(b, h) + aoff + m * 2048 + k * 1024); } while (0)
; #define PG8_MMA(ai, bj, At, Bt) do { __builtin_amdgcn_s_setprio(1); _Pragma("unroll") for (int m = 0; m < 4; ++m) _Pragma("unroll") for (int n = 0; n < 2; ++n) _Pragma("unroll") for (int k = 0; k < 2; ++k) \
;         acc[ai][bj][m][n] = __builtin_amdgcn_mfma_f32_16x16x32_bf16(Bt[n][k], At[m][k], acc[ai][bj][m][n], 0, 0, 0); __builtin_amdgcn_s_setprio(0); } while (0)
; #define PG8_WAIT_V(n) asm volatile("s_waitcnt vmcnt(" #n ")" ::: "memory")
; #define PG8_WAIT_L(n) asm volatile("s_waitcnt lgkmcnt(" #n ")" ::: "memory")
; #define PG8_BAR __builtin_amdgcn_s_barrier()
; #define PG8_SCHED __builtin_amdgcn_sched_barrier(0)
; template <class Epi, class Sched, bool ALIGN_EPI = false, bool SP2 = false>
; __device__ __forceinline__ void gemm_phase(PG8_LAS unsigned char* lds, const Gemm g, const Sched& S, const Epi& E) {
;     ...
;             PG8_WAIT_V(8); PG8_WAIT_L(0); PG8_BAR; PG8_MMA(0, 0, At, B0); PG8_MMA(0, 1, At, B1); PG8_BAR; PG8_SCHED;
;             PG8_LDA(At, 0, 1); PG8_STAGE(PG8_SB(0, 0), b2, voffB); PG8_STAGE(PG8_SB(0, 1), b2 + hstep, voffB); PG8_STAGE(PG8_SA(0, 0), a2, voffA);
;             PG8_WAIT_V(8); PG8_WAIT_L(0); PG8_BAR; PG8_MMA(1, 0, At, B0); PG8_MMA(1, 1, At, B1); PG8_BAR; PG8_SCHED;
	s_setprio 1
	s_waitcnt lgkmcnt(0)
	v_mfma_f32_16x16x32_bf16 v[124:127], v[144:147], v[186:189], v[124:127]
	v_mfma_f32_16x16x32_bf16 v[120:123], v[160:163], v[186:189], v[120:123]
	v_mfma_f32_16x16x32_bf16 v[108:111], v[144:147], v[194:197], v[108:111]
	v_mfma_f32_16x16x32_bf16 v[104:107], v[160:163], v[194:197], v[104:107]
	v_mfma_f32_16x16x32_bf16 v[92:95], v[144:147], v[208:211], v[92:95]
	v_mfma_f32_16x16x32_bf16 v[88:91], v[160:163], v[208:211], v[88:91]
	v_mfma_f32_16x16x32_bf16 v[76:79], v[144:147], v[216:219], v[76:79]
	v_mfma_f32_16x16x32_bf16 v[72:75], v[160:163], v[216:219], v[72:75]
	v_mfma_f32_16x16x32_bf16 v[124:127], v[156:159], v[190:193], v[124:127]
	v_mfma_f32_16x16x32_bf16 v[120:123], v[164:167], v[190:193], v[120:123]
	v_mfma_f32_16x16x32_bf16 v[108:111], v[156:159], v[198:201], v[108:111]
	v_mfma_f32_16x16x32_bf16 v[104:107], v[164:167], v[198:201], v[104:107]
	v_mfma_f32_16x16x32_bf16 v[92:95], v[156:159], v[212:215], v[92:95]
	v_mfma_f32_16x16x32_bf16 v[88:91], v[164:167], v[212:215], v[88:91]
	v_mfma_f32_16x16x32_bf16 v[76:79], v[156:159], v[220:223], v[76:79]
	v_mfma_f32_16x16x32_bf16 v[72:75], v[164:167], v[220:223], v[72:75]
	s_setprio 0
	s_setprio 1
	v_mfma_f32_16x16x32_bf16 v[116:119], v[168:171], v[186:189], v[116:119]
	v_mfma_f32_16x16x32_bf16 v[112:115], v[176:179], v[186:189], v[112:115]
	v_mfma_f32_16x16x32_bf16 v[100:103], v[168:171], v[194:197], v[100:103]
	v_mfma_f32_16x16x32_bf16 v[96:99], v[176:179], v[194:197], v[96:99]
	v_mfma_f32_16x16x32_bf16 v[84:87], v[168:171], v[208:211], v[84:87]
	v_mfma_f32_16x16x32_bf16 v[80:83], v[176:179], v[208:211], v[80:83]
	v_mfma_f32_16x16x32_bf16 v[68:71], v[168:171], v[216:219], v[68:71]
	v_mfma_f32_16x16x32_bf16 v[64:67], v[176:179], v[216:219], v[64:67]
	v_mfma_f32_16x16x32_bf16 v[116:119], v[172:175], v[190:193], v[116:119]
	v_mfma_f32_16x16x32_bf16 v[112:115], v[182:185], v[190:193], v[112:115]
	v_mfma_f32_16x16x32_bf16 v[100:103], v[172:175], v[198:201], v[100:103]
	v_mfma_f32_16x16x32_bf16 v[96:99], v[182:185], v[198:201], v[96:99]
	v_mfma_f32_16x16x32_bf16 v[84:87], v[172:175], v[212:215], v[84:87]
	v_mfma_f32_16x16x32_bf16 v[80:83], v[182:185], v[212:215], v[80:83]
	v_mfma_f32_16x16x32_bf16 v[68:71], v[172:175], v[220:223], v[68:71]
	v_mfma_f32_16x16x32_bf16 v[64:67], v[182:185], v[220:223], v[64:67]
	s_setprio 0
	s_barrier
	s_add_i32 s50, s64, s33
	v_lshl_add_u64 v[224:225], s[54:55], 0, v[130:131]
	s_mov_b32 m0, s50
	ds_read_b128 v[186:189], v153 offset:16384
	ds_read_b128 v[190:193], v153 offset:17408
	ds_read_b128 v[194:197], v153 offset:18432
	ds_read_b128 v[198:201], v153 offset:19456
	ds_read_b128 v[208:211], v153 offset:20480
	ds_read_b128 v[212:215], v153 offset:21504
	ds_read_b128 v[216:219], v153 offset:22528
	ds_read_b128 v[220:223], v153 offset:23552
	global_load_lds_dwordx4 v[224:225], off
	s_add_i32 m0, s50, 0x2000
	s_add_u32 s50, s54, 0xb0000
	v_lshl_add_u64 v[226:227], s[54:55], 0, v[134:135]
	s_addc_u32 s51, s55, 0
	s_add_i32 s78, s65, s33
	global_load_lds_dwordx4 v[226:227], off
	v_lshl_add_u64 v[228:229], s[50:51], 0, v[130:131]
	s_mov_b32 m0, s78
	global_load_lds_dwordx4 v[228:229], off
	v_lshl_add_u64 v[228:229], s[50:51], 0, v[134:135]
	s_add_i32 m0, s78, 0x2000
	s_nop 0
	global_load_lds_dwordx4 v[228:229], off
	v_lshl_add_u64 v[228:229], s[56:57], 0, v[128:129]
	s_mov_b32 m0, s34
	s_nop 0
	global_load_lds_dwordx4 v[228:229], off
	v_lshl_add_u64 v[230:231], s[56:57], 0, v[132:133]
	s_mov_b32 m0, s58
	s_nop 0
	global_load_lds_dwordx4 v[230:231], off
	s_waitcnt vmcnt(8)
	s_waitcnt lgkmcnt(0)
	s_barrier
	s_setprio 1
	s_waitcnt lgkmcnt(0)
	v_mfma_f32_16x16x32_bf16 v[60:63], v[144:147], v[186:189], v[60:63]
	v_mfma_f32_16x16x32_bf16 v[56:59], v[160:163], v[186:189], v[56:59]
	v_mfma_f32_16x16x32_bf16 v[44:47], v[144:147], v[194:197], v[44:47]
	v_mfma_f32_16x16x32_bf16 v[40:43], v[160:163], v[194:197], v[40:43]
	v_mfma_f32_16x16x32_bf16 v[28:31], v[144:147], v[208:211], v[28:31]
	v_mfma_f32_16x16x32_bf16 v[24:27], v[160:163], v[208:211], v[24:27]
	v_mfma_f32_16x16x32_bf16 v[12:15], v[144:147], v[216:219], v[12:15]
	v_mfma_f32_16x16x32_bf16 v[8:11], v[160:163], v[216:219], v[8:11]
	v_mfma_f32_16x16x32_bf16 v[60:63], v[156:159], v[190:193], v[60:63]
	v_mfma_f32_16x16x32_bf16 v[56:59], v[164:167], v[190:193], v[56:59]
	v_mfma_f32_16x16x32_bf16 v[44:47], v[156:159], v[198:201], v[44:47]
	v_mfma_f32_16x16x32_bf16 v[40:43], v[164:167], v[198:201], v[40:43]
	v_mfma_f32_16x16x32_bf16 v[28:31], v[156:159], v[212:215], v[28:31]
	v_mfma_f32_16x16x32_bf16 v[24:27], v[164:167], v[212:215], v[24:27]
	v_mfma_f32_16x16x32_bf16 v[12:15], v[156:159], v[220:223], v[12:15]
	v_mfma_f32_16x16x32_bf16 v[8:11], v[164:167], v[220:223], v[8:11]
	s_setprio 0
	s_setprio 1
	v_mfma_f32_16x16x32_bf16 v[52:55], v[168:171], v[186:189], v[52:55]
	v_mfma_f32_16x16x32_bf16 v[48:51], v[176:179], v[186:189], v[48:51]
	v_mfma_f32_16x16x32_bf16 v[36:39], v[168:171], v[194:197], v[36:39]
	v_mfma_f32_16x16x32_bf16 v[32:35], v[176:179], v[194:197], v[32:35]
	v_mfma_f32_16x16x32_bf16 v[20:23], v[168:171], v[208:211], v[20:23]
	v_mfma_f32_16x16x32_bf16 v[16:19], v[176:179], v[208:211], v[16:19]
	v_mfma_f32_16x16x32_bf16 v[4:7], v[168:171], v[216:219], v[4:7]
	v_mfma_f32_16x16x32_bf16 v[0:3], v[176:179], v[216:219], v[0:3]
	v_mfma_f32_16x16x32_bf16 v[52:55], v[172:175], v[190:193], v[52:55]
	v_mfma_f32_16x16x32_bf16 v[48:51], v[182:185], v[190:193], v[48:51]
	v_mfma_f32_16x16x32_bf16 v[36:39], v[172:175], v[198:201], v[36:39]
	v_mfma_f32_16x16x32_bf16 v[32:35], v[182:185], v[198:201], v[32:35]
	v_mfma_f32_16x16x32_bf16 v[20:23], v[172:175], v[212:215], v[20:23]
	v_mfma_f32_16x16x32_bf16 v[16:19], v[182:185], v[212:215], v[16:19]
	v_mfma_f32_16x16x32_bf16 v[4:7], v[172:175], v[220:223], v[4:7]
	v_mfma_f32_16x16x32_bf16 v[0:3], v[182:185], v[220:223], v[0:3]
	s_setprio 0
	s_barrier
; #define PG8_STAGE(bufoff, gbase, voff) do { _Pragma("unroll") for (int _i = 0; _i < 2; ++_i) \
;         __builtin_amdgcn_global_load_lds((const unsigned*)((const char*)(gbase) + (voff)[_i]), (PG8_LAS unsigned*)(lds + (bufoff) + ldsw + _i * 8192), 16, 0, 0); } while (0)
; #define PG8_LDA(dst, b, h) do { _Pragma("unroll") for (int m = 0; m < 4; ++m) _Pragma("unroll") for (int k = 0; k < 2; ++k) dst[m][k] = *(const PG8_LAS bf16x8*)(lds + PG8_SA(b, h) + aoff + m * 2048 + k * 1024); } while (0)
; #define PG8_LDB(dst, b, h) do { _Pragma("unroll") for (int n = 0; n < 2; ++n) _Pragma("unroll") for (int k = 0; k < 2; ++k) dst[n][k] = *(const PG8_LAS bf16x8*)(lds + PG8_SB(b, h) + boff + n * 2048 + k * 1024); } while (0)
; #define PG8_MMA(ai, bj, At, Bt) do { __builtin_amdgcn_s_setprio(1); _Pragma("unroll") for (int m = 0; m < 4; ++m) _Pragma("unroll") for (int n = 0; n < 2; ++n) _Pragma("unroll") for (int k = 0; k < 2; ++k) \
;         acc[ai][bj][m][n] = __builtin_amdgcn_mfma_f32_16x16x32_bf16(Bt[n][k], At[m][k], acc[ai][bj][m][n], 0, 0, 0); __builtin_amdgcn_s_setprio(0); } while (0)
; #define PG8_WAIT_V(n) asm volatile("s_waitcnt vmcnt(" #n ")" ::: "memory")
; #define PG8_WAIT_L(n) asm volatile("s_waitcnt lgkmcnt(" #n ")" ::: "memory")
; #define PG8_BAR __builtin_amdgcn_s_barrier()
; #define PG8_SCHED __builtin_amdgcn_sched_barrier(0)
; template <class Epi, class Sched, bool ALIGN_EPI = false, bool SP2 = false>
; __device__ __forceinline__ void gemm_phase(PG8_LAS unsigned char* lds, const Gemm g, const Sched& S, const Epi& E) {
;     ...
;             PG8_LDB(B0, 1, 0); PG8_LDB(B1, 1, 1); PG8_SCHED; PG8_LDA(At, 1, 0); PG8_STAGE(PG8_SA(0, 1), a2 + hstep, voffA);
;             PG8_WAIT_V(8); PG8_WAIT_L(0); PG8_BAR; PG8_MMA(0, 0, At, B0); PG8_MMA(0, 1, At, B1); PG8_BAR; PG8_SCHED;
	s_add_i32 s78, 0, 0x18000
	v_add_u32_e32 v155, s78, v149
	s_add_i32 s79, 0, 0x1c000
	ds_read_b128 v[144:147], v155
	ds_read_b128 v[156:159], v155 offset:1024
	ds_read_b128 v[160:163], v155 offset:2048
	ds_read_b128 v[164:167], v155 offset:3072
	v_add_u32_e32 v155, s79, v149
	ds_read_b128 v[168:171], v155
	ds_read_b128 v[172:175], v155 offset:1024
	ds_read_b128 v[176:179], v155 offset:2048
	ds_read_b128 v[182:185], v155 offset:3072
	s_add_u32 s50, s56, 0xb0000
	s_addc_u32 s51, s57, 0
	s_mov_b32 m0, s59
	v_lshl_add_u64 v[232:233], s[50:51], 0, v[128:129]
	ds_read_b128 v[186:189], v153 offset:32768
	ds_read_b128 v[190:193], v153 offset:33792
	ds_read_b128 v[194:197], v153 offset:34816
	ds_read_b128 v[198:201], v153 offset:35840
	ds_read_b128 v[208:211], v153 offset:36864
	ds_read_b128 v[212:215], v153 offset:37888
	ds_read_b128 v[216:219], v153 offset:38912
	ds_read_b128 v[220:223], v153 offset:39936
	global_load_lds_dwordx4 v[232:233], off
	v_lshl_add_u64 v[232:233], s[50:51], 0, v[132:133]
	s_mov_b32 m0, s60
	s_nop 0
	global_load_lds_dwordx4 v[232:233], off
	s_waitcnt vmcnt(8)
	s_waitcnt lgkmcnt(0)
	s_barrier
	s_setprio 1
	s_waitcnt lgkmcnt(0)
	v_mfma_f32_16x16x32_bf16 v[124:127], v[144:147], v[186:189], v[124:127]
	v_mfma_f32_16x16x32_bf16 v[120:123], v[160:163], v[186:189], v[120:123]
	v_mfma_f32_16x16x32_bf16 v[108:111], v[144:147], v[194:197], v[108:111]
	v_mfma_f32_16x16x32_bf16 v[104:107], v[160:163], v[194:197], v[104:107]
	v_mfma_f32_16x16x32_bf16 v[92:95], v[144:147], v[208:211], v[92:95]
	v_mfma_f32_16x16x32_bf16 v[88:91], v[160:163], v[208:211], v[88:91]
	v_mfma_f32_16x16x32_bf16 v[76:79], v[144:147], v[216:219], v[76:79]
	v_mfma_f32_16x16x32_bf16 v[72:75], v[160:163], v[216:219], v[72:75]
	v_mfma_f32_16x16x32_bf16 v[124:127], v[156:159], v[190:193], v[124:127]
	v_mfma_f32_16x16x32_bf16 v[120:123], v[164:167], v[190:193], v[120:123]
	v_mfma_f32_16x16x32_bf16 v[108:111], v[156:159], v[198:201], v[108:111]
	v_mfma_f32_16x16x32_bf16 v[104:107], v[164:167], v[198:201], v[104:107]
	v_mfma_f32_16x16x32_bf16 v[92:95], v[156:159], v[212:215], v[92:95]
	v_mfma_f32_16x16x32_bf16 v[88:91], v[164:167], v[212:215], v[88:91]
	v_mfma_f32_16x16x32_bf16 v[76:79], v[156:159], v[220:223], v[76:79]
	v_mfma_f32_16x16x32_bf16 v[72:75], v[164:167], v[220:223], v[72:75]
	s_setprio 0
	s_setprio 1
	v_mfma_f32_16x16x32_bf16 v[116:119], v[168:171], v[186:189], v[116:119]
	v_mfma_f32_16x16x32_bf16 v[112:115], v[176:179], v[186:189], v[112:115]
	v_mfma_f32_16x16x32_bf16 v[100:103], v[168:171], v[194:197], v[100:103]
	v_mfma_f32_16x16x32_bf16 v[96:99], v[176:179], v[194:197], v[96:99]
	v_mfma_f32_16x16x32_bf16 v[84:87], v[168:171], v[208:211], v[84:87]
	v_mfma_f32_16x16x32_bf16 v[80:83], v[176:179], v[208:211], v[80:83]
	v_mfma_f32_16x16x32_bf16 v[68:71], v[168:171], v[216:219], v[68:71]
	v_mfma_f32_16x16x32_bf16 v[64:67], v[176:179], v[216:219], v[64:67]
	v_mfma_f32_16x16x32_bf16 v[116:119], v[172:175], v[190:193], v[116:119]
	v_mfma_f32_16x16x32_bf16 v[112:115], v[182:185], v[190:193], v[112:115]
	v_mfma_f32_16x16x32_bf16 v[100:103], v[172:175], v[198:201], v[100:103]
	v_mfma_f32_16x16x32_bf16 v[96:99], v[182:185], v[198:201], v[96:99]
	v_mfma_f32_16x16x32_bf16 v[84:87], v[172:175], v[212:215], v[84:87]
	v_mfma_f32_16x16x32_bf16 v[80:83], v[182:185], v[212:215], v[80:83]
	v_mfma_f32_16x16x32_bf16 v[68:71], v[172:175], v[220:223], v[68:71]
	v_mfma_f32_16x16x32_bf16 v[64:67], v[182:185], v[220:223], v[64:67]
	s_setprio 0
	s_barrier
; #define PG8_STAGE(bufoff, gbase, voff) do { _Pragma("unroll") for (int _i = 0; _i < 2; ++_i) \
;         __builtin_amdgcn_global_load_lds((const unsigned*)((const char*)(gbase) + (voff)[_i]), (PG8_LAS unsigned*)(lds + (bufoff) + ldsw + _i * 8192), 16, 0, 0); } while (0)
; #define PG8_LDA(dst, b, h) do { _Pragma("unroll") for (int m = 0; m < 4; ++m) _Pragma("unroll") for (int k = 0; k < 2; ++k) dst[m][k] = *(const PG8_LAS bf16x8*)(lds + PG8_SA(b, h) + aoff + m * 2048 + k * 1024); } while (0)
; #define PG8_MMA(ai, bj, At, Bt) do { __builtin_amdgcn_s_setprio(1); _Pragma("unroll") for (int m = 0; m < 4; ++m) _Pragma("unroll") for (int n = 0; n < 2; ++n) _Pragma("unroll") for (int k = 0; k < 2; ++k) \
;         acc[ai][bj][m][n] = __builtin_amdgcn_mfma_f32_16x16x32_bf16(Bt[n][k], At[m][k], acc[ai][bj][m][n], 0, 0, 0); __builtin_amdgcn_s_setprio(0); } while (0)
; #define PG8_WAIT_V(n) asm volatile("s_waitcnt vmcnt(" #n ")" ::: "memory")
; #define PG8_WAIT_L(n) asm volatile("s_waitcnt lgkmcnt(" #n ")" ::: "memory")
; #define PG8_BAR __builtin_amdgcn_s_barrier()
; #define PG8_SCHED __builtin_amdgcn_sched_barrier(0)
; template <class Epi, class Sched, bool ALIGN_EPI = false, bool SP2 = false>
; __device__ __forceinline__ void gemm_phase(PG8_LAS unsigned char* lds, const Gemm g, const Sched& S, const Epi& E) {
;     ...
;             PG8_LDA(At, 1, 1); PG8_STAGE(PG8_SB(1, 0), b3, voffB); PG8_STAGE(PG8_SB(1, 1), b3 + hstep, voffB); PG8_STAGE(PG8_SA(1, 0), a3, voffA);
;             PG8_WAIT_V(8); PG8_WAIT_L(0); PG8_BAR; PG8_MMA(1, 0, At, B0); PG8_MMA(1, 1, At, B1); PG8_BAR; PG8_SCHED;
	s_add_i32 s50, s78, s33
	v_lshl_add_u64 v[224:225], v[224:225], 0, s[42:43]
	s_mov_b32 m0, s50
	ds_read_b128 v[186:189], v153 offset:49152
	ds_read_b128 v[190:193], v153 offset:50176
	ds_read_b128 v[194:197], v153 offset:51200
	ds_read_b128 v[198:201], v153 offset:52224
	ds_read_b128 v[208:211], v153 offset:53248
	ds_read_b128 v[212:215], v153 offset:54272
	ds_read_b128 v[216:219], v153 offset:55296
	ds_read_b128 v[220:223], v153 offset:56320
	global_load_lds_dwordx4 v[224:225], off
	s_add_i32 m0, s50, 0x2000
	s_add_u32 s50, s54, 0xb0080
	v_lshl_add_u64 v[224:225], v[226:227], 0, s[42:43]
	s_addc_u32 s51, s55, 0
	s_add_i32 s54, s79, s33
	global_load_lds_dwordx4 v[224:225], off
	v_lshl_add_u64 v[224:225], s[50:51], 0, v[130:131]
	s_mov_b32 m0, s54
	s_nop 0
	global_load_lds_dwordx4 v[224:225], off
	v_lshl_add_u64 v[224:225], s[50:51], 0, v[134:135]
	s_add_i32 m0, s54, 0x2000
	s_nop 0
	global_load_lds_dwordx4 v[224:225], off
	v_lshl_add_u64 v[224:225], v[228:229], 0, s[42:43]
	s_mov_b32 m0, s62
	s_nop 0
	global_load_lds_dwordx4 v[224:225], off
	v_lshl_add_u64 v[224:225], v[230:231], 0, s[42:43]
	s_mov_b32 m0, s63
	s_nop 0
	global_load_lds_dwordx4 v[224:225], off
	s_waitcnt vmcnt(8)
	s_waitcnt lgkmcnt(0)
	s_barrier
	s_setprio 1
	s_waitcnt lgkmcnt(0)
	v_mfma_f32_16x16x32_bf16 v[60:63], v[144:147], v[186:189], v[60:63]
	v_mfma_f32_16x16x32_bf16 v[56:59], v[160:163], v[186:189], v[56:59]
	v_mfma_f32_16x16x32_bf16 v[44:47], v[144:147], v[194:197], v[44:47]
	v_mfma_f32_16x16x32_bf16 v[40:43], v[160:163], v[194:197], v[40:43]
	v_mfma_f32_16x16x32_bf16 v[28:31], v[144:147], v[208:211], v[28:31]
	v_mfma_f32_16x16x32_bf16 v[24:27], v[160:163], v[208:211], v[24:27]
	v_mfma_f32_16x16x32_bf16 v[12:15], v[144:147], v[216:219], v[12:15]
	v_mfma_f32_16x16x32_bf16 v[8:11], v[160:163], v[216:219], v[8:11]
	v_mfma_f32_16x16x32_bf16 v[60:63], v[156:159], v[190:193], v[60:63]
	v_mfma_f32_16x16x32_bf16 v[56:59], v[164:167], v[190:193], v[56:59]
	v_mfma_f32_16x16x32_bf16 v[44:47], v[156:159], v[198:201], v[44:47]
	v_mfma_f32_16x16x32_bf16 v[40:43], v[164:167], v[198:201], v[40:43]
	v_mfma_f32_16x16x32_bf16 v[28:31], v[156:159], v[212:215], v[28:31]
	v_mfma_f32_16x16x32_bf16 v[24:27], v[164:167], v[212:215], v[24:27]
	v_mfma_f32_16x16x32_bf16 v[12:15], v[156:159], v[220:223], v[12:15]
	v_mfma_f32_16x16x32_bf16 v[8:11], v[164:167], v[220:223], v[8:11]
	s_setprio 0
	s_setprio 1
	v_mfma_f32_16x16x32_bf16 v[52:55], v[168:171], v[186:189], v[52:55]
	v_mfma_f32_16x16x32_bf16 v[48:51], v[176:179], v[186:189], v[48:51]
	v_mfma_f32_16x16x32_bf16 v[36:39], v[168:171], v[194:197], v[36:39]
	v_mfma_f32_16x16x32_bf16 v[32:35], v[176:179], v[194:197], v[32:35]
	v_mfma_f32_16x16x32_bf16 v[20:23], v[168:171], v[208:211], v[20:23]
	v_mfma_f32_16x16x32_bf16 v[16:19], v[176:179], v[208:211], v[16:19]
	v_mfma_f32_16x16x32_bf16 v[4:7], v[168:171], v[216:219], v[4:7]
	v_mfma_f32_16x16x32_bf16 v[0:3], v[176:179], v[216:219], v[0:3]
	v_mfma_f32_16x16x32_bf16 v[52:55], v[172:175], v[190:193], v[52:55]
	v_mfma_f32_16x16x32_bf16 v[48:51], v[182:185], v[190:193], v[48:51]
	v_mfma_f32_16x16x32_bf16 v[36:39], v[172:175], v[198:201], v[36:39]
	v_mfma_f32_16x16x32_bf16 v[32:35], v[182:185], v[198:201], v[32:35]
	v_mfma_f32_16x16x32_bf16 v[20:23], v[172:175], v[212:215], v[20:23]
	v_mfma_f32_16x16x32_bf16 v[16:19], v[182:185], v[212:215], v[16:19]
	v_mfma_f32_16x16x32_bf16 v[4:7], v[172:175], v[220:223], v[4:7]
	v_mfma_f32_16x16x32_bf16 v[0:3], v[182:185], v[220:223], v[0:3]
	s_setprio 0
	s_barrier
	s_add_i32 s84, s84, 2
	s_add_u32 s82, s82, 0x100
	s_addc_u32 s83, s83, 0
	s_cmp_gt_u32 s84, 41
	s_mov_b64 s[50:51], s[52:53]
	s_cbranch_scc0 .LBB0_1197
	s_and_b64 vcc, exec, s[44:45]
	s_cbranch_vccz .LBB0_1200
	s_barrier

; #define PG8_STAGE(bufoff, gbase, voff) do { _Pragma("unroll") for (int _i = 0; _i < 2; ++_i) \
;         __builtin_amdgcn_global_load_lds((const unsigned*)((const char*)(gbase) + (voff)[_i]), (PG8_LAS unsigned*)(lds + (bufoff) + ldsw + _i * 8192), 16, 0, 0); } while (0)
; #define PG8_LDA(dst, b, h) do { _Pragma("unroll") for (int m = 0; m < 4; ++m) _Pragma("unroll") for (int k = 0; k < 2; ++k) dst[m][k] = *(const PG8_LAS bf16x8*)(lds + PG8_SA(b, h) + aoff + m * 2048 + k * 1024); } while (0)
; #define PG8_LDB(dst, b, h) do { _Pragma("unroll") for (int n = 0; n < 2; ++n) _Pragma("unroll") for (int k = 0; k < 2; ++k) dst[n][k] = *(const PG8_LAS bf16x8*)(lds + PG8_SB(b, h) + boff + n * 2048 + k * 1024); } while (0)
; #define PG8_MMA(ai, bj, At, Bt) do { __builtin_amdgcn_s_setprio(1); _Pragma("unroll") for (int m = 0; m < 4; ++m) _Pragma("unroll") for (int n = 0; n < 2; ++n) _Pragma("unroll") for (int k = 0; k < 2; ++k) \
;         acc[ai][bj][m][n] = __builtin_amdgcn_mfma_f32_16x16x32_bf16(Bt[n][k], At[m][k], acc[ai][bj][m][n], 0, 0, 0); __builtin_amdgcn_s_setprio(0); } while (0)
; template <class Epi, class Sched, bool ALIGN_EPI = false, bool SP2 = false>
; __device__ __forceinline__ void gemm_phase(PG8_LAS unsigned char* lds, const Gemm g, const Sched& S, const Epi& E) {
;     ...
;         const bool has_next = S.next(ui + 1, nxt);
;         const char* nA = has_next ? (const char*)g.A + (size_t)nxt.pm * tstep : cA; const char* nB = has_next ? (const char*)g.Bt + (size_t)nxt.pn * tstep : cB;
;         for (int t = 0; t < nt; t += 2) {
;             const bool last = (t == nt - 2);
;             const char* a1 = cA + (size_t)(t + 1) * kstep;
;             const char* a2 = last ? nA : cA + (size_t)(t + 2) * kstep; const char* b2 = last ? nB : cB + (size_t)(t + 2) * kstep;
;             const char* a3 = a2 + kstep; const char* b3 = b2 + kstep;
;     ...
;             PG8_LDB(B0, 0, 0); PG8_LDB(B1, 0, 1); PG8_SCHED; PG8_LDA(At, 0, 0); PG8_STAGE(PG8_SA(1, 1), a1 + hstep, voffA);
;             PG8_WAIT_V(8); PG8_WAIT_L(0); PG8_BAR; PG8_MMA(0, 0, At, B0); PG8_MMA(0, 1, At, B1); PG8_BAR; PG8_SCHED;
;             PG8_LDA(At, 0, 1); PG8_STAGE(PG8_SB(0, 0), b2, voffB); PG8_STAGE(PG8_SB(0, 1), b2 + hstep, voffB); PG8_STAGE(PG8_SA(0, 0), a2, voffA);
;             PG8_WAIT_V(8); PG8_WAIT_L(0); PG8_BAR; PG8_MMA(1, 0, At, B0); PG8_MMA(1, 1, At, B1); PG8_BAR; PG8_SCHED;
.LBB0_1592:
	s_ashr_i32 s39, s38, 31
	s_lshl_b64 s[42:43], s[38:39], 19
	s_add_u32 s42, s40, s42
	s_addc_u32 s43, s41, s43
	s_and_b64 s[44:45], s[10:11], exec
	s_cselect_b32 s39, s43, s51
	s_cselect_b32 s47, s42, s50
	s_ashr_i32 s37, s36, 31
	s_lshl_b64 s[44:45], s[36:37], 19
	v_readlane_b32 s54, v250, 11
	v_readlane_b32 s55, v250, 12
	s_add_u32 s44, s54, s44
	s_addc_u32 s45, s55, s45
	s_and_b64 s[54:55], s[10:11], exec
	s_cselect_b32 s37, s45, s53
	s_cselect_b32 s64, s44, s52
	s_add_u32 s50, s50, 0x40080
	s_addc_u32 s51, s51, 0
	s_add_u32 s65, s52, 0x100
	s_addc_u32 s66, s53, 0
	s_mov_b32 s67, -2
	s_waitcnt lgkmcnt(0)
	ds_read_b128 v[146:149], v152
	ds_read_b128 v[156:159], v152 offset:1024
	ds_read_b128 v[160:163], v152 offset:2048
	ds_read_b128 v[164:167], v152 offset:3072
	ds_read_b128 v[168:171], v153
	ds_read_b128 v[172:175], v153 offset:1024
	ds_read_b128 v[180:183], v153 offset:2048
	ds_read_b128 v[184:187], v153 offset:3072
	s_add_u32 s52, s50, 0xfffc0080
	s_addc_u32 s53, s51, -1
	s_cmp_eq_u32 s67, 12
	s_cselect_b32 s55, s39, s53
	s_cselect_b32 s54, s47, s52
	s_cselect_b32 s53, s37, s66
	s_cselect_b32 s52, s64, s65
	v_lshl_add_u64 v[200:201], s[50:51], 0, v[136:137]
	s_add_i32 m0, s33, 0xc000
	ds_read_b128 v[188:191], v154
	ds_read_b128 v[192:195], v154 offset:1024
	ds_read_b128 v[196:199], v154 offset:2048
	ds_read_b128 v[206:209], v154 offset:3072
	ds_read_b128 v[210:213], v154 offset:4096
	ds_read_b128 v[214:217], v154 offset:5120
	ds_read_b128 v[218:221], v154 offset:6144
	ds_read_b128 v[222:225], v154 offset:7168
	global_load_lds_dwordx4 v[200:201], off
	v_lshl_add_u64 v[200:201], s[50:51], 0, v[138:139]
	s_add_i32 m0, s33, 0xe000
	s_nop 0
	global_load_lds_dwordx4 v[200:201], off
	s_waitcnt vmcnt(8)
	s_waitcnt lgkmcnt(0)
	s_barrier
	s_setprio 1
	s_waitcnt lgkmcnt(0)
	v_mfma_f32_16x16x32_bf16 v[124:127], v[146:149], v[188:191], 0
	v_mfma_f32_16x16x32_bf16 v[120:123], v[160:163], v[188:191], 0
	v_mfma_f32_16x16x32_bf16 v[108:111], v[146:149], v[196:199], 0
	v_mfma_f32_16x16x32_bf16 v[104:107], v[160:163], v[196:199], 0
	v_mfma_f32_16x16x32_bf16 v[92:95], v[146:149], v[210:213], 0
	v_mfma_f32_16x16x32_bf16 v[88:91], v[160:163], v[210:213], 0
	v_mfma_f32_16x16x32_bf16 v[76:79], v[146:149], v[218:221], 0
	v_mfma_f32_16x16x32_bf16 v[72:75], v[160:163], v[218:221], 0
	v_mfma_f32_16x16x32_bf16 v[124:127], v[156:159], v[192:195], v[124:127]
	v_mfma_f32_16x16x32_bf16 v[120:123], v[164:167], v[192:195], v[120:123]
	v_mfma_f32_16x16x32_bf16 v[108:111], v[156:159], v[206:209], v[108:111]
	v_mfma_f32_16x16x32_bf16 v[104:107], v[164:167], v[206:209], v[104:107]
	v_mfma_f32_16x16x32_bf16 v[92:95], v[156:159], v[214:217], v[92:95]
	v_mfma_f32_16x16x32_bf16 v[88:91], v[164:167], v[214:217], v[88:91]
	v_mfma_f32_16x16x32_bf16 v[76:79], v[156:159], v[222:225], v[76:79]
	v_mfma_f32_16x16x32_bf16 v[72:75], v[164:167], v[222:225], v[72:75]
	s_setprio 0
	s_setprio 1
	v_mfma_f32_16x16x32_bf16 v[116:119], v[168:171], v[188:191], 0
	v_mfma_f32_16x16x32_bf16 v[112:115], v[180:183], v[188:191], 0
	v_mfma_f32_16x16x32_bf16 v[100:103], v[168:171], v[196:199], 0
	v_mfma_f32_16x16x32_bf16 v[96:99], v[180:183], v[196:199], 0
	v_mfma_f32_16x16x32_bf16 v[84:87], v[168:171], v[210:213], 0
	v_mfma_f32_16x16x32_bf16 v[80:83], v[180:183], v[210:213], 0
	v_mfma_f32_16x16x32_bf16 v[68:71], v[168:171], v[218:221], 0
	v_mfma_f32_16x16x32_bf16 v[64:67], v[180:183], v[218:221], 0
	v_mfma_f32_16x16x32_bf16 v[116:119], v[172:175], v[192:195], v[116:119]
	v_mfma_f32_16x16x32_bf16 v[112:115], v[184:187], v[192:195], v[112:115]
	v_mfma_f32_16x16x32_bf16 v[100:103], v[172:175], v[206:209], v[100:103]
	v_mfma_f32_16x16x32_bf16 v[96:99], v[184:187], v[206:209], v[96:99]
	v_mfma_f32_16x16x32_bf16 v[84:87], v[172:175], v[214:217], v[84:87]
	v_mfma_f32_16x16x32_bf16 v[80:83], v[184:187], v[214:217], v[80:83]
	v_mfma_f32_16x16x32_bf16 v[68:71], v[172:175], v[222:225], v[68:71]
	v_mfma_f32_16x16x32_bf16 v[64:67], v[184:187], v[222:225], v[64:67]
	s_setprio 0
	s_barrier
	s_add_i32 s74, s60, s15
	v_lshl_add_u64 v[200:201], s[52:53], 0, v[130:131]
	s_mov_b32 m0, s74
	ds_read_b128 v[188:191], v154 offset:16384
	ds_read_b128 v[192:195], v154 offset:17408
	ds_read_b128 v[196:199], v154 offset:18432
	ds_read_b128 v[206:209], v154 offset:19456
	ds_read_b128 v[210:213], v154 offset:20480
	ds_read_b128 v[214:217], v154 offset:21504
	ds_read_b128 v[218:221], v154 offset:22528
	ds_read_b128 v[222:225], v154 offset:23552
	global_load_lds_dwordx4 v[200:201], off
	s_add_i32 m0, s74, 0x2000
	s_add_u32 s74, s52, 0x40000
	v_lshl_add_u64 v[226:227], s[52:53], 0, v[134:135]
	s_addc_u32 s75, s53, 0
	s_add_i32 s76, s61, s15
	global_load_lds_dwordx4 v[226:227], off
	v_lshl_add_u64 v[228:229], s[74:75], 0, v[130:131]
	s_mov_b32 m0, s76
	global_load_lds_dwordx4 v[228:229], off
	v_lshl_add_u64 v[228:229], s[74:75], 0, v[134:135]
	s_add_i32 m0, s76, 0x2000
	s_nop 0
	global_load_lds_dwordx4 v[228:229], off
	v_lshl_add_u64 v[228:229], s[54:55], 0, v[128:129]
	s_mov_b32 m0, s33
	s_nop 0
	global_load_lds_dwordx4 v[228:229], off
	v_lshl_add_u64 v[230:231], s[54:55], 0, v[132:133]
	s_mov_b32 m0, s34
	s_nop 0
	global_load_lds_dwordx4 v[230:231], off
	s_waitcnt vmcnt(8)
	s_waitcnt lgkmcnt(0)
	s_barrier
; #define PG8_STAGE(bufoff, gbase, voff) do { _Pragma("unroll") for (int _i = 0; _i < 2; ++_i) \
;         __builtin_amdgcn_global_load_lds((const unsigned*)((const char*)(gbase) + (voff)[_i]), (PG8_LAS unsigned*)(lds + (bufoff) + ldsw + _i * 8192), 16, 0, 0); } while (0)
; #define PG8_LDA(dst, b, h) do { _Pragma("unroll") for (int m = 0; m < 4; ++m) _Pragma("unroll") for (int k = 0; k < 2; ++k) dst[m][k] = *(const PG8_LAS bf16x8*)(lds + PG8_SA(b, h) + aoff + m * 2048 + k * 1024); } while (0)
; #define PG8_LDB(dst, b, h) do { _Pragma("unroll") for (int n = 0; n < 2; ++n) _Pragma("unroll") for (int k = 0; k < 2; ++k) dst[n][k] = *(const PG8_LAS bf16x8*)(lds + PG8_SB(b, h) + boff + n * 2048 + k * 1024); } while (0)
; #define PG8_MMA(ai, bj, At, Bt) do { __builtin_amdgcn_s_setprio(1); _Pragma("unroll") for (int m = 0; m < 4; ++m) _Pragma("unroll") for (int n = 0; n < 2; ++n) _Pragma("unroll") for (int k = 0; k < 2; ++k) \
;         acc[ai][bj][m][n] = __builtin_amdgcn_mfma_f32_16x16x32_bf16(Bt[n][k], At[m][k], acc[ai][bj][m][n], 0, 0, 0); __builtin_amdgcn_s_setprio(0); } while (0)
; #define PG8_WAIT_V(n) asm volatile("s_waitcnt vmcnt(" #n ")" ::: "memory")
; #define PG8_WAIT_L(n) asm volatile("s_waitcnt lgkmcnt(" #n ")" ::: "memory")
; #define PG8_BAR __builtin_amdgcn_s_barrier()
; #define PG8_SCHED __builtin_amdgcn_sched_barrier(0)
; template <class Epi, class Sched, bool ALIGN_EPI = false, bool SP2 = false>
; __device__ __forceinline__ void gemm_phase(PG8_LAS unsigned char* lds, const Gemm g, const Sched& S, const Epi& E) {
;     ...
;             PG8_WAIT_V(8); PG8_WAIT_L(0); PG8_BAR; PG8_MMA(1, 0, At, B0); PG8_MMA(1, 1, At, B1); PG8_BAR; PG8_SCHED;
;             PG8_LDB(B0, 1, 0); PG8_LDB(B1, 1, 1); PG8_SCHED; PG8_LDA(At, 1, 0); PG8_STAGE(PG8_SA(0, 1), a2 + hstep, voffA);
;             PG8_WAIT_V(8); PG8_WAIT_L(0); PG8_BAR; PG8_MMA(0, 0, At, B0); PG8_MMA(0, 1, At, B1); PG8_BAR; PG8_SCHED;
	s_setprio 1
	s_waitcnt lgkmcnt(0)
	v_mfma_f32_16x16x32_bf16 v[60:63], v[146:149], v[188:191], 0
	v_mfma_f32_16x16x32_bf16 v[56:59], v[160:163], v[188:191], 0
	v_mfma_f32_16x16x32_bf16 v[44:47], v[146:149], v[196:199], 0
	v_mfma_f32_16x16x32_bf16 v[40:43], v[160:163], v[196:199], 0
	v_mfma_f32_16x16x32_bf16 v[28:31], v[146:149], v[210:213], 0
	v_mfma_f32_16x16x32_bf16 v[24:27], v[160:163], v[210:213], 0
	v_mfma_f32_16x16x32_bf16 v[12:15], v[146:149], v[218:221], 0
	v_mfma_f32_16x16x32_bf16 v[8:11], v[160:163], v[218:221], 0
	v_mfma_f32_16x16x32_bf16 v[60:63], v[156:159], v[192:195], v[60:63]
	v_mfma_f32_16x16x32_bf16 v[56:59], v[164:167], v[192:195], v[56:59]
	v_mfma_f32_16x16x32_bf16 v[44:47], v[156:159], v[206:209], v[44:47]
	v_mfma_f32_16x16x32_bf16 v[40:43], v[164:167], v[206:209], v[40:43]
	v_mfma_f32_16x16x32_bf16 v[28:31], v[156:159], v[214:217], v[28:31]
	v_mfma_f32_16x16x32_bf16 v[24:27], v[164:167], v[214:217], v[24:27]
	v_mfma_f32_16x16x32_bf16 v[12:15], v[156:159], v[222:225], v[12:15]
	v_mfma_f32_16x16x32_bf16 v[8:11], v[164:167], v[222:225], v[8:11]
	s_setprio 0
	s_setprio 1
	v_mfma_f32_16x16x32_bf16 v[52:55], v[168:171], v[188:191], 0
	v_mfma_f32_16x16x32_bf16 v[48:51], v[180:183], v[188:191], 0
	v_mfma_f32_16x16x32_bf16 v[36:39], v[168:171], v[196:199], 0
	v_mfma_f32_16x16x32_bf16 v[32:35], v[180:183], v[196:199], 0
	v_mfma_f32_16x16x32_bf16 v[20:23], v[168:171], v[210:213], 0
	v_mfma_f32_16x16x32_bf16 v[16:19], v[180:183], v[210:213], 0
	v_mfma_f32_16x16x32_bf16 v[4:7], v[168:171], v[218:221], 0
	v_mfma_f32_16x16x32_bf16 v[0:3], v[180:183], v[218:221], 0
	v_mfma_f32_16x16x32_bf16 v[52:55], v[172:175], v[192:195], v[52:55]
	v_mfma_f32_16x16x32_bf16 v[48:51], v[184:187], v[192:195], v[48:51]
	v_mfma_f32_16x16x32_bf16 v[36:39], v[172:175], v[206:209], v[36:39]
	v_mfma_f32_16x16x32_bf16 v[32:35], v[184:187], v[206:209], v[32:35]
	v_mfma_f32_16x16x32_bf16 v[20:23], v[172:175], v[214:217], v[20:23]
	v_mfma_f32_16x16x32_bf16 v[16:19], v[184:187], v[214:217], v[16:19]
	v_mfma_f32_16x16x32_bf16 v[4:7], v[172:175], v[222:225], v[4:7]
	v_mfma_f32_16x16x32_bf16 v[0:3], v[184:187], v[222:225], v[0:3]
	s_setprio 0
	s_barrier
	s_add_i32 s74, 0, 0x18000
	s_add_i32 s75, 0, 0x1c000
	v_add_u32_e32 v164, s74, v150
	v_add_u32_e32 v179, s75, v150
	ds_read_b128 v[146:149], v164
	ds_read_b128 v[156:159], v164 offset:1024
	ds_read_b128 v[160:163], v164 offset:2048
	ds_read_b128 v[164:167], v164 offset:3072
	ds_read_b128 v[168:171], v179
	ds_read_b128 v[172:175], v179 offset:1024
	ds_read_b128 v[180:183], v179 offset:2048
	ds_read_b128 v[184:187], v179 offset:3072
	s_add_u32 s54, s54, 0x40000
	s_addc_u32 s55, s55, 0
	s_mov_b32 m0, s49
	v_lshl_add_u64 v[232:233], s[54:55], 0, v[128:129]
	ds_read_b128 v[188:191], v154 offset:32768
	ds_read_b128 v[192:195], v154 offset:33792
	ds_read_b128 v[196:199], v154 offset:34816
	ds_read_b128 v[206:209], v154 offset:35840
	ds_read_b128 v[210:213], v154 offset:36864
	ds_read_b128 v[214:217], v154 offset:37888
	ds_read_b128 v[218:221], v154 offset:38912
	ds_read_b128 v[222:225], v154 offset:39936
	global_load_lds_dwordx4 v[232:233], off
	v_lshl_add_u64 v[232:233], s[54:55], 0, v[132:133]
	s_mov_b32 m0, s56
	s_nop 0
	global_load_lds_dwordx4 v[232:233], off
	s_waitcnt vmcnt(8)
	s_waitcnt lgkmcnt(0)
	s_barrier
	s_setprio 1
	s_waitcnt lgkmcnt(0)
	v_mfma_f32_16x16x32_bf16 v[124:127], v[146:149], v[188:191], v[124:127]
	v_mfma_f32_16x16x32_bf16 v[120:123], v[160:163], v[188:191], v[120:123]
	v_mfma_f32_16x16x32_bf16 v[108:111], v[146:149], v[196:199], v[108:111]
	v_mfma_f32_16x16x32_bf16 v[104:107], v[160:163], v[196:199], v[104:107]
	v_mfma_f32_16x16x32_bf16 v[92:95], v[146:149], v[210:213], v[92:95]
	v_mfma_f32_16x16x32_bf16 v[88:91], v[160:163], v[210:213], v[88:91]
	v_mfma_f32_16x16x32_bf16 v[76:79], v[146:149], v[218:221], v[76:79]
	v_mfma_f32_16x16x32_bf16 v[72:75], v[160:163], v[218:221], v[72:75]
	v_mfma_f32_16x16x32_bf16 v[124:127], v[156:159], v[192:195], v[124:127]
	v_mfma_f32_16x16x32_bf16 v[120:123], v[164:167], v[192:195], v[120:123]
	v_mfma_f32_16x16x32_bf16 v[108:111], v[156:159], v[206:209], v[108:111]
	v_mfma_f32_16x16x32_bf16 v[104:107], v[164:167], v[206:209], v[104:107]
	v_mfma_f32_16x16x32_bf16 v[92:95], v[156:159], v[214:217], v[92:95]
	v_mfma_f32_16x16x32_bf16 v[88:91], v[164:167], v[214:217], v[88:91]
	v_mfma_f32_16x16x32_bf16 v[76:79], v[156:159], v[222:225], v[76:79]
	v_mfma_f32_16x16x32_bf16 v[72:75], v[164:167], v[222:225], v[72:75]
	s_setprio 0
	s_setprio 1
	v_mfma_f32_16x16x32_bf16 v[116:119], v[168:171], v[188:191], v[116:119]
	v_mfma_f32_16x16x32_bf16 v[112:115], v[180:183], v[188:191], v[112:115]
	v_mfma_f32_16x16x32_bf16 v[100:103], v[168:171], v[196:199], v[100:103]
	v_mfma_f32_16x16x32_bf16 v[96:99], v[180:183], v[196:199], v[96:99]
	v_mfma_f32_16x16x32_bf16 v[84:87], v[168:171], v[210:213], v[84:87]
	v_mfma_f32_16x16x32_bf16 v[80:83], v[180:183], v[210:213], v[80:83]
	v_mfma_f32_16x16x32_bf16 v[68:71], v[168:171], v[218:221], v[68:71]
	v_mfma_f32_16x16x32_bf16 v[64:67], v[180:183], v[218:221], v[64:67]
	v_mfma_f32_16x16x32_bf16 v[116:119], v[172:175], v[192:195], v[116:119]
	v_mfma_f32_16x16x32_bf16 v[112:115], v[184:187], v[192:195], v[112:115]
	v_mfma_f32_16x16x32_bf16 v[100:103], v[172:175], v[206:209], v[100:103]
	v_mfma_f32_16x16x32_bf16 v[96:99], v[184:187], v[206:209], v[96:99]
	v_mfma_f32_16x16x32_bf16 v[84:87], v[172:175], v[214:217], v[84:87]
	v_mfma_f32_16x16x32_bf16 v[80:83], v[184:187], v[214:217], v[80:83]
	v_mfma_f32_16x16x32_bf16 v[68:71], v[172:175], v[222:225], v[68:71]
	v_mfma_f32_16x16x32_bf16 v[64:67], v[184:187], v[222:225], v[64:67]
	s_setprio 0
	s_barrier
; #define PG8_STAGE(bufoff, gbase, voff) do { _Pragma("unroll") for (int _i = 0; _i < 2; ++_i) \
;         __builtin_amdgcn_global_load_lds((const unsigned*)((const char*)(gbase) + (voff)[_i]), (PG8_LAS unsigned*)(lds + (bufoff) + ldsw + _i * 8192), 16, 0, 0); } while (0)
; #define PG8_LDA(dst, b, h) do { _Pragma("unroll") for (int m = 0; m < 4; ++m) _Pragma("unroll") for (int k = 0; k < 2; ++k) dst[m][k] = *(const PG8_LAS bf16x8*)(lds + PG8_SA(b, h) + aoff + m * 2048 + k * 1024); } while (0)
; #define PG8_LDB(dst, b, h) do { _Pragma("unroll") for (int n = 0; n < 2; ++n) _Pragma("unroll") for (int k = 0; k < 2; ++k) dst[n][k] = *(const PG8_LAS bf16x8*)(lds + PG8_SB(b, h) + boff + n * 2048 + k * 1024); } while (0)
; #define PG8_MMA(ai, bj, At, Bt) do { __builtin_amdgcn_s_setprio(1); _Pragma("unroll") for (int m = 0; m < 4; ++m) _Pragma("unroll") for (int n = 0; n < 2; ++n) _Pragma("unroll") for (int k = 0; k < 2; ++k) \
;         acc[ai][bj][m][n] = __builtin_amdgcn_mfma_f32_16x16x32_bf16(Bt[n][k], At[m][k], acc[ai][bj][m][n], 0, 0, 0); __builtin_amdgcn_s_setprio(0); } while (0)
; #define PG8_WAIT_V(n) asm volatile("s_waitcnt vmcnt(" #n ")" ::: "memory")
; #define PG8_WAIT_L(n) asm volatile("s_waitcnt lgkmcnt(" #n ")" ::: "memory")
; #define PG8_BAR __builtin_amdgcn_s_barrier()
; #define PG8_SCHED __builtin_amdgcn_sched_barrier(0)
; template <class Epi, class Sched, bool ALIGN_EPI = false, bool SP2 = false>
; __device__ __forceinline__ void gemm_phase(PG8_LAS unsigned char* lds, const Gemm g, const Sched& S, const Epi& E) {
;     ...
;             PG8_LDB(B0, 0, 0); PG8_LDB(B1, 0, 1); PG8_SCHED; PG8_LDA(At, 0, 0); PG8_STAGE(PG8_SA(1, 1), a1 + hstep, voffA);
;             PG8_WAIT_V(8); PG8_WAIT_L(0); PG8_BAR; PG8_MMA(0, 0, At, B0); PG8_MMA(0, 1, At, B1); PG8_BAR; PG8_SCHED;
;     ...
;             PG8_LDA(At, 1, 1); PG8_STAGE(PG8_SB(1, 0), b3, voffB); PG8_STAGE(PG8_SB(1, 1), b3 + hstep, voffB); PG8_STAGE(PG8_SA(1, 0), a3, voffA);
;             PG8_WAIT_V(8); PG8_WAIT_L(0); PG8_BAR; PG8_MMA(1, 0, At, B0); PG8_MMA(1, 1, At, B1); PG8_BAR; PG8_SCHED;
	s_add_i32 s54, s74, s15
	v_lshl_add_u64 v[200:201], v[200:201], 0, s[26:27]
	s_mov_b32 m0, s54
	ds_read_b128 v[188:191], v154 offset:49152
	ds_read_b128 v[192:195], v154 offset:50176
	ds_read_b128 v[196:199], v154 offset:51200
	ds_read_b128 v[206:209], v154 offset:52224
	ds_read_b128 v[210:213], v154 offset:53248
	ds_read_b128 v[214:217], v154 offset:54272
	ds_read_b128 v[218:221], v154 offset:55296
	ds_read_b128 v[222:225], v154 offset:56320
	global_load_lds_dwordx4 v[200:201], off
	s_add_i32 m0, s54, 0x2000
	s_add_u32 s52, s52, 0x40080
	v_lshl_add_u64 v[200:201], v[226:227], 0, s[26:27]
	s_addc_u32 s53, s53, 0
	s_add_i32 s54, s75, s15
	global_load_lds_dwordx4 v[200:201], off
	v_lshl_add_u64 v[200:201], s[52:53], 0, v[130:131]
	s_mov_b32 m0, s54
	s_nop 0
	global_load_lds_dwordx4 v[200:201], off
	v_lshl_add_u64 v[200:201], s[52:53], 0, v[134:135]
	s_add_i32 m0, s54, 0x2000
	s_nop 0
	global_load_lds_dwordx4 v[200:201], off
	v_lshl_add_u64 v[200:201], v[228:229], 0, s[26:27]
	s_mov_b32 m0, s58
	s_nop 0
	global_load_lds_dwordx4 v[200:201], off
	v_lshl_add_u64 v[200:201], v[230:231], 0, s[26:27]
	s_mov_b32 m0, s59
	s_nop 0
	global_load_lds_dwordx4 v[200:201], off
	s_waitcnt vmcnt(8)
	s_waitcnt lgkmcnt(0)
	s_barrier
	s_setprio 1
	s_waitcnt lgkmcnt(0)
	v_mfma_f32_16x16x32_bf16 v[60:63], v[146:149], v[188:191], v[60:63]
	v_mfma_f32_16x16x32_bf16 v[56:59], v[160:163], v[188:191], v[56:59]
	v_mfma_f32_16x16x32_bf16 v[44:47], v[146:149], v[196:199], v[44:47]
	v_mfma_f32_16x16x32_bf16 v[40:43], v[160:163], v[196:199], v[40:43]
	v_mfma_f32_16x16x32_bf16 v[28:31], v[146:149], v[210:213], v[28:31]
	v_mfma_f32_16x16x32_bf16 v[24:27], v[160:163], v[210:213], v[24:27]
	v_mfma_f32_16x16x32_bf16 v[12:15], v[146:149], v[218:221], v[12:15]
	v_mfma_f32_16x16x32_bf16 v[8:11], v[160:163], v[218:221], v[8:11]
	v_mfma_f32_16x16x32_bf16 v[60:63], v[156:159], v[192:195], v[60:63]
	v_mfma_f32_16x16x32_bf16 v[56:59], v[164:167], v[192:195], v[56:59]
	v_mfma_f32_16x16x32_bf16 v[44:47], v[156:159], v[206:209], v[44:47]
	v_mfma_f32_16x16x32_bf16 v[40:43], v[164:167], v[206:209], v[40:43]
	v_mfma_f32_16x16x32_bf16 v[28:31], v[156:159], v[214:217], v[28:31]
	v_mfma_f32_16x16x32_bf16 v[24:27], v[164:167], v[214:217], v[24:27]
	v_mfma_f32_16x16x32_bf16 v[12:15], v[156:159], v[222:225], v[12:15]
	v_mfma_f32_16x16x32_bf16 v[8:11], v[164:167], v[222:225], v[8:11]
	s_setprio 0
	s_setprio 1
	v_mfma_f32_16x16x32_bf16 v[52:55], v[168:171], v[188:191], v[52:55]
	v_mfma_f32_16x16x32_bf16 v[48:51], v[180:183], v[188:191], v[48:51]
	v_mfma_f32_16x16x32_bf16 v[36:39], v[168:171], v[196:199], v[36:39]
	v_mfma_f32_16x16x32_bf16 v[32:35], v[180:183], v[196:199], v[32:35]
	v_mfma_f32_16x16x32_bf16 v[20:23], v[168:171], v[210:213], v[20:23]
	v_mfma_f32_16x16x32_bf16 v[16:19], v[180:183], v[210:213], v[16:19]
	v_mfma_f32_16x16x32_bf16 v[4:7], v[168:171], v[218:221], v[4:7]
	v_mfma_f32_16x16x32_bf16 v[0:3], v[180:183], v[218:221], v[0:3]
	v_mfma_f32_16x16x32_bf16 v[52:55], v[172:175], v[192:195], v[52:55]
	v_mfma_f32_16x16x32_bf16 v[48:51], v[184:187], v[192:195], v[48:51]
	v_mfma_f32_16x16x32_bf16 v[36:39], v[172:175], v[206:209], v[36:39]
	v_mfma_f32_16x16x32_bf16 v[32:35], v[184:187], v[206:209], v[32:35]
	v_mfma_f32_16x16x32_bf16 v[20:23], v[172:175], v[214:217], v[20:23]
	v_mfma_f32_16x16x32_bf16 v[16:19], v[184:187], v[214:217], v[16:19]
	v_mfma_f32_16x16x32_bf16 v[4:7], v[172:175], v[222:225], v[4:7]
	v_mfma_f32_16x16x32_bf16 v[0:3], v[184:187], v[222:225], v[0:3]
	s_setprio 0
	s_barrier
	s_add_i32 s67, s67, 2
	s_add_u32 s50, s50, 0x100
	s_addc_u32 s51, s51, 0
	s_add_u32 s65, s65, 0x100
	s_addc_u32 s66, s66, 0
.LBB0_1593:
	ds_read_b128 v[146:149], v152
	ds_read_b128 v[156:159], v152 offset:1024
	ds_read_b128 v[160:163], v152 offset:2048
	ds_read_b128 v[164:167], v152 offset:3072
	ds_read_b128 v[168:171], v153
	ds_read_b128 v[172:175], v153 offset:1024
	ds_read_b128 v[180:183], v153 offset:2048
	ds_read_b128 v[184:187], v153 offset:3072
	s_add_u32 s52, s50, 0xfffc0080
	s_addc_u32 s53, s51, -1
	s_cmp_eq_u32 s67, 12
	s_cselect_b32 s55, s39, s53
	s_cselect_b32 s54, s47, s52
	s_cselect_b32 s53, s37, s66
	s_cselect_b32 s52, s64, s65
	v_lshl_add_u64 v[200:201], s[50:51], 0, v[136:137]
	s_add_i32 m0, s33, 0xc000
	ds_read_b128 v[188:191], v154
	ds_read_b128 v[192:195], v154 offset:1024
	ds_read_b128 v[196:199], v154 offset:2048
	ds_read_b128 v[206:209], v154 offset:3072
	ds_read_b128 v[210:213], v154 offset:4096
	ds_read_b128 v[214:217], v154 offset:5120
	ds_read_b128 v[218:221], v154 offset:6144
	ds_read_b128 v[222:225], v154 offset:7168
	global_load_lds_dwordx4 v[200:201], off
	v_lshl_add_u64 v[200:201], s[50:51], 0, v[138:139]
	s_add_i32 m0, s33, 0xe000
	s_nop 0
	global_load_lds_dwordx4 v[200:201], off
	s_waitcnt vmcnt(8)
	s_waitcnt lgkmcnt(0)
	s_barrier
; #define PG8_STAGE(bufoff, gbase, voff) do { _Pragma("unroll") for (int _i = 0; _i < 2; ++_i) \
;         __builtin_amdgcn_global_load_lds((const unsigned*)((const char*)(gbase) + (voff)[_i]), (PG8_LAS unsigned*)(lds + (bufoff) + ldsw + _i * 8192), 16, 0, 0); } while (0)
; #define PG8_LDA(dst, b, h) do { _Pragma("unroll") for (int m = 0; m < 4; ++m) _Pragma("unroll") for (int k = 0; k < 2; ++k) dst[m][k] = *(const PG8_LAS bf16x8*)(lds + PG8_SA(b, h) + aoff + m * 2048 + k * 1024); } while (0)
; #define PG8_MMA(ai, bj, At, Bt) do { __builtin_amdgcn_s_setprio(1); _Pragma("unroll") for (int m = 0; m < 4; ++m) _Pragma("unroll") for (int n = 0; n < 2; ++n) _Pragma("unroll") for (int k = 0; k < 2; ++k) \
;         acc[ai][bj][m][n] = __builtin_amdgcn_mfma_f32_16x16x32_bf16(Bt[n][k], At[m][k], acc[ai][bj][m][n], 0, 0, 0); __builtin_amdgcn_s_setprio(0); } while (0)
; #define PG8_WAIT_V(n) asm volatile("s_waitcnt vmcnt(" #n ")" ::: "memory")
; #define PG8_WAIT_L(n) asm volatile("s_waitcnt lgkmcnt(" #n ")" ::: "memory")
; #define PG8_BAR __builtin_amdgcn_s_barrier()
; #define PG8_SCHED __builtin_amdgcn_sched_barrier(0)
; template <class Epi, class Sched, bool ALIGN_EPI = false, bool SP2 = false>
; __device__ __forceinline__ void gemm_phase(PG8_LAS unsigned char* lds, const Gemm g, const Sched& S, const Epi& E) {
;     ...
;             PG8_WAIT_V(8); PG8_WAIT_L(0); PG8_BAR; PG8_MMA(0, 0, At, B0); PG8_MMA(0, 1, At, B1); PG8_BAR; PG8_SCHED;
;             PG8_LDA(At, 0, 1); PG8_STAGE(PG8_SB(0, 0), b2, voffB); PG8_STAGE(PG8_SB(0, 1), b2 + hstep, voffB); PG8_STAGE(PG8_SA(0, 0), a2, voffA);
;             PG8_WAIT_V(8); PG8_WAIT_L(0); PG8_BAR; PG8_MMA(1, 0, At, B0); PG8_MMA(1, 1, At, B1); PG8_BAR; PG8_SCHED;
	s_setprio 1
	s_waitcnt lgkmcnt(0)
	v_mfma_f32_16x16x32_bf16 v[124:127], v[146:149], v[188:191], v[124:127]
	v_mfma_f32_16x16x32_bf16 v[120:123], v[160:163], v[188:191], v[120:123]
	v_mfma_f32_16x16x32_bf16 v[108:111], v[146:149], v[196:199], v[108:111]
	v_mfma_f32_16x16x32_bf16 v[104:107], v[160:163], v[196:199], v[104:107]
	v_mfma_f32_16x16x32_bf16 v[92:95], v[146:149], v[210:213], v[92:95]
	v_mfma_f32_16x16x32_bf16 v[88:91], v[160:163], v[210:213], v[88:91]
	v_mfma_f32_16x16x32_bf16 v[76:79], v[146:149], v[218:221], v[76:79]
	v_mfma_f32_16x16x32_bf16 v[72:75], v[160:163], v[218:221], v[72:75]
	v_mfma_f32_16x16x32_bf16 v[124:127], v[156:159], v[192:195], v[124:127]
	v_mfma_f32_16x16x32_bf16 v[120:123], v[164:167], v[192:195], v[120:123]
	v_mfma_f32_16x16x32_bf16 v[108:111], v[156:159], v[206:209], v[108:111]
	v_mfma_f32_16x16x32_bf16 v[104:107], v[164:167], v[206:209], v[104:107]
	v_mfma_f32_16x16x32_bf16 v[92:95], v[156:159], v[214:217], v[92:95]
	v_mfma_f32_16x16x32_bf16 v[88:91], v[164:167], v[214:217], v[88:91]
	v_mfma_f32_16x16x32_bf16 v[76:79], v[156:159], v[222:225], v[76:79]
	v_mfma_f32_16x16x32_bf16 v[72:75], v[164:167], v[222:225], v[72:75]
	s_setprio 0
	s_setprio 1
	v_mfma_f32_16x16x32_bf16 v[116:119], v[168:171], v[188:191], v[116:119]
	v_mfma_f32_16x16x32_bf16 v[112:115], v[180:183], v[188:191], v[112:115]
	v_mfma_f32_16x16x32_bf16 v[100:103], v[168:171], v[196:199], v[100:103]
	v_mfma_f32_16x16x32_bf16 v[96:99], v[180:183], v[196:199], v[96:99]
	v_mfma_f32_16x16x32_bf16 v[84:87], v[168:171], v[210:213], v[84:87]
	v_mfma_f32_16x16x32_bf16 v[80:83], v[180:183], v[210:213], v[80:83]
	v_mfma_f32_16x16x32_bf16 v[68:71], v[168:171], v[218:221], v[68:71]
	v_mfma_f32_16x16x32_bf16 v[64:67], v[180:183], v[218:221], v[64:67]
	v_mfma_f32_16x16x32_bf16 v[116:119], v[172:175], v[192:195], v[116:119]
	v_mfma_f32_16x16x32_bf16 v[112:115], v[184:187], v[192:195], v[112:115]
	v_mfma_f32_16x16x32_bf16 v[100:103], v[172:175], v[206:209], v[100:103]
	v_mfma_f32_16x16x32_bf16 v[96:99], v[184:187], v[206:209], v[96:99]
	v_mfma_f32_16x16x32_bf16 v[84:87], v[172:175], v[214:217], v[84:87]
	v_mfma_f32_16x16x32_bf16 v[80:83], v[184:187], v[214:217], v[80:83]
	v_mfma_f32_16x16x32_bf16 v[68:71], v[172:175], v[222:225], v[68:71]
	v_mfma_f32_16x16x32_bf16 v[64:67], v[184:187], v[222:225], v[64:67]
	s_setprio 0
	s_barrier
	s_add_i32 s74, s60, s15
	v_lshl_add_u64 v[200:201], s[52:53], 0, v[130:131]
	s_mov_b32 m0, s74
	ds_read_b128 v[188:191], v154 offset:16384
	ds_read_b128 v[192:195], v154 offset:17408
	ds_read_b128 v[196:199], v154 offset:18432
	ds_read_b128 v[206:209], v154 offset:19456
	ds_read_b128 v[210:213], v154 offset:20480
	ds_read_b128 v[214:217], v154 offset:21504
	ds_read_b128 v[218:221], v154 offset:22528
	ds_read_b128 v[222:225], v154 offset:23552
	global_load_lds_dwordx4 v[200:201], off
	s_add_i32 m0, s74, 0x2000
	s_add_u32 s74, s52, 0x40000
	v_lshl_add_u64 v[226:227], s[52:53], 0, v[134:135]
	s_addc_u32 s75, s53, 0
	s_add_i32 s76, s61, s15
	global_load_lds_dwordx4 v[226:227], off
	v_lshl_add_u64 v[228:229], s[74:75], 0, v[130:131]
	s_mov_b32 m0, s76
	global_load_lds_dwordx4 v[228:229], off
	v_lshl_add_u64 v[228:229], s[74:75], 0, v[134:135]
	s_add_i32 m0, s76, 0x2000
	s_nop 0
	global_load_lds_dwordx4 v[228:229], off
	v_lshl_add_u64 v[228:229], s[54:55], 0, v[128:129]
	s_mov_b32 m0, s33
	s_nop 0
	global_load_lds_dwordx4 v[228:229], off
	v_lshl_add_u64 v[230:231], s[54:55], 0, v[132:133]
	s_mov_b32 m0, s34
	s_nop 0
	global_load_lds_dwordx4 v[230:231], off
	s_waitcnt vmcnt(8)
	s_waitcnt lgkmcnt(0)
	s_barrier
	s_setprio 1
	s_waitcnt lgkmcnt(0)
	v_mfma_f32_16x16x32_bf16 v[60:63], v[146:149], v[188:191], v[60:63]
	v_mfma_f32_16x16x32_bf16 v[56:59], v[160:163], v[188:191], v[56:59]
	v_mfma_f32_16x16x32_bf16 v[44:47], v[146:149], v[196:199], v[44:47]
	v_mfma_f32_16x16x32_bf16 v[40:43], v[160:163], v[196:199], v[40:43]
	v_mfma_f32_16x16x32_bf16 v[28:31], v[146:149], v[210:213], v[28:31]
	v_mfma_f32_16x16x32_bf16 v[24:27], v[160:163], v[210:213], v[24:27]
	v_mfma_f32_16x16x32_bf16 v[12:15], v[146:149], v[218:221], v[12:15]
	v_mfma_f32_16x16x32_bf16 v[8:11], v[160:163], v[218:221], v[8:11]
	v_mfma_f32_16x16x32_bf16 v[60:63], v[156:159], v[192:195], v[60:63]
	v_mfma_f32_16x16x32_bf16 v[56:59], v[164:167], v[192:195], v[56:59]
	v_mfma_f32_16x16x32_bf16 v[44:47], v[156:159], v[206:209], v[44:47]
	v_mfma_f32_16x16x32_bf16 v[40:43], v[164:167], v[206:209], v[40:43]
	v_mfma_f32_16x16x32_bf16 v[28:31], v[156:159], v[214:217], v[28:31]
	v_mfma_f32_16x16x32_bf16 v[24:27], v[164:167], v[214:217], v[24:27]
	v_mfma_f32_16x16x32_bf16 v[12:15], v[156:159], v[222:225], v[12:15]
	v_mfma_f32_16x16x32_bf16 v[8:11], v[164:167], v[222:225], v[8:11]
	s_setprio 0
	s_setprio 1
	v_mfma_f32_16x16x32_bf16 v[52:55], v[168:171], v[188:191], v[52:55]
	v_mfma_f32_16x16x32_bf16 v[48:51], v[180:183], v[188:191], v[48:51]
	v_mfma_f32_16x16x32_bf16 v[36:39], v[168:171], v[196:199], v[36:39]
	v_mfma_f32_16x16x32_bf16 v[32:35], v[180:183], v[196:199], v[32:35]
	v_mfma_f32_16x16x32_bf16 v[20:23], v[168:171], v[210:213], v[20:23]
	v_mfma_f32_16x16x32_bf16 v[16:19], v[180:183], v[210:213], v[16:19]
	v_mfma_f32_16x16x32_bf16 v[4:7], v[168:171], v[218:221], v[4:7]
	v_mfma_f32_16x16x32_bf16 v[0:3], v[180:183], v[218:221], v[0:3]
	v_mfma_f32_16x16x32_bf16 v[52:55], v[172:175], v[192:195], v[52:55]
	v_mfma_f32_16x16x32_bf16 v[48:51], v[184:187], v[192:195], v[48:51]
	v_mfma_f32_16x16x32_bf16 v[36:39], v[172:175], v[206:209], v[36:39]
	v_mfma_f32_16x16x32_bf16 v[32:35], v[184:187], v[206:209], v[32:35]
	v_mfma_f32_16x16x32_bf16 v[20:23], v[172:175], v[214:217], v[20:23]
	v_mfma_f32_16x16x32_bf16 v[16:19], v[184:187], v[214:217], v[16:19]
	v_mfma_f32_16x16x32_bf16 v[4:7], v[172:175], v[222:225], v[4:7]
	v_mfma_f32_16x16x32_bf16 v[0:3], v[184:187], v[222:225], v[0:3]
	s_setprio 0
	s_barrier
; #define PG8_STAGE(bufoff, gbase, voff) do { _Pragma("unroll") for (int _i = 0; _i < 2; ++_i) \
;         __builtin_amdgcn_global_load_lds((const unsigned*)((const char*)(gbase) + (voff)[_i]), (PG8_LAS unsigned*)(lds + (bufoff) + ldsw + _i * 8192), 16, 0, 0); } while (0)
; #define PG8_LDA(dst, b, h) do { _Pragma("unroll") for (int m = 0; m < 4; ++m) _Pragma("unroll") for (int k = 0; k < 2; ++k) dst[m][k] = *(const PG8_LAS bf16x8*)(lds + PG8_SA(b, h) + aoff + m * 2048 + k * 1024); } while (0)
; #define PG8_LDB(dst, b, h) do { _Pragma("unroll") for (int n = 0; n < 2; ++n) _Pragma("unroll") for (int k = 0; k < 2; ++k) dst[n][k] = *(const PG8_LAS bf16x8*)(lds + PG8_SB(b, h) + boff + n * 2048 + k * 1024); } while (0)
; #define PG8_MMA(ai, bj, At, Bt) do { __builtin_amdgcn_s_setprio(1); _Pragma("unroll") for (int m = 0; m < 4; ++m) _Pragma("unroll") for (int n = 0; n < 2; ++n) _Pragma("unroll") for (int k = 0; k < 2; ++k) \
;         acc[ai][bj][m][n] = __builtin_amdgcn_mfma_f32_16x16x32_bf16(Bt[n][k], At[m][k], acc[ai][bj][m][n], 0, 0, 0); __builtin_amdgcn_s_setprio(0); } while (0)
; #define PG8_WAIT_V(n) asm volatile("s_waitcnt vmcnt(" #n ")" ::: "memory")
; #define PG8_WAIT_L(n) asm volatile("s_waitcnt lgkmcnt(" #n ")" ::: "memory")
; #define PG8_BAR __builtin_amdgcn_s_barrier()
; #define PG8_SCHED __builtin_amdgcn_sched_barrier(0)
; template <class Epi, class Sched, bool ALIGN_EPI = false, bool SP2 = false>
; __device__ __forceinline__ void gemm_phase(PG8_LAS unsigned char* lds, const Gemm g, const Sched& S, const Epi& E) {
;     ...
;             PG8_LDB(B0, 1, 0); PG8_LDB(B1, 1, 1); PG8_SCHED; PG8_LDA(At, 1, 0); PG8_STAGE(PG8_SA(0, 1), a2 + hstep, voffA);
;             PG8_WAIT_V(8); PG8_WAIT_L(0); PG8_BAR; PG8_MMA(0, 0, At, B0); PG8_MMA(0, 1, At, B1); PG8_BAR; PG8_SCHED;
	s_add_i32 s74, 0, 0x18000
	s_add_i32 s75, 0, 0x1c000
	v_add_u32_e32 v164, s74, v150
	v_add_u32_e32 v179, s75, v150
	ds_read_b128 v[146:149], v164
	ds_read_b128 v[156:159], v164 offset:1024
	ds_read_b128 v[160:163], v164 offset:2048
	ds_read_b128 v[164:167], v164 offset:3072
	ds_read_b128 v[168:171], v179
	ds_read_b128 v[172:175], v179 offset:1024
	ds_read_b128 v[180:183], v179 offset:2048
	ds_read_b128 v[184:187], v179 offset:3072
	s_add_u32 s54, s54, 0x40000
	s_addc_u32 s55, s55, 0
	s_mov_b32 m0, s49
	v_lshl_add_u64 v[232:233], s[54:55], 0, v[128:129]
	ds_read_b128 v[188:191], v154 offset:32768
	ds_read_b128 v[192:195], v154 offset:33792
	ds_read_b128 v[196:199], v154 offset:34816
	ds_read_b128 v[206:209], v154 offset:35840
	ds_read_b128 v[210:213], v154 offset:36864
	ds_read_b128 v[214:217], v154 offset:37888
	ds_read_b128 v[218:221], v154 offset:38912
	ds_read_b128 v[222:225], v154 offset:39936
	global_load_lds_dwordx4 v[232:233], off
	v_lshl_add_u64 v[232:233], s[54:55], 0, v[132:133]
	s_mov_b32 m0, s56
	s_nop 0
	global_load_lds_dwordx4 v[232:233], off
	s_waitcnt vmcnt(8)
	s_waitcnt lgkmcnt(0)
	s_barrier
	s_setprio 1
	s_waitcnt lgkmcnt(0)
	v_mfma_f32_16x16x32_bf16 v[124:127], v[146:149], v[188:191], v[124:127]
	v_mfma_f32_16x16x32_bf16 v[120:123], v[160:163], v[188:191], v[120:123]
	v_mfma_f32_16x16x32_bf16 v[108:111], v[146:149], v[196:199], v[108:111]
	v_mfma_f32_16x16x32_bf16 v[104:107], v[160:163], v[196:199], v[104:107]
	v_mfma_f32_16x16x32_bf16 v[92:95], v[146:149], v[210:213], v[92:95]
	v_mfma_f32_16x16x32_bf16 v[88:91], v[160:163], v[210:213], v[88:91]
	v_mfma_f32_16x16x32_bf16 v[76:79], v[146:149], v[218:221], v[76:79]
	v_mfma_f32_16x16x32_bf16 v[72:75], v[160:163], v[218:221], v[72:75]
	v_mfma_f32_16x16x32_bf16 v[124:127], v[156:159], v[192:195], v[124:127]
	v_mfma_f32_16x16x32_bf16 v[120:123], v[164:167], v[192:195], v[120:123]
	v_mfma_f32_16x16x32_bf16 v[108:111], v[156:159], v[206:209], v[108:111]
	v_mfma_f32_16x16x32_bf16 v[104:107], v[164:167], v[206:209], v[104:107]
	v_mfma_f32_16x16x32_bf16 v[92:95], v[156:159], v[214:217], v[92:95]
	v_mfma_f32_16x16x32_bf16 v[88:91], v[164:167], v[214:217], v[88:91]
	v_mfma_f32_16x16x32_bf16 v[76:79], v[156:159], v[222:225], v[76:79]
	v_mfma_f32_16x16x32_bf16 v[72:75], v[164:167], v[222:225], v[72:75]
	s_setprio 0
	s_setprio 1
	v_mfma_f32_16x16x32_bf16 v[116:119], v[168:171], v[188:191], v[116:119]
	v_mfma_f32_16x16x32_bf16 v[112:115], v[180:183], v[188:191], v[112:115]
	v_mfma_f32_16x16x32_bf16 v[100:103], v[168:171], v[196:199], v[100:103]
	v_mfma_f32_16x16x32_bf16 v[96:99], v[180:183], v[196:199], v[96:99]
	v_mfma_f32_16x16x32_bf16 v[84:87], v[168:171], v[210:213], v[84:87]
	v_mfma_f32_16x16x32_bf16 v[80:83], v[180:183], v[210:213], v[80:83]
	v_mfma_f32_16x16x32_bf16 v[68:71], v[168:171], v[218:221], v[68:71]
	v_mfma_f32_16x16x32_bf16 v[64:67], v[180:183], v[218:221], v[64:67]
	v_mfma_f32_16x16x32_bf16 v[116:119], v[172:175], v[192:195], v[116:119]
	v_mfma_f32_16x16x32_bf16 v[112:115], v[184:187], v[192:195], v[112:115]
	v_mfma_f32_16x16x32_bf16 v[100:103], v[172:175], v[206:209], v[100:103]
	v_mfma_f32_16x16x32_bf16 v[96:99], v[184:187], v[206:209], v[96:99]
	v_mfma_f32_16x16x32_bf16 v[84:87], v[172:175], v[214:217], v[84:87]
	v_mfma_f32_16x16x32_bf16 v[80:83], v[184:187], v[214:217], v[80:83]
	v_mfma_f32_16x16x32_bf16 v[68:71], v[172:175], v[222:225], v[68:71]
	v_mfma_f32_16x16x32_bf16 v[64:67], v[184:187], v[222:225], v[64:67]
	s_setprio 0
	s_barrier
; #define PG8_STAGE(bufoff, gbase, voff) do { _Pragma("unroll") for (int _i = 0; _i < 2; ++_i) \
;         __builtin_amdgcn_global_load_lds((const unsigned*)((const char*)(gbase) + (voff)[_i]), (PG8_LAS unsigned*)(lds + (bufoff) + ldsw + _i * 8192), 16, 0, 0); } while (0)
; #define PG8_LDA(dst, b, h) do { _Pragma("unroll") for (int m = 0; m < 4; ++m) _Pragma("unroll") for (int k = 0; k < 2; ++k) dst[m][k] = *(const PG8_LAS bf16x8*)(lds + PG8_SA(b, h) + aoff + m * 2048 + k * 1024); } while (0)
; #define PG8_MMA(ai, bj, At, Bt) do { __builtin_amdgcn_s_setprio(1); _Pragma("unroll") for (int m = 0; m < 4; ++m) _Pragma("unroll") for (int n = 0; n < 2; ++n) _Pragma("unroll") for (int k = 0; k < 2; ++k) \
;         acc[ai][bj][m][n] = __builtin_amdgcn_mfma_f32_16x16x32_bf16(Bt[n][k], At[m][k], acc[ai][bj][m][n], 0, 0, 0); __builtin_amdgcn_s_setprio(0); } while (0)
; #define PG8_WAIT_V(n) asm volatile("s_waitcnt vmcnt(" #n ")" ::: "memory")
; #define PG8_WAIT_L(n) asm volatile("s_waitcnt lgkmcnt(" #n ")" ::: "memory")
; #define PG8_BAR __builtin_amdgcn_s_barrier()
; #define PG8_SCHED __builtin_amdgcn_sched_barrier(0)
; template <class Epi, class Sched, bool ALIGN_EPI = false, bool SP2 = false>
; __device__ __forceinline__ void gemm_phase(PG8_LAS unsigned char* lds, const Gemm g, const Sched& S, const Epi& E) {
;     ...
;             PG8_LDA(At, 1, 1); PG8_STAGE(PG8_SB(1, 0), b3, voffB); PG8_STAGE(PG8_SB(1, 1), b3 + hstep, voffB); PG8_STAGE(PG8_SA(1, 0), a3, voffA);
;             PG8_WAIT_V(8); PG8_WAIT_L(0); PG8_BAR; PG8_MMA(1, 0, At, B0); PG8_MMA(1, 1, At, B1); PG8_BAR; PG8_SCHED;
	s_add_i32 s54, s74, s15
	v_lshl_add_u64 v[200:201], v[200:201], 0, s[26:27]
	s_mov_b32 m0, s54
	ds_read_b128 v[188:191], v154 offset:49152
	ds_read_b128 v[192:195], v154 offset:50176
	ds_read_b128 v[196:199], v154 offset:51200
	ds_read_b128 v[206:209], v154 offset:52224
	ds_read_b128 v[210:213], v154 offset:53248
	ds_read_b128 v[214:217], v154 offset:54272
	ds_read_b128 v[218:221], v154 offset:55296
	ds_read_b128 v[222:225], v154 offset:56320
	global_load_lds_dwordx4 v[200:201], off
	s_add_i32 m0, s54, 0x2000
	s_add_u32 s52, s52, 0x40080
	v_lshl_add_u64 v[200:201], v[226:227], 0, s[26:27]
	s_addc_u32 s53, s53, 0
	s_add_i32 s54, s75, s15
	global_load_lds_dwordx4 v[200:201], off
	v_lshl_add_u64 v[200:201], s[52:53], 0, v[130:131]
	s_mov_b32 m0, s54
	s_nop 0
	global_load_lds_dwordx4 v[200:201], off
	v_lshl_add_u64 v[200:201], s[52:53], 0, v[134:135]
	s_add_i32 m0, s54, 0x2000
	s_nop 0
	global_load_lds_dwordx4 v[200:201], off
	v_lshl_add_u64 v[200:201], v[228:229], 0, s[26:27]
	s_mov_b32 m0, s58
	s_nop 0
	global_load_lds_dwordx4 v[200:201], off
	v_lshl_add_u64 v[200:201], v[230:231], 0, s[26:27]
	s_mov_b32 m0, s59
	s_nop 0
	global_load_lds_dwordx4 v[200:201], off
	s_waitcnt vmcnt(8)
	s_waitcnt lgkmcnt(0)
	s_barrier
	s_setprio 1
	s_waitcnt lgkmcnt(0)
	v_mfma_f32_16x16x32_bf16 v[60:63], v[146:149], v[188:191], v[60:63]
	v_mfma_f32_16x16x32_bf16 v[56:59], v[160:163], v[188:191], v[56:59]
	v_mfma_f32_16x16x32_bf16 v[44:47], v[146:149], v[196:199], v[44:47]
	v_mfma_f32_16x16x32_bf16 v[40:43], v[160:163], v[196:199], v[40:43]
	v_mfma_f32_16x16x32_bf16 v[28:31], v[146:149], v[210:213], v[28:31]
	v_mfma_f32_16x16x32_bf16 v[24:27], v[160:163], v[210:213], v[24:27]
	v_mfma_f32_16x16x32_bf16 v[12:15], v[146:149], v[218:221], v[12:15]
	v_mfma_f32_16x16x32_bf16 v[8:11], v[160:163], v[218:221], v[8:11]
	v_mfma_f32_16x16x32_bf16 v[60:63], v[156:159], v[192:195], v[60:63]
	v_mfma_f32_16x16x32_bf16 v[56:59], v[164:167], v[192:195], v[56:59]
	v_mfma_f32_16x16x32_bf16 v[44:47], v[156:159], v[206:209], v[44:47]
	v_mfma_f32_16x16x32_bf16 v[40:43], v[164:167], v[206:209], v[40:43]
	v_mfma_f32_16x16x32_bf16 v[28:31], v[156:159], v[214:217], v[28:31]
	v_mfma_f32_16x16x32_bf16 v[24:27], v[164:167], v[214:217], v[24:27]
	v_mfma_f32_16x16x32_bf16 v[12:15], v[156:159], v[222:225], v[12:15]
	v_mfma_f32_16x16x32_bf16 v[8:11], v[164:167], v[222:225], v[8:11]
	s_setprio 0
	s_setprio 1
	v_mfma_f32_16x16x32_bf16 v[52:55], v[168:171], v[188:191], v[52:55]
	v_mfma_f32_16x16x32_bf16 v[48:51], v[180:183], v[188:191], v[48:51]
	v_mfma_f32_16x16x32_bf16 v[36:39], v[168:171], v[196:199], v[36:39]
	v_mfma_f32_16x16x32_bf16 v[32:35], v[180:183], v[196:199], v[32:35]
	v_mfma_f32_16x16x32_bf16 v[20:23], v[168:171], v[210:213], v[20:23]
	v_mfma_f32_16x16x32_bf16 v[16:19], v[180:183], v[210:213], v[16:19]
	v_mfma_f32_16x16x32_bf16 v[4:7], v[168:171], v[218:221], v[4:7]
	v_mfma_f32_16x16x32_bf16 v[0:3], v[180:183], v[218:221], v[0:3]
	v_mfma_f32_16x16x32_bf16 v[52:55], v[172:175], v[192:195], v[52:55]
	v_mfma_f32_16x16x32_bf16 v[48:51], v[184:187], v[192:195], v[48:51]
	v_mfma_f32_16x16x32_bf16 v[36:39], v[172:175], v[206:209], v[36:39]
	v_mfma_f32_16x16x32_bf16 v[32:35], v[184:187], v[206:209], v[32:35]
	v_mfma_f32_16x16x32_bf16 v[20:23], v[172:175], v[214:217], v[20:23]
	v_mfma_f32_16x16x32_bf16 v[16:19], v[184:187], v[214:217], v[16:19]
	v_mfma_f32_16x16x32_bf16 v[4:7], v[172:175], v[222:225], v[4:7]
	v_mfma_f32_16x16x32_bf16 v[0:3], v[184:187], v[222:225], v[0:3]
	s_setprio 0
	s_barrier
	s_add_i32 s67, s67, 2
	s_add_u32 s50, s50, 0x100
	s_addc_u32 s51, s51, 0
	s_add_u32 s65, s65, 0x100
	s_addc_u32 s66, s66, 0
	s_cmp_gt_u32 s67, 13
	s_cbranch_scc0 .LBB0_1593
	s_and_b64 vcc, exec, s[28:29]
	s_cbranch_vccz .LBB0_1596
	s_barrier

; #define PG8_STAGE(bufoff, gbase, voff) do { _Pragma("unroll") for (int _i = 0; _i < 2; ++_i) \
;         __builtin_amdgcn_global_load_lds((const unsigned*)((const char*)(gbase) + (voff)[_i]), (PG8_LAS unsigned*)(lds + (bufoff) + ldsw + _i * 8192), 16, 0, 0); } while (0)
; #define PG8_LDA(dst, b, h) do { _Pragma("unroll") for (int m = 0; m < 4; ++m) _Pragma("unroll") for (int k = 0; k < 2; ++k) dst[m][k] = *(const PG8_LAS bf16x8*)(lds + PG8_SA(b, h) + aoff + m * 2048 + k * 1024); } while (0)
; #define PG8_LDB(dst, b, h) do { _Pragma("unroll") for (int n = 0; n < 2; ++n) _Pragma("unroll") for (int k = 0; k < 2; ++k) dst[n][k] = *(const PG8_LAS bf16x8*)(lds + PG8_SB(b, h) + boff + n * 2048 + k * 1024); } while (0)
; #define PG8_MMA(ai, bj, At, Bt) do { __builtin_amdgcn_s_setprio(1); _Pragma("unroll") for (int m = 0; m < 4; ++m) _Pragma("unroll") for (int n = 0; n < 2; ++n) _Pragma("unroll") for (int k = 0; k < 2; ++k) \
;         acc[ai][bj][m][n] = __builtin_amdgcn_mfma_f32_16x16x32_bf16(Bt[n][k], At[m][k], acc[ai][bj][m][n], 0, 0, 0); __builtin_amdgcn_s_setprio(0); } while (0)
; template <class Epi, class Sched, bool ALIGN_EPI = false, bool SP2 = false>
; __device__ __forceinline__ void gemm_phase(PG8_LAS unsigned char* lds, const Gemm g, const Sched& S, const Epi& E) {
;     ...
;         const bool has_next = S.next(ui + 1, nxt);
;         const char* nA = has_next ? (const char*)g.A + (size_t)nxt.pm * tstep : cA; const char* nB = has_next ? (const char*)g.Bt + (size_t)nxt.pn * tstep : cB;
;         for (int t = 0; t < nt; t += 2) {
;             const bool last = (t == nt - 2);
;             const char* a1 = cA + (size_t)(t + 1) * kstep;
;             const char* a2 = last ? nA : cA + (size_t)(t + 2) * kstep; const char* b2 = last ? nB : cB + (size_t)(t + 2) * kstep;
;             const char* a3 = a2 + kstep; const char* b3 = b2 + kstep;
;     ...
;             PG8_LDB(B0, 0, 0); PG8_LDB(B1, 0, 1); PG8_SCHED; PG8_LDA(At, 0, 0); PG8_STAGE(PG8_SA(1, 1), a1 + hstep, voffA);
;             PG8_WAIT_V(8); PG8_WAIT_L(0); PG8_BAR; PG8_MMA(0, 0, At, B0); PG8_MMA(0, 1, At, B1); PG8_BAR; PG8_SCHED;
;             PG8_LDA(At, 0, 1); PG8_STAGE(PG8_SB(0, 0), b2, voffB); PG8_STAGE(PG8_SB(0, 1), b2 + hstep, voffB); PG8_STAGE(PG8_SA(0, 0), a2, voffA);
;             PG8_WAIT_V(8); PG8_WAIT_L(0); PG8_BAR; PG8_MMA(1, 0, At, B0); PG8_MMA(1, 1, At, B1); PG8_BAR; PG8_SCHED;
.LBB0_1815:
	s_ashr_i32 s29, s28, 31
	s_lshl_b64 s[36:37], s[28:29], 18
	s_add_u32 s36, s92, s36
	s_addc_u32 s37, s93, s37
	s_and_b64 s[38:39], s[6:7], exec
	s_cselect_b32 s29, s37, s45
	s_cselect_b32 s41, s36, s44
	s_ashr_i32 s27, s26, 31
	s_lshl_b64 s[38:39], s[26:27], 18
	s_add_u32 s38, s3, s38
	s_addc_u32 s39, s14, s39
	s_and_b64 s[48:49], s[6:7], exec
	s_cselect_b32 s27, s39, s47
	s_cselect_b32 s58, s38, s46
	s_add_u32 s44, s44, 0x20080
	s_addc_u32 s45, s45, 0
	s_add_u32 s59, s46, 0x100
	s_addc_u32 s60, s47, 0
	s_mov_b32 s61, -2
	s_waitcnt lgkmcnt(0)
	ds_read_b128 v[144:147], v151
	ds_read_b128 v[156:159], v151 offset:1024
	ds_read_b128 v[160:163], v151 offset:2048
	ds_read_b128 v[164:167], v151 offset:3072
	ds_read_b128 v[168:171], v152
	ds_read_b128 v[172:175], v152 offset:1024
	ds_read_b128 v[176:179], v152 offset:2048
	ds_read_b128 v[180:183], v152 offset:3072
	s_add_u32 s46, s44, 0xfffe0080
	s_addc_u32 s47, s45, -1
	s_cmp_eq_u32 s61, 4
	s_cselect_b32 s49, s29, s47
	s_cselect_b32 s48, s41, s46
	s_cselect_b32 s47, s27, s60
	s_cselect_b32 s46, s58, s59
	v_lshl_add_u64 v[218:219], s[44:45], 0, v[136:137]
	s_add_i32 m0, s33, 0xc000
	ds_read_b128 v[184:187], v153
	ds_read_b128 v[188:191], v153 offset:1024
	ds_read_b128 v[192:195], v153 offset:2048
	ds_read_b128 v[196:199], v153 offset:3072
	ds_read_b128 v[200:203], v153 offset:4096
	ds_read_b128 v[206:209], v153 offset:5120
	ds_read_b128 v[210:213], v153 offset:6144
	ds_read_b128 v[214:217], v153 offset:7168
	global_load_lds_dwordx4 v[218:219], off
	v_lshl_add_u64 v[218:219], s[44:45], 0, v[138:139]
	s_add_i32 m0, s33, 0xe000
	s_nop 0
	global_load_lds_dwordx4 v[218:219], off
	s_waitcnt vmcnt(8)
	s_waitcnt lgkmcnt(0)
	s_barrier
	s_setprio 1
	s_waitcnt lgkmcnt(0)
	v_mfma_f32_16x16x32_bf16 v[124:127], v[144:147], v[184:187], 0
	v_mfma_f32_16x16x32_bf16 v[120:123], v[160:163], v[184:187], 0
	v_mfma_f32_16x16x32_bf16 v[108:111], v[144:147], v[192:195], 0
	v_mfma_f32_16x16x32_bf16 v[104:107], v[160:163], v[192:195], 0
	v_mfma_f32_16x16x32_bf16 v[92:95], v[144:147], v[200:203], 0
	v_mfma_f32_16x16x32_bf16 v[88:91], v[160:163], v[200:203], 0
	v_mfma_f32_16x16x32_bf16 v[76:79], v[144:147], v[210:213], 0
	v_mfma_f32_16x16x32_bf16 v[72:75], v[160:163], v[210:213], 0
	v_mfma_f32_16x16x32_bf16 v[124:127], v[156:159], v[188:191], v[124:127]
	v_mfma_f32_16x16x32_bf16 v[120:123], v[164:167], v[188:191], v[120:123]
	v_mfma_f32_16x16x32_bf16 v[108:111], v[156:159], v[196:199], v[108:111]
	v_mfma_f32_16x16x32_bf16 v[104:107], v[164:167], v[196:199], v[104:107]
	v_mfma_f32_16x16x32_bf16 v[92:95], v[156:159], v[206:209], v[92:95]
	v_mfma_f32_16x16x32_bf16 v[88:91], v[164:167], v[206:209], v[88:91]
	v_mfma_f32_16x16x32_bf16 v[76:79], v[156:159], v[214:217], v[76:79]
	v_mfma_f32_16x16x32_bf16 v[72:75], v[164:167], v[214:217], v[72:75]
	s_setprio 0
	s_setprio 1
	v_mfma_f32_16x16x32_bf16 v[116:119], v[168:171], v[184:187], 0
	v_mfma_f32_16x16x32_bf16 v[112:115], v[176:179], v[184:187], 0
	v_mfma_f32_16x16x32_bf16 v[100:103], v[168:171], v[192:195], 0
	v_mfma_f32_16x16x32_bf16 v[96:99], v[176:179], v[192:195], 0
	v_mfma_f32_16x16x32_bf16 v[84:87], v[168:171], v[200:203], 0
	v_mfma_f32_16x16x32_bf16 v[80:83], v[176:179], v[200:203], 0
	v_mfma_f32_16x16x32_bf16 v[68:71], v[168:171], v[210:213], 0
	v_mfma_f32_16x16x32_bf16 v[64:67], v[176:179], v[210:213], 0
	v_mfma_f32_16x16x32_bf16 v[116:119], v[172:175], v[188:191], v[116:119]
	v_mfma_f32_16x16x32_bf16 v[112:115], v[180:183], v[188:191], v[112:115]
	v_mfma_f32_16x16x32_bf16 v[100:103], v[172:175], v[196:199], v[100:103]
	v_mfma_f32_16x16x32_bf16 v[96:99], v[180:183], v[196:199], v[96:99]
	v_mfma_f32_16x16x32_bf16 v[84:87], v[172:175], v[206:209], v[84:87]
	v_mfma_f32_16x16x32_bf16 v[80:83], v[180:183], v[206:209], v[80:83]
	v_mfma_f32_16x16x32_bf16 v[68:71], v[172:175], v[214:217], v[68:71]
	v_mfma_f32_16x16x32_bf16 v[64:67], v[180:183], v[214:217], v[64:67]
	s_setprio 0
	s_barrier
	s_add_i32 s62, s54, s15
	v_lshl_add_u64 v[218:219], s[46:47], 0, v[130:131]
	s_mov_b32 m0, s62
	ds_read_b128 v[184:187], v153 offset:16384
	ds_read_b128 v[188:191], v153 offset:17408
	ds_read_b128 v[192:195], v153 offset:18432
	ds_read_b128 v[196:199], v153 offset:19456
	ds_read_b128 v[200:203], v153 offset:20480
	ds_read_b128 v[206:209], v153 offset:21504
	ds_read_b128 v[210:213], v153 offset:22528
	ds_read_b128 v[214:217], v153 offset:23552
	global_load_lds_dwordx4 v[218:219], off
	s_add_i32 m0, s62, 0x2000
	s_add_u32 s62, s46, 0x20000
	v_lshl_add_u64 v[220:221], s[46:47], 0, v[134:135]
	s_addc_u32 s63, s47, 0
	s_add_i32 s64, s55, s15
	global_load_lds_dwordx4 v[220:221], off
	v_lshl_add_u64 v[222:223], s[62:63], 0, v[130:131]
	s_mov_b32 m0, s64
	global_load_lds_dwordx4 v[222:223], off
	v_lshl_add_u64 v[222:223], s[62:63], 0, v[134:135]
	s_add_i32 m0, s64, 0x2000
	s_nop 0
	global_load_lds_dwordx4 v[222:223], off
	v_lshl_add_u64 v[222:223], s[48:49], 0, v[128:129]
	s_mov_b32 m0, s33
	s_nop 0
	global_load_lds_dwordx4 v[222:223], off
	v_lshl_add_u64 v[224:225], s[48:49], 0, v[132:133]
	s_mov_b32 m0, s34
	s_nop 0
	global_load_lds_dwordx4 v[224:225], off
	s_waitcnt vmcnt(8)
	s_waitcnt lgkmcnt(0)
	s_barrier
; #define PG8_STAGE(bufoff, gbase, voff) do { _Pragma("unroll") for (int _i = 0; _i < 2; ++_i) \
;         __builtin_amdgcn_global_load_lds((const unsigned*)((const char*)(gbase) + (voff)[_i]), (PG8_LAS unsigned*)(lds + (bufoff) + ldsw + _i * 8192), 16, 0, 0); } while (0)
; #define PG8_LDA(dst, b, h) do { _Pragma("unroll") for (int m = 0; m < 4; ++m) _Pragma("unroll") for (int k = 0; k < 2; ++k) dst[m][k] = *(const PG8_LAS bf16x8*)(lds + PG8_SA(b, h) + aoff + m * 2048 + k * 1024); } while (0)
; #define PG8_LDB(dst, b, h) do { _Pragma("unroll") for (int n = 0; n < 2; ++n) _Pragma("unroll") for (int k = 0; k < 2; ++k) dst[n][k] = *(const PG8_LAS bf16x8*)(lds + PG8_SB(b, h) + boff + n * 2048 + k * 1024); } while (0)
; #define PG8_MMA(ai, bj, At, Bt) do { __builtin_amdgcn_s_setprio(1); _Pragma("unroll") for (int m = 0; m < 4; ++m) _Pragma("unroll") for (int n = 0; n < 2; ++n) _Pragma("unroll") for (int k = 0; k < 2; ++k) \
;         acc[ai][bj][m][n] = __builtin_amdgcn_mfma_f32_16x16x32_bf16(Bt[n][k], At[m][k], acc[ai][bj][m][n], 0, 0, 0); __builtin_amdgcn_s_setprio(0); } while (0)
; #define PG8_WAIT_V(n) asm volatile("s_waitcnt vmcnt(" #n ")" ::: "memory")
; #define PG8_WAIT_L(n) asm volatile("s_waitcnt lgkmcnt(" #n ")" ::: "memory")
; #define PG8_BAR __builtin_amdgcn_s_barrier()
; #define PG8_SCHED __builtin_amdgcn_sched_barrier(0)
; template <class Epi, class Sched, bool ALIGN_EPI = false, bool SP2 = false>
; __device__ __forceinline__ void gemm_phase(PG8_LAS unsigned char* lds, const Gemm g, const Sched& S, const Epi& E) {
;     ...
;             PG8_WAIT_V(8); PG8_WAIT_L(0); PG8_BAR; PG8_MMA(1, 0, At, B0); PG8_MMA(1, 1, At, B1); PG8_BAR; PG8_SCHED;
;             PG8_LDB(B0, 1, 0); PG8_LDB(B1, 1, 1); PG8_SCHED; PG8_LDA(At, 1, 0); PG8_STAGE(PG8_SA(0, 1), a2 + hstep, voffA);
;             PG8_WAIT_V(8); PG8_WAIT_L(0); PG8_BAR; PG8_MMA(0, 0, At, B0); PG8_MMA(0, 1, At, B1); PG8_BAR; PG8_SCHED;
	s_setprio 1
	s_waitcnt lgkmcnt(0)
	v_mfma_f32_16x16x32_bf16 v[60:63], v[144:147], v[184:187], 0
	v_mfma_f32_16x16x32_bf16 v[56:59], v[160:163], v[184:187], 0
	v_mfma_f32_16x16x32_bf16 v[44:47], v[144:147], v[192:195], 0
	v_mfma_f32_16x16x32_bf16 v[40:43], v[160:163], v[192:195], 0
	v_mfma_f32_16x16x32_bf16 v[28:31], v[144:147], v[200:203], 0
	v_mfma_f32_16x16x32_bf16 v[24:27], v[160:163], v[200:203], 0
	v_mfma_f32_16x16x32_bf16 v[12:15], v[144:147], v[210:213], 0
	v_mfma_f32_16x16x32_bf16 v[8:11], v[160:163], v[210:213], 0
	v_mfma_f32_16x16x32_bf16 v[60:63], v[156:159], v[188:191], v[60:63]
	v_mfma_f32_16x16x32_bf16 v[56:59], v[164:167], v[188:191], v[56:59]
	v_mfma_f32_16x16x32_bf16 v[44:47], v[156:159], v[196:199], v[44:47]
	v_mfma_f32_16x16x32_bf16 v[40:43], v[164:167], v[196:199], v[40:43]
	v_mfma_f32_16x16x32_bf16 v[28:31], v[156:159], v[206:209], v[28:31]
	v_mfma_f32_16x16x32_bf16 v[24:27], v[164:167], v[206:209], v[24:27]
	v_mfma_f32_16x16x32_bf16 v[12:15], v[156:159], v[214:217], v[12:15]
	v_mfma_f32_16x16x32_bf16 v[8:11], v[164:167], v[214:217], v[8:11]
	s_setprio 0
	s_setprio 1
	v_mfma_f32_16x16x32_bf16 v[52:55], v[168:171], v[184:187], 0
	v_mfma_f32_16x16x32_bf16 v[48:51], v[176:179], v[184:187], 0
	v_mfma_f32_16x16x32_bf16 v[36:39], v[168:171], v[192:195], 0
	v_mfma_f32_16x16x32_bf16 v[32:35], v[176:179], v[192:195], 0
	v_mfma_f32_16x16x32_bf16 v[20:23], v[168:171], v[200:203], 0
	v_mfma_f32_16x16x32_bf16 v[16:19], v[176:179], v[200:203], 0
	v_mfma_f32_16x16x32_bf16 v[4:7], v[168:171], v[210:213], 0
	v_mfma_f32_16x16x32_bf16 v[0:3], v[176:179], v[210:213], 0
	v_mfma_f32_16x16x32_bf16 v[52:55], v[172:175], v[188:191], v[52:55]
	v_mfma_f32_16x16x32_bf16 v[48:51], v[180:183], v[188:191], v[48:51]
	v_mfma_f32_16x16x32_bf16 v[36:39], v[172:175], v[196:199], v[36:39]
	v_mfma_f32_16x16x32_bf16 v[32:35], v[180:183], v[196:199], v[32:35]
	v_mfma_f32_16x16x32_bf16 v[20:23], v[172:175], v[206:209], v[20:23]
	v_mfma_f32_16x16x32_bf16 v[16:19], v[180:183], v[206:209], v[16:19]
	v_mfma_f32_16x16x32_bf16 v[4:7], v[172:175], v[214:217], v[4:7]
	v_mfma_f32_16x16x32_bf16 v[0:3], v[180:183], v[214:217], v[0:3]
	s_setprio 0
	s_barrier
	s_add_i32 s62, 0, 0x18000
	v_add_u32_e32 v155, s62, v149
	s_add_i32 s63, 0, 0x1c000
	ds_read_b128 v[144:147], v155
	ds_read_b128 v[156:159], v155 offset:1024
	ds_read_b128 v[160:163], v155 offset:2048
	ds_read_b128 v[164:167], v155 offset:3072
	v_add_u32_e32 v155, s63, v149
	ds_read_b128 v[168:171], v155
	ds_read_b128 v[172:175], v155 offset:1024
	ds_read_b128 v[176:179], v155 offset:2048
	ds_read_b128 v[180:183], v155 offset:3072
	s_add_u32 s48, s48, 0x20000
	s_addc_u32 s49, s49, 0
	s_mov_b32 m0, s43
	v_lshl_add_u64 v[226:227], s[48:49], 0, v[128:129]
	ds_read_b128 v[184:187], v153 offset:32768
	ds_read_b128 v[188:191], v153 offset:33792
	ds_read_b128 v[192:195], v153 offset:34816
	ds_read_b128 v[196:199], v153 offset:35840
	ds_read_b128 v[200:203], v153 offset:36864
	ds_read_b128 v[206:209], v153 offset:37888
	ds_read_b128 v[210:213], v153 offset:38912
	ds_read_b128 v[214:217], v153 offset:39936
	global_load_lds_dwordx4 v[226:227], off
	v_lshl_add_u64 v[226:227], s[48:49], 0, v[132:133]
	s_mov_b32 m0, s50
	s_nop 0
	global_load_lds_dwordx4 v[226:227], off
	s_waitcnt vmcnt(8)
	s_waitcnt lgkmcnt(0)
	s_barrier
	s_setprio 1
	s_waitcnt lgkmcnt(0)
	v_mfma_f32_16x16x32_bf16 v[124:127], v[144:147], v[184:187], v[124:127]
	v_mfma_f32_16x16x32_bf16 v[120:123], v[160:163], v[184:187], v[120:123]
	v_mfma_f32_16x16x32_bf16 v[108:111], v[144:147], v[192:195], v[108:111]
	v_mfma_f32_16x16x32_bf16 v[104:107], v[160:163], v[192:195], v[104:107]
	v_mfma_f32_16x16x32_bf16 v[92:95], v[144:147], v[200:203], v[92:95]
	v_mfma_f32_16x16x32_bf16 v[88:91], v[160:163], v[200:203], v[88:91]
	v_mfma_f32_16x16x32_bf16 v[76:79], v[144:147], v[210:213], v[76:79]
	v_mfma_f32_16x16x32_bf16 v[72:75], v[160:163], v[210:213], v[72:75]
	v_mfma_f32_16x16x32_bf16 v[124:127], v[156:159], v[188:191], v[124:127]
	v_mfma_f32_16x16x32_bf16 v[120:123], v[164:167], v[188:191], v[120:123]
	v_mfma_f32_16x16x32_bf16 v[108:111], v[156:159], v[196:199], v[108:111]
	v_mfma_f32_16x16x32_bf16 v[104:107], v[164:167], v[196:199], v[104:107]
	v_mfma_f32_16x16x32_bf16 v[92:95], v[156:159], v[206:209], v[92:95]
	v_mfma_f32_16x16x32_bf16 v[88:91], v[164:167], v[206:209], v[88:91]
	v_mfma_f32_16x16x32_bf16 v[76:79], v[156:159], v[214:217], v[76:79]
	v_mfma_f32_16x16x32_bf16 v[72:75], v[164:167], v[214:217], v[72:75]
	s_setprio 0
	s_setprio 1
	v_mfma_f32_16x16x32_bf16 v[116:119], v[168:171], v[184:187], v[116:119]
	v_mfma_f32_16x16x32_bf16 v[112:115], v[176:179], v[184:187], v[112:115]
	v_mfma_f32_16x16x32_bf16 v[100:103], v[168:171], v[192:195], v[100:103]
	v_mfma_f32_16x16x32_bf16 v[96:99], v[176:179], v[192:195], v[96:99]
	v_mfma_f32_16x16x32_bf16 v[84:87], v[168:171], v[200:203], v[84:87]
	v_mfma_f32_16x16x32_bf16 v[80:83], v[176:179], v[200:203], v[80:83]
	v_mfma_f32_16x16x32_bf16 v[68:71], v[168:171], v[210:213], v[68:71]
	v_mfma_f32_16x16x32_bf16 v[64:67], v[176:179], v[210:213], v[64:67]
	v_mfma_f32_16x16x32_bf16 v[116:119], v[172:175], v[188:191], v[116:119]
	v_mfma_f32_16x16x32_bf16 v[112:115], v[180:183], v[188:191], v[112:115]
	v_mfma_f32_16x16x32_bf16 v[100:103], v[172:175], v[196:199], v[100:103]
	v_mfma_f32_16x16x32_bf16 v[96:99], v[180:183], v[196:199], v[96:99]
	v_mfma_f32_16x16x32_bf16 v[84:87], v[172:175], v[206:209], v[84:87]
	v_mfma_f32_16x16x32_bf16 v[80:83], v[180:183], v[206:209], v[80:83]
	v_mfma_f32_16x16x32_bf16 v[68:71], v[172:175], v[214:217], v[68:71]
	v_mfma_f32_16x16x32_bf16 v[64:67], v[180:183], v[214:217], v[64:67]
	s_setprio 0
	s_barrier
; #define PG8_STAGE(bufoff, gbase, voff) do { _Pragma("unroll") for (int _i = 0; _i < 2; ++_i) \
;         __builtin_amdgcn_global_load_lds((const unsigned*)((const char*)(gbase) + (voff)[_i]), (PG8_LAS unsigned*)(lds + (bufoff) + ldsw + _i * 8192), 16, 0, 0); } while (0)
; #define PG8_LDA(dst, b, h) do { _Pragma("unroll") for (int m = 0; m < 4; ++m) _Pragma("unroll") for (int k = 0; k < 2; ++k) dst[m][k] = *(const PG8_LAS bf16x8*)(lds + PG8_SA(b, h) + aoff + m * 2048 + k * 1024); } while (0)
; #define PG8_LDB(dst, b, h) do { _Pragma("unroll") for (int n = 0; n < 2; ++n) _Pragma("unroll") for (int k = 0; k < 2; ++k) dst[n][k] = *(const PG8_LAS bf16x8*)(lds + PG8_SB(b, h) + boff + n * 2048 + k * 1024); } while (0)
; #define PG8_MMA(ai, bj, At, Bt) do { __builtin_amdgcn_s_setprio(1); _Pragma("unroll") for (int m = 0; m < 4; ++m) _Pragma("unroll") for (int n = 0; n < 2; ++n) _Pragma("unroll") for (int k = 0; k < 2; ++k) \
;         acc[ai][bj][m][n] = __builtin_amdgcn_mfma_f32_16x16x32_bf16(Bt[n][k], At[m][k], acc[ai][bj][m][n], 0, 0, 0); __builtin_amdgcn_s_setprio(0); } while (0)
; #define PG8_WAIT_V(n) asm volatile("s_waitcnt vmcnt(" #n ")" ::: "memory")
; #define PG8_WAIT_L(n) asm volatile("s_waitcnt lgkmcnt(" #n ")" ::: "memory")
; #define PG8_BAR __builtin_amdgcn_s_barrier()
; #define PG8_SCHED __builtin_amdgcn_sched_barrier(0)
; template <class Epi, class Sched, bool ALIGN_EPI = false, bool SP2 = false>
; __device__ __forceinline__ void gemm_phase(PG8_LAS unsigned char* lds, const Gemm g, const Sched& S, const Epi& E) {
;     ...
;             PG8_LDB(B0, 0, 0); PG8_LDB(B1, 0, 1); PG8_SCHED; PG8_LDA(At, 0, 0); PG8_STAGE(PG8_SA(1, 1), a1 + hstep, voffA);
;             PG8_WAIT_V(8); PG8_WAIT_L(0); PG8_BAR; PG8_MMA(0, 0, At, B0); PG8_MMA(0, 1, At, B1); PG8_BAR; PG8_SCHED;
;     ...
;             PG8_LDA(At, 1, 1); PG8_STAGE(PG8_SB(1, 0), b3, voffB); PG8_STAGE(PG8_SB(1, 1), b3 + hstep, voffB); PG8_STAGE(PG8_SA(1, 0), a3, voffA);
;             PG8_WAIT_V(8); PG8_WAIT_L(0); PG8_BAR; PG8_MMA(1, 0, At, B0); PG8_MMA(1, 1, At, B1); PG8_BAR; PG8_SCHED;
	s_add_i32 s48, s62, s15
	v_lshl_add_u64 v[218:219], v[218:219], 0, s[12:13]
	s_mov_b32 m0, s48
	ds_read_b128 v[184:187], v153 offset:49152
	ds_read_b128 v[188:191], v153 offset:50176
	ds_read_b128 v[192:195], v153 offset:51200
	ds_read_b128 v[196:199], v153 offset:52224
	ds_read_b128 v[200:203], v153 offset:53248
	ds_read_b128 v[206:209], v153 offset:54272
	ds_read_b128 v[210:213], v153 offset:55296
	ds_read_b128 v[214:217], v153 offset:56320
	global_load_lds_dwordx4 v[218:219], off
	s_add_i32 m0, s48, 0x2000
	s_add_u32 s46, s46, 0x20080
	v_lshl_add_u64 v[218:219], v[220:221], 0, s[12:13]
	s_addc_u32 s47, s47, 0
	s_add_i32 s48, s63, s15
	global_load_lds_dwordx4 v[218:219], off
	v_lshl_add_u64 v[218:219], s[46:47], 0, v[130:131]
	s_mov_b32 m0, s48
	s_nop 0
	global_load_lds_dwordx4 v[218:219], off
	v_lshl_add_u64 v[218:219], s[46:47], 0, v[134:135]
	s_add_i32 m0, s48, 0x2000
	s_nop 0
	global_load_lds_dwordx4 v[218:219], off
	v_lshl_add_u64 v[218:219], v[222:223], 0, s[12:13]
	s_mov_b32 m0, s52
	s_nop 0
	global_load_lds_dwordx4 v[218:219], off
	v_lshl_add_u64 v[218:219], v[224:225], 0, s[12:13]
	s_mov_b32 m0, s53
	s_nop 0
	global_load_lds_dwordx4 v[218:219], off
	s_waitcnt vmcnt(8)
	s_waitcnt lgkmcnt(0)
	s_barrier
	s_setprio 1
	s_waitcnt lgkmcnt(0)
	v_mfma_f32_16x16x32_bf16 v[60:63], v[144:147], v[184:187], v[60:63]
	v_mfma_f32_16x16x32_bf16 v[56:59], v[160:163], v[184:187], v[56:59]
	v_mfma_f32_16x16x32_bf16 v[44:47], v[144:147], v[192:195], v[44:47]
	v_mfma_f32_16x16x32_bf16 v[40:43], v[160:163], v[192:195], v[40:43]
	v_mfma_f32_16x16x32_bf16 v[28:31], v[144:147], v[200:203], v[28:31]
	v_mfma_f32_16x16x32_bf16 v[24:27], v[160:163], v[200:203], v[24:27]
	v_mfma_f32_16x16x32_bf16 v[12:15], v[144:147], v[210:213], v[12:15]
	v_mfma_f32_16x16x32_bf16 v[8:11], v[160:163], v[210:213], v[8:11]
	v_mfma_f32_16x16x32_bf16 v[60:63], v[156:159], v[188:191], v[60:63]
	v_mfma_f32_16x16x32_bf16 v[56:59], v[164:167], v[188:191], v[56:59]
	v_mfma_f32_16x16x32_bf16 v[44:47], v[156:159], v[196:199], v[44:47]
	v_mfma_f32_16x16x32_bf16 v[40:43], v[164:167], v[196:199], v[40:43]
	v_mfma_f32_16x16x32_bf16 v[28:31], v[156:159], v[206:209], v[28:31]
	v_mfma_f32_16x16x32_bf16 v[24:27], v[164:167], v[206:209], v[24:27]
	v_mfma_f32_16x16x32_bf16 v[12:15], v[156:159], v[214:217], v[12:15]
	v_mfma_f32_16x16x32_bf16 v[8:11], v[164:167], v[214:217], v[8:11]
	s_setprio 0
	s_setprio 1
	v_mfma_f32_16x16x32_bf16 v[52:55], v[168:171], v[184:187], v[52:55]
	v_mfma_f32_16x16x32_bf16 v[48:51], v[176:179], v[184:187], v[48:51]
	v_mfma_f32_16x16x32_bf16 v[36:39], v[168:171], v[192:195], v[36:39]
	v_mfma_f32_16x16x32_bf16 v[32:35], v[176:179], v[192:195], v[32:35]
	v_mfma_f32_16x16x32_bf16 v[20:23], v[168:171], v[200:203], v[20:23]
	v_mfma_f32_16x16x32_bf16 v[16:19], v[176:179], v[200:203], v[16:19]
	v_mfma_f32_16x16x32_bf16 v[4:7], v[168:171], v[210:213], v[4:7]
	v_mfma_f32_16x16x32_bf16 v[0:3], v[176:179], v[210:213], v[0:3]
	v_mfma_f32_16x16x32_bf16 v[52:55], v[172:175], v[188:191], v[52:55]
	v_mfma_f32_16x16x32_bf16 v[48:51], v[180:183], v[188:191], v[48:51]
	v_mfma_f32_16x16x32_bf16 v[36:39], v[172:175], v[196:199], v[36:39]
	v_mfma_f32_16x16x32_bf16 v[32:35], v[180:183], v[196:199], v[32:35]
	v_mfma_f32_16x16x32_bf16 v[20:23], v[172:175], v[206:209], v[20:23]
	v_mfma_f32_16x16x32_bf16 v[16:19], v[180:183], v[206:209], v[16:19]
	v_mfma_f32_16x16x32_bf16 v[4:7], v[172:175], v[214:217], v[4:7]
	v_mfma_f32_16x16x32_bf16 v[0:3], v[180:183], v[214:217], v[0:3]
	s_setprio 0
	s_barrier
	s_add_i32 s61, s61, 2
	s_add_u32 s44, s44, 0x100
	s_addc_u32 s45, s45, 0
	s_add_u32 s59, s59, 0x100
	s_addc_u32 s60, s60, 0
.LBB0_1816:
	ds_read_b128 v[144:147], v151
	ds_read_b128 v[156:159], v151 offset:1024
	ds_read_b128 v[160:163], v151 offset:2048
	ds_read_b128 v[164:167], v151 offset:3072
	ds_read_b128 v[168:171], v152
	ds_read_b128 v[172:175], v152 offset:1024
	ds_read_b128 v[176:179], v152 offset:2048
	ds_read_b128 v[180:183], v152 offset:3072
	s_add_u32 s46, s44, 0xfffe0080
	s_addc_u32 s47, s45, -1
	s_cmp_eq_u32 s61, 4
	s_cselect_b32 s49, s29, s47
	s_cselect_b32 s48, s41, s46
	s_cselect_b32 s47, s27, s60
	s_cselect_b32 s46, s58, s59
	v_lshl_add_u64 v[218:219], s[44:45], 0, v[136:137]
	s_add_i32 m0, s33, 0xc000
	ds_read_b128 v[184:187], v153
	ds_read_b128 v[188:191], v153 offset:1024
	ds_read_b128 v[192:195], v153 offset:2048
	ds_read_b128 v[196:199], v153 offset:3072
	ds_read_b128 v[200:203], v153 offset:4096
	ds_read_b128 v[206:209], v153 offset:5120
	ds_read_b128 v[210:213], v153 offset:6144
	ds_read_b128 v[214:217], v153 offset:7168
	global_load_lds_dwordx4 v[218:219], off
	v_lshl_add_u64 v[218:219], s[44:45], 0, v[138:139]
	s_add_i32 m0, s33, 0xe000
	s_nop 0
	global_load_lds_dwordx4 v[218:219], off
	s_waitcnt vmcnt(8)
	s_waitcnt lgkmcnt(0)
	s_barrier
; #define PG8_STAGE(bufoff, gbase, voff) do { _Pragma("unroll") for (int _i = 0; _i < 2; ++_i) \
;         __builtin_amdgcn_global_load_lds((const unsigned*)((const char*)(gbase) + (voff)[_i]), (PG8_LAS unsigned*)(lds + (bufoff) + ldsw + _i * 8192), 16, 0, 0); } while (0)
; #define PG8_LDA(dst, b, h) do { _Pragma("unroll") for (int m = 0; m < 4; ++m) _Pragma("unroll") for (int k = 0; k < 2; ++k) dst[m][k] = *(const PG8_LAS bf16x8*)(lds + PG8_SA(b, h) + aoff + m * 2048 + k * 1024); } while (0)
; #define PG8_MMA(ai, bj, At, Bt) do { __builtin_amdgcn_s_setprio(1); _Pragma("unroll") for (int m = 0; m < 4; ++m) _Pragma("unroll") for (int n = 0; n < 2; ++n) _Pragma("unroll") for (int k = 0; k < 2; ++k) \
;         acc[ai][bj][m][n] = __builtin_amdgcn_mfma_f32_16x16x32_bf16(Bt[n][k], At[m][k], acc[ai][bj][m][n], 0, 0, 0); __builtin_amdgcn_s_setprio(0); } while (0)
; #define PG8_WAIT_V(n) asm volatile("s_waitcnt vmcnt(" #n ")" ::: "memory")
; #define PG8_WAIT_L(n) asm volatile("s_waitcnt lgkmcnt(" #n ")" ::: "memory")
; #define PG8_BAR __builtin_amdgcn_s_barrier()
; #define PG8_SCHED __builtin_amdgcn_sched_barrier(0)
; template <class Epi, class Sched, bool ALIGN_EPI = false, bool SP2 = false>
; __device__ __forceinline__ void gemm_phase(PG8_LAS unsigned char* lds, const Gemm g, const Sched& S, const Epi& E) {
;     ...
;             PG8_WAIT_V(8); PG8_WAIT_L(0); PG8_BAR; PG8_MMA(0, 0, At, B0); PG8_MMA(0, 1, At, B1); PG8_BAR; PG8_SCHED;
;             PG8_LDA(At, 0, 1); PG8_STAGE(PG8_SB(0, 0), b2, voffB); PG8_STAGE(PG8_SB(0, 1), b2 + hstep, voffB); PG8_STAGE(PG8_SA(0, 0), a2, voffA);
;             PG8_WAIT_V(8); PG8_WAIT_L(0); PG8_BAR; PG8_MMA(1, 0, At, B0); PG8_MMA(1, 1, At, B1); PG8_BAR; PG8_SCHED;
	s_setprio 1
	s_waitcnt lgkmcnt(0)
	v_mfma_f32_16x16x32_bf16 v[124:127], v[144:147], v[184:187], v[124:127]
	v_mfma_f32_16x16x32_bf16 v[120:123], v[160:163], v[184:187], v[120:123]
	v_mfma_f32_16x16x32_bf16 v[108:111], v[144:147], v[192:195], v[108:111]
	v_mfma_f32_16x16x32_bf16 v[104:107], v[160:163], v[192:195], v[104:107]
	v_mfma_f32_16x16x32_bf16 v[92:95], v[144:147], v[200:203], v[92:95]
	v_mfma_f32_16x16x32_bf16 v[88:91], v[160:163], v[200:203], v[88:91]
	v_mfma_f32_16x16x32_bf16 v[76:79], v[144:147], v[210:213], v[76:79]
	v_mfma_f32_16x16x32_bf16 v[72:75], v[160:163], v[210:213], v[72:75]
	v_mfma_f32_16x16x32_bf16 v[124:127], v[156:159], v[188:191], v[124:127]
	v_mfma_f32_16x16x32_bf16 v[120:123], v[164:167], v[188:191], v[120:123]
	v_mfma_f32_16x16x32_bf16 v[108:111], v[156:159], v[196:199], v[108:111]
	v_mfma_f32_16x16x32_bf16 v[104:107], v[164:167], v[196:199], v[104:107]
	v_mfma_f32_16x16x32_bf16 v[92:95], v[156:159], v[206:209], v[92:95]
	v_mfma_f32_16x16x32_bf16 v[88:91], v[164:167], v[206:209], v[88:91]
	v_mfma_f32_16x16x32_bf16 v[76:79], v[156:159], v[214:217], v[76:79]
	v_mfma_f32_16x16x32_bf16 v[72:75], v[164:167], v[214:217], v[72:75]
	s_setprio 0
	s_setprio 1
	v_mfma_f32_16x16x32_bf16 v[116:119], v[168:171], v[184:187], v[116:119]
	v_mfma_f32_16x16x32_bf16 v[112:115], v[176:179], v[184:187], v[112:115]
	v_mfma_f32_16x16x32_bf16 v[100:103], v[168:171], v[192:195], v[100:103]
	v_mfma_f32_16x16x32_bf16 v[96:99], v[176:179], v[192:195], v[96:99]
	v_mfma_f32_16x16x32_bf16 v[84:87], v[168:171], v[200:203], v[84:87]
	v_mfma_f32_16x16x32_bf16 v[80:83], v[176:179], v[200:203], v[80:83]
	v_mfma_f32_16x16x32_bf16 v[68:71], v[168:171], v[210:213], v[68:71]
	v_mfma_f32_16x16x32_bf16 v[64:67], v[176:179], v[210:213], v[64:67]
	v_mfma_f32_16x16x32_bf16 v[116:119], v[172:175], v[188:191], v[116:119]
	v_mfma_f32_16x16x32_bf16 v[112:115], v[180:183], v[188:191], v[112:115]
	v_mfma_f32_16x16x32_bf16 v[100:103], v[172:175], v[196:199], v[100:103]
	v_mfma_f32_16x16x32_bf16 v[96:99], v[180:183], v[196:199], v[96:99]
	v_mfma_f32_16x16x32_bf16 v[84:87], v[172:175], v[206:209], v[84:87]
	v_mfma_f32_16x16x32_bf16 v[80:83], v[180:183], v[206:209], v[80:83]
	v_mfma_f32_16x16x32_bf16 v[68:71], v[172:175], v[214:217], v[68:71]
	v_mfma_f32_16x16x32_bf16 v[64:67], v[180:183], v[214:217], v[64:67]
	s_setprio 0
	s_barrier
	s_add_i32 s62, s54, s15
	v_lshl_add_u64 v[218:219], s[46:47], 0, v[130:131]
	s_mov_b32 m0, s62
	ds_read_b128 v[184:187], v153 offset:16384
	ds_read_b128 v[188:191], v153 offset:17408
	ds_read_b128 v[192:195], v153 offset:18432
	ds_read_b128 v[196:199], v153 offset:19456
	ds_read_b128 v[200:203], v153 offset:20480
	ds_read_b128 v[206:209], v153 offset:21504
	ds_read_b128 v[210:213], v153 offset:22528
	ds_read_b128 v[214:217], v153 offset:23552
	global_load_lds_dwordx4 v[218:219], off
	s_add_i32 m0, s62, 0x2000
	s_add_u32 s62, s46, 0x20000
	v_lshl_add_u64 v[220:221], s[46:47], 0, v[134:135]
	s_addc_u32 s63, s47, 0
	s_add_i32 s64, s55, s15
	global_load_lds_dwordx4 v[220:221], off
	v_lshl_add_u64 v[222:223], s[62:63], 0, v[130:131]
	s_mov_b32 m0, s64
	global_load_lds_dwordx4 v[222:223], off
	v_lshl_add_u64 v[222:223], s[62:63], 0, v[134:135]
	s_add_i32 m0, s64, 0x2000
	s_nop 0
	global_load_lds_dwordx4 v[222:223], off
	v_lshl_add_u64 v[222:223], s[48:49], 0, v[128:129]
	s_mov_b32 m0, s33
	s_nop 0
	global_load_lds_dwordx4 v[222:223], off
	v_lshl_add_u64 v[224:225], s[48:49], 0, v[132:133]
	s_mov_b32 m0, s34
	s_nop 0
	global_load_lds_dwordx4 v[224:225], off
	s_waitcnt vmcnt(8)
	s_waitcnt lgkmcnt(0)
	s_barrier
	s_setprio 1
	s_waitcnt lgkmcnt(0)
	v_mfma_f32_16x16x32_bf16 v[60:63], v[144:147], v[184:187], v[60:63]
	v_mfma_f32_16x16x32_bf16 v[56:59], v[160:163], v[184:187], v[56:59]
	v_mfma_f32_16x16x32_bf16 v[44:47], v[144:147], v[192:195], v[44:47]
	v_mfma_f32_16x16x32_bf16 v[40:43], v[160:163], v[192:195], v[40:43]
	v_mfma_f32_16x16x32_bf16 v[28:31], v[144:147], v[200:203], v[28:31]
	v_mfma_f32_16x16x32_bf16 v[24:27], v[160:163], v[200:203], v[24:27]
	v_mfma_f32_16x16x32_bf16 v[12:15], v[144:147], v[210:213], v[12:15]
	v_mfma_f32_16x16x32_bf16 v[8:11], v[160:163], v[210:213], v[8:11]
	v_mfma_f32_16x16x32_bf16 v[60:63], v[156:159], v[188:191], v[60:63]
	v_mfma_f32_16x16x32_bf16 v[56:59], v[164:167], v[188:191], v[56:59]
	v_mfma_f32_16x16x32_bf16 v[44:47], v[156:159], v[196:199], v[44:47]
	v_mfma_f32_16x16x32_bf16 v[40:43], v[164:167], v[196:199], v[40:43]
	v_mfma_f32_16x16x32_bf16 v[28:31], v[156:159], v[206:209], v[28:31]
	v_mfma_f32_16x16x32_bf16 v[24:27], v[164:167], v[206:209], v[24:27]
	v_mfma_f32_16x16x32_bf16 v[12:15], v[156:159], v[214:217], v[12:15]
	v_mfma_f32_16x16x32_bf16 v[8:11], v[164:167], v[214:217], v[8:11]
	s_setprio 0
	s_setprio 1
	v_mfma_f32_16x16x32_bf16 v[52:55], v[168:171], v[184:187], v[52:55]
	v_mfma_f32_16x16x32_bf16 v[48:51], v[176:179], v[184:187], v[48:51]
	v_mfma_f32_16x16x32_bf16 v[36:39], v[168:171], v[192:195], v[36:39]
	v_mfma_f32_16x16x32_bf16 v[32:35], v[176:179], v[192:195], v[32:35]
	v_mfma_f32_16x16x32_bf16 v[20:23], v[168:171], v[200:203], v[20:23]
	v_mfma_f32_16x16x32_bf16 v[16:19], v[176:179], v[200:203], v[16:19]
	v_mfma_f32_16x16x32_bf16 v[4:7], v[168:171], v[210:213], v[4:7]
	v_mfma_f32_16x16x32_bf16 v[0:3], v[176:179], v[210:213], v[0:3]
	v_mfma_f32_16x16x32_bf16 v[52:55], v[172:175], v[188:191], v[52:55]
	v_mfma_f32_16x16x32_bf16 v[48:51], v[180:183], v[188:191], v[48:51]
	v_mfma_f32_16x16x32_bf16 v[36:39], v[172:175], v[196:199], v[36:39]
	v_mfma_f32_16x16x32_bf16 v[32:35], v[180:183], v[196:199], v[32:35]
	v_mfma_f32_16x16x32_bf16 v[20:23], v[172:175], v[206:209], v[20:23]
	v_mfma_f32_16x16x32_bf16 v[16:19], v[180:183], v[206:209], v[16:19]
	v_mfma_f32_16x16x32_bf16 v[4:7], v[172:175], v[214:217], v[4:7]
	v_mfma_f32_16x16x32_bf16 v[0:3], v[180:183], v[214:217], v[0:3]
	s_setprio 0
	s_barrier
; #define PG8_STAGE(bufoff, gbase, voff) do { _Pragma("unroll") for (int _i = 0; _i < 2; ++_i) \
;         __builtin_amdgcn_global_load_lds((const unsigned*)((const char*)(gbase) + (voff)[_i]), (PG8_LAS unsigned*)(lds + (bufoff) + ldsw + _i * 8192), 16, 0, 0); } while (0)
; #define PG8_LDA(dst, b, h) do { _Pragma("unroll") for (int m = 0; m < 4; ++m) _Pragma("unroll") for (int k = 0; k < 2; ++k) dst[m][k] = *(const PG8_LAS bf16x8*)(lds + PG8_SA(b, h) + aoff + m * 2048 + k * 1024); } while (0)
; #define PG8_LDB(dst, b, h) do { _Pragma("unroll") for (int n = 0; n < 2; ++n) _Pragma("unroll") for (int k = 0; k < 2; ++k) dst[n][k] = *(const PG8_LAS bf16x8*)(lds + PG8_SB(b, h) + boff + n * 2048 + k * 1024); } while (0)
; #define PG8_MMA(ai, bj, At, Bt) do { __builtin_amdgcn_s_setprio(1); _Pragma("unroll") for (int m = 0; m < 4; ++m) _Pragma("unroll") for (int n = 0; n < 2; ++n) _Pragma("unroll") for (int k = 0; k < 2; ++k) \
;         acc[ai][bj][m][n] = __builtin_amdgcn_mfma_f32_16x16x32_bf16(Bt[n][k], At[m][k], acc[ai][bj][m][n], 0, 0, 0); __builtin_amdgcn_s_setprio(0); } while (0)
; #define PG8_WAIT_V(n) asm volatile("s_waitcnt vmcnt(" #n ")" ::: "memory")
; #define PG8_WAIT_L(n) asm volatile("s_waitcnt lgkmcnt(" #n ")" ::: "memory")
; #define PG8_BAR __builtin_amdgcn_s_barrier()
; #define PG8_SCHED __builtin_amdgcn_sched_barrier(0)
; template <class Epi, class Sched, bool ALIGN_EPI = false, bool SP2 = false>
; __device__ __forceinline__ void gemm_phase(PG8_LAS unsigned char* lds, const Gemm g, const Sched& S, const Epi& E) {
;     ...
;             PG8_LDB(B0, 1, 0); PG8_LDB(B1, 1, 1); PG8_SCHED; PG8_LDA(At, 1, 0); PG8_STAGE(PG8_SA(0, 1), a2 + hstep, voffA);
;             PG8_WAIT_V(8); PG8_WAIT_L(0); PG8_BAR; PG8_MMA(0, 0, At, B0); PG8_MMA(0, 1, At, B1); PG8_BAR; PG8_SCHED;
	s_add_i32 s62, 0, 0x18000
	v_add_u32_e32 v155, s62, v149
	s_add_i32 s63, 0, 0x1c000
	ds_read_b128 v[144:147], v155
	ds_read_b128 v[156:159], v155 offset:1024
	ds_read_b128 v[160:163], v155 offset:2048
	ds_read_b128 v[164:167], v155 offset:3072
	v_add_u32_e32 v155, s63, v149
	ds_read_b128 v[168:171], v155
	ds_read_b128 v[172:175], v155 offset:1024
	ds_read_b128 v[176:179], v155 offset:2048
	ds_read_b128 v[180:183], v155 offset:3072
	s_add_u32 s48, s48, 0x20000
	s_addc_u32 s49, s49, 0
	s_mov_b32 m0, s43
	v_lshl_add_u64 v[226:227], s[48:49], 0, v[128:129]
	ds_read_b128 v[184:187], v153 offset:32768
	ds_read_b128 v[188:191], v153 offset:33792
	ds_read_b128 v[192:195], v153 offset:34816
	ds_read_b128 v[196:199], v153 offset:35840
	ds_read_b128 v[200:203], v153 offset:36864
	ds_read_b128 v[206:209], v153 offset:37888
	ds_read_b128 v[210:213], v153 offset:38912
	ds_read_b128 v[214:217], v153 offset:39936
	global_load_lds_dwordx4 v[226:227], off
	v_lshl_add_u64 v[226:227], s[48:49], 0, v[132:133]
	s_mov_b32 m0, s50
	s_nop 0
	global_load_lds_dwordx4 v[226:227], off
	s_waitcnt vmcnt(8)
	s_waitcnt lgkmcnt(0)
	s_barrier
	s_setprio 1
	s_waitcnt lgkmcnt(0)
	v_mfma_f32_16x16x32_bf16 v[124:127], v[144:147], v[184:187], v[124:127]
	v_mfma_f32_16x16x32_bf16 v[120:123], v[160:163], v[184:187], v[120:123]
	v_mfma_f32_16x16x32_bf16 v[108:111], v[144:147], v[192:195], v[108:111]
	v_mfma_f32_16x16x32_bf16 v[104:107], v[160:163], v[192:195], v[104:107]
	v_mfma_f32_16x16x32_bf16 v[92:95], v[144:147], v[200:203], v[92:95]
	v_mfma_f32_16x16x32_bf16 v[88:91], v[160:163], v[200:203], v[88:91]
	v_mfma_f32_16x16x32_bf16 v[76:79], v[144:147], v[210:213], v[76:79]
	v_mfma_f32_16x16x32_bf16 v[72:75], v[160:163], v[210:213], v[72:75]
	v_mfma_f32_16x16x32_bf16 v[124:127], v[156:159], v[188:191], v[124:127]
	v_mfma_f32_16x16x32_bf16 v[120:123], v[164:167], v[188:191], v[120:123]
	v_mfma_f32_16x16x32_bf16 v[108:111], v[156:159], v[196:199], v[108:111]
	v_mfma_f32_16x16x32_bf16 v[104:107], v[164:167], v[196:199], v[104:107]
	v_mfma_f32_16x16x32_bf16 v[92:95], v[156:159], v[206:209], v[92:95]
	v_mfma_f32_16x16x32_bf16 v[88:91], v[164:167], v[206:209], v[88:91]
	v_mfma_f32_16x16x32_bf16 v[76:79], v[156:159], v[214:217], v[76:79]
	v_mfma_f32_16x16x32_bf16 v[72:75], v[164:167], v[214:217], v[72:75]
	s_setprio 0
	s_setprio 1
	v_mfma_f32_16x16x32_bf16 v[116:119], v[168:171], v[184:187], v[116:119]
	v_mfma_f32_16x16x32_bf16 v[112:115], v[176:179], v[184:187], v[112:115]
	v_mfma_f32_16x16x32_bf16 v[100:103], v[168:171], v[192:195], v[100:103]
	v_mfma_f32_16x16x32_bf16 v[96:99], v[176:179], v[192:195], v[96:99]
	v_mfma_f32_16x16x32_bf16 v[84:87], v[168:171], v[200:203], v[84:87]
	v_mfma_f32_16x16x32_bf16 v[80:83], v[176:179], v[200:203], v[80:83]
	v_mfma_f32_16x16x32_bf16 v[68:71], v[168:171], v[210:213], v[68:71]
	v_mfma_f32_16x16x32_bf16 v[64:67], v[176:179], v[210:213], v[64:67]
	v_mfma_f32_16x16x32_bf16 v[116:119], v[172:175], v[188:191], v[116:119]
	v_mfma_f32_16x16x32_bf16 v[112:115], v[180:183], v[188:191], v[112:115]
	v_mfma_f32_16x16x32_bf16 v[100:103], v[172:175], v[196:199], v[100:103]
	v_mfma_f32_16x16x32_bf16 v[96:99], v[180:183], v[196:199], v[96:99]
	v_mfma_f32_16x16x32_bf16 v[84:87], v[172:175], v[206:209], v[84:87]
	v_mfma_f32_16x16x32_bf16 v[80:83], v[180:183], v[206:209], v[80:83]
	v_mfma_f32_16x16x32_bf16 v[68:71], v[172:175], v[214:217], v[68:71]
	v_mfma_f32_16x16x32_bf16 v[64:67], v[180:183], v[214:217], v[64:67]
	s_setprio 0
	s_barrier
; #define PG8_STAGE(bufoff, gbase, voff) do { _Pragma("unroll") for (int _i = 0; _i < 2; ++_i) \
;         __builtin_amdgcn_global_load_lds((const unsigned*)((const char*)(gbase) + (voff)[_i]), (PG8_LAS unsigned*)(lds + (bufoff) + ldsw + _i * 8192), 16, 0, 0); } while (0)
; #define PG8_LDA(dst, b, h) do { _Pragma("unroll") for (int m = 0; m < 4; ++m) _Pragma("unroll") for (int k = 0; k < 2; ++k) dst[m][k] = *(const PG8_LAS bf16x8*)(lds + PG8_SA(b, h) + aoff + m * 2048 + k * 1024); } while (0)
; #define PG8_MMA(ai, bj, At, Bt) do { __builtin_amdgcn_s_setprio(1); _Pragma("unroll") for (int m = 0; m < 4; ++m) _Pragma("unroll") for (int n = 0; n < 2; ++n) _Pragma("unroll") for (int k = 0; k < 2; ++k) \
;         acc[ai][bj][m][n] = __builtin_amdgcn_mfma_f32_16x16x32_bf16(Bt[n][k], At[m][k], acc[ai][bj][m][n], 0, 0, 0); __builtin_amdgcn_s_setprio(0); } while (0)
; #define PG8_WAIT_V(n) asm volatile("s_waitcnt vmcnt(" #n ")" ::: "memory")
; #define PG8_WAIT_L(n) asm volatile("s_waitcnt lgkmcnt(" #n ")" ::: "memory")
; #define PG8_BAR __builtin_amdgcn_s_barrier()
; #define PG8_SCHED __builtin_amdgcn_sched_barrier(0)
; template <class Epi, class Sched, bool ALIGN_EPI = false, bool SP2 = false>
; __device__ __forceinline__ void gemm_phase(PG8_LAS unsigned char* lds, const Gemm g, const Sched& S, const Epi& E) {
;     ...
;             PG8_LDA(At, 1, 1); PG8_STAGE(PG8_SB(1, 0), b3, voffB); PG8_STAGE(PG8_SB(1, 1), b3 + hstep, voffB); PG8_STAGE(PG8_SA(1, 0), a3, voffA);
;             PG8_WAIT_V(8); PG8_WAIT_L(0); PG8_BAR; PG8_MMA(1, 0, At, B0); PG8_MMA(1, 1, At, B1); PG8_BAR; PG8_SCHED;
	s_add_i32 s48, s62, s15
	v_lshl_add_u64 v[218:219], v[218:219], 0, s[12:13]
	s_mov_b32 m0, s48
	ds_read_b128 v[184:187], v153 offset:49152
	ds_read_b128 v[188:191], v153 offset:50176
	ds_read_b128 v[192:195], v153 offset:51200
	ds_read_b128 v[196:199], v153 offset:52224
	ds_read_b128 v[200:203], v153 offset:53248
	ds_read_b128 v[206:209], v153 offset:54272
	ds_read_b128 v[210:213], v153 offset:55296
	ds_read_b128 v[214:217], v153 offset:56320
	global_load_lds_dwordx4 v[218:219], off
	s_add_i32 m0, s48, 0x2000
	s_add_u32 s46, s46, 0x20080
	v_lshl_add_u64 v[218:219], v[220:221], 0, s[12:13]
	s_addc_u32 s47, s47, 0
	s_add_i32 s48, s63, s15
	global_load_lds_dwordx4 v[218:219], off
	v_lshl_add_u64 v[218:219], s[46:47], 0, v[130:131]
	s_mov_b32 m0, s48
	s_nop 0
	global_load_lds_dwordx4 v[218:219], off
	v_lshl_add_u64 v[218:219], s[46:47], 0, v[134:135]
	s_add_i32 m0, s48, 0x2000
	s_nop 0
	global_load_lds_dwordx4 v[218:219], off
	v_lshl_add_u64 v[218:219], v[222:223], 0, s[12:13]
	s_mov_b32 m0, s52
	s_nop 0
	global_load_lds_dwordx4 v[218:219], off
	v_lshl_add_u64 v[218:219], v[224:225], 0, s[12:13]
	s_mov_b32 m0, s53
	s_nop 0
	global_load_lds_dwordx4 v[218:219], off
	s_waitcnt vmcnt(8)
	s_waitcnt lgkmcnt(0)
	s_barrier
	s_setprio 1
	s_waitcnt lgkmcnt(0)
	v_mfma_f32_16x16x32_bf16 v[60:63], v[144:147], v[184:187], v[60:63]
	v_mfma_f32_16x16x32_bf16 v[56:59], v[160:163], v[184:187], v[56:59]
	v_mfma_f32_16x16x32_bf16 v[44:47], v[144:147], v[192:195], v[44:47]
	v_mfma_f32_16x16x32_bf16 v[40:43], v[160:163], v[192:195], v[40:43]
	v_mfma_f32_16x16x32_bf16 v[28:31], v[144:147], v[200:203], v[28:31]
	v_mfma_f32_16x16x32_bf16 v[24:27], v[160:163], v[200:203], v[24:27]
	v_mfma_f32_16x16x32_bf16 v[12:15], v[144:147], v[210:213], v[12:15]
	v_mfma_f32_16x16x32_bf16 v[8:11], v[160:163], v[210:213], v[8:11]
	v_mfma_f32_16x16x32_bf16 v[60:63], v[156:159], v[188:191], v[60:63]
	v_mfma_f32_16x16x32_bf16 v[56:59], v[164:167], v[188:191], v[56:59]
	v_mfma_f32_16x16x32_bf16 v[44:47], v[156:159], v[196:199], v[44:47]
	v_mfma_f32_16x16x32_bf16 v[40:43], v[164:167], v[196:199], v[40:43]
	v_mfma_f32_16x16x32_bf16 v[28:31], v[156:159], v[206:209], v[28:31]
	v_mfma_f32_16x16x32_bf16 v[24:27], v[164:167], v[206:209], v[24:27]
	v_mfma_f32_16x16x32_bf16 v[12:15], v[156:159], v[214:217], v[12:15]
	v_mfma_f32_16x16x32_bf16 v[8:11], v[164:167], v[214:217], v[8:11]
	s_setprio 0
	s_setprio 1
	v_mfma_f32_16x16x32_bf16 v[52:55], v[168:171], v[184:187], v[52:55]
	v_mfma_f32_16x16x32_bf16 v[48:51], v[176:179], v[184:187], v[48:51]
	v_mfma_f32_16x16x32_bf16 v[36:39], v[168:171], v[192:195], v[36:39]
	v_mfma_f32_16x16x32_bf16 v[32:35], v[176:179], v[192:195], v[32:35]
	v_mfma_f32_16x16x32_bf16 v[20:23], v[168:171], v[200:203], v[20:23]
	v_mfma_f32_16x16x32_bf16 v[16:19], v[176:179], v[200:203], v[16:19]
	v_mfma_f32_16x16x32_bf16 v[4:7], v[168:171], v[210:213], v[4:7]
	v_mfma_f32_16x16x32_bf16 v[0:3], v[176:179], v[210:213], v[0:3]
	v_mfma_f32_16x16x32_bf16 v[52:55], v[172:175], v[188:191], v[52:55]
	v_mfma_f32_16x16x32_bf16 v[48:51], v[180:183], v[188:191], v[48:51]
	v_mfma_f32_16x16x32_bf16 v[36:39], v[172:175], v[196:199], v[36:39]
	v_mfma_f32_16x16x32_bf16 v[32:35], v[180:183], v[196:199], v[32:35]
	v_mfma_f32_16x16x32_bf16 v[20:23], v[172:175], v[206:209], v[20:23]
	v_mfma_f32_16x16x32_bf16 v[16:19], v[180:183], v[206:209], v[16:19]
	v_mfma_f32_16x16x32_bf16 v[4:7], v[172:175], v[214:217], v[4:7]
	v_mfma_f32_16x16x32_bf16 v[0:3], v[180:183], v[214:217], v[0:3]
	s_setprio 0
	s_barrier
	s_add_i32 s61, s61, 2
	s_add_u32 s44, s44, 0x100
	s_addc_u32 s45, s45, 0
	s_add_u32 s59, s59, 0x100
	s_addc_u32 s60, s60, 0
	s_cmp_gt_u32 s61, 5
	s_cbranch_scc0 .LBB0_1816
	s_and_b64 vcc, exec, s[24:25]
	s_cbranch_vccz .LBB0_1819
	s_barrier

; #define PG8_STAGE(bufoff, gbase, voff) do { _Pragma("unroll") for (int _i = 0; _i < 2; ++_i) \
;         __builtin_amdgcn_global_load_lds((const unsigned*)((const char*)(gbase) + (voff)[_i]), (PG8_LAS unsigned*)(lds + (bufoff) + ldsw + _i * 8192), 16, 0, 0); } while (0)
; #define PG8_LDA(dst, b, h) do { _Pragma("unroll") for (int m = 0; m < 4; ++m) _Pragma("unroll") for (int k = 0; k < 2; ++k) dst[m][k] = *(const PG8_LAS bf16x8*)(lds + PG8_SA(b, h) + aoff + m * 2048 + k * 1024); } while (0)
; #define PG8_LDB(dst, b, h) do { _Pragma("unroll") for (int n = 0; n < 2; ++n) _Pragma("unroll") for (int k = 0; k < 2; ++k) dst[n][k] = *(const PG8_LAS bf16x8*)(lds + PG8_SB(b, h) + boff + n * 2048 + k * 1024); } while (0)
; #define PG8_MMA(ai, bj, At, Bt) do { __builtin_amdgcn_s_setprio(1); _Pragma("unroll") for (int m = 0; m < 4; ++m) _Pragma("unroll") for (int n = 0; n < 2; ++n) _Pragma("unroll") for (int k = 0; k < 2; ++k) \
;         acc[ai][bj][m][n] = __builtin_amdgcn_mfma_f32_16x16x32_bf16(Bt[n][k], At[m][k], acc[ai][bj][m][n], 0, 0, 0); __builtin_amdgcn_s_setprio(0); } while (0)
; #define PG8_WAIT_V(n) asm volatile("s_waitcnt vmcnt(" #n ")" ::: "memory")
; #define PG8_WAIT_L(n) asm volatile("s_waitcnt lgkmcnt(" #n ")" ::: "memory")
; #define PG8_BAR __builtin_amdgcn_s_barrier()
; template <class Epi, class Sched, bool ALIGN_EPI = false, bool SP2 = false>
; __device__ __forceinline__ void gemm_phase(PG8_LAS unsigned char* lds, const Gemm g, const Sched& S, const Epi& E) {
;     ...
;             const char* a1 = cA + (size_t)(t + 1) * kstep;
;             const char* a2 = last ? nA : cA + (size_t)(t + 2) * kstep; const char* b2 = last ? nB : cB + (size_t)(t + 2) * kstep;
;             const char* a3 = a2 + kstep; const char* b3 = b2 + kstep;
;             if (last && has_next) S.a_ready(nxt);
;             if constexpr (SP2) {
;             PG8_LDB(B0, 0, 0); PG8_LDB(B1, 0, 1); PG8_SCHED; PG8_LDA(At, 0, 0); PG8_STAGE(PG8_SA(1, 1), a1 + hstep, voffA);
;             PG8_WAIT_V(8); PG8_WAIT_L(0); PG8_BAR; PG8_MMA(0, 0, At, B0); PG8_MMA(0, 1, At, B1); PG8_BAR; PG8_SCHED;
;             PG8_LDA(At, 0, 1); PG8_STAGE(PG8_SB(0, 0), b2, voffB); PG8_STAGE(PG8_SB(0, 1), b2 + hstep, voffB); PG8_STAGE(PG8_SA(0, 0), a2, voffA);
;             PG8_WAIT_V(8); PG8_WAIT_L(0); PG8_BAR; PG8_MMA(1, 0, At, B0); PG8_MMA(1, 1, At, B1); PG8_BAR; PG8_SCHED;
.LBB0_1977:
	s_add_u32 s53, s28, 0x100
	s_addc_u32 s54, s29, 0
	s_mov_b32 s55, -2
	s_waitcnt lgkmcnt(0)
	ds_read_b128 v[144:147], v151
	ds_read_b128 v[156:159], v151 offset:1024
	ds_read_b128 v[160:163], v151 offset:2048
	ds_read_b128 v[164:167], v151 offset:3072
	ds_read_b128 v[168:171], v152
	ds_read_b128 v[172:175], v152 offset:1024
	ds_read_b128 v[176:179], v152 offset:2048
	ds_read_b128 v[180:183], v152 offset:3072
	s_add_u32 s28, s26, 0x100
	s_addc_u32 s29, s27, 0
	s_cmp_eq_u32 s55, 40
	s_cselect_b32 s39, s1, s29
	s_cselect_b32 s38, s0, s28
	s_cselect_b32 s37, s25, s54
	s_cselect_b32 s36, s24, s53
	v_lshl_add_u64 v[218:219], s[26:27], 0, v[136:137]
	s_add_i32 m0, s33, 0xc000
	ds_read_b128 v[184:187], v153
	ds_read_b128 v[188:191], v153 offset:1024
	ds_read_b128 v[192:195], v153 offset:2048
	ds_read_b128 v[196:199], v153 offset:3072
	ds_read_b128 v[200:203], v153 offset:4096
	ds_read_b128 v[206:209], v153 offset:5120
	ds_read_b128 v[210:213], v153 offset:6144
	ds_read_b128 v[214:217], v153 offset:7168
	global_load_lds_dwordx4 v[218:219], off
	v_lshl_add_u64 v[218:219], s[26:27], 0, v[138:139]
	s_add_i32 m0, s33, 0xe000
	s_nop 0
	global_load_lds_dwordx4 v[218:219], off
	s_waitcnt vmcnt(8)
	s_waitcnt lgkmcnt(0)
	s_barrier
	s_setprio 1
	s_waitcnt lgkmcnt(0)
	v_mfma_f32_16x16x32_bf16 v[124:127], v[144:147], v[184:187], 0
	v_mfma_f32_16x16x32_bf16 v[120:123], v[160:163], v[184:187], 0
	v_mfma_f32_16x16x32_bf16 v[108:111], v[144:147], v[192:195], 0
	v_mfma_f32_16x16x32_bf16 v[104:107], v[160:163], v[192:195], 0
	v_mfma_f32_16x16x32_bf16 v[92:95], v[144:147], v[200:203], 0
	v_mfma_f32_16x16x32_bf16 v[88:91], v[160:163], v[200:203], 0
	v_mfma_f32_16x16x32_bf16 v[76:79], v[144:147], v[210:213], 0
	v_mfma_f32_16x16x32_bf16 v[72:75], v[160:163], v[210:213], 0
	v_mfma_f32_16x16x32_bf16 v[124:127], v[156:159], v[188:191], v[124:127]
	v_mfma_f32_16x16x32_bf16 v[120:123], v[164:167], v[188:191], v[120:123]
	v_mfma_f32_16x16x32_bf16 v[108:111], v[156:159], v[196:199], v[108:111]
	v_mfma_f32_16x16x32_bf16 v[104:107], v[164:167], v[196:199], v[104:107]
	v_mfma_f32_16x16x32_bf16 v[92:95], v[156:159], v[206:209], v[92:95]
	v_mfma_f32_16x16x32_bf16 v[88:91], v[164:167], v[206:209], v[88:91]
	v_mfma_f32_16x16x32_bf16 v[76:79], v[156:159], v[214:217], v[76:79]
	v_mfma_f32_16x16x32_bf16 v[72:75], v[164:167], v[214:217], v[72:75]
	s_setprio 0
	s_setprio 1
	v_mfma_f32_16x16x32_bf16 v[116:119], v[168:171], v[184:187], 0
	v_mfma_f32_16x16x32_bf16 v[112:115], v[176:179], v[184:187], 0
	v_mfma_f32_16x16x32_bf16 v[100:103], v[168:171], v[192:195], 0
	v_mfma_f32_16x16x32_bf16 v[96:99], v[176:179], v[192:195], 0
	v_mfma_f32_16x16x32_bf16 v[84:87], v[168:171], v[200:203], 0
	v_mfma_f32_16x16x32_bf16 v[80:83], v[176:179], v[200:203], 0
	v_mfma_f32_16x16x32_bf16 v[68:71], v[168:171], v[210:213], 0
	v_mfma_f32_16x16x32_bf16 v[64:67], v[176:179], v[210:213], 0
	v_mfma_f32_16x16x32_bf16 v[116:119], v[172:175], v[188:191], v[116:119]
	v_mfma_f32_16x16x32_bf16 v[112:115], v[180:183], v[188:191], v[112:115]
	v_mfma_f32_16x16x32_bf16 v[100:103], v[172:175], v[196:199], v[100:103]
	v_mfma_f32_16x16x32_bf16 v[96:99], v[180:183], v[196:199], v[96:99]
	v_mfma_f32_16x16x32_bf16 v[84:87], v[172:175], v[206:209], v[84:87]
	v_mfma_f32_16x16x32_bf16 v[80:83], v[180:183], v[206:209], v[80:83]
	v_mfma_f32_16x16x32_bf16 v[68:71], v[172:175], v[214:217], v[68:71]
	v_mfma_f32_16x16x32_bf16 v[64:67], v[180:183], v[214:217], v[64:67]
	s_setprio 0
	s_barrier
	s_add_i32 s26, s45, s15
	v_lshl_add_u64 v[218:219], s[36:37], 0, v[130:131]
	s_mov_b32 m0, s26
	ds_read_b128 v[184:187], v153 offset:16384
	ds_read_b128 v[188:191], v153 offset:17408
	ds_read_b128 v[192:195], v153 offset:18432
	ds_read_b128 v[196:199], v153 offset:19456
	ds_read_b128 v[200:203], v153 offset:20480
	ds_read_b128 v[206:209], v153 offset:21504
	ds_read_b128 v[210:213], v153 offset:22528
	ds_read_b128 v[214:217], v153 offset:23552
	global_load_lds_dwordx4 v[218:219], off
	s_add_i32 m0, s26, 0x2000
	s_add_u32 s26, s36, 0xb0000
	v_lshl_add_u64 v[220:221], s[36:37], 0, v[134:135]
	s_addc_u32 s27, s37, 0
	s_add_i32 s56, s46, s15
	global_load_lds_dwordx4 v[220:221], off
	v_lshl_add_u64 v[222:223], s[26:27], 0, v[130:131]
	s_mov_b32 m0, s56
	global_load_lds_dwordx4 v[222:223], off
	v_lshl_add_u64 v[222:223], s[26:27], 0, v[134:135]
	s_add_i32 m0, s56, 0x2000
	s_nop 0
	global_load_lds_dwordx4 v[222:223], off
	v_lshl_add_u64 v[222:223], s[38:39], 0, v[128:129]
	s_mov_b32 m0, s33
	s_nop 0
	global_load_lds_dwordx4 v[222:223], off
	v_lshl_add_u64 v[224:225], s[38:39], 0, v[132:133]
	s_mov_b32 m0, s34
	s_nop 0
	global_load_lds_dwordx4 v[224:225], off
	s_waitcnt vmcnt(8)
	s_waitcnt lgkmcnt(0)
	s_barrier
; #define PG8_STAGE(bufoff, gbase, voff) do { _Pragma("unroll") for (int _i = 0; _i < 2; ++_i) \
;         __builtin_amdgcn_global_load_lds((const unsigned*)((const char*)(gbase) + (voff)[_i]), (PG8_LAS unsigned*)(lds + (bufoff) + ldsw + _i * 8192), 16, 0, 0); } while (0)
; #define PG8_LDA(dst, b, h) do { _Pragma("unroll") for (int m = 0; m < 4; ++m) _Pragma("unroll") for (int k = 0; k < 2; ++k) dst[m][k] = *(const PG8_LAS bf16x8*)(lds + PG8_SA(b, h) + aoff + m * 2048 + k * 1024); } while (0)
; #define PG8_LDB(dst, b, h) do { _Pragma("unroll") for (int n = 0; n < 2; ++n) _Pragma("unroll") for (int k = 0; k < 2; ++k) dst[n][k] = *(const PG8_LAS bf16x8*)(lds + PG8_SB(b, h) + boff + n * 2048 + k * 1024); } while (0)
; #define PG8_MMA(ai, bj, At, Bt) do { __builtin_amdgcn_s_setprio(1); _Pragma("unroll") for (int m = 0; m < 4; ++m) _Pragma("unroll") for (int n = 0; n < 2; ++n) _Pragma("unroll") for (int k = 0; k < 2; ++k) \
;         acc[ai][bj][m][n] = __builtin_amdgcn_mfma_f32_16x16x32_bf16(Bt[n][k], At[m][k], acc[ai][bj][m][n], 0, 0, 0); __builtin_amdgcn_s_setprio(0); } while (0)
; #define PG8_WAIT_V(n) asm volatile("s_waitcnt vmcnt(" #n ")" ::: "memory")
; #define PG8_WAIT_L(n) asm volatile("s_waitcnt lgkmcnt(" #n ")" ::: "memory")
; #define PG8_BAR __builtin_amdgcn_s_barrier()
; #define PG8_SCHED __builtin_amdgcn_sched_barrier(0)
; template <class Epi, class Sched, bool ALIGN_EPI = false, bool SP2 = false>
; __device__ __forceinline__ void gemm_phase(PG8_LAS unsigned char* lds, const Gemm g, const Sched& S, const Epi& E) {
;     ...
;             PG8_WAIT_V(8); PG8_WAIT_L(0); PG8_BAR; PG8_MMA(1, 0, At, B0); PG8_MMA(1, 1, At, B1); PG8_BAR; PG8_SCHED;
;             PG8_LDB(B0, 1, 0); PG8_LDB(B1, 1, 1); PG8_SCHED; PG8_LDA(At, 1, 0); PG8_STAGE(PG8_SA(0, 1), a2 + hstep, voffA);
;             PG8_WAIT_V(8); PG8_WAIT_L(0); PG8_BAR; PG8_MMA(0, 0, At, B0); PG8_MMA(0, 1, At, B1); PG8_BAR; PG8_SCHED;
	s_setprio 1
	s_waitcnt lgkmcnt(0)
	v_mfma_f32_16x16x32_bf16 v[60:63], v[144:147], v[184:187], 0
	v_mfma_f32_16x16x32_bf16 v[56:59], v[160:163], v[184:187], 0
	v_mfma_f32_16x16x32_bf16 v[44:47], v[144:147], v[192:195], 0
	v_mfma_f32_16x16x32_bf16 v[40:43], v[160:163], v[192:195], 0
	v_mfma_f32_16x16x32_bf16 v[28:31], v[144:147], v[200:203], 0
	v_mfma_f32_16x16x32_bf16 v[24:27], v[160:163], v[200:203], 0
	v_mfma_f32_16x16x32_bf16 v[12:15], v[144:147], v[210:213], 0
	v_mfma_f32_16x16x32_bf16 v[8:11], v[160:163], v[210:213], 0
	v_mfma_f32_16x16x32_bf16 v[60:63], v[156:159], v[188:191], v[60:63]
	v_mfma_f32_16x16x32_bf16 v[56:59], v[164:167], v[188:191], v[56:59]
	v_mfma_f32_16x16x32_bf16 v[44:47], v[156:159], v[196:199], v[44:47]
	v_mfma_f32_16x16x32_bf16 v[40:43], v[164:167], v[196:199], v[40:43]
	v_mfma_f32_16x16x32_bf16 v[28:31], v[156:159], v[206:209], v[28:31]
	v_mfma_f32_16x16x32_bf16 v[24:27], v[164:167], v[206:209], v[24:27]
	v_mfma_f32_16x16x32_bf16 v[12:15], v[156:159], v[214:217], v[12:15]
	v_mfma_f32_16x16x32_bf16 v[8:11], v[164:167], v[214:217], v[8:11]
	s_setprio 0
	s_setprio 1
	v_mfma_f32_16x16x32_bf16 v[52:55], v[168:171], v[184:187], 0
	v_mfma_f32_16x16x32_bf16 v[48:51], v[176:179], v[184:187], 0
	v_mfma_f32_16x16x32_bf16 v[36:39], v[168:171], v[192:195], 0
	v_mfma_f32_16x16x32_bf16 v[32:35], v[176:179], v[192:195], 0
	v_mfma_f32_16x16x32_bf16 v[20:23], v[168:171], v[200:203], 0
	v_mfma_f32_16x16x32_bf16 v[16:19], v[176:179], v[200:203], 0
	v_mfma_f32_16x16x32_bf16 v[4:7], v[168:171], v[210:213], 0
	v_mfma_f32_16x16x32_bf16 v[0:3], v[176:179], v[210:213], 0
	v_mfma_f32_16x16x32_bf16 v[52:55], v[172:175], v[188:191], v[52:55]
	v_mfma_f32_16x16x32_bf16 v[48:51], v[180:183], v[188:191], v[48:51]
	v_mfma_f32_16x16x32_bf16 v[36:39], v[172:175], v[196:199], v[36:39]
	v_mfma_f32_16x16x32_bf16 v[32:35], v[180:183], v[196:199], v[32:35]
	v_mfma_f32_16x16x32_bf16 v[20:23], v[172:175], v[206:209], v[20:23]
	v_mfma_f32_16x16x32_bf16 v[16:19], v[180:183], v[206:209], v[16:19]
	v_mfma_f32_16x16x32_bf16 v[4:7], v[172:175], v[214:217], v[4:7]
	v_mfma_f32_16x16x32_bf16 v[0:3], v[180:183], v[214:217], v[0:3]
	s_setprio 0
	s_barrier
	s_add_i32 s56, 0, 0x18000
	v_add_u32_e32 v155, s56, v149
	s_add_i32 s57, 0, 0x1c000
	ds_read_b128 v[144:147], v155
	ds_read_b128 v[156:159], v155 offset:1024
	ds_read_b128 v[160:163], v155 offset:2048
	ds_read_b128 v[164:167], v155 offset:3072
	v_add_u32_e32 v155, s57, v149
	ds_read_b128 v[168:171], v155
	ds_read_b128 v[172:175], v155 offset:1024
	ds_read_b128 v[176:179], v155 offset:2048
	ds_read_b128 v[180:183], v155 offset:3072
	s_add_u32 s26, s38, 0xb0000
	s_addc_u32 s27, s39, 0
	s_mov_b32 m0, s40
	v_lshl_add_u64 v[226:227], s[26:27], 0, v[128:129]
	ds_read_b128 v[184:187], v153 offset:32768
	ds_read_b128 v[188:191], v153 offset:33792
	ds_read_b128 v[192:195], v153 offset:34816
	ds_read_b128 v[196:199], v153 offset:35840
	ds_read_b128 v[200:203], v153 offset:36864
	ds_read_b128 v[206:209], v153 offset:37888
	ds_read_b128 v[210:213], v153 offset:38912
	ds_read_b128 v[214:217], v153 offset:39936
	global_load_lds_dwordx4 v[226:227], off
	v_lshl_add_u64 v[226:227], s[26:27], 0, v[132:133]
	s_mov_b32 m0, s41
	s_nop 0
	global_load_lds_dwordx4 v[226:227], off
	s_waitcnt vmcnt(8)
	s_waitcnt lgkmcnt(0)
	s_barrier
	s_setprio 1
	s_waitcnt lgkmcnt(0)
	v_mfma_f32_16x16x32_bf16 v[124:127], v[144:147], v[184:187], v[124:127]
	v_mfma_f32_16x16x32_bf16 v[120:123], v[160:163], v[184:187], v[120:123]
	v_mfma_f32_16x16x32_bf16 v[108:111], v[144:147], v[192:195], v[108:111]
	v_mfma_f32_16x16x32_bf16 v[104:107], v[160:163], v[192:195], v[104:107]
	v_mfma_f32_16x16x32_bf16 v[92:95], v[144:147], v[200:203], v[92:95]
	v_mfma_f32_16x16x32_bf16 v[88:91], v[160:163], v[200:203], v[88:91]
	v_mfma_f32_16x16x32_bf16 v[76:79], v[144:147], v[210:213], v[76:79]
	v_mfma_f32_16x16x32_bf16 v[72:75], v[160:163], v[210:213], v[72:75]
	v_mfma_f32_16x16x32_bf16 v[124:127], v[156:159], v[188:191], v[124:127]
	v_mfma_f32_16x16x32_bf16 v[120:123], v[164:167], v[188:191], v[120:123]
	v_mfma_f32_16x16x32_bf16 v[108:111], v[156:159], v[196:199], v[108:111]
	v_mfma_f32_16x16x32_bf16 v[104:107], v[164:167], v[196:199], v[104:107]
	v_mfma_f32_16x16x32_bf16 v[92:95], v[156:159], v[206:209], v[92:95]
	v_mfma_f32_16x16x32_bf16 v[88:91], v[164:167], v[206:209], v[88:91]
	v_mfma_f32_16x16x32_bf16 v[76:79], v[156:159], v[214:217], v[76:79]
	v_mfma_f32_16x16x32_bf16 v[72:75], v[164:167], v[214:217], v[72:75]
	s_setprio 0
	s_setprio 1
	v_mfma_f32_16x16x32_bf16 v[116:119], v[168:171], v[184:187], v[116:119]
	v_mfma_f32_16x16x32_bf16 v[112:115], v[176:179], v[184:187], v[112:115]
	v_mfma_f32_16x16x32_bf16 v[100:103], v[168:171], v[192:195], v[100:103]
	v_mfma_f32_16x16x32_bf16 v[96:99], v[176:179], v[192:195], v[96:99]
	v_mfma_f32_16x16x32_bf16 v[84:87], v[168:171], v[200:203], v[84:87]
	v_mfma_f32_16x16x32_bf16 v[80:83], v[176:179], v[200:203], v[80:83]
	v_mfma_f32_16x16x32_bf16 v[68:71], v[168:171], v[210:213], v[68:71]
	v_mfma_f32_16x16x32_bf16 v[64:67], v[176:179], v[210:213], v[64:67]
	v_mfma_f32_16x16x32_bf16 v[116:119], v[172:175], v[188:191], v[116:119]
	v_mfma_f32_16x16x32_bf16 v[112:115], v[180:183], v[188:191], v[112:115]
	v_mfma_f32_16x16x32_bf16 v[100:103], v[172:175], v[196:199], v[100:103]
	v_mfma_f32_16x16x32_bf16 v[96:99], v[180:183], v[196:199], v[96:99]
	v_mfma_f32_16x16x32_bf16 v[84:87], v[172:175], v[206:209], v[84:87]
	v_mfma_f32_16x16x32_bf16 v[80:83], v[180:183], v[206:209], v[80:83]
	v_mfma_f32_16x16x32_bf16 v[68:71], v[172:175], v[214:217], v[68:71]
	v_mfma_f32_16x16x32_bf16 v[64:67], v[180:183], v[214:217], v[64:67]
	s_setprio 0
	s_barrier
; #define PG8_STAGE(bufoff, gbase, voff) do { _Pragma("unroll") for (int _i = 0; _i < 2; ++_i) \
;         __builtin_amdgcn_global_load_lds((const unsigned*)((const char*)(gbase) + (voff)[_i]), (PG8_LAS unsigned*)(lds + (bufoff) + ldsw + _i * 8192), 16, 0, 0); } while (0)
; #define PG8_LDA(dst, b, h) do { _Pragma("unroll") for (int m = 0; m < 4; ++m) _Pragma("unroll") for (int k = 0; k < 2; ++k) dst[m][k] = *(const PG8_LAS bf16x8*)(lds + PG8_SA(b, h) + aoff + m * 2048 + k * 1024); } while (0)
; #define PG8_LDB(dst, b, h) do { _Pragma("unroll") for (int n = 0; n < 2; ++n) _Pragma("unroll") for (int k = 0; k < 2; ++k) dst[n][k] = *(const PG8_LAS bf16x8*)(lds + PG8_SB(b, h) + boff + n * 2048 + k * 1024); } while (0)
; #define PG8_MMA(ai, bj, At, Bt) do { __builtin_amdgcn_s_setprio(1); _Pragma("unroll") for (int m = 0; m < 4; ++m) _Pragma("unroll") for (int n = 0; n < 2; ++n) _Pragma("unroll") for (int k = 0; k < 2; ++k) \
;         acc[ai][bj][m][n] = __builtin_amdgcn_mfma_f32_16x16x32_bf16(Bt[n][k], At[m][k], acc[ai][bj][m][n], 0, 0, 0); __builtin_amdgcn_s_setprio(0); } while (0)
; #define PG8_WAIT_V(n) asm volatile("s_waitcnt vmcnt(" #n ")" ::: "memory")
; #define PG8_WAIT_L(n) asm volatile("s_waitcnt lgkmcnt(" #n ")" ::: "memory")
; #define PG8_BAR __builtin_amdgcn_s_barrier()
; #define PG8_SCHED __builtin_amdgcn_sched_barrier(0)
; template <class Epi, class Sched, bool ALIGN_EPI = false, bool SP2 = false>
; __device__ __forceinline__ void gemm_phase(PG8_LAS unsigned char* lds, const Gemm g, const Sched& S, const Epi& E) {
;     ...
;             PG8_LDB(B0, 0, 0); PG8_LDB(B1, 0, 1); PG8_SCHED; PG8_LDA(At, 0, 0); PG8_STAGE(PG8_SA(1, 1), a1 + hstep, voffA);
;             PG8_WAIT_V(8); PG8_WAIT_L(0); PG8_BAR; PG8_MMA(0, 0, At, B0); PG8_MMA(0, 1, At, B1); PG8_BAR; PG8_SCHED;
;     ...
;             PG8_LDA(At, 1, 1); PG8_STAGE(PG8_SB(1, 0), b3, voffB); PG8_STAGE(PG8_SB(1, 1), b3 + hstep, voffB); PG8_STAGE(PG8_SA(1, 0), a3, voffA);
;             PG8_WAIT_V(8); PG8_WAIT_L(0); PG8_BAR; PG8_MMA(1, 0, At, B0); PG8_MMA(1, 1, At, B1); PG8_BAR; PG8_SCHED;
	s_add_i32 s26, s56, s15
	v_lshl_add_u64 v[218:219], v[218:219], 0, s[12:13]
	s_mov_b32 m0, s26
	ds_read_b128 v[184:187], v153 offset:49152
	ds_read_b128 v[188:191], v153 offset:50176
	ds_read_b128 v[192:195], v153 offset:51200
	ds_read_b128 v[196:199], v153 offset:52224
	ds_read_b128 v[200:203], v153 offset:53248
	ds_read_b128 v[206:209], v153 offset:54272
	ds_read_b128 v[210:213], v153 offset:55296
	ds_read_b128 v[214:217], v153 offset:56320
	global_load_lds_dwordx4 v[218:219], off
	s_add_i32 m0, s26, 0x2000
	s_add_u32 s26, s36, 0xb0080
	v_lshl_add_u64 v[218:219], v[220:221], 0, s[12:13]
	s_addc_u32 s27, s37, 0
	s_add_i32 s36, s57, s15
	global_load_lds_dwordx4 v[218:219], off
	v_lshl_add_u64 v[218:219], s[26:27], 0, v[130:131]
	s_mov_b32 m0, s36
	s_nop 0
	global_load_lds_dwordx4 v[218:219], off
	v_lshl_add_u64 v[218:219], s[26:27], 0, v[134:135]
	s_add_i32 m0, s36, 0x2000
	s_nop 0
	global_load_lds_dwordx4 v[218:219], off
	v_lshl_add_u64 v[218:219], v[222:223], 0, s[12:13]
	s_mov_b32 m0, s43
	s_nop 0
	global_load_lds_dwordx4 v[218:219], off
	v_lshl_add_u64 v[218:219], v[224:225], 0, s[12:13]
	s_mov_b32 m0, s44
	s_nop 0
	global_load_lds_dwordx4 v[218:219], off
	s_waitcnt vmcnt(8)
	s_waitcnt lgkmcnt(0)
	s_barrier
	s_setprio 1
	s_waitcnt lgkmcnt(0)
	v_mfma_f32_16x16x32_bf16 v[60:63], v[144:147], v[184:187], v[60:63]
	v_mfma_f32_16x16x32_bf16 v[56:59], v[160:163], v[184:187], v[56:59]
	v_mfma_f32_16x16x32_bf16 v[44:47], v[144:147], v[192:195], v[44:47]
	v_mfma_f32_16x16x32_bf16 v[40:43], v[160:163], v[192:195], v[40:43]
	v_mfma_f32_16x16x32_bf16 v[28:31], v[144:147], v[200:203], v[28:31]
	v_mfma_f32_16x16x32_bf16 v[24:27], v[160:163], v[200:203], v[24:27]
	v_mfma_f32_16x16x32_bf16 v[12:15], v[144:147], v[210:213], v[12:15]
	v_mfma_f32_16x16x32_bf16 v[8:11], v[160:163], v[210:213], v[8:11]
	v_mfma_f32_16x16x32_bf16 v[60:63], v[156:159], v[188:191], v[60:63]
	v_mfma_f32_16x16x32_bf16 v[56:59], v[164:167], v[188:191], v[56:59]
	v_mfma_f32_16x16x32_bf16 v[44:47], v[156:159], v[196:199], v[44:47]
	v_mfma_f32_16x16x32_bf16 v[40:43], v[164:167], v[196:199], v[40:43]
	v_mfma_f32_16x16x32_bf16 v[28:31], v[156:159], v[206:209], v[28:31]
	v_mfma_f32_16x16x32_bf16 v[24:27], v[164:167], v[206:209], v[24:27]
	v_mfma_f32_16x16x32_bf16 v[12:15], v[156:159], v[214:217], v[12:15]
	v_mfma_f32_16x16x32_bf16 v[8:11], v[164:167], v[214:217], v[8:11]
	s_setprio 0
	s_setprio 1
	v_mfma_f32_16x16x32_bf16 v[52:55], v[168:171], v[184:187], v[52:55]
	v_mfma_f32_16x16x32_bf16 v[48:51], v[176:179], v[184:187], v[48:51]
	v_mfma_f32_16x16x32_bf16 v[36:39], v[168:171], v[192:195], v[36:39]
	v_mfma_f32_16x16x32_bf16 v[32:35], v[176:179], v[192:195], v[32:35]
	v_mfma_f32_16x16x32_bf16 v[20:23], v[168:171], v[200:203], v[20:23]
	v_mfma_f32_16x16x32_bf16 v[16:19], v[176:179], v[200:203], v[16:19]
	v_mfma_f32_16x16x32_bf16 v[4:7], v[168:171], v[210:213], v[4:7]
	v_mfma_f32_16x16x32_bf16 v[0:3], v[176:179], v[210:213], v[0:3]
	v_mfma_f32_16x16x32_bf16 v[52:55], v[172:175], v[188:191], v[52:55]
	v_mfma_f32_16x16x32_bf16 v[48:51], v[180:183], v[188:191], v[48:51]
	v_mfma_f32_16x16x32_bf16 v[36:39], v[172:175], v[196:199], v[36:39]
	v_mfma_f32_16x16x32_bf16 v[32:35], v[180:183], v[196:199], v[32:35]
	v_mfma_f32_16x16x32_bf16 v[20:23], v[172:175], v[206:209], v[20:23]
	v_mfma_f32_16x16x32_bf16 v[16:19], v[180:183], v[206:209], v[16:19]
	v_mfma_f32_16x16x32_bf16 v[4:7], v[172:175], v[214:217], v[4:7]
	v_mfma_f32_16x16x32_bf16 v[0:3], v[180:183], v[214:217], v[0:3]
	s_setprio 0
	s_barrier
	s_add_i32 s55, s55, 2
	s_add_u32 s53, s53, 0x100
	s_addc_u32 s54, s54, 0
	s_mov_b64 s[26:27], s[28:29]
.LBB0_1978:
	ds_read_b128 v[144:147], v151
	ds_read_b128 v[156:159], v151 offset:1024
	ds_read_b128 v[160:163], v151 offset:2048
	ds_read_b128 v[164:167], v151 offset:3072
	ds_read_b128 v[168:171], v152
	ds_read_b128 v[172:175], v152 offset:1024
	ds_read_b128 v[176:179], v152 offset:2048
	ds_read_b128 v[180:183], v152 offset:3072
	s_add_u32 s28, s26, 0x100
	s_addc_u32 s29, s27, 0
	s_cmp_eq_u32 s55, 40
	s_cselect_b32 s39, s1, s29
	s_cselect_b32 s38, s0, s28
	s_cselect_b32 s37, s25, s54
	s_cselect_b32 s36, s24, s53
	v_lshl_add_u64 v[218:219], s[26:27], 0, v[136:137]
	s_add_i32 m0, s33, 0xc000
	ds_read_b128 v[184:187], v153
	ds_read_b128 v[188:191], v153 offset:1024
	ds_read_b128 v[192:195], v153 offset:2048
	ds_read_b128 v[196:199], v153 offset:3072
	ds_read_b128 v[200:203], v153 offset:4096
	ds_read_b128 v[206:209], v153 offset:5120
	ds_read_b128 v[210:213], v153 offset:6144
	ds_read_b128 v[214:217], v153 offset:7168
	global_load_lds_dwordx4 v[218:219], off
	v_lshl_add_u64 v[218:219], s[26:27], 0, v[138:139]
	s_add_i32 m0, s33, 0xe000
	s_nop 0
	global_load_lds_dwordx4 v[218:219], off
	s_waitcnt vmcnt(8)
	s_waitcnt lgkmcnt(0)
	s_barrier
; #define PG8_STAGE(bufoff, gbase, voff) do { _Pragma("unroll") for (int _i = 0; _i < 2; ++_i) \
;         __builtin_amdgcn_global_load_lds((const unsigned*)((const char*)(gbase) + (voff)[_i]), (PG8_LAS unsigned*)(lds + (bufoff) + ldsw + _i * 8192), 16, 0, 0); } while (0)
; #define PG8_LDA(dst, b, h) do { _Pragma("unroll") for (int m = 0; m < 4; ++m) _Pragma("unroll") for (int k = 0; k < 2; ++k) dst[m][k] = *(const PG8_LAS bf16x8*)(lds + PG8_SA(b, h) + aoff + m * 2048 + k * 1024); } while (0)
; #define PG8_MMA(ai, bj, At, Bt) do { __builtin_amdgcn_s_setprio(1); _Pragma("unroll") for (int m = 0; m < 4; ++m) _Pragma("unroll") for (int n = 0; n < 2; ++n) _Pragma("unroll") for (int k = 0; k < 2; ++k) \
;         acc[ai][bj][m][n] = __builtin_amdgcn_mfma_f32_16x16x32_bf16(Bt[n][k], At[m][k], acc[ai][bj][m][n], 0, 0, 0); __builtin_amdgcn_s_setprio(0); } while (0)
; #define PG8_WAIT_V(n) asm volatile("s_waitcnt vmcnt(" #n ")" ::: "memory")
; #define PG8_WAIT_L(n) asm volatile("s_waitcnt lgkmcnt(" #n ")" ::: "memory")
; #define PG8_BAR __builtin_amdgcn_s_barrier()
; #define PG8_SCHED __builtin_amdgcn_sched_barrier(0)
; template <class Epi, class Sched, bool ALIGN_EPI = false, bool SP2 = false>
; __device__ __forceinline__ void gemm_phase(PG8_LAS unsigned char* lds, const Gemm g, const Sched& S, const Epi& E) {
;     ...
;             PG8_WAIT_V(8); PG8_WAIT_L(0); PG8_BAR; PG8_MMA(0, 0, At, B0); PG8_MMA(0, 1, At, B1); PG8_BAR; PG8_SCHED;
;             PG8_LDA(At, 0, 1); PG8_STAGE(PG8_SB(0, 0), b2, voffB); PG8_STAGE(PG8_SB(0, 1), b2 + hstep, voffB); PG8_STAGE(PG8_SA(0, 0), a2, voffA);
;             PG8_WAIT_V(8); PG8_WAIT_L(0); PG8_BAR; PG8_MMA(1, 0, At, B0); PG8_MMA(1, 1, At, B1); PG8_BAR; PG8_SCHED;
	s_setprio 1
	s_waitcnt lgkmcnt(0)
	v_mfma_f32_16x16x32_bf16 v[124:127], v[144:147], v[184:187], v[124:127]
	v_mfma_f32_16x16x32_bf16 v[120:123], v[160:163], v[184:187], v[120:123]
	v_mfma_f32_16x16x32_bf16 v[108:111], v[144:147], v[192:195], v[108:111]
	v_mfma_f32_16x16x32_bf16 v[104:107], v[160:163], v[192:195], v[104:107]
	v_mfma_f32_16x16x32_bf16 v[92:95], v[144:147], v[200:203], v[92:95]
	v_mfma_f32_16x16x32_bf16 v[88:91], v[160:163], v[200:203], v[88:91]
	v_mfma_f32_16x16x32_bf16 v[76:79], v[144:147], v[210:213], v[76:79]
	v_mfma_f32_16x16x32_bf16 v[72:75], v[160:163], v[210:213], v[72:75]
	v_mfma_f32_16x16x32_bf16 v[124:127], v[156:159], v[188:191], v[124:127]
	v_mfma_f32_16x16x32_bf16 v[120:123], v[164:167], v[188:191], v[120:123]
	v_mfma_f32_16x16x32_bf16 v[108:111], v[156:159], v[196:199], v[108:111]
	v_mfma_f32_16x16x32_bf16 v[104:107], v[164:167], v[196:199], v[104:107]
	v_mfma_f32_16x16x32_bf16 v[92:95], v[156:159], v[206:209], v[92:95]
	v_mfma_f32_16x16x32_bf16 v[88:91], v[164:167], v[206:209], v[88:91]
	v_mfma_f32_16x16x32_bf16 v[76:79], v[156:159], v[214:217], v[76:79]
	v_mfma_f32_16x16x32_bf16 v[72:75], v[164:167], v[214:217], v[72:75]
	s_setprio 0
	s_setprio 1
	v_mfma_f32_16x16x32_bf16 v[116:119], v[168:171], v[184:187], v[116:119]
	v_mfma_f32_16x16x32_bf16 v[112:115], v[176:179], v[184:187], v[112:115]
	v_mfma_f32_16x16x32_bf16 v[100:103], v[168:171], v[192:195], v[100:103]
	v_mfma_f32_16x16x32_bf16 v[96:99], v[176:179], v[192:195], v[96:99]
	v_mfma_f32_16x16x32_bf16 v[84:87], v[168:171], v[200:203], v[84:87]
	v_mfma_f32_16x16x32_bf16 v[80:83], v[176:179], v[200:203], v[80:83]
	v_mfma_f32_16x16x32_bf16 v[68:71], v[168:171], v[210:213], v[68:71]
	v_mfma_f32_16x16x32_bf16 v[64:67], v[176:179], v[210:213], v[64:67]
	v_mfma_f32_16x16x32_bf16 v[116:119], v[172:175], v[188:191], v[116:119]
	v_mfma_f32_16x16x32_bf16 v[112:115], v[180:183], v[188:191], v[112:115]
	v_mfma_f32_16x16x32_bf16 v[100:103], v[172:175], v[196:199], v[100:103]
	v_mfma_f32_16x16x32_bf16 v[96:99], v[180:183], v[196:199], v[96:99]
	v_mfma_f32_16x16x32_bf16 v[84:87], v[172:175], v[206:209], v[84:87]
	v_mfma_f32_16x16x32_bf16 v[80:83], v[180:183], v[206:209], v[80:83]
	v_mfma_f32_16x16x32_bf16 v[68:71], v[172:175], v[214:217], v[68:71]
	v_mfma_f32_16x16x32_bf16 v[64:67], v[180:183], v[214:217], v[64:67]
	s_setprio 0
	s_barrier
	s_add_i32 s26, s45, s15
	v_lshl_add_u64 v[218:219], s[36:37], 0, v[130:131]
	s_mov_b32 m0, s26
	ds_read_b128 v[184:187], v153 offset:16384
	ds_read_b128 v[188:191], v153 offset:17408
	ds_read_b128 v[192:195], v153 offset:18432
	ds_read_b128 v[196:199], v153 offset:19456
	ds_read_b128 v[200:203], v153 offset:20480
	ds_read_b128 v[206:209], v153 offset:21504
	ds_read_b128 v[210:213], v153 offset:22528
	ds_read_b128 v[214:217], v153 offset:23552
	global_load_lds_dwordx4 v[218:219], off
	s_add_i32 m0, s26, 0x2000
	s_add_u32 s26, s36, 0xb0000
	v_lshl_add_u64 v[220:221], s[36:37], 0, v[134:135]
	s_addc_u32 s27, s37, 0
	s_add_i32 s56, s46, s15
	global_load_lds_dwordx4 v[220:221], off
	v_lshl_add_u64 v[222:223], s[26:27], 0, v[130:131]
	s_mov_b32 m0, s56
	global_load_lds_dwordx4 v[222:223], off
	v_lshl_add_u64 v[222:223], s[26:27], 0, v[134:135]
	s_add_i32 m0, s56, 0x2000
	s_nop 0
	global_load_lds_dwordx4 v[222:223], off
	v_lshl_add_u64 v[222:223], s[38:39], 0, v[128:129]
	s_mov_b32 m0, s33
	s_nop 0
	global_load_lds_dwordx4 v[222:223], off
	v_lshl_add_u64 v[224:225], s[38:39], 0, v[132:133]
	s_mov_b32 m0, s34
	s_nop 0
	global_load_lds_dwordx4 v[224:225], off
	s_waitcnt vmcnt(8)
	s_waitcnt lgkmcnt(0)
	s_barrier
	s_setprio 1
	s_waitcnt lgkmcnt(0)
	v_mfma_f32_16x16x32_bf16 v[60:63], v[144:147], v[184:187], v[60:63]
	v_mfma_f32_16x16x32_bf16 v[56:59], v[160:163], v[184:187], v[56:59]
	v_mfma_f32_16x16x32_bf16 v[44:47], v[144:147], v[192:195], v[44:47]
	v_mfma_f32_16x16x32_bf16 v[40:43], v[160:163], v[192:195], v[40:43]
	v_mfma_f32_16x16x32_bf16 v[28:31], v[144:147], v[200:203], v[28:31]
	v_mfma_f32_16x16x32_bf16 v[24:27], v[160:163], v[200:203], v[24:27]
	v_mfma_f32_16x16x32_bf16 v[12:15], v[144:147], v[210:213], v[12:15]
	v_mfma_f32_16x16x32_bf16 v[8:11], v[160:163], v[210:213], v[8:11]
	v_mfma_f32_16x16x32_bf16 v[60:63], v[156:159], v[188:191], v[60:63]
	v_mfma_f32_16x16x32_bf16 v[56:59], v[164:167], v[188:191], v[56:59]
	v_mfma_f32_16x16x32_bf16 v[44:47], v[156:159], v[196:199], v[44:47]
	v_mfma_f32_16x16x32_bf16 v[40:43], v[164:167], v[196:199], v[40:43]
	v_mfma_f32_16x16x32_bf16 v[28:31], v[156:159], v[206:209], v[28:31]
	v_mfma_f32_16x16x32_bf16 v[24:27], v[164:167], v[206:209], v[24:27]
	v_mfma_f32_16x16x32_bf16 v[12:15], v[156:159], v[214:217], v[12:15]
	v_mfma_f32_16x16x32_bf16 v[8:11], v[164:167], v[214:217], v[8:11]
	s_setprio 0
	s_setprio 1
	v_mfma_f32_16x16x32_bf16 v[52:55], v[168:171], v[184:187], v[52:55]
	v_mfma_f32_16x16x32_bf16 v[48:51], v[176:179], v[184:187], v[48:51]
	v_mfma_f32_16x16x32_bf16 v[36:39], v[168:171], v[192:195], v[36:39]
	v_mfma_f32_16x16x32_bf16 v[32:35], v[176:179], v[192:195], v[32:35]
	v_mfma_f32_16x16x32_bf16 v[20:23], v[168:171], v[200:203], v[20:23]
	v_mfma_f32_16x16x32_bf16 v[16:19], v[176:179], v[200:203], v[16:19]
	v_mfma_f32_16x16x32_bf16 v[4:7], v[168:171], v[210:213], v[4:7]
	v_mfma_f32_16x16x32_bf16 v[0:3], v[176:179], v[210:213], v[0:3]
	v_mfma_f32_16x16x32_bf16 v[52:55], v[172:175], v[188:191], v[52:55]
	v_mfma_f32_16x16x32_bf16 v[48:51], v[180:183], v[188:191], v[48:51]
	v_mfma_f32_16x16x32_bf16 v[36:39], v[172:175], v[196:199], v[36:39]
	v_mfma_f32_16x16x32_bf16 v[32:35], v[180:183], v[196:199], v[32:35]
	v_mfma_f32_16x16x32_bf16 v[20:23], v[172:175], v[206:209], v[20:23]
	v_mfma_f32_16x16x32_bf16 v[16:19], v[180:183], v[206:209], v[16:19]
	v_mfma_f32_16x16x32_bf16 v[4:7], v[172:175], v[214:217], v[4:7]
	v_mfma_f32_16x16x32_bf16 v[0:3], v[180:183], v[214:217], v[0:3]
	s_setprio 0
	s_barrier
; #define PG8_STAGE(bufoff, gbase, voff) do { _Pragma("unroll") for (int _i = 0; _i < 2; ++_i) \
;         __builtin_amdgcn_global_load_lds((const unsigned*)((const char*)(gbase) + (voff)[_i]), (PG8_LAS unsigned*)(lds + (bufoff) + ldsw + _i * 8192), 16, 0, 0); } while (0)
; #define PG8_LDA(dst, b, h) do { _Pragma("unroll") for (int m = 0; m < 4; ++m) _Pragma("unroll") for (int k = 0; k < 2; ++k) dst[m][k] = *(const PG8_LAS bf16x8*)(lds + PG8_SA(b, h) + aoff + m * 2048 + k * 1024); } while (0)
; #define PG8_LDB(dst, b, h) do { _Pragma("unroll") for (int n = 0; n < 2; ++n) _Pragma("unroll") for (int k = 0; k < 2; ++k) dst[n][k] = *(const PG8_LAS bf16x8*)(lds + PG8_SB(b, h) + boff + n * 2048 + k * 1024); } while (0)
; #define PG8_MMA(ai, bj, At, Bt) do { __builtin_amdgcn_s_setprio(1); _Pragma("unroll") for (int m = 0; m < 4; ++m) _Pragma("unroll") for (int n = 0; n < 2; ++n) _Pragma("unroll") for (int k = 0; k < 2; ++k) \
;         acc[ai][bj][m][n] = __builtin_amdgcn_mfma_f32_16x16x32_bf16(Bt[n][k], At[m][k], acc[ai][bj][m][n], 0, 0, 0); __builtin_amdgcn_s_setprio(0); } while (0)
; #define PG8_WAIT_V(n) asm volatile("s_waitcnt vmcnt(" #n ")" ::: "memory")
; #define PG8_WAIT_L(n) asm volatile("s_waitcnt lgkmcnt(" #n ")" ::: "memory")
; #define PG8_BAR __builtin_amdgcn_s_barrier()
; #define PG8_SCHED __builtin_amdgcn_sched_barrier(0)
; template <class Epi, class Sched, bool ALIGN_EPI = false, bool SP2 = false>
; __device__ __forceinline__ void gemm_phase(PG8_LAS unsigned char* lds, const Gemm g, const Sched& S, const Epi& E) {
;     ...
;             PG8_LDB(B0, 1, 0); PG8_LDB(B1, 1, 1); PG8_SCHED; PG8_LDA(At, 1, 0); PG8_STAGE(PG8_SA(0, 1), a2 + hstep, voffA);
;             PG8_WAIT_V(8); PG8_WAIT_L(0); PG8_BAR; PG8_MMA(0, 0, At, B0); PG8_MMA(0, 1, At, B1); PG8_BAR; PG8_SCHED;
	s_add_i32 s56, 0, 0x18000
	v_add_u32_e32 v155, s56, v149
	s_add_i32 s57, 0, 0x1c000
	ds_read_b128 v[144:147], v155
	ds_read_b128 v[156:159], v155 offset:1024
	ds_read_b128 v[160:163], v155 offset:2048
	ds_read_b128 v[164:167], v155 offset:3072
	v_add_u32_e32 v155, s57, v149
	ds_read_b128 v[168:171], v155
	ds_read_b128 v[172:175], v155 offset:1024
	ds_read_b128 v[176:179], v155 offset:2048
	ds_read_b128 v[180:183], v155 offset:3072
	s_add_u32 s26, s38, 0xb0000
	s_addc_u32 s27, s39, 0
	s_mov_b32 m0, s40
	v_lshl_add_u64 v[226:227], s[26:27], 0, v[128:129]
	ds_read_b128 v[184:187], v153 offset:32768
	ds_read_b128 v[188:191], v153 offset:33792
	ds_read_b128 v[192:195], v153 offset:34816
	ds_read_b128 v[196:199], v153 offset:35840
	ds_read_b128 v[200:203], v153 offset:36864
	ds_read_b128 v[206:209], v153 offset:37888
	ds_read_b128 v[210:213], v153 offset:38912
	ds_read_b128 v[214:217], v153 offset:39936
	global_load_lds_dwordx4 v[226:227], off
	v_lshl_add_u64 v[226:227], s[26:27], 0, v[132:133]
	s_mov_b32 m0, s41
	s_nop 0
	global_load_lds_dwordx4 v[226:227], off
	s_waitcnt vmcnt(8)
	s_waitcnt lgkmcnt(0)
	s_barrier
	s_setprio 1
	s_waitcnt lgkmcnt(0)
	v_mfma_f32_16x16x32_bf16 v[124:127], v[144:147], v[184:187], v[124:127]
	v_mfma_f32_16x16x32_bf16 v[120:123], v[160:163], v[184:187], v[120:123]
	v_mfma_f32_16x16x32_bf16 v[108:111], v[144:147], v[192:195], v[108:111]
	v_mfma_f32_16x16x32_bf16 v[104:107], v[160:163], v[192:195], v[104:107]
	v_mfma_f32_16x16x32_bf16 v[92:95], v[144:147], v[200:203], v[92:95]
	v_mfma_f32_16x16x32_bf16 v[88:91], v[160:163], v[200:203], v[88:91]
	v_mfma_f32_16x16x32_bf16 v[76:79], v[144:147], v[210:213], v[76:79]
	v_mfma_f32_16x16x32_bf16 v[72:75], v[160:163], v[210:213], v[72:75]
	v_mfma_f32_16x16x32_bf16 v[124:127], v[156:159], v[188:191], v[124:127]
	v_mfma_f32_16x16x32_bf16 v[120:123], v[164:167], v[188:191], v[120:123]
	v_mfma_f32_16x16x32_bf16 v[108:111], v[156:159], v[196:199], v[108:111]
	v_mfma_f32_16x16x32_bf16 v[104:107], v[164:167], v[196:199], v[104:107]
	v_mfma_f32_16x16x32_bf16 v[92:95], v[156:159], v[206:209], v[92:95]
	v_mfma_f32_16x16x32_bf16 v[88:91], v[164:167], v[206:209], v[88:91]
	v_mfma_f32_16x16x32_bf16 v[76:79], v[156:159], v[214:217], v[76:79]
	v_mfma_f32_16x16x32_bf16 v[72:75], v[164:167], v[214:217], v[72:75]
	s_setprio 0
	s_setprio 1
	v_mfma_f32_16x16x32_bf16 v[116:119], v[168:171], v[184:187], v[116:119]
	v_mfma_f32_16x16x32_bf16 v[112:115], v[176:179], v[184:187], v[112:115]
	v_mfma_f32_16x16x32_bf16 v[100:103], v[168:171], v[192:195], v[100:103]
	v_mfma_f32_16x16x32_bf16 v[96:99], v[176:179], v[192:195], v[96:99]
	v_mfma_f32_16x16x32_bf16 v[84:87], v[168:171], v[200:203], v[84:87]
	v_mfma_f32_16x16x32_bf16 v[80:83], v[176:179], v[200:203], v[80:83]
	v_mfma_f32_16x16x32_bf16 v[68:71], v[168:171], v[210:213], v[68:71]
	v_mfma_f32_16x16x32_bf16 v[64:67], v[176:179], v[210:213], v[64:67]
	v_mfma_f32_16x16x32_bf16 v[116:119], v[172:175], v[188:191], v[116:119]
	v_mfma_f32_16x16x32_bf16 v[112:115], v[180:183], v[188:191], v[112:115]
	v_mfma_f32_16x16x32_bf16 v[100:103], v[172:175], v[196:199], v[100:103]
	v_mfma_f32_16x16x32_bf16 v[96:99], v[180:183], v[196:199], v[96:99]
	v_mfma_f32_16x16x32_bf16 v[84:87], v[172:175], v[206:209], v[84:87]
	v_mfma_f32_16x16x32_bf16 v[80:83], v[180:183], v[206:209], v[80:83]
	v_mfma_f32_16x16x32_bf16 v[68:71], v[172:175], v[214:217], v[68:71]
	v_mfma_f32_16x16x32_bf16 v[64:67], v[180:183], v[214:217], v[64:67]
	s_setprio 0
	s_barrier
; #define PG8_STAGE(bufoff, gbase, voff) do { _Pragma("unroll") for (int _i = 0; _i < 2; ++_i) \
;         __builtin_amdgcn_global_load_lds((const unsigned*)((const char*)(gbase) + (voff)[_i]), (PG8_LAS unsigned*)(lds + (bufoff) + ldsw + _i * 8192), 16, 0, 0); } while (0)
; #define PG8_LDA(dst, b, h) do { _Pragma("unroll") for (int m = 0; m < 4; ++m) _Pragma("unroll") for (int k = 0; k < 2; ++k) dst[m][k] = *(const PG8_LAS bf16x8*)(lds + PG8_SA(b, h) + aoff + m * 2048 + k * 1024); } while (0)
; #define PG8_MMA(ai, bj, At, Bt) do { __builtin_amdgcn_s_setprio(1); _Pragma("unroll") for (int m = 0; m < 4; ++m) _Pragma("unroll") for (int n = 0; n < 2; ++n) _Pragma("unroll") for (int k = 0; k < 2; ++k) \
;         acc[ai][bj][m][n] = __builtin_amdgcn_mfma_f32_16x16x32_bf16(Bt[n][k], At[m][k], acc[ai][bj][m][n], 0, 0, 0); __builtin_amdgcn_s_setprio(0); } while (0)
; #define PG8_WAIT_V(n) asm volatile("s_waitcnt vmcnt(" #n ")" ::: "memory")
; #define PG8_WAIT_L(n) asm volatile("s_waitcnt lgkmcnt(" #n ")" ::: "memory")
; #define PG8_BAR __builtin_amdgcn_s_barrier()
; #define PG8_SCHED __builtin_amdgcn_sched_barrier(0)
; template <class Epi, class Sched, bool ALIGN_EPI = false, bool SP2 = false>
; __device__ __forceinline__ void gemm_phase(PG8_LAS unsigned char* lds, const Gemm g, const Sched& S, const Epi& E) {
;     ...
;             PG8_LDA(At, 1, 1); PG8_STAGE(PG8_SB(1, 0), b3, voffB); PG8_STAGE(PG8_SB(1, 1), b3 + hstep, voffB); PG8_STAGE(PG8_SA(1, 0), a3, voffA);
;             PG8_WAIT_V(8); PG8_WAIT_L(0); PG8_BAR; PG8_MMA(1, 0, At, B0); PG8_MMA(1, 1, At, B1); PG8_BAR; PG8_SCHED;
	s_add_i32 s26, s56, s15
	v_lshl_add_u64 v[218:219], v[218:219], 0, s[12:13]
	s_mov_b32 m0, s26
	ds_read_b128 v[184:187], v153 offset:49152
	ds_read_b128 v[188:191], v153 offset:50176
	ds_read_b128 v[192:195], v153 offset:51200
	ds_read_b128 v[196:199], v153 offset:52224
	ds_read_b128 v[200:203], v153 offset:53248
	ds_read_b128 v[206:209], v153 offset:54272
	ds_read_b128 v[210:213], v153 offset:55296
	ds_read_b128 v[214:217], v153 offset:56320
	global_load_lds_dwordx4 v[218:219], off
	s_add_i32 m0, s26, 0x2000
	s_add_u32 s26, s36, 0xb0080
	v_lshl_add_u64 v[218:219], v[220:221], 0, s[12:13]
	s_addc_u32 s27, s37, 0
	s_add_i32 s36, s57, s15
	global_load_lds_dwordx4 v[218:219], off
	v_lshl_add_u64 v[218:219], s[26:27], 0, v[130:131]
	s_mov_b32 m0, s36
	s_nop 0
	global_load_lds_dwordx4 v[218:219], off
	v_lshl_add_u64 v[218:219], s[26:27], 0, v[134:135]
	s_add_i32 m0, s36, 0x2000
	s_nop 0
	global_load_lds_dwordx4 v[218:219], off
	v_lshl_add_u64 v[218:219], v[222:223], 0, s[12:13]
	s_mov_b32 m0, s43
	s_nop 0
	global_load_lds_dwordx4 v[218:219], off
	v_lshl_add_u64 v[218:219], v[224:225], 0, s[12:13]
	s_mov_b32 m0, s44
	s_nop 0
	global_load_lds_dwordx4 v[218:219], off
	s_waitcnt vmcnt(8)
	s_waitcnt lgkmcnt(0)
	s_barrier
	s_setprio 1
	s_waitcnt lgkmcnt(0)
	v_mfma_f32_16x16x32_bf16 v[60:63], v[144:147], v[184:187], v[60:63]
	v_mfma_f32_16x16x32_bf16 v[56:59], v[160:163], v[184:187], v[56:59]
	v_mfma_f32_16x16x32_bf16 v[44:47], v[144:147], v[192:195], v[44:47]
	v_mfma_f32_16x16x32_bf16 v[40:43], v[160:163], v[192:195], v[40:43]
	v_mfma_f32_16x16x32_bf16 v[28:31], v[144:147], v[200:203], v[28:31]
	v_mfma_f32_16x16x32_bf16 v[24:27], v[160:163], v[200:203], v[24:27]
	v_mfma_f32_16x16x32_bf16 v[12:15], v[144:147], v[210:213], v[12:15]
	v_mfma_f32_16x16x32_bf16 v[8:11], v[160:163], v[210:213], v[8:11]
	v_mfma_f32_16x16x32_bf16 v[60:63], v[156:159], v[188:191], v[60:63]
	v_mfma_f32_16x16x32_bf16 v[56:59], v[164:167], v[188:191], v[56:59]
	v_mfma_f32_16x16x32_bf16 v[44:47], v[156:159], v[196:199], v[44:47]
	v_mfma_f32_16x16x32_bf16 v[40:43], v[164:167], v[196:199], v[40:43]
	v_mfma_f32_16x16x32_bf16 v[28:31], v[156:159], v[206:209], v[28:31]
	v_mfma_f32_16x16x32_bf16 v[24:27], v[164:167], v[206:209], v[24:27]
	v_mfma_f32_16x16x32_bf16 v[12:15], v[156:159], v[214:217], v[12:15]
	v_mfma_f32_16x16x32_bf16 v[8:11], v[164:167], v[214:217], v[8:11]
	s_setprio 0
	s_setprio 1
	v_mfma_f32_16x16x32_bf16 v[52:55], v[168:171], v[184:187], v[52:55]
	v_mfma_f32_16x16x32_bf16 v[48:51], v[176:179], v[184:187], v[48:51]
	v_mfma_f32_16x16x32_bf16 v[36:39], v[168:171], v[192:195], v[36:39]
	v_mfma_f32_16x16x32_bf16 v[32:35], v[176:179], v[192:195], v[32:35]
	v_mfma_f32_16x16x32_bf16 v[20:23], v[168:171], v[200:203], v[20:23]
	v_mfma_f32_16x16x32_bf16 v[16:19], v[176:179], v[200:203], v[16:19]
	v_mfma_f32_16x16x32_bf16 v[4:7], v[168:171], v[210:213], v[4:7]
	v_mfma_f32_16x16x32_bf16 v[0:3], v[176:179], v[210:213], v[0:3]
	v_mfma_f32_16x16x32_bf16 v[52:55], v[172:175], v[188:191], v[52:55]
	v_mfma_f32_16x16x32_bf16 v[48:51], v[180:183], v[188:191], v[48:51]
	v_mfma_f32_16x16x32_bf16 v[36:39], v[172:175], v[196:199], v[36:39]
	v_mfma_f32_16x16x32_bf16 v[32:35], v[180:183], v[196:199], v[32:35]
	v_mfma_f32_16x16x32_bf16 v[20:23], v[172:175], v[206:209], v[20:23]
	v_mfma_f32_16x16x32_bf16 v[16:19], v[180:183], v[206:209], v[16:19]
	v_mfma_f32_16x16x32_bf16 v[4:7], v[172:175], v[214:217], v[4:7]
	v_mfma_f32_16x16x32_bf16 v[0:3], v[180:183], v[214:217], v[0:3]
	s_setprio 0
	s_barrier
	s_add_i32 s55, s55, 2
	s_add_u32 s53, s53, 0x100
	s_addc_u32 s54, s54, 0
	s_cmp_gt_u32 s55, 41
	s_mov_b64 s[26:27], s[28:29]
	s_cbranch_scc0 .LBB0_1978
	s_and_b64 vcc, exec, s[16:17]
	s_cbranch_vccz .LBB0_1981
	s_barrier
